# first DMA piece of the next stage issued immediately after the mid-step barrier, ahead of the next sub-step's LDS fragment reads
# speedup vs baseline: 1.0116x; 1.0043x over previous
; DI f32x16 mfma(bf16x8 a, bf16x8 b, f32x16 c) { return __builtin_amdgcn_mfma_f32_32x32x16_bf16(a, b, c, 0, 0, 0); }
; template <int BK> DI int swz(int row) { constexpr int CPR = BK / 8; return (row / (16 / CPR)) % CPR; }
; DI void wait_vm0() { asm volatile("s_waitcnt vmcnt(0)" ::: "memory"); }
;   DI void pre(int grow0, int gcol0, int lane, int w, char* lds) { xpass(0, grow0, gcol0, lane, w, lds); }
;     ...
;   for (int kt = 0; kt < nk; ++kt) {
;     char* cur = lds + (kt & 1) * STG; char* nxt = lds + ((kt + 1) & 1) * STG;
;     const bool more = kt + 1 < nk;
;     const bf16_t* An = Ag + (kt + 1) * BK; const bf16_t* Bn = Bg + (kt + 1) * BK;
;     if (!more) epi.pre(row0 + wm * 64, col0 + wn * (32 * NTW), lane, w, lds);
;     bf16x8 fa[2][2], fb[2][NTW];
; #pragma unroll
;     for (int mt = 0; mt < 2; ++mt) { int row = wm * 64 + mt * 32 + l31; fa[0][mt] = *(const bf16x8*)(cur + row * (BK * 2) + ((hh ^ swz<BK>(row)) << 4)); }
; #pragma unroll
;     for (int nt = 0; nt < NTW; ++nt) { int row = wn * (32 * NTW) + nt * 32 + l31; fb[0][nt] = *(const bf16x8*)(cur + ABYTES + row * (BK * 2) + ((hh ^ swz<BK>(row)) << 4)); }
; #pragma unroll
;     for (int kk = 0; kk < NKK; ++kk) {
;       if (kk + 1 < NKK) {
;         const int ch = (kk + 1) * 2 + hh;
; #pragma unroll
;         for (int mt = 0; mt < 2; ++mt) { int row = wm * 64 + mt * 32 + l31; fa[(kk + 1) & 1][mt] = *(const bf16x8*)(cur + row * (BK * 2) + ((ch ^ swz<BK>(row)) << 4)); }
; #pragma unroll
;         for (int nt = 0; nt < NTW; ++nt) { int row = wn * (32 * NTW) + nt * 32 + l31; fb[(kk + 1) & 1][nt] = *(const bf16x8*)(cur + ABYTES + row * (BK * 2) + ((ch ^ swz<BK>(row)) << 4)); }
;       }
;       if (more) {
; #pragma unroll
;         for (int q = 0; q < PPK; ++q) {
;           const int pi = kk * PPK + q;
;           if (pi < NPA) stage_piece<BM, BK>(An, lda, nxt, tid, pi, wv);
;           else if (pi < NP) stage_piece<BN, BK>(Bn, ldb, nxt + ABYTES, tid, pi - NPA, wv);
;         }
;       }
;       __builtin_amdgcn_s_setprio(1);
; #pragma unroll
;       for (int mt = 0; mt < 2; ++mt)
; #pragma unroll
;         for (int nt = 0; nt < NTW; ++nt) acc[mt][nt] = mfma(fa[kk & 1][mt], fb[kk & 1][nt], acc[mt][nt]);
;       __builtin_amdgcn_s_setprio(0);
;       __builtin_amdgcn_sched_barrier(0);
;     }
;     wait_vm0();
;     __syncthreads();
.LBB0_173:
	s_and_b32 s30, s3, 0x10000
	s_xor_b32 s100, s30, 0x10000
	v_add3_u32 v194, s100, v136, v166
	v_add3_u32 v198, s100, v144, v167
	ds_read_b128 v[194:197], v194
	v_add3_u32 v202, s100, v145, v161
	ds_read_b128 v[198:201], v198
	v_add3_u32 v206, s100, v152, v163
	ds_read_b128 v[202:205], v202 offset:32768
	v_add3_u32 v210, s100, v155, v159
	ds_read_b128 v[206:209], v206 offset:32768
	v_add3_u32 v226, s100, v158, v160
	ds_read_b128 v[210:213], v210 offset:32768
	ds_read_b128 v[226:229], v226 offset:32768
	s_waitcnt lgkmcnt(6)
	s_mov_b32 m0, s31
	v_lshl_add_u64 v[232:233], v[214:215], 0, s[28:29]
	v_mfma_f32_32x32x16_bf16 v[114:129], v[170:173], v[178:181], v[114:129]
	global_load_lds_dwordx4 v[232:233], off
	s_add_i32 m0, s31, 0x2000
	v_lshl_add_u64 v[232:233], v[214:215], 0, s[24:25]
	v_mfma_f32_32x32x16_bf16 v[98:113], v[170:173], v[182:185], v[98:113]
	v_mfma_f32_32x32x16_bf16 v[82:97], v[170:173], v[186:189], v[82:97]
	global_load_lds_dwordx4 v[232:233], off
	s_add_i32 m0, s31, 0x4000
	v_lshl_add_u64 v[232:233], v[214:215], 0, s[26:27]
	v_mfma_f32_32x32x16_bf16 v[66:81], v[170:173], v[190:193], v[66:81]
	v_mfma_f32_32x32x16_bf16 v[50:65], v[174:177], v[178:181], v[50:65]
	global_load_lds_dwordx4 v[232:233], off
	s_add_i32 m0, s31, 0x6000
	v_lshl_add_u64 v[232:233], v[214:215], 0, s[38:39]
	v_mfma_f32_32x32x16_bf16 v[34:49], v[174:177], v[182:185], v[34:49]
	v_mfma_f32_32x32x16_bf16 v[18:33], v[174:177], v[186:189], v[18:33]
	global_load_lds_dwordx4 v[232:233], off
	v_mfma_f32_32x32x16_bf16 v[2:17], v[174:177], v[190:193], v[2:17]
	v_add3_u32 v170, s100, v136, v153
	v_add3_u32 v174, s100, v144, v154
	ds_read_b128 v[170:173], v170
	v_add3_u32 v178, s100, v145, v149
	ds_read_b128 v[174:177], v174
	v_add3_u32 v182, s100, v152, v150
	ds_read_b128 v[178:181], v178 offset:32768
	v_add3_u32 v186, s100, v155, v147
	ds_read_b128 v[182:185], v182 offset:32768
	v_add3_u32 v190, s100, v158, v148
	ds_read_b128 v[186:189], v186 offset:32768
	ds_read_b128 v[190:193], v190 offset:32768
	s_waitcnt lgkmcnt(6)
	v_mfma_f32_32x32x16_bf16 v[114:129], v[194:197], v[202:205], v[114:129]
	v_mfma_f32_32x32x16_bf16 v[98:113], v[194:197], v[206:209], v[98:113]
	v_mfma_f32_32x32x16_bf16 v[82:97], v[194:197], v[210:213], v[82:97]
	v_mfma_f32_32x32x16_bf16 v[66:81], v[194:197], v[226:229], v[66:81]
	v_mfma_f32_32x32x16_bf16 v[50:65], v[198:201], v[202:205], v[50:65]
	v_mfma_f32_32x32x16_bf16 v[34:49], v[198:201], v[206:209], v[34:49]
	v_mfma_f32_32x32x16_bf16 v[18:33], v[198:201], v[210:213], v[18:33]
	v_mfma_f32_32x32x16_bf16 v[2:17], v[198:201], v[226:229], v[2:17]
	v_add3_u32 v194, s100, v136, v141
	v_add3_u32 v198, s100, v144, v142
	ds_read_b128 v[194:197], v194
	v_add3_u32 v202, s100, v145, v139
	ds_read_b128 v[198:201], v198
	v_add3_u32 v206, s100, v152, v140
	ds_read_b128 v[202:205], v202 offset:32768
	v_add3_u32 v210, s100, v155, v137
	ds_read_b128 v[206:209], v206 offset:32768
	v_add3_u32 v226, s100, v158, v138
	ds_read_b128 v[210:213], v210 offset:32768
	ds_read_b128 v[226:229], v226 offset:32768
	s_waitcnt lgkmcnt(6)
	v_mfma_f32_32x32x16_bf16 v[114:129], v[170:173], v[178:181], v[114:129]
	v_mfma_f32_32x32x16_bf16 v[98:113], v[170:173], v[182:185], v[98:113]
	v_mfma_f32_32x32x16_bf16 v[82:97], v[170:173], v[186:189], v[82:97]
	v_mfma_f32_32x32x16_bf16 v[66:81], v[170:173], v[190:193], v[66:81]
	v_mfma_f32_32x32x16_bf16 v[50:65], v[174:177], v[178:181], v[50:65]
	v_mfma_f32_32x32x16_bf16 v[34:49], v[174:177], v[182:185], v[34:49]
	v_mfma_f32_32x32x16_bf16 v[18:33], v[174:177], v[186:189], v[18:33]
	v_mfma_f32_32x32x16_bf16 v[2:17], v[174:177], v[190:193], v[2:17]
	s_add_u32 s6, s6, 0x80
	s_addc_u32 s7, s7, 0
	s_add_i32 s3, s3, 0x10000
	s_waitcnt vmcnt(0) lgkmcnt(0)
	s_barrier
	s_cmpk_lg_i32 s6, 0x780
	s_cbranch_scc0 .Lk173_exit
	s_add_i32 s31, s100, s2
	v_lshl_add_u64 v[214:215], v[132:133], 0, s[6:7]
	v_lshl_add_u64 v[230:231], v[130:131], 0, s[6:7]
	s_add_i32 m0, s31, 0x8000
	v_lshl_add_u64 v[232:233], v[230:231], 0, s[28:29]
	v_mfma_f32_32x32x16_bf16 v[114:129], v[194:197], v[202:205], v[114:129]
	global_load_lds_dwordx4 v[232:233], off
	v_add3_u32 v170, s30, v136, v143
	v_add3_u32 v174, s30, v144, v146
	ds_read_b128 v[170:173], v170
	v_add3_u32 v178, s30, v145, v151
	ds_read_b128 v[174:177], v174
	v_add3_u32 v182, s30, v152, v156
	ds_read_b128 v[178:181], v178 offset:32768
	v_add3_u32 v186, s30, v155, v157
	ds_read_b128 v[182:185], v182 offset:32768
	v_add3_u32 v190, s30, v158, v168
	ds_read_b128 v[186:189], v186 offset:32768
	ds_read_b128 v[190:193], v190 offset:32768
	s_add_i32 m0, s31, 0xa000
	v_lshl_add_u64 v[232:233], v[230:231], 0, s[24:25]
	v_mfma_f32_32x32x16_bf16 v[98:113], v[194:197], v[206:209], v[98:113]
	v_mfma_f32_32x32x16_bf16 v[82:97], v[194:197], v[210:213], v[82:97]
	global_load_lds_dwordx4 v[232:233], off
	s_add_i32 m0, s31, 0xc000
	v_lshl_add_u64 v[232:233], v[230:231], 0, s[26:27]
	v_mfma_f32_32x32x16_bf16 v[66:81], v[194:197], v[226:229], v[66:81]
	v_mfma_f32_32x32x16_bf16 v[50:65], v[198:201], v[202:205], v[50:65]
	global_load_lds_dwordx4 v[232:233], off
	s_add_i32 m0, s31, 0xe000
	v_lshl_add_u64 v[232:233], v[230:231], 0, s[38:39]
	v_mfma_f32_32x32x16_bf16 v[34:49], v[198:201], v[206:209], v[34:49]
	v_mfma_f32_32x32x16_bf16 v[18:33], v[198:201], v[210:213], v[18:33]
	global_load_lds_dwordx4 v[232:233], off
	v_mfma_f32_32x32x16_bf16 v[2:17], v[198:201], v[226:229], v[2:17]
	s_branch .LBB0_173
; DI f32x16 mfma(bf16x8 a, bf16x8 b, f32x16 c) { return __builtin_amdgcn_mfma_f32_32x32x16_bf16(a, b, c, 0, 0, 0); }
;     ...
;   for (int kt = 0; kt < nk; ++kt) {
;     char* cur = lds + (kt & 1) * STG; char* nxt = lds + ((kt + 1) & 1) * STG;
;     const bool more = kt + 1 < nk;
;     const bf16_t* An = Ag + (kt + 1) * BK; const bf16_t* Bn = Bg + (kt + 1) * BK;
;     if (!more) epi.pre(row0 + wm * 64, col0 + wn * (32 * NTW), lane, w, lds);
;     bf16x8 fa[2][2], fb[2][NTW];
; #pragma unroll
;     for (int mt = 0; mt < 2; ++mt) { int row = wm * 64 + mt * 32 + l31; fa[0][mt] = *(const bf16x8*)(cur + row * (BK * 2) + ((hh ^ swz<BK>(row)) << 4)); }
; #pragma unroll
;     for (int nt = 0; nt < NTW; ++nt) { int row = wn * (32 * NTW) + nt * 32 + l31; fb[0][nt] = *(const bf16x8*)(cur + ABYTES + row * (BK * 2) + ((hh ^ swz<BK>(row)) << 4)); }
; #pragma unroll
;     for (int kk = 0; kk < NKK; ++kk) {
;       if (kk + 1 < NKK) {
;         const int ch = (kk + 1) * 2 + hh;
; #pragma unroll
;         for (int mt = 0; mt < 2; ++mt) { int row = wm * 64 + mt * 32 + l31; fa[(kk + 1) & 1][mt] = *(const bf16x8*)(cur + row * (BK * 2) + ((ch ^ swz<BK>(row)) << 4)); }
; #pragma unroll
;         for (int nt = 0; nt < NTW; ++nt) { int row = wn * (32 * NTW) + nt * 32 + l31; fb[(kk + 1) & 1][nt] = *(const bf16x8*)(cur + ABYTES + row * (BK * 2) + ((ch ^ swz<BK>(row)) << 4)); }
;       }
;       if (more) {
; #pragma unroll
;         for (int q = 0; q < PPK; ++q) {
;           const int pi = kk * PPK + q;
;           if (pi < NPA) stage_piece<BM, BK>(An, lda, nxt, tid, pi, wv);
;           else if (pi < NP) stage_piece<BN, BK>(Bn, ldb, nxt + ABYTES, tid, pi - NPA, wv);
;         }
;       }
;       __builtin_amdgcn_s_setprio(1);
; #pragma unroll
;       for (int mt = 0; mt < 2; ++mt)
; #pragma unroll
;         for (int nt = 0; nt < NTW; ++nt) acc[mt][nt] = mfma(fa[kk & 1][mt], fb[kk & 1][nt], acc[mt][nt]);
;       __builtin_amdgcn_s_setprio(0);
;       __builtin_amdgcn_sched_barrier(0);
;     }
;     wait_vm0();
;     __syncthreads();
;   DI void xpass(int ps, int grow0, int gcol0, int lane, int w, char* lds) const {
;     char* xs = lds + (ps & 1) * 65536 + __builtin_amdgcn_readfirstlane(w) * 8192;
;     const float* xsrc = Xin + (size_t)(grow0 + (ps >> 1) * 32 + (ps & 1) * 16 + (lane >> 5)) * D_ + gcol0 + (lane & 31) * 4;
; #pragma unroll
;     for (int pc = 0; pc < 8; ++pc)
.Lk173_exit:
	v_add3_u32 v170, s30, v136, v143
	v_add3_u32 v174, s30, v144, v146
	ds_read_b128 v[170:173], v170
	v_add3_u32 v178, s30, v145, v151
	ds_read_b128 v[174:177], v174
	v_add3_u32 v182, s30, v152, v156
	ds_read_b128 v[178:181], v178 offset:32768
	v_add3_u32 v186, s30, v155, v157
	ds_read_b128 v[182:185], v182 offset:32768
	v_add3_u32 v190, s30, v158, v168
	ds_read_b128 v[186:189], v186 offset:32768
	ds_read_b128 v[190:193], v190 offset:32768
	v_mfma_f32_32x32x16_bf16 v[114:129], v[194:197], v[202:205], v[114:129]
	v_mfma_f32_32x32x16_bf16 v[98:113], v[194:197], v[206:209], v[98:113]
	v_mfma_f32_32x32x16_bf16 v[82:97], v[194:197], v[210:213], v[82:97]
	v_mfma_f32_32x32x16_bf16 v[66:81], v[194:197], v[226:229], v[66:81]
	v_mfma_f32_32x32x16_bf16 v[50:65], v[198:201], v[202:205], v[50:65]
	v_mfma_f32_32x32x16_bf16 v[34:49], v[198:201], v[206:209], v[34:49]
	v_mfma_f32_32x32x16_bf16 v[18:33], v[198:201], v[210:213], v[18:33]
	v_mfma_f32_32x32x16_bf16 v[2:17], v[198:201], v[226:229], v[2:17]
	s_waitcnt lgkmcnt(0)
	v_readlane_b32 s3, v253, 9
	v_readlane_b32 s6, v253, 27
	v_readfirstlane_b32 s2, v134
	v_or_b32_e32 v130, s3, v135
	v_add_u32_e32 v130, v130, v169
	v_ashrrev_i32_e32 v131, 31, v130
	v_lshlrev_b64 v[130:131], 12, v[130:131]
	v_add_u32_e32 v132, s6, v164
	v_ashrrev_i32_e32 v133, 31, v132
	v_lshl_add_u64 v[130:131], s[10:11], 0, v[130:131]
	v_lshlrev_b32_e32 v0, 4, v0
	s_lshl_b32 s2, s2, 13
	v_lshl_add_u64 v[130:131], v[132:133], 2, v[130:131]
	v_and_b32_e32 v132, 0x1f0, v0
	v_mov_b32_e32 v133, v1
	v_lshl_add_u64 v[130:131], v[130:131], 0, v[132:133]
	s_mov_b32 m0, s2
	s_mov_b64 s[34:35], 0x2000
	global_load_lds_dwordx4 v[130:131], off
	v_lshl_add_u64 v[132:133], v[130:131], 0, s[34:35]
	s_or_b32 m0, s2, 0x400
	s_mov_b64 s[36:37], 0x4000
	global_load_lds_dwordx4 v[132:133], off
	v_lshl_add_u64 v[132:133], v[130:131], 0, s[36:37]
	s_or_b32 m0, s2, 0x800
	s_mov_b64 s[40:41], 0x6000
	global_load_lds_dwordx4 v[132:133], off
	v_lshl_add_u64 v[132:133], v[130:131], 0, s[40:41]
	s_or_b32 m0, s2, 0xc00
	s_mov_b64 s[44:45], 0x8000
	global_load_lds_dwordx4 v[132:133], off
	v_lshl_add_u64 v[132:133], v[130:131], 0, s[44:45]
	s_or_b32 m0, s2, 0x1000
	s_mov_b64 s[46:47], 0xa000
	global_load_lds_dwordx4 v[132:133], off
	v_lshl_add_u64 v[132:133], v[130:131], 0, s[46:47]
	s_or_b32 m0, s2, 0x1400
	s_mov_b64 s[52:53], 0xc000
	global_load_lds_dwordx4 v[132:133], off
	v_lshl_add_u64 v[132:133], v[130:131], 0, s[52:53]
	s_or_b32 m0, s2, 0x1800
	s_mov_b64 s[54:55], 0xe000
	global_load_lds_dwordx4 v[132:133], off
	v_lshl_add_u64 v[130:131], v[130:131], 0, s[54:55]
	s_or_b32 m0, s2, 0x1c00
	v_add_u32_e32 v0, s30, v136
	global_load_lds_dwordx4 v[130:131], off
	v_add_u32_e32 v134, s30, v144
	v_add_u32_e32 v130, v0, v143
	v_add_u32_e32 v135, v134, v146
	ds_read_b128 v[130:133], v130
	ds_read_b128 v[170:173], v135
	v_add_u32_e32 v135, s30, v145
	v_add_u32_e32 v136, v135, v151
	v_add_u32_e32 v143, s30, v152
	v_add_u32_e32 v144, v143, v156
	ds_read_b128 v[174:177], v136 offset:32768
	ds_read_b128 v[178:181], v144 offset:32768
	v_add_u32_e32 v136, s30, v155
	v_add_u32_e32 v144, v136, v157
	v_add_u32_e32 v164, s30, v158
	v_add_u32_e32 v145, v164, v168
	ds_read_b128 v[182:185], v144 offset:32768
	ds_read_b128 v[186:189], v145 offset:32768
	v_add_u32_e32 v144, v0, v166
	v_add_u32_e32 v145, v134, v167
	ds_read_b128 v[166:169], v144
	ds_read_b128 v[190:193], v145
	v_add_u32_e32 v144, v135, v161
	v_add_u32_e32 v145, v143, v163
	ds_read_b128 v[194:197], v144 offset:32768
	ds_read_b128 v[198:201], v145 offset:32768
	v_add_u32_e32 v144, v136, v159
	v_add_u32_e32 v145, v164, v160
	ds_read_b128 v[156:159], v144 offset:32768
	ds_read_b128 v[202:205], v145 offset:32768
	v_readlane_b32 s7, v253, 28
	s_setprio 1
	s_waitcnt lgkmcnt(0)
	v_mfma_f32_32x32x16_bf16 v[114:129], v[130:133], v[174:177], v[114:129]
	v_mfma_f32_32x32x16_bf16 v[98:113], v[130:133], v[178:181], v[98:113]
	v_mfma_f32_32x32x16_bf16 v[82:97], v[130:133], v[182:185], v[82:97]
	v_mfma_f32_32x32x16_bf16 v[66:81], v[130:133], v[186:189], v[66:81]
	v_mfma_f32_32x32x16_bf16 v[50:65], v[170:173], v[174:177], v[50:65]
	v_mfma_f32_32x32x16_bf16 v[34:49], v[170:173], v[178:181], v[34:49]
	v_mfma_f32_32x32x16_bf16 v[18:33], v[170:173], v[182:185], v[18:33]
	v_mfma_f32_32x32x16_bf16 v[2:17], v[170:173], v[186:189], v[2:17]
	s_setprio 0
	v_add_u32_e32 v130, v0, v153
	v_add_u32_e32 v144, v134, v154
	ds_read_b128 v[130:133], v130
	ds_read_b128 v[152:155], v144
	v_add_u32_e32 v144, v135, v149
	v_add_u32_e32 v145, v143, v150
	ds_read_b128 v[170:173], v144 offset:32768
	ds_read_b128 v[174:177], v145 offset:32768
	v_add_u32_e32 v144, v136, v147
	v_add_u32_e32 v148, v164, v148
	ds_read_b128 v[144:147], v144 offset:32768
	ds_read_b128 v[148:151], v148 offset:32768
	s_setprio 1
	v_mfma_f32_32x32x16_bf16 v[114:129], v[166:169], v[194:197], v[114:129]
	v_mfma_f32_32x32x16_bf16 v[98:113], v[166:169], v[198:201], v[98:113]
	v_mfma_f32_32x32x16_bf16 v[82:97], v[166:169], v[156:159], v[82:97]
	v_mfma_f32_32x32x16_bf16 v[66:81], v[166:169], v[202:205], v[66:81]
	v_mfma_f32_32x32x16_bf16 v[50:65], v[190:193], v[194:197], v[50:65]
	v_mfma_f32_32x32x16_bf16 v[34:49], v[190:193], v[198:201], v[34:49]
	v_mfma_f32_32x32x16_bf16 v[18:33], v[190:193], v[156:159], v[18:33]
	v_mfma_f32_32x32x16_bf16 v[2:17], v[190:193], v[202:205], v[2:17]
	s_setprio 0
	v_add_u32_e32 v0, v0, v141
	v_add_u32_e32 v134, v134, v142
	ds_read_b128 v[156:159], v0
	ds_read_b128 v[166:169], v134
	v_add_u32_e32 v0, v135, v139
	v_add_u32_e32 v134, v143, v140
	ds_read_b128 v[140:143], v0 offset:32768
	ds_read_b128 v[178:181], v134 offset:32768
	v_add_u32_e32 v0, v136, v137
	v_add_u32_e32 v138, v164, v138
	ds_read_b128 v[134:137], v0 offset:32768
	ds_read_b128 v[182:185], v138 offset:32768
	s_setprio 1
	s_waitcnt lgkmcnt(9)
;   DI void xpass(int ps, int grow0, int gcol0, int lane, int w, char* lds) const {
;     char* xs = lds + (ps & 1) * 65536 + __builtin_amdgcn_readfirstlane(w) * 8192;
;     const float* xsrc = Xin + (size_t)(grow0 + (ps >> 1) * 32 + (ps & 1) * 16 + (lane >> 5)) * D_ + gcol0 + (lane & 31) * 4;
; #pragma unroll
;     for (int pc = 0; pc < 8; ++pc)
;       __builtin_amdgcn_global_load_lds((const unsigned*)(xsrc + (size_t)(2 * pc) * D_), (__attribute__((address_space(3))) unsigned*)(xs + pc * 1024), 16, 0, 0);
;   }
;   DI void operator()(f32x16 (&acc)[2][4], int grow0, int gcol0, int lane, int w, char* lds) {
;     float* red = (float*)(lds + 131072); float* stat = (float*)lds;
;     const int l31 = lane & 31, hh = lane >> 5, tid = w * 64 + lane;
;     const int pm = grow0 >> 8, pn = gcol0 >> 8, wn = (gcol0 >> 7) & 1, lrow0 = grow0 & 255;
;     float bia[4], csc[4];
; #pragma unroll
;     for (int nt = 0; nt < 4; ++nt) { int c = gcol0 + nt * 32 + l31; bia[nt] = bias ? bias[c] : 0.f; csc[nt] = cscale ? cscale[c] : 1.f; }
;     float* redw = red + ((wn * 2 + ((lane >> 4) & 1)) * 256 + lrow0 + 4 * hh) * 2;
; #pragma unroll
;     for (int ps = 0; ps < 4; ++ps) {
;       const int mt = ps >> 1;
;       if (ps + 1 < 4) {
;         if (ps >= 1) asm volatile("s_waitcnt lgkmcnt(0)" ::: "memory");
;         xpass(ps + 1, grow0, gcol0, lane, w, lds);
;         if (ps >= 1) asm volatile("s_waitcnt vmcnt(8)" ::: "memory");
;       } else asm volatile("s_waitcnt vmcnt(0)" ::: "memory");
;       const char* xs = lds + (ps & 1) * 65536 + w * 8192;
; #pragma unroll
;       for (int qq = 0; qq < 2; ++qq)
; #pragma unroll
;         for (int e = 0; e < 4; ++e) {
;           const int i = 4 * (2 * (ps & 1) + qq) + e;
;           const float* xr = (const float*)(xs + (8 * qq + 4 * hh + e) * 512) + l31;
;           float s1 = 0.f, s2 = 0.f;
; #pragma unroll
;           for (int nt = 0; nt < 4; ++nt) {
;             float v = (acc[mt][nt][i] + bia[nt]) * csc[nt];
;             float z = ALPHA * xr[nt * 32] + hs * v;
;             acc[mt][nt][i] = z; s1 += z; s2 += z * z;
;           }
;           s1 = row16_sum(s1); s2 = row16_sum(s2);
;           if ((lane & 15) == 0) { f32x2 sv = {s1, s2}; *(f32x2*)(redw + (mt * 32 + (i & 3) + 8 * (i >> 2)) * 2) = sv; }
;         }
	v_mfma_f32_32x32x16_bf16 v[114:129], v[130:133], v[170:173], v[114:129]
	s_waitcnt lgkmcnt(8)
	v_mfma_f32_32x32x16_bf16 v[98:113], v[130:133], v[174:177], v[98:113]
	s_waitcnt lgkmcnt(7)
	v_mfma_f32_32x32x16_bf16 v[82:97], v[130:133], v[144:147], v[82:97]
	s_waitcnt lgkmcnt(6)
	v_mfma_f32_32x32x16_bf16 v[66:81], v[130:133], v[148:151], v[66:81]
	v_mfma_f32_32x32x16_bf16 v[50:65], v[152:155], v[170:173], v[50:65]
	v_mfma_f32_32x32x16_bf16 v[34:49], v[152:155], v[174:177], v[34:49]
	v_mfma_f32_32x32x16_bf16 v[18:33], v[152:155], v[144:147], v[18:33]
	v_mfma_f32_32x32x16_bf16 v[2:17], v[152:155], v[148:151], v[2:17]
	s_setprio 0
	s_setprio 1
	s_waitcnt lgkmcnt(3)
	v_mfma_f32_32x32x16_bf16 v[114:129], v[156:159], v[140:143], v[114:129]
	s_waitcnt lgkmcnt(2)
	v_mfma_f32_32x32x16_bf16 v[98:113], v[156:159], v[178:181], v[98:113]
	s_waitcnt lgkmcnt(1)
	v_mfma_f32_32x32x16_bf16 v[82:97], v[156:159], v[134:137], v[82:97]
	s_waitcnt lgkmcnt(0)
	v_mfma_f32_32x32x16_bf16 v[66:81], v[156:159], v[182:185], v[66:81]
	v_mfma_f32_32x32x16_bf16 v[50:65], v[166:169], v[140:143], v[50:65]
	v_mfma_f32_32x32x16_bf16 v[34:49], v[166:169], v[178:181], v[34:49]
	v_mfma_f32_32x32x16_bf16 v[18:33], v[166:169], v[134:137], v[18:33]
	v_mfma_f32_32x32x16_bf16 v[2:17], v[166:169], v[182:185], v[2:17]
	s_setprio 0
	v_mov_b32_e32 v164, v216
	s_waitcnt vmcnt(0)
	s_barrier
	v_mov_b32_e32 v133, v1
	v_ashrrev_i32_e32 v158, 6, v164
	v_lshrrev_b32_e32 v0, 30, v158
	v_add_u32_e32 v0, v158, v0
	v_ashrrev_i32_e32 v134, 2, v0
	v_mul_i32_i24_e32 v0, 4, v134
	v_sub_u32_e32 v0, v158, v0
	v_lshlrev_b32_e32 v135, 6, v0
	v_add_u32_e32 v163, s3, v135
	v_bfe_u32 v0, v164, 5, 1
	v_or_b32_e32 v159, v163, v0
	v_or_b32_e32 v130, 16, v159
	v_lshlrev_b32_e32 v200, 2, v164
	v_ashrrev_i32_e32 v131, 31, v130
	v_lshl_add_u32 v184, v134, 7, s6
	v_and_b32_e32 v0, 0x7c, v200
	v_lshlrev_b64 v[130:131], 12, v[130:131]
	v_ashrrev_i32_e32 v185, 31, v184
	v_readfirstlane_b32 s2, v158
	v_lshl_add_u64 v[130:131], s[10:11], 0, v[130:131]
	v_lshlrev_b32_e32 v0, 2, v0
	s_lshl_b32 s2, s2, 13
	v_lshl_add_u64 v[130:131], v[184:185], 2, v[130:131]
	v_mov_b32_e32 v132, v0
	s_add_i32 m0, s2, 0x10000
	v_lshl_add_u64 v[130:131], v[130:131], 0, v[132:133]
	global_load_lds_dwordx4 v[130:131], off
	v_lshl_add_u64 v[132:133], v[130:131], 0, s[34:35]
	s_add_i32 m0, s2, 0x10400
	v_and_b32_e32 v210, 0xc0, v135
	global_load_lds_dwordx4 v[132:133], off
	v_lshl_add_u64 v[132:133], v[130:131], 0, s[36:37]
	s_add_i32 m0, s2, 0x10800
	v_mov_b32_e32 v136, v114
	global_load_lds_dwordx4 v[132:133], off
	v_lshl_add_u64 v[132:133], v[130:131], 0, s[40:41]
	s_add_i32 m0, s2, 0x10c00
	v_mov_b32_e32 v137, v82
	global_load_lds_dwordx4 v[132:133], off
	v_lshl_add_u64 v[132:133], v[130:131], 0, s[44:45]
	s_add_i32 m0, s2, 0x11000
	v_mov_b32_e32 v140, v98
	global_load_lds_dwordx4 v[132:133], off
	v_lshl_add_u64 v[132:133], v[130:131], 0, s[46:47]
	s_add_i32 m0, s2, 0x11400
	v_mov_b32_e32 v141, v82
	global_load_lds_dwordx4 v[132:133], off
	v_lshl_add_u64 v[132:133], v[130:131], 0, s[52:53]
	s_add_i32 m0, s2, 0x11800
	v_lshl_add_u64 v[130:131], v[130:131], 0, s[54:55]
	global_load_lds_dwordx4 v[132:133], off
	s_add_i32 m0, s2, 0x11c00
	v_bfe_u32 v132, v164, 4, 1
	global_load_lds_dwordx4 v[130:131], off
	v_and_b32_e32 v130, 31, v164
	v_lshlrev_b32_e32 v131, 1, v134
	v_bfe_u32 v134, v164, 3, 3
	v_and_or_b32 v131, v131, 2, v132
	v_and_b32_e32 v132, 4, v134
	v_lshlrev_b32_e32 v130, 2, v130
	v_lshl_or_b32 v138, v158, 13, v130
	v_lshlrev_b32_e32 v154, 9, v132
	v_or_b32_e32 v133, v210, v132
	v_and_b32_e32 v130, 15, v164
	v_or_b32_e32 v132, v138, v154
	v_lshlrev_b32_e32 v135, 3, v133
	v_lshl_or_b32 v139, v131, 11, v221
	v_cmp_eq_u32_e32 vcc, 0, v130
	s_waitcnt vmcnt(8)
	ds_read2_b32 v[130:131], v132 offset1:32
	ds_read2_b32 v[132:133], v132 offset0:64 offset1:96
	v_pk_add_f32 v[136:137], v[136:137], 0 op_sel_hi:[1,0]
	v_pk_add_f32 v[140:141], v[140:141], 0 op_sel_hi:[1,0]
	s_mov_b32 s2, s67
	s_waitcnt lgkmcnt(0)
	v_mov_b32_e32 v142, v130
	v_mov_b32_e32 v143, v132
	v_mov_b32_e32 v130, v131
	v_mov_b32_e32 v131, v132
	v_pk_fma_f32 v[186:187], v[142:143], s[2:3], v[136:137] op_sel_hi:[1,0,1]
	v_pk_fma_f32 v[188:189], v[130:131], s[2:3], v[140:141] op_sel_hi:[1,0,1]
	v_pk_mul_f32 v[144:145], v[142:143], s[2:3] op_sel_hi:[1,0]
	v_pk_mul_f32 v[142:143], v[186:187], v[186:187]
	v_pk_mul_f32 v[130:131], v[188:189], v[188:189]
	v_pk_mov_b32 v[136:137], v[136:137], v[142:143] op_sel:[1,0]
	v_pk_mov_b32 v[130:131], v[144:145], v[130:131] op_sel:[1,0]
	v_add_f32_e32 v180, 0, v66
	v_pk_add_f32 v[130:131], v[136:137], v[130:131]
	v_pk_add_f32 v[136:137], v[186:187], v[188:189]
	v_pk_mul_f32 v[140:141], v[186:187], v[188:189]
	v_fmac_f32_e32 v180, 0x3fd744fd, v133
	v_mov_b32_e32 v137, v141
	v_pk_add_f32 v[130:131], v[136:137], v[130:131]
	v_mul_f32_e32 v181, v180, v180
	v_pk_add_f32 v[130:131], v[130:131], v[180:181]
	v_add_u32_e32 v181, v139, v135
	s_nop 0
	v_mov_b32_dpp v132, v130 quad_perm:[1,0,3,2] row_mask:0xf bank_mask:0xf bound_ctrl:1
	v_mov_b32_dpp v133, v131 quad_perm:[1,0,3,2] row_mask:0xf bank_mask:0xf bound_ctrl:1
	v_pk_add_f32 v[130:131], v[130:131], v[132:133]
	s_nop 1
	v_mov_b32_dpp v132, v130 quad_perm:[2,3,0,1] row_mask:0xf bank_mask:0xf bound_ctrl:1
	v_mov_b32_dpp v133, v131 quad_perm:[2,3,0,1] row_mask:0xf bank_mask:0xf bound_ctrl:1
	v_pk_add_f32 v[130:131], v[130:131], v[132:133]
	s_nop 1
	v_mov_b32_dpp v132, v130 row_half_mirror row_mask:0xf bank_mask:0xf bound_ctrl:1
	v_mov_b32_dpp v133, v131 row_half_mirror row_mask:0xf bank_mask:0xf bound_ctrl:1
	v_pk_add_f32 v[130:131], v[130:131], v[132:133]
	s_nop 1
	v_mov_b32_dpp v132, v130 row_mirror row_mask:0xf bank_mask:0xf bound_ctrl:1
	v_mov_b32_dpp v133, v131 row_mirror row_mask:0xf bank_mask:0xf bound_ctrl:1
	s_and_saveexec_b64 s[6:7], vcc
	v_pk_add_f32 v[130:131], v[130:131], v[132:133]
	ds_write_b64 v181, v[130:131]
	s_or_b64 exec, exec, s[6:7]
	v_add_u32_e32 v168, v138, v154
	ds_read2_b32 v[130:131], v168 offset0:128 offset1:160
	ds_read2_b32 v[132:133], v168 offset0:192 offset1:224
	v_mov_b32_e32 v82, v115
	v_add_f32_e32 v152, 0, v67
	v_pk_add_f32 v[66:67], v[82:83], 0 op_sel_hi:[1,0]
	v_mov_b32_e32 v82, v99
	v_pk_add_f32 v[82:83], v[82:83], 0 op_sel_hi:[1,0]
	s_waitcnt lgkmcnt(1)
;   DI void operator()(f32x16 (&acc)[2][4], int grow0, int gcol0, int lane, int w, char* lds) {
;     ...
;         for (int e = 0; e < 4; ++e) {
;           const int i = 4 * (2 * (ps & 1) + qq) + e;
;           const float* xr = (const float*)(xs + (8 * qq + 4 * hh + e) * 512) + l31;
;           float s1 = 0.f, s2 = 0.f;
; #pragma unroll
;           for (int nt = 0; nt < 4; ++nt) {
;             float v = (acc[mt][nt][i] + bia[nt]) * csc[nt];
;             float z = ALPHA * xr[nt * 32] + hs * v;
;             acc[mt][nt][i] = z; s1 += z; s2 += z * z;
;           }
;           s1 = row16_sum(s1); s2 = row16_sum(s2);
;           if ((lane & 15) == 0) { f32x2 sv = {s1, s2}; *(f32x2*)(redw + (mt * 32 + (i & 3) + 8 * (i >> 2)) * 2) = sv; }
	v_mov_b32_e32 v98, v130
	s_waitcnt lgkmcnt(0)
	v_mov_b32_e32 v99, v132
	s_mov_b32 s2, s67
	v_mov_b32_e32 v130, v131
	v_mov_b32_e32 v131, v132
	v_pk_fma_f32 v[166:167], v[98:99], s[2:3], v[66:67] op_sel_hi:[1,0,1]
	v_pk_fma_f32 v[172:173], v[130:131], s[2:3], v[82:83] op_sel_hi:[1,0,1]
	v_pk_mul_f32 v[114:115], v[98:99], s[2:3] op_sel_hi:[1,0]
	v_pk_mul_f32 v[98:99], v[166:167], v[166:167]
	v_pk_mul_f32 v[82:83], v[172:173], v[172:173]
	v_pk_mov_b32 v[66:67], v[66:67], v[98:99] op_sel:[1,0]
	v_pk_mov_b32 v[82:83], v[114:115], v[82:83] op_sel:[1,0]
	v_pk_mul_f32 v[98:99], v[166:167], v[172:173]
	v_pk_add_f32 v[66:67], v[66:67], v[82:83]
	v_pk_add_f32 v[82:83], v[166:167], v[172:173]
	v_fmac_f32_e32 v152, 0x3fd744fd, v133
	v_mov_b32_e32 v83, v99
	v_pk_add_f32 v[66:67], v[82:83], v[66:67]
	v_mul_f32_e32 v153, v152, v152
	v_pk_add_f32 v[66:67], v[66:67], v[152:153]
	s_nop 1
	v_mov_b32_dpp v82, v66 quad_perm:[1,0,3,2] row_mask:0xf bank_mask:0xf bound_ctrl:1
	v_mov_b32_dpp v83, v67 quad_perm:[1,0,3,2] row_mask:0xf bank_mask:0xf bound_ctrl:1
	v_pk_add_f32 v[66:67], v[66:67], v[82:83]
	s_nop 1
	v_mov_b32_dpp v82, v66 quad_perm:[2,3,0,1] row_mask:0xf bank_mask:0xf bound_ctrl:1
	v_mov_b32_dpp v83, v67 quad_perm:[2,3,0,1] row_mask:0xf bank_mask:0xf bound_ctrl:1
	v_pk_add_f32 v[66:67], v[66:67], v[82:83]
	s_nop 1
	v_mov_b32_dpp v82, v66 row_half_mirror row_mask:0xf bank_mask:0xf bound_ctrl:1
	v_mov_b32_dpp v83, v67 row_half_mirror row_mask:0xf bank_mask:0xf bound_ctrl:1
	v_pk_add_f32 v[66:67], v[66:67], v[82:83]
	s_nop 1
	v_mov_b32_dpp v82, v66 row_mirror row_mask:0xf bank_mask:0xf bound_ctrl:1
	v_mov_b32_dpp v83, v67 row_mirror row_mask:0xf bank_mask:0xf bound_ctrl:1
	s_and_saveexec_b64 s[6:7], vcc
	v_pk_add_f32 v[66:67], v[66:67], v[82:83]
	ds_write_b64 v181, v[66:67] offset:8
	s_or_b64 exec, exec, s[6:7]
	v_add_u32_e32 v153, 0x400, v168
	ds_read2_b32 v[82:83], v153 offset1:32
	ds_read2_b32 v[98:99], v153 offset0:64 offset1:96
	v_mov_b32_e32 v114, v116
	v_mov_b32_e32 v115, v84
	v_mov_b32_e32 v130, v100
	v_mov_b32_e32 v131, v84
	v_pk_add_f32 v[114:115], v[114:115], 0 op_sel_hi:[1,0]
	v_pk_add_f32 v[130:131], v[130:131], 0 op_sel_hi:[1,0]
	s_waitcnt lgkmcnt(1)
	v_mov_b32_e32 v132, v82
	s_waitcnt lgkmcnt(0)
	v_mov_b32_e32 v133, v98
	s_mov_b32 s2, s67
	v_mov_b32_e32 v140, v83
	v_mov_b32_e32 v141, v98
	v_pk_fma_f32 v[82:83], v[132:133], s[2:3], v[114:115] op_sel_hi:[1,0,1]
	v_pk_fma_f32 v[150:151], v[140:141], s[2:3], v[130:131] op_sel_hi:[1,0,1]
	v_pk_mul_f32 v[136:137], v[132:133], s[2:3] op_sel_hi:[1,0]
	v_pk_mul_f32 v[132:133], v[82:83], v[82:83]
	v_pk_mul_f32 v[130:131], v[150:151], v[150:151]
	v_pk_mov_b32 v[114:115], v[114:115], v[132:133] op_sel:[1,0]
	v_pk_mov_b32 v[130:131], v[136:137], v[130:131] op_sel:[1,0]
	v_add_f32_e32 v66, 0, v68
	v_pk_add_f32 v[114:115], v[114:115], v[130:131]
	v_pk_add_f32 v[130:131], v[82:83], v[150:151]
	v_pk_mul_f32 v[132:133], v[82:83], v[150:151]
	v_fmac_f32_e32 v66, 0x3fd744fd, v99
	v_mov_b32_e32 v131, v133
	v_pk_add_f32 v[114:115], v[130:131], v[114:115]
	v_mul_f32_e32 v67, v66, v66
	v_pk_add_f32 v[98:99], v[114:115], v[66:67]
	s_nop 1
	v_mov_b32_dpp v114, v98 quad_perm:[1,0,3,2] row_mask:0xf bank_mask:0xf bound_ctrl:1
	v_mov_b32_dpp v115, v99 quad_perm:[1,0,3,2] row_mask:0xf bank_mask:0xf bound_ctrl:1
	v_pk_add_f32 v[98:99], v[98:99], v[114:115]
	s_nop 1
	v_mov_b32_dpp v114, v98 quad_perm:[2,3,0,1] row_mask:0xf bank_mask:0xf bound_ctrl:1
	v_mov_b32_dpp v115, v99 quad_perm:[2,3,0,1] row_mask:0xf bank_mask:0xf bound_ctrl:1
	v_pk_add_f32 v[98:99], v[98:99], v[114:115]
	s_nop 1
	v_mov_b32_dpp v114, v98 row_half_mirror row_mask:0xf bank_mask:0xf bound_ctrl:1
	v_mov_b32_dpp v115, v99 row_half_mirror row_mask:0xf bank_mask:0xf bound_ctrl:1
	v_pk_add_f32 v[98:99], v[98:99], v[114:115]
	s_nop 1
	v_mov_b32_dpp v114, v98 row_mirror row_mask:0xf bank_mask:0xf bound_ctrl:1
	v_mov_b32_dpp v115, v99 row_mirror row_mask:0xf bank_mask:0xf bound_ctrl:1
	s_and_saveexec_b64 s[6:7], vcc
	v_pk_add_f32 v[98:99], v[98:99], v[114:115]
	ds_write_b64 v181, v[98:99] offset:16
	s_or_b64 exec, exec, s[6:7]
	v_lshlrev_b32_e32 v139, 9, v134
	v_or_b32_e32 v146, 0x600, v139
	v_add_u32_e32 v151, v138, v146
	ds_read2_b32 v[98:99], v151 offset1:32
	ds_read2_b32 v[114:115], v151 offset0:64 offset1:96
	v_mov_b32_e32 v84, v117
	v_pk_add_f32 v[116:117], v[84:85], 0 op_sel_hi:[1,0]
	v_mov_b32_e32 v84, v101
	v_pk_add_f32 v[84:85], v[84:85], 0 op_sel_hi:[1,0]
	s_waitcnt lgkmcnt(1)
	v_mov_b32_e32 v100, v98
	s_waitcnt lgkmcnt(0)
	v_mov_b32_e32 v101, v114
	s_mov_b32 s2, s67
	v_mov_b32_e32 v132, v99
	v_mov_b32_e32 v133, v114
	v_pk_mul_f32 v[130:131], v[100:101], s[2:3] op_sel_hi:[1,0]
	v_pk_fma_f32 v[98:99], v[100:101], s[2:3], v[116:117] op_sel_hi:[1,0,1]
	v_pk_fma_f32 v[100:101], v[132:133], s[2:3], v[84:85] op_sel_hi:[1,0,1]
	v_pk_mul_f32 v[134:135], v[98:99], v[98:99]
	v_pk_mul_f32 v[84:85], v[100:101], v[100:101]
	v_pk_mov_b32 v[116:117], v[116:117], v[134:135] op_sel:[1,0]
	v_pk_mov_b32 v[84:85], v[130:131], v[84:85] op_sel:[1,0]
	v_add_f32_e32 v68, 0, v69
	v_pk_add_f32 v[84:85], v[116:117], v[84:85]
	v_pk_add_f32 v[116:117], v[98:99], v[100:101]
	v_pk_mul_f32 v[130:131], v[98:99], v[100:101]
	v_fmac_f32_e32 v68, 0x3fd744fd, v115
	v_mov_b32_e32 v117, v131
	v_pk_add_f32 v[84:85], v[116:117], v[84:85]
	v_mul_f32_e32 v69, v68, v68
	v_pk_add_f32 v[84:85], v[84:85], v[68:69]
	s_nop 1
	v_mov_b32_dpp v114, v84 quad_perm:[1,0,3,2] row_mask:0xf bank_mask:0xf bound_ctrl:1
	v_mov_b32_dpp v115, v85 quad_perm:[1,0,3,2] row_mask:0xf bank_mask:0xf bound_ctrl:1
	v_pk_add_f32 v[84:85], v[84:85], v[114:115]
	s_nop 1
	v_mov_b32_dpp v114, v84 quad_perm:[2,3,0,1] row_mask:0xf bank_mask:0xf bound_ctrl:1
	v_mov_b32_dpp v115, v85 quad_perm:[2,3,0,1] row_mask:0xf bank_mask:0xf bound_ctrl:1
	v_pk_add_f32 v[84:85], v[84:85], v[114:115]
	s_nop 1
	v_mov_b32_dpp v114, v84 row_half_mirror row_mask:0xf bank_mask:0xf bound_ctrl:1
	v_mov_b32_dpp v115, v85 row_half_mirror row_mask:0xf bank_mask:0xf bound_ctrl:1
	v_pk_add_f32 v[84:85], v[84:85], v[114:115]
	s_nop 1
	v_mov_b32_dpp v114, v84 row_mirror row_mask:0xf bank_mask:0xf bound_ctrl:1
	v_mov_b32_dpp v115, v85 row_mirror row_mask:0xf bank_mask:0xf bound_ctrl:1
	s_and_saveexec_b64 s[6:7], vcc
	v_pk_add_f32 v[84:85], v[84:85], v[114:115]
	ds_write_b64 v181, v[84:85] offset:24
	s_or_b64 exec, exec, s[6:7]
	v_add_u32_e32 v67, 0x1000, v168
	ds_read2_b32 v[114:115], v67 offset1:32
	ds_read2_b32 v[130:131], v67 offset0:64 offset1:96
	v_mov_b32_e32 v116, v118
	v_mov_b32_e32 v117, v86
	v_pk_add_f32 v[132:133], v[116:117], 0 op_sel_hi:[1,0]
	v_mov_b32_e32 v116, v102
	v_pk_add_f32 v[116:117], v[116:117], 0 op_sel_hi:[1,0]
	s_waitcnt lgkmcnt(1)
;   DI void operator()(f32x16 (&acc)[2][4], int grow0, int gcol0, int lane, int w, char* lds) {
;     ...
;         for (int e = 0; e < 4; ++e) {
;           const int i = 4 * (2 * (ps & 1) + qq) + e;
;           const float* xr = (const float*)(xs + (8 * qq + 4 * hh + e) * 512) + l31;
;           float s1 = 0.f, s2 = 0.f;
; #pragma unroll
;           for (int nt = 0; nt < 4; ++nt) {
;             float v = (acc[mt][nt][i] + bia[nt]) * csc[nt];
;             float z = ALPHA * xr[nt * 32] + hs * v;
;             acc[mt][nt][i] = z; s1 += z; s2 += z * z;
;           }
;           s1 = row16_sum(s1); s2 = row16_sum(s2);
;           if ((lane & 15) == 0) { f32x2 sv = {s1, s2}; *(f32x2*)(redw + (mt * 32 + (i & 3) + 8 * (i >> 2)) * 2) = sv; }
	v_mov_b32_e32 v134, v114
	s_waitcnt lgkmcnt(0)
	v_mov_b32_e32 v135, v130
	s_mov_b32 s2, s67
	v_mov_b32_e32 v140, v115
	v_mov_b32_e32 v141, v130
	v_pk_fma_f32 v[114:115], v[134:135], s[2:3], v[132:133] op_sel_hi:[1,0,1]
	v_pk_fma_f32 v[116:117], v[140:141], s[2:3], v[116:117] op_sel_hi:[1,0,1]
	v_pk_mul_f32 v[136:137], v[134:135], s[2:3] op_sel_hi:[1,0]
	v_pk_mul_f32 v[134:135], v[114:115], v[114:115]
	v_pk_mul_f32 v[140:141], v[116:117], v[116:117]
	v_pk_mov_b32 v[132:133], v[132:133], v[134:135] op_sel:[1,0]
	v_pk_mov_b32 v[134:135], v[136:137], v[140:141] op_sel:[1,0]
	v_add_f32_e32 v84, 0, v70
	v_pk_add_f32 v[132:133], v[132:133], v[134:135]
	v_pk_add_f32 v[134:135], v[114:115], v[116:117]
	v_pk_mul_f32 v[136:137], v[114:115], v[116:117]
	v_fmac_f32_e32 v84, 0x3fd744fd, v131
	v_mov_b32_e32 v135, v137
	v_pk_add_f32 v[132:133], v[134:135], v[132:133]
	v_mul_f32_e32 v85, v84, v84
	v_pk_add_f32 v[130:131], v[132:133], v[84:85]
	s_nop 1
	v_mov_b32_dpp v132, v130 quad_perm:[1,0,3,2] row_mask:0xf bank_mask:0xf bound_ctrl:1
	v_mov_b32_dpp v133, v131 quad_perm:[1,0,3,2] row_mask:0xf bank_mask:0xf bound_ctrl:1
	v_pk_add_f32 v[130:131], v[130:131], v[132:133]
	s_nop 1
	v_mov_b32_dpp v132, v130 quad_perm:[2,3,0,1] row_mask:0xf bank_mask:0xf bound_ctrl:1
	v_mov_b32_dpp v133, v131 quad_perm:[2,3,0,1] row_mask:0xf bank_mask:0xf bound_ctrl:1
	v_pk_add_f32 v[130:131], v[130:131], v[132:133]
	s_nop 1
	v_mov_b32_dpp v132, v130 row_half_mirror row_mask:0xf bank_mask:0xf bound_ctrl:1
	v_mov_b32_dpp v133, v131 row_half_mirror row_mask:0xf bank_mask:0xf bound_ctrl:1
	v_pk_add_f32 v[130:131], v[130:131], v[132:133]
	s_nop 1
	v_mov_b32_dpp v132, v130 row_mirror row_mask:0xf bank_mask:0xf bound_ctrl:1
	v_mov_b32_dpp v133, v131 row_mirror row_mask:0xf bank_mask:0xf bound_ctrl:1
	s_and_saveexec_b64 s[6:7], vcc
	v_pk_add_f32 v[130:131], v[130:131], v[132:133]
	ds_write_b64 v181, v[130:131] offset:64
	s_or_b64 exec, exec, s[6:7]
	ds_read2_b32 v[130:131], v67 offset0:128 offset1:160
	ds_read2_b32 v[132:133], v67 offset0:192 offset1:224
	v_mov_b32_e32 v86, v119
	v_pk_add_f32 v[134:135], v[86:87], 0 op_sel_hi:[1,0]
	v_mov_b32_e32 v86, v103
	v_pk_add_f32 v[86:87], v[86:87], 0 op_sel_hi:[1,0]
	s_waitcnt lgkmcnt(1)
	v_mov_b32_e32 v102, v130
	s_waitcnt lgkmcnt(0)
	v_mov_b32_e32 v103, v132
	s_mov_b32 s2, s67
	v_mov_b32_e32 v118, v131
	v_mov_b32_e32 v119, v132
	v_pk_mul_f32 v[136:137], v[102:103], s[2:3] op_sel_hi:[1,0]
	v_pk_fma_f32 v[102:103], v[102:103], s[2:3], v[134:135] op_sel_hi:[1,0,1]
	v_pk_fma_f32 v[118:119], v[118:119], s[2:3], v[86:87] op_sel_hi:[1,0,1]
	v_pk_mul_f32 v[130:131], v[102:103], v[102:103]
	v_pk_mul_f32 v[86:87], v[118:119], v[118:119]
	v_pk_mov_b32 v[130:131], v[134:135], v[130:131] op_sel:[1,0]
	v_pk_mov_b32 v[86:87], v[136:137], v[86:87] op_sel:[1,0]
	v_add_f32_e32 v70, 0, v71
	v_pk_add_f32 v[86:87], v[130:131], v[86:87]
	v_pk_add_f32 v[130:131], v[102:103], v[118:119]
	v_pk_mul_f32 v[134:135], v[102:103], v[118:119]
	v_fmac_f32_e32 v70, 0x3fd744fd, v133
	v_mov_b32_e32 v131, v135
	v_pk_add_f32 v[86:87], v[130:131], v[86:87]
	v_mul_f32_e32 v71, v70, v70
	v_pk_add_f32 v[86:87], v[86:87], v[70:71]
	s_nop 1
	v_mov_b32_dpp v130, v86 quad_perm:[1,0,3,2] row_mask:0xf bank_mask:0xf bound_ctrl:1
	v_mov_b32_dpp v131, v87 quad_perm:[1,0,3,2] row_mask:0xf bank_mask:0xf bound_ctrl:1
	v_pk_add_f32 v[86:87], v[86:87], v[130:131]
	s_nop 1
	v_mov_b32_dpp v130, v86 quad_perm:[2,3,0,1] row_mask:0xf bank_mask:0xf bound_ctrl:1
	v_mov_b32_dpp v131, v87 quad_perm:[2,3,0,1] row_mask:0xf bank_mask:0xf bound_ctrl:1
	v_pk_add_f32 v[86:87], v[86:87], v[130:131]
	s_nop 1
	v_mov_b32_dpp v130, v86 row_half_mirror row_mask:0xf bank_mask:0xf bound_ctrl:1
	v_mov_b32_dpp v131, v87 row_half_mirror row_mask:0xf bank_mask:0xf bound_ctrl:1
	v_pk_add_f32 v[86:87], v[86:87], v[130:131]
	s_nop 1
	v_mov_b32_dpp v130, v86 row_mirror row_mask:0xf bank_mask:0xf bound_ctrl:1
	v_mov_b32_dpp v131, v87 row_mirror row_mask:0xf bank_mask:0xf bound_ctrl:1
	s_and_saveexec_b64 s[6:7], vcc
	v_pk_add_f32 v[86:87], v[86:87], v[130:131]
	ds_write_b64 v181, v[86:87] offset:72
	s_or_b64 exec, exec, s[6:7]
	v_add_u32_e32 v69, 0x1400, v168
	ds_read2_b32 v[130:131], v69 offset1:32
	ds_read2_b32 v[134:135], v69 offset0:64 offset1:96
	v_mov_b32_e32 v132, v120
	v_mov_b32_e32 v133, v88
	v_pk_add_f32 v[136:137], v[132:133], 0 op_sel_hi:[1,0]
	v_mov_b32_e32 v132, v104
	v_pk_add_f32 v[132:133], v[132:133], 0 op_sel_hi:[1,0]
	s_waitcnt lgkmcnt(1)
	v_mov_b32_e32 v140, v130
	s_waitcnt lgkmcnt(0)
	v_mov_b32_e32 v141, v134
	s_mov_b32 s2, s67
	v_mov_b32_e32 v144, v131
	v_mov_b32_e32 v145, v134
	v_pk_fma_f32 v[130:131], v[140:141], s[2:3], v[136:137] op_sel_hi:[1,0,1]
	v_pk_fma_f32 v[132:133], v[144:145], s[2:3], v[132:133] op_sel_hi:[1,0,1]
	v_pk_mul_f32 v[142:143], v[140:141], s[2:3] op_sel_hi:[1,0]
	v_pk_mul_f32 v[140:141], v[130:131], v[130:131]
	v_pk_mul_f32 v[144:145], v[132:133], v[132:133]
	v_pk_mov_b32 v[136:137], v[136:137], v[140:141] op_sel:[1,0]
	v_pk_mov_b32 v[140:141], v[142:143], v[144:145] op_sel:[1,0]
	v_add_f32_e32 v86, 0, v72
	v_pk_add_f32 v[136:137], v[136:137], v[140:141]
	v_pk_add_f32 v[140:141], v[130:131], v[132:133]
	v_pk_mul_f32 v[142:143], v[130:131], v[132:133]
	v_fmac_f32_e32 v86, 0x3fd744fd, v135
	v_mov_b32_e32 v141, v143
	v_pk_add_f32 v[136:137], v[140:141], v[136:137]
	v_mul_f32_e32 v87, v86, v86
	v_pk_add_f32 v[134:135], v[136:137], v[86:87]
	s_nop 1
	v_mov_b32_dpp v136, v134 quad_perm:[1,0,3,2] row_mask:0xf bank_mask:0xf bound_ctrl:1
	v_mov_b32_dpp v137, v135 quad_perm:[1,0,3,2] row_mask:0xf bank_mask:0xf bound_ctrl:1
	v_pk_add_f32 v[134:135], v[134:135], v[136:137]
	s_nop 1
	v_mov_b32_dpp v136, v134 quad_perm:[2,3,0,1] row_mask:0xf bank_mask:0xf bound_ctrl:1
	v_mov_b32_dpp v137, v135 quad_perm:[2,3,0,1] row_mask:0xf bank_mask:0xf bound_ctrl:1
	v_pk_add_f32 v[134:135], v[134:135], v[136:137]
	s_nop 1
	v_mov_b32_dpp v136, v134 row_half_mirror row_mask:0xf bank_mask:0xf bound_ctrl:1
	v_mov_b32_dpp v137, v135 row_half_mirror row_mask:0xf bank_mask:0xf bound_ctrl:1
	v_pk_add_f32 v[134:135], v[134:135], v[136:137]
	s_nop 1
	v_mov_b32_dpp v136, v134 row_mirror row_mask:0xf bank_mask:0xf bound_ctrl:1
	v_mov_b32_dpp v137, v135 row_mirror row_mask:0xf bank_mask:0xf bound_ctrl:1
	s_and_saveexec_b64 s[6:7], vcc
	v_pk_add_f32 v[134:135], v[134:135], v[136:137]
	ds_write_b64 v181, v[134:135] offset:80
	s_or_b64 exec, exec, s[6:7]
	v_or_b32_e32 v101, 0x1600, v139
	v_add_u32_e32 v71, v138, v101
	ds_read2_b32 v[134:135], v71 offset1:32
	ds_read2_b32 v[136:137], v71 offset0:64 offset1:96
	v_mov_b32_e32 v88, v121
	v_pk_add_f32 v[120:121], v[88:89], 0 op_sel_hi:[1,0]
	v_mov_b32_e32 v88, v105
	v_pk_add_f32 v[104:105], v[88:89], 0 op_sel_hi:[1,0]
	s_waitcnt lgkmcnt(1)
;   DI void operator()(f32x16 (&acc)[2][4], int grow0, int gcol0, int lane, int w, char* lds) {
;     ...
;     for (int ps = 0; ps < 4; ++ps) {
;       const int mt = ps >> 1;
;       if (ps + 1 < 4) {
;         if (ps >= 1) asm volatile("s_waitcnt lgkmcnt(0)" ::: "memory");
;         xpass(ps + 1, grow0, gcol0, lane, w, lds);
;         if (ps >= 1) asm volatile("s_waitcnt vmcnt(8)" ::: "memory");
;       } else asm volatile("s_waitcnt vmcnt(0)" ::: "memory");
;       const char* xs = lds + (ps & 1) * 65536 + w * 8192;
; #pragma unroll
;       for (int qq = 0; qq < 2; ++qq)
; #pragma unroll
;         for (int e = 0; e < 4; ++e) {
;           const int i = 4 * (2 * (ps & 1) + qq) + e;
;           const float* xr = (const float*)(xs + (8 * qq + 4 * hh + e) * 512) + l31;
;           float s1 = 0.f, s2 = 0.f;
; #pragma unroll
;           for (int nt = 0; nt < 4; ++nt) {
;             float v = (acc[mt][nt][i] + bia[nt]) * csc[nt];
;             float z = ALPHA * xr[nt * 32] + hs * v;
;             acc[mt][nt][i] = z; s1 += z; s2 += z * z;
;           }
;           s1 = row16_sum(s1); s2 = row16_sum(s2);
;           if ((lane & 15) == 0) { f32x2 sv = {s1, s2}; *(f32x2*)(redw + (mt * 32 + (i & 3) + 8 * (i >> 2)) * 2) = sv; }
	v_mov_b32_e32 v88, v134
	s_waitcnt lgkmcnt(0)
	v_mov_b32_e32 v89, v136
	s_mov_b32 s2, s67
	v_mov_b32_e32 v134, v135
	v_mov_b32_e32 v135, v136
	v_pk_mul_f32 v[140:141], v[88:89], s[2:3] op_sel_hi:[1,0]
	v_pk_fma_f32 v[88:89], v[88:89], s[2:3], v[120:121] op_sel_hi:[1,0,1]
	v_pk_fma_f32 v[104:105], v[134:135], s[2:3], v[104:105] op_sel_hi:[1,0,1]
	v_pk_mul_f32 v[142:143], v[88:89], v[88:89]
	v_pk_mul_f32 v[134:135], v[104:105], v[104:105]
	v_pk_mov_b32 v[120:121], v[120:121], v[142:143] op_sel:[1,0]
	v_pk_mov_b32 v[134:135], v[140:141], v[134:135] op_sel:[1,0]
	v_add_f32_e32 v72, 0, v73
	v_pk_add_f32 v[120:121], v[120:121], v[134:135]
	v_pk_add_f32 v[134:135], v[88:89], v[104:105]
	v_pk_mul_f32 v[140:141], v[88:89], v[104:105]
	v_fmac_f32_e32 v72, 0x3fd744fd, v137
	v_mov_b32_e32 v135, v141
	v_pk_add_f32 v[120:121], v[134:135], v[120:121]
	v_mul_f32_e32 v73, v72, v72
	v_pk_add_f32 v[120:121], v[120:121], v[72:73]
	s_nop 1
	v_mov_b32_dpp v134, v120 quad_perm:[1,0,3,2] row_mask:0xf bank_mask:0xf bound_ctrl:1
	v_mov_b32_dpp v135, v121 quad_perm:[1,0,3,2] row_mask:0xf bank_mask:0xf bound_ctrl:1
	v_pk_add_f32 v[120:121], v[120:121], v[134:135]
	s_nop 1
	v_mov_b32_dpp v134, v120 quad_perm:[2,3,0,1] row_mask:0xf bank_mask:0xf bound_ctrl:1
	v_mov_b32_dpp v135, v121 quad_perm:[2,3,0,1] row_mask:0xf bank_mask:0xf bound_ctrl:1
	v_pk_add_f32 v[120:121], v[120:121], v[134:135]
	s_nop 1
	v_mov_b32_dpp v134, v120 row_half_mirror row_mask:0xf bank_mask:0xf bound_ctrl:1
	v_mov_b32_dpp v135, v121 row_half_mirror row_mask:0xf bank_mask:0xf bound_ctrl:1
	v_pk_add_f32 v[120:121], v[120:121], v[134:135]
	s_nop 1
	v_mov_b32_dpp v134, v120 row_mirror row_mask:0xf bank_mask:0xf bound_ctrl:1
	v_mov_b32_dpp v135, v121 row_mirror row_mask:0xf bank_mask:0xf bound_ctrl:1
	s_and_saveexec_b64 s[6:7], vcc
	v_pk_add_f32 v[120:121], v[120:121], v[134:135]
	ds_write_b64 v181, v[120:121] offset:88
	s_or_b64 exec, exec, s[6:7]
	v_or_b32_e32 v120, 32, v159
	v_ashrrev_i32_e32 v121, 31, v120
	v_lshlrev_b64 v[120:121], 12, v[120:121]
	v_readfirstlane_b32 s2, v158
	v_lshl_add_u64 v[120:121], s[10:11], 0, v[120:121]
	s_lshl_b32 s2, s2, 13
	v_lshl_add_u64 v[120:121], v[184:185], 2, v[120:121]
	s_waitcnt lgkmcnt(0)
	v_lshl_add_u64 v[120:121], v[120:121], 0, v[0:1]
	s_mov_b32 m0, s2
	s_mov_b64 s[6:7], 0x2000
	global_load_lds_dwordx4 v[120:121], off
	v_lshl_add_u64 v[134:135], v[120:121], 0, s[6:7]
	s_or_b32 m0, s2, 0x400
	s_mov_b64 s[6:7], 0x4000
	global_load_lds_dwordx4 v[134:135], off
	v_lshl_add_u64 v[134:135], v[120:121], 0, s[6:7]
	s_or_b32 m0, s2, 0x800
	s_mov_b64 s[6:7], 0x6000
	global_load_lds_dwordx4 v[134:135], off
	v_lshl_add_u64 v[134:135], v[120:121], 0, s[6:7]
	s_or_b32 m0, s2, 0xc00
	s_mov_b64 s[6:7], 0x8000
	global_load_lds_dwordx4 v[134:135], off
	v_lshl_add_u64 v[134:135], v[120:121], 0, s[6:7]
	s_or_b32 m0, s2, 0x1000
	s_mov_b64 s[6:7], 0xa000
	global_load_lds_dwordx4 v[134:135], off
	v_lshl_add_u64 v[134:135], v[120:121], 0, s[6:7]
	s_or_b32 m0, s2, 0x1400
	s_mov_b64 s[6:7], 0xc000
	global_load_lds_dwordx4 v[134:135], off
	v_lshl_add_u64 v[134:135], v[120:121], 0, s[6:7]
	s_or_b32 m0, s2, 0x1800
	s_mov_b64 s[6:7], 0xe000
	global_load_lds_dwordx4 v[134:135], off
	v_lshl_add_u64 v[120:121], v[120:121], 0, s[6:7]
	s_or_b32 m0, s2, 0x1c00
	v_add_u32_e32 v105, 0x10000, v138
	global_load_lds_dwordx4 v[120:121], off
	s_waitcnt vmcnt(8)
	v_add_u32_e32 v73, v105, v154
	ds_read2_b32 v[134:135], v73 offset1:32
	ds_read2_b32 v[138:139], v73 offset0:64 offset1:96
	v_mov_b32_e32 v136, v122
	v_mov_b32_e32 v137, v90
	v_pk_add_f32 v[140:141], v[136:137], 0 op_sel_hi:[1,0]
	v_mov_b32_e32 v136, v106
	v_pk_add_f32 v[136:137], v[136:137], 0 op_sel_hi:[1,0]
	s_waitcnt lgkmcnt(0)
	v_mov_b32_e32 v142, v134
	v_mov_b32_e32 v143, v138
	s_mov_b32 s2, s67
	v_mov_b32_e32 v148, v135
	v_mov_b32_e32 v149, v138
	v_pk_fma_f32 v[134:135], v[142:143], s[2:3], v[140:141] op_sel_hi:[1,0,1]
	v_pk_fma_f32 v[136:137], v[148:149], s[2:3], v[136:137] op_sel_hi:[1,0,1]
	v_pk_mul_f32 v[144:145], v[142:143], s[2:3] op_sel_hi:[1,0]
	v_pk_mul_f32 v[142:143], v[134:135], v[134:135]
	v_pk_mul_f32 v[148:149], v[136:137], v[136:137]
	v_pk_mov_b32 v[140:141], v[140:141], v[142:143] op_sel:[1,0]
	v_pk_mov_b32 v[142:143], v[144:145], v[148:149] op_sel:[1,0]
	v_add_f32_e32 v120, 0, v74
	v_pk_add_f32 v[140:141], v[140:141], v[142:143]
	v_pk_add_f32 v[142:143], v[134:135], v[136:137]
	v_pk_mul_f32 v[144:145], v[134:135], v[136:137]
	v_fmac_f32_e32 v120, 0x3fd744fd, v139
	v_mov_b32_e32 v143, v145
	v_pk_add_f32 v[140:141], v[142:143], v[140:141]
	v_mul_f32_e32 v121, v120, v120
	v_pk_add_f32 v[138:139], v[140:141], v[120:121]
	s_nop 1
	v_mov_b32_dpp v140, v138 quad_perm:[1,0,3,2] row_mask:0xf bank_mask:0xf bound_ctrl:1
	v_mov_b32_dpp v141, v139 quad_perm:[1,0,3,2] row_mask:0xf bank_mask:0xf bound_ctrl:1
	v_pk_add_f32 v[138:139], v[138:139], v[140:141]
	s_nop 1
	v_mov_b32_dpp v140, v138 quad_perm:[2,3,0,1] row_mask:0xf bank_mask:0xf bound_ctrl:1
	v_mov_b32_dpp v141, v139 quad_perm:[2,3,0,1] row_mask:0xf bank_mask:0xf bound_ctrl:1
	v_pk_add_f32 v[138:139], v[138:139], v[140:141]
	s_nop 1
	v_mov_b32_dpp v140, v138 row_half_mirror row_mask:0xf bank_mask:0xf bound_ctrl:1
	v_mov_b32_dpp v141, v139 row_half_mirror row_mask:0xf bank_mask:0xf bound_ctrl:1
	v_pk_add_f32 v[138:139], v[138:139], v[140:141]
	s_nop 1
	v_mov_b32_dpp v140, v138 row_mirror row_mask:0xf bank_mask:0xf bound_ctrl:1
	v_mov_b32_dpp v141, v139 row_mirror row_mask:0xf bank_mask:0xf bound_ctrl:1
	s_and_saveexec_b64 s[6:7], vcc
	v_pk_add_f32 v[138:139], v[138:139], v[140:141]
	ds_write_b64 v181, v[138:139] offset:128
	s_or_b64 exec, exec, s[6:7]
	v_or_b32_e32 v74, 0x200, v154
	v_add_u32_e32 v85, v105, v74
	ds_read2_b32 v[138:139], v85 offset1:32
	ds_read2_b32 v[140:141], v85 offset0:64 offset1:96
	v_mov_b32_e32 v90, v123
	v_pk_add_f32 v[142:143], v[90:91], 0 op_sel_hi:[1,0]
	v_mov_b32_e32 v90, v107
	v_pk_add_f32 v[90:91], v[90:91], 0 op_sel_hi:[1,0]
	s_waitcnt lgkmcnt(1)
;   DI void operator()(f32x16 (&acc)[2][4], int grow0, int gcol0, int lane, int w, char* lds) {
;     ...
;         for (int e = 0; e < 4; ++e) {
;           const int i = 4 * (2 * (ps & 1) + qq) + e;
;           const float* xr = (const float*)(xs + (8 * qq + 4 * hh + e) * 512) + l31;
;           float s1 = 0.f, s2 = 0.f;
; #pragma unroll
;           for (int nt = 0; nt < 4; ++nt) {
;             float v = (acc[mt][nt][i] + bia[nt]) * csc[nt];
;             float z = ALPHA * xr[nt * 32] + hs * v;
;             acc[mt][nt][i] = z; s1 += z; s2 += z * z;
;           }
;           s1 = row16_sum(s1); s2 = row16_sum(s2);
;           if ((lane & 15) == 0) { f32x2 sv = {s1, s2}; *(f32x2*)(redw + (mt * 32 + (i & 3) + 8 * (i >> 2)) * 2) = sv; }
	v_mov_b32_e32 v106, v138
	s_waitcnt lgkmcnt(0)
	v_mov_b32_e32 v107, v140
	s_mov_b32 s2, s67
	v_mov_b32_e32 v122, v139
	v_mov_b32_e32 v123, v140
	v_pk_mul_f32 v[144:145], v[106:107], s[2:3] op_sel_hi:[1,0]
	v_pk_fma_f32 v[106:107], v[106:107], s[2:3], v[142:143] op_sel_hi:[1,0,1]
	v_pk_fma_f32 v[122:123], v[122:123], s[2:3], v[90:91] op_sel_hi:[1,0,1]
	v_pk_mul_f32 v[138:139], v[106:107], v[106:107]
	v_pk_mul_f32 v[90:91], v[122:123], v[122:123]
	v_pk_mov_b32 v[138:139], v[142:143], v[138:139] op_sel:[1,0]
	v_pk_mov_b32 v[90:91], v[144:145], v[90:91] op_sel:[1,0]
	v_add_f32_e32 v74, 0, v75
	v_pk_add_f32 v[90:91], v[138:139], v[90:91]
	v_pk_add_f32 v[138:139], v[106:107], v[122:123]
	v_pk_mul_f32 v[142:143], v[106:107], v[122:123]
	v_fmac_f32_e32 v74, 0x3fd744fd, v141
	v_mov_b32_e32 v139, v143
	v_pk_add_f32 v[90:91], v[138:139], v[90:91]
	v_mul_f32_e32 v75, v74, v74
	v_pk_add_f32 v[90:91], v[90:91], v[74:75]
	s_nop 1
	v_mov_b32_dpp v138, v90 quad_perm:[1,0,3,2] row_mask:0xf bank_mask:0xf bound_ctrl:1
	v_mov_b32_dpp v139, v91 quad_perm:[1,0,3,2] row_mask:0xf bank_mask:0xf bound_ctrl:1
	v_pk_add_f32 v[90:91], v[90:91], v[138:139]
	s_nop 1
	v_mov_b32_dpp v138, v90 quad_perm:[2,3,0,1] row_mask:0xf bank_mask:0xf bound_ctrl:1
	v_mov_b32_dpp v139, v91 quad_perm:[2,3,0,1] row_mask:0xf bank_mask:0xf bound_ctrl:1
	v_pk_add_f32 v[90:91], v[90:91], v[138:139]
	s_nop 1
	v_mov_b32_dpp v138, v90 row_half_mirror row_mask:0xf bank_mask:0xf bound_ctrl:1
	v_mov_b32_dpp v139, v91 row_half_mirror row_mask:0xf bank_mask:0xf bound_ctrl:1
	v_pk_add_f32 v[90:91], v[90:91], v[138:139]
	s_nop 1
	v_mov_b32_dpp v138, v90 row_mirror row_mask:0xf bank_mask:0xf bound_ctrl:1
	v_mov_b32_dpp v139, v91 row_mirror row_mask:0xf bank_mask:0xf bound_ctrl:1
	s_and_saveexec_b64 s[6:7], vcc
	v_pk_add_f32 v[90:91], v[90:91], v[138:139]
	ds_write_b64 v181, v[90:91] offset:136
	s_or_b64 exec, exec, s[6:7]
	v_or_b32_e32 v75, 0x400, v154
	v_add_u32_e32 v75, v105, v75
	ds_read2_b32 v[138:139], v75 offset1:32
	ds_read2_b32 v[142:143], v75 offset0:64 offset1:96
	v_mov_b32_e32 v140, v124
	v_mov_b32_e32 v141, v92
	v_pk_add_f32 v[144:145], v[140:141], 0 op_sel_hi:[1,0]
	v_mov_b32_e32 v140, v108
	v_pk_add_f32 v[140:141], v[140:141], 0 op_sel_hi:[1,0]
	s_waitcnt lgkmcnt(1)
	v_mov_b32_e32 v148, v138
	s_waitcnt lgkmcnt(0)
	v_mov_b32_e32 v149, v142
	s_mov_b32 s2, s67
	v_mov_b32_e32 v160, v139
	v_mov_b32_e32 v161, v142
	v_pk_fma_f32 v[138:139], v[148:149], s[2:3], v[144:145] op_sel_hi:[1,0,1]
	v_pk_fma_f32 v[140:141], v[160:161], s[2:3], v[140:141] op_sel_hi:[1,0,1]
	v_pk_mul_f32 v[156:157], v[148:149], s[2:3] op_sel_hi:[1,0]
	v_pk_mul_f32 v[148:149], v[138:139], v[138:139]
	v_pk_mul_f32 v[160:161], v[140:141], v[140:141]
	v_pk_mov_b32 v[144:145], v[144:145], v[148:149] op_sel:[1,0]
	v_pk_mov_b32 v[148:149], v[156:157], v[160:161] op_sel:[1,0]
	v_add_f32_e32 v90, 0, v76
	v_pk_add_f32 v[144:145], v[144:145], v[148:149]
	v_pk_add_f32 v[148:149], v[138:139], v[140:141]
	v_pk_mul_f32 v[156:157], v[138:139], v[140:141]
	v_fmac_f32_e32 v90, 0x3fd744fd, v143
	v_mov_b32_e32 v149, v157
	v_pk_add_f32 v[144:145], v[148:149], v[144:145]
	v_mul_f32_e32 v91, v90, v90
	v_pk_add_f32 v[142:143], v[144:145], v[90:91]
	s_nop 1
	v_mov_b32_dpp v144, v142 quad_perm:[1,0,3,2] row_mask:0xf bank_mask:0xf bound_ctrl:1
	v_mov_b32_dpp v145, v143 quad_perm:[1,0,3,2] row_mask:0xf bank_mask:0xf bound_ctrl:1
	v_pk_add_f32 v[142:143], v[142:143], v[144:145]
	s_nop 1
	v_mov_b32_dpp v144, v142 quad_perm:[2,3,0,1] row_mask:0xf bank_mask:0xf bound_ctrl:1
	v_mov_b32_dpp v145, v143 quad_perm:[2,3,0,1] row_mask:0xf bank_mask:0xf bound_ctrl:1
	v_pk_add_f32 v[142:143], v[142:143], v[144:145]
	s_nop 1
	v_mov_b32_dpp v144, v142 row_half_mirror row_mask:0xf bank_mask:0xf bound_ctrl:1
	v_mov_b32_dpp v145, v143 row_half_mirror row_mask:0xf bank_mask:0xf bound_ctrl:1
	v_pk_add_f32 v[142:143], v[142:143], v[144:145]
	s_nop 1
	v_mov_b32_dpp v144, v142 row_mirror row_mask:0xf bank_mask:0xf bound_ctrl:1
	v_mov_b32_dpp v145, v143 row_mirror row_mask:0xf bank_mask:0xf bound_ctrl:1
	s_and_saveexec_b64 s[6:7], vcc
	v_pk_add_f32 v[142:143], v[142:143], v[144:145]
	ds_write_b64 v181, v[142:143] offset:144
	s_or_b64 exec, exec, s[6:7]
	v_add_u32_e32 v87, v105, v146
	ds_read2_b32 v[142:143], v87 offset1:32
	ds_read2_b32 v[144:145], v87 offset0:64 offset1:96
	v_mov_b32_e32 v92, v125
	v_pk_add_f32 v[146:147], v[92:93], 0 op_sel_hi:[1,0]
	v_mov_b32_e32 v92, v109
	v_pk_add_f32 v[92:93], v[92:93], 0 op_sel_hi:[1,0]
	s_waitcnt lgkmcnt(1)
	v_mov_b32_e32 v108, v142
	s_waitcnt lgkmcnt(0)
;   DI void operator()(f32x16 (&acc)[2][4], int grow0, int gcol0, int lane, int w, char* lds) {
;     ...
;         for (int e = 0; e < 4; ++e) {
;           const int i = 4 * (2 * (ps & 1) + qq) + e;
;           const float* xr = (const float*)(xs + (8 * qq + 4 * hh + e) * 512) + l31;
;           float s1 = 0.f, s2 = 0.f;
; #pragma unroll
;           for (int nt = 0; nt < 4; ++nt) {
;             float v = (acc[mt][nt][i] + bia[nt]) * csc[nt];
;             float z = ALPHA * xr[nt * 32] + hs * v;
;             acc[mt][nt][i] = z; s1 += z; s2 += z * z;
;           }
;           s1 = row16_sum(s1); s2 = row16_sum(s2);
;           if ((lane & 15) == 0) { f32x2 sv = {s1, s2}; *(f32x2*)(redw + (mt * 32 + (i & 3) + 8 * (i >> 2)) * 2) = sv; }
	v_mov_b32_e32 v109, v144
	s_mov_b32 s2, s67
	v_mov_b32_e32 v124, v143
	v_mov_b32_e32 v125, v144
	v_pk_mul_f32 v[148:149], v[108:109], s[2:3] op_sel_hi:[1,0]
	v_pk_fma_f32 v[108:109], v[108:109], s[2:3], v[146:147] op_sel_hi:[1,0,1]
	v_pk_fma_f32 v[124:125], v[124:125], s[2:3], v[92:93] op_sel_hi:[1,0,1]
	v_pk_mul_f32 v[142:143], v[108:109], v[108:109]
	v_pk_mul_f32 v[92:93], v[124:125], v[124:125]
	v_pk_mov_b32 v[142:143], v[146:147], v[142:143] op_sel:[1,0]
	v_pk_mov_b32 v[92:93], v[148:149], v[92:93] op_sel:[1,0]
	v_add_f32_e32 v76, 0, v77
	v_pk_add_f32 v[92:93], v[142:143], v[92:93]
	v_pk_add_f32 v[142:143], v[108:109], v[124:125]
	v_pk_mul_f32 v[146:147], v[108:109], v[124:125]
	v_fmac_f32_e32 v76, 0x3fd744fd, v145
	v_mov_b32_e32 v143, v147
	v_pk_add_f32 v[92:93], v[142:143], v[92:93]
	v_mul_f32_e32 v77, v76, v76
	v_pk_add_f32 v[92:93], v[92:93], v[76:77]
	s_nop 1
	v_mov_b32_dpp v142, v92 quad_perm:[1,0,3,2] row_mask:0xf bank_mask:0xf bound_ctrl:1
	v_mov_b32_dpp v143, v93 quad_perm:[1,0,3,2] row_mask:0xf bank_mask:0xf bound_ctrl:1
	v_pk_add_f32 v[92:93], v[92:93], v[142:143]
	s_nop 1
	v_mov_b32_dpp v142, v92 quad_perm:[2,3,0,1] row_mask:0xf bank_mask:0xf bound_ctrl:1
	v_mov_b32_dpp v143, v93 quad_perm:[2,3,0,1] row_mask:0xf bank_mask:0xf bound_ctrl:1
	v_pk_add_f32 v[92:93], v[92:93], v[142:143]
	s_nop 1
	v_mov_b32_dpp v142, v92 row_half_mirror row_mask:0xf bank_mask:0xf bound_ctrl:1
	v_mov_b32_dpp v143, v93 row_half_mirror row_mask:0xf bank_mask:0xf bound_ctrl:1
	v_pk_add_f32 v[92:93], v[92:93], v[142:143]
	s_nop 1
	v_mov_b32_dpp v142, v92 row_mirror row_mask:0xf bank_mask:0xf bound_ctrl:1
	v_mov_b32_dpp v143, v93 row_mirror row_mask:0xf bank_mask:0xf bound_ctrl:1
	s_and_saveexec_b64 s[6:7], vcc
	v_pk_add_f32 v[92:93], v[92:93], v[142:143]
	ds_write_b64 v181, v[92:93] offset:152
	s_or_b64 exec, exec, s[6:7]
	v_or_b32_e32 v77, 0x1000, v154
	v_add_u32_e32 v77, v105, v77
	ds_read2_b32 v[142:143], v77 offset1:32
	ds_read2_b32 v[146:147], v77 offset0:64 offset1:96
	v_mov_b32_e32 v144, v126
	v_mov_b32_e32 v145, v94
	v_pk_add_f32 v[148:149], v[144:145], 0 op_sel_hi:[1,0]
	v_mov_b32_e32 v144, v110
	v_pk_add_f32 v[144:145], v[144:145], 0 op_sel_hi:[1,0]
	s_waitcnt lgkmcnt(1)
	v_mov_b32_e32 v156, v142
	s_waitcnt lgkmcnt(0)
	v_mov_b32_e32 v157, v146
	s_mov_b32 s2, s67
	v_mov_b32_e32 v170, v143
	v_mov_b32_e32 v171, v146
	v_pk_fma_f32 v[142:143], v[156:157], s[2:3], v[148:149] op_sel_hi:[1,0,1]
	v_pk_fma_f32 v[144:145], v[170:171], s[2:3], v[144:145] op_sel_hi:[1,0,1]
	v_pk_mul_f32 v[160:161], v[156:157], s[2:3] op_sel_hi:[1,0]
	v_pk_mul_f32 v[156:157], v[142:143], v[142:143]
	v_pk_mul_f32 v[170:171], v[144:145], v[144:145]
	v_pk_mov_b32 v[148:149], v[148:149], v[156:157] op_sel:[1,0]
	v_pk_mov_b32 v[156:157], v[160:161], v[170:171] op_sel:[1,0]
	v_add_f32_e32 v92, 0, v78
	v_pk_add_f32 v[148:149], v[148:149], v[156:157]
	v_pk_add_f32 v[156:157], v[142:143], v[144:145]
	v_pk_mul_f32 v[160:161], v[142:143], v[144:145]
	v_fmac_f32_e32 v92, 0x3fd744fd, v147
	v_mov_b32_e32 v157, v161
	v_pk_add_f32 v[148:149], v[156:157], v[148:149]
	v_mul_f32_e32 v93, v92, v92
	v_pk_add_f32 v[146:147], v[148:149], v[92:93]
	s_nop 1
	v_mov_b32_dpp v148, v146 quad_perm:[1,0,3,2] row_mask:0xf bank_mask:0xf bound_ctrl:1
	v_mov_b32_dpp v149, v147 quad_perm:[1,0,3,2] row_mask:0xf bank_mask:0xf bound_ctrl:1
	v_pk_add_f32 v[146:147], v[146:147], v[148:149]
	s_nop 1
	v_mov_b32_dpp v148, v146 quad_perm:[2,3,0,1] row_mask:0xf bank_mask:0xf bound_ctrl:1
	v_mov_b32_dpp v149, v147 quad_perm:[2,3,0,1] row_mask:0xf bank_mask:0xf bound_ctrl:1
	v_pk_add_f32 v[146:147], v[146:147], v[148:149]
	s_nop 1
	v_mov_b32_dpp v148, v146 row_half_mirror row_mask:0xf bank_mask:0xf bound_ctrl:1
	v_mov_b32_dpp v149, v147 row_half_mirror row_mask:0xf bank_mask:0xf bound_ctrl:1
	v_pk_add_f32 v[146:147], v[146:147], v[148:149]
	s_nop 1
	v_mov_b32_dpp v148, v146 row_mirror row_mask:0xf bank_mask:0xf bound_ctrl:1
	v_mov_b32_dpp v149, v147 row_mirror row_mask:0xf bank_mask:0xf bound_ctrl:1
	s_and_saveexec_b64 s[6:7], vcc
	v_pk_add_f32 v[146:147], v[146:147], v[148:149]
	ds_write_b64 v181, v[146:147] offset:192
	s_or_b64 exec, exec, s[6:7]
	v_or_b32_e32 v78, 0x1200, v154
	v_add_u32_e32 v91, v105, v78
	ds_read2_b32 v[146:147], v91 offset1:32
	ds_read2_b32 v[148:149], v91 offset0:64 offset1:96
	v_mov_b32_e32 v94, v127
	v_pk_add_f32 v[156:157], v[94:95], 0 op_sel_hi:[1,0]
	v_mov_b32_e32 v94, v111
	v_pk_add_f32 v[94:95], v[94:95], 0 op_sel_hi:[1,0]
	s_waitcnt lgkmcnt(1)
	v_mov_b32_e32 v110, v146
	s_waitcnt lgkmcnt(0)
	v_mov_b32_e32 v111, v148
	s_mov_b32 s2, s67
	v_mov_b32_e32 v126, v147
	v_mov_b32_e32 v127, v148
	v_pk_mul_f32 v[160:161], v[110:111], s[2:3] op_sel_hi:[1,0]
	v_pk_fma_f32 v[110:111], v[110:111], s[2:3], v[156:157] op_sel_hi:[1,0,1]
	v_pk_fma_f32 v[126:127], v[126:127], s[2:3], v[94:95] op_sel_hi:[1,0,1]
	v_pk_mul_f32 v[146:147], v[110:111], v[110:111]
	v_pk_mul_f32 v[94:95], v[126:127], v[126:127]
	v_pk_mov_b32 v[146:147], v[156:157], v[146:147] op_sel:[1,0]
	v_pk_mov_b32 v[94:95], v[160:161], v[94:95] op_sel:[1,0]
	v_add_f32_e32 v78, 0, v79
	v_pk_add_f32 v[94:95], v[146:147], v[94:95]
	v_pk_add_f32 v[146:147], v[110:111], v[126:127]
	v_pk_mul_f32 v[156:157], v[110:111], v[126:127]
	v_fmac_f32_e32 v78, 0x3fd744fd, v149
	v_mov_b32_e32 v147, v157
	v_pk_add_f32 v[94:95], v[146:147], v[94:95]
	v_mul_f32_e32 v79, v78, v78
	v_pk_add_f32 v[94:95], v[94:95], v[78:79]
	s_nop 1
	v_mov_b32_dpp v146, v94 quad_perm:[1,0,3,2] row_mask:0xf bank_mask:0xf bound_ctrl:1
	v_mov_b32_dpp v147, v95 quad_perm:[1,0,3,2] row_mask:0xf bank_mask:0xf bound_ctrl:1
	v_pk_add_f32 v[94:95], v[94:95], v[146:147]
	s_nop 1
	v_mov_b32_dpp v146, v94 quad_perm:[2,3,0,1] row_mask:0xf bank_mask:0xf bound_ctrl:1
	v_mov_b32_dpp v147, v95 quad_perm:[2,3,0,1] row_mask:0xf bank_mask:0xf bound_ctrl:1
	v_pk_add_f32 v[94:95], v[94:95], v[146:147]
	s_nop 1
	v_mov_b32_dpp v146, v94 row_half_mirror row_mask:0xf bank_mask:0xf bound_ctrl:1
	v_mov_b32_dpp v147, v95 row_half_mirror row_mask:0xf bank_mask:0xf bound_ctrl:1
	v_pk_add_f32 v[94:95], v[94:95], v[146:147]
	s_nop 1
	v_mov_b32_dpp v146, v94 row_mirror row_mask:0xf bank_mask:0xf bound_ctrl:1
	v_mov_b32_dpp v147, v95 row_mirror row_mask:0xf bank_mask:0xf bound_ctrl:1
	s_and_saveexec_b64 s[6:7], vcc
	v_pk_add_f32 v[94:95], v[94:95], v[146:147]
	ds_write_b64 v181, v[94:95] offset:200
	s_or_b64 exec, exec, s[6:7]
	v_or_b32_e32 v79, 0x1400, v154
	v_add_u32_e32 v79, v105, v79
	ds_read2_b32 v[146:147], v79 offset1:32
	ds_read2_b32 v[154:155], v79 offset0:64 offset1:96
	v_mov_b32_e32 v148, v128
	v_mov_b32_e32 v149, v96
	v_pk_add_f32 v[156:157], v[148:149], 0 op_sel_hi:[1,0]
	v_mov_b32_e32 v148, v112
	v_pk_add_f32 v[148:149], v[148:149], 0 op_sel_hi:[1,0]
	s_waitcnt lgkmcnt(1)
;   DI void operator()(f32x16 (&acc)[2][4], int grow0, int gcol0, int lane, int w, char* lds) {
;     ...
;     for (int ps = 0; ps < 4; ++ps) {
;       const int mt = ps >> 1;
;       if (ps + 1 < 4) {
;         if (ps >= 1) asm volatile("s_waitcnt lgkmcnt(0)" ::: "memory");
;         xpass(ps + 1, grow0, gcol0, lane, w, lds);
;         if (ps >= 1) asm volatile("s_waitcnt vmcnt(8)" ::: "memory");
;       } else asm volatile("s_waitcnt vmcnt(0)" ::: "memory");
;       const char* xs = lds + (ps & 1) * 65536 + w * 8192;
; #pragma unroll
;       for (int qq = 0; qq < 2; ++qq)
; #pragma unroll
;         for (int e = 0; e < 4; ++e) {
;           const int i = 4 * (2 * (ps & 1) + qq) + e;
;           const float* xr = (const float*)(xs + (8 * qq + 4 * hh + e) * 512) + l31;
;           float s1 = 0.f, s2 = 0.f;
; #pragma unroll
;           for (int nt = 0; nt < 4; ++nt) {
;             float v = (acc[mt][nt][i] + bia[nt]) * csc[nt];
;             float z = ALPHA * xr[nt * 32] + hs * v;
;             acc[mt][nt][i] = z; s1 += z; s2 += z * z;
;           }
;           s1 = row16_sum(s1); s2 = row16_sum(s2);
;           if ((lane & 15) == 0) { f32x2 sv = {s1, s2}; *(f32x2*)(redw + (mt * 32 + (i & 3) + 8 * (i >> 2)) * 2) = sv; }
	v_mov_b32_e32 v160, v146
	s_waitcnt lgkmcnt(0)
	v_mov_b32_e32 v161, v154
	s_mov_b32 s2, s67
	v_mov_b32_e32 v174, v147
	v_mov_b32_e32 v175, v154
	v_pk_fma_f32 v[146:147], v[160:161], s[2:3], v[156:157] op_sel_hi:[1,0,1]
	v_pk_fma_f32 v[148:149], v[174:175], s[2:3], v[148:149] op_sel_hi:[1,0,1]
	v_pk_mul_f32 v[170:171], v[160:161], s[2:3] op_sel_hi:[1,0]
	v_pk_mul_f32 v[160:161], v[146:147], v[146:147]
	v_pk_mul_f32 v[174:175], v[148:149], v[148:149]
	v_pk_mov_b32 v[156:157], v[156:157], v[160:161] op_sel:[1,0]
	v_pk_mov_b32 v[160:161], v[170:171], v[174:175] op_sel:[1,0]
	v_add_f32_e32 v94, 0, v80
	v_pk_add_f32 v[156:157], v[156:157], v[160:161]
	v_pk_add_f32 v[160:161], v[146:147], v[148:149]
	v_pk_mul_f32 v[170:171], v[146:147], v[148:149]
	v_fmac_f32_e32 v94, 0x3fd744fd, v155
	v_mov_b32_e32 v161, v171
	v_pk_add_f32 v[156:157], v[160:161], v[156:157]
	v_mul_f32_e32 v95, v94, v94
	v_pk_add_f32 v[154:155], v[156:157], v[94:95]
	s_nop 1
	v_mov_b32_dpp v156, v154 quad_perm:[1,0,3,2] row_mask:0xf bank_mask:0xf bound_ctrl:1
	v_mov_b32_dpp v157, v155 quad_perm:[1,0,3,2] row_mask:0xf bank_mask:0xf bound_ctrl:1
	v_pk_add_f32 v[154:155], v[154:155], v[156:157]
	s_nop 1
	v_mov_b32_dpp v156, v154 quad_perm:[2,3,0,1] row_mask:0xf bank_mask:0xf bound_ctrl:1
	v_mov_b32_dpp v157, v155 quad_perm:[2,3,0,1] row_mask:0xf bank_mask:0xf bound_ctrl:1
	v_pk_add_f32 v[154:155], v[154:155], v[156:157]
	s_nop 1
	v_mov_b32_dpp v156, v154 row_half_mirror row_mask:0xf bank_mask:0xf bound_ctrl:1
	v_mov_b32_dpp v157, v155 row_half_mirror row_mask:0xf bank_mask:0xf bound_ctrl:1
	v_pk_add_f32 v[154:155], v[154:155], v[156:157]
	s_nop 1
	v_mov_b32_dpp v156, v154 row_mirror row_mask:0xf bank_mask:0xf bound_ctrl:1
	v_mov_b32_dpp v157, v155 row_mirror row_mask:0xf bank_mask:0xf bound_ctrl:1
	s_and_saveexec_b64 s[6:7], vcc
	v_pk_add_f32 v[154:155], v[154:155], v[156:157]
	ds_write_b64 v181, v[154:155] offset:208
	s_or_b64 exec, exec, s[6:7]
	v_add_u32_e32 v93, v105, v101
	ds_read2_b32 v[154:155], v93 offset1:32
	ds_read2_b32 v[156:157], v93 offset0:64 offset1:96
	v_mov_b32_e32 v96, v129
	v_pk_add_f32 v[128:129], v[96:97], 0 op_sel_hi:[1,0]
	v_mov_b32_e32 v96, v113
	v_pk_add_f32 v[112:113], v[96:97], 0 op_sel_hi:[1,0]
	s_waitcnt lgkmcnt(1)
	v_mov_b32_e32 v96, v154
	s_waitcnt lgkmcnt(0)
	v_mov_b32_e32 v97, v156
	s_mov_b32 s2, s67
	v_mov_b32_e32 v154, v155
	v_mov_b32_e32 v155, v156
	v_pk_mul_f32 v[160:161], v[96:97], s[2:3] op_sel_hi:[1,0]
	v_pk_fma_f32 v[96:97], v[96:97], s[2:3], v[128:129] op_sel_hi:[1,0,1]
	v_pk_fma_f32 v[112:113], v[154:155], s[2:3], v[112:113] op_sel_hi:[1,0,1]
	v_pk_mul_f32 v[170:171], v[96:97], v[96:97]
	v_pk_mul_f32 v[154:155], v[112:113], v[112:113]
	v_pk_mov_b32 v[128:129], v[128:129], v[170:171] op_sel:[1,0]
	v_pk_mov_b32 v[154:155], v[160:161], v[154:155] op_sel:[1,0]
	v_add_f32_e32 v80, 0, v81
	v_pk_add_f32 v[128:129], v[128:129], v[154:155]
	v_pk_add_f32 v[154:155], v[96:97], v[112:113]
	v_pk_mul_f32 v[160:161], v[96:97], v[112:113]
	v_fmac_f32_e32 v80, 0x3fd744fd, v157
	v_mov_b32_e32 v155, v161
	v_pk_add_f32 v[128:129], v[154:155], v[128:129]
	v_mul_f32_e32 v81, v80, v80
	v_pk_add_f32 v[128:129], v[128:129], v[80:81]
	s_nop 1
	v_mov_b32_dpp v154, v128 quad_perm:[1,0,3,2] row_mask:0xf bank_mask:0xf bound_ctrl:1
	v_mov_b32_dpp v155, v129 quad_perm:[1,0,3,2] row_mask:0xf bank_mask:0xf bound_ctrl:1
	v_pk_add_f32 v[128:129], v[128:129], v[154:155]
	s_nop 1
	v_mov_b32_dpp v154, v128 quad_perm:[2,3,0,1] row_mask:0xf bank_mask:0xf bound_ctrl:1
	v_mov_b32_dpp v155, v129 quad_perm:[2,3,0,1] row_mask:0xf bank_mask:0xf bound_ctrl:1
	v_pk_add_f32 v[128:129], v[128:129], v[154:155]
	s_nop 1
	v_mov_b32_dpp v154, v128 row_half_mirror row_mask:0xf bank_mask:0xf bound_ctrl:1
	v_mov_b32_dpp v155, v129 row_half_mirror row_mask:0xf bank_mask:0xf bound_ctrl:1
	v_pk_add_f32 v[128:129], v[128:129], v[154:155]
	s_nop 1
	v_mov_b32_dpp v154, v128 row_mirror row_mask:0xf bank_mask:0xf bound_ctrl:1
	v_mov_b32_dpp v155, v129 row_mirror row_mask:0xf bank_mask:0xf bound_ctrl:1
	s_and_saveexec_b64 s[6:7], vcc
	v_pk_add_f32 v[128:129], v[128:129], v[154:155]
	ds_write_b64 v181, v[128:129] offset:216
	s_or_b64 exec, exec, s[6:7]
	v_or_b32_e32 v128, 48, v159
	v_ashrrev_i32_e32 v129, 31, v128
	v_lshlrev_b64 v[128:129], 12, v[128:129]
	v_readfirstlane_b32 s2, v158
	v_lshl_add_u64 v[128:129], s[10:11], 0, v[128:129]
	s_lshl_b32 s2, s2, 13
	v_lshl_add_u64 v[128:129], v[184:185], 2, v[128:129]
	s_waitcnt lgkmcnt(0)
	s_add_i32 m0, s2, 0x10000
	v_lshl_add_u64 v[128:129], v[128:129], 0, v[0:1]
	s_mov_b64 s[6:7], 0x2000
	global_load_lds_dwordx4 v[128:129], off
	v_lshl_add_u64 v[154:155], v[128:129], 0, s[6:7]
	s_add_i32 m0, s2, 0x10400
	s_mov_b64 s[6:7], 0x4000
	global_load_lds_dwordx4 v[154:155], off
	v_lshl_add_u64 v[154:155], v[128:129], 0, s[6:7]
	s_add_i32 m0, s2, 0x10800
	s_mov_b64 s[6:7], 0x6000
	global_load_lds_dwordx4 v[154:155], off
	v_lshl_add_u64 v[154:155], v[128:129], 0, s[6:7]
	s_add_i32 m0, s2, 0x10c00
	s_mov_b64 s[6:7], 0x8000
	global_load_lds_dwordx4 v[154:155], off
	v_lshl_add_u64 v[154:155], v[128:129], 0, s[6:7]
	s_add_i32 m0, s2, 0x11000
	s_mov_b64 s[6:7], 0xa000
	global_load_lds_dwordx4 v[154:155], off
	v_lshl_add_u64 v[154:155], v[128:129], 0, s[6:7]
	s_add_i32 m0, s2, 0x11400
	s_mov_b64 s[6:7], 0xc000
	global_load_lds_dwordx4 v[154:155], off
	v_lshl_add_u64 v[154:155], v[128:129], 0, s[6:7]
	s_add_i32 m0, s2, 0x11800
	s_mov_b64 s[6:7], 0xe000
	global_load_lds_dwordx4 v[154:155], off
	v_lshl_add_u64 v[128:129], v[128:129], 0, s[6:7]
	s_add_i32 m0, s2, 0x11c00
	v_mov_b32_e32 v156, v50
	global_load_lds_dwordx4 v[128:129], off
	s_waitcnt vmcnt(8)
;   DI void operator()(f32x16 (&acc)[2][4], int grow0, int gcol0, int lane, int w, char* lds) {
;     ...
;         for (int e = 0; e < 4; ++e) {
;           const int i = 4 * (2 * (ps & 1) + qq) + e;
;           const float* xr = (const float*)(xs + (8 * qq + 4 * hh + e) * 512) + l31;
;           float s1 = 0.f, s2 = 0.f;
; #pragma unroll
;           for (int nt = 0; nt < 4; ++nt) {
;             float v = (acc[mt][nt][i] + bia[nt]) * csc[nt];
;             float z = ALPHA * xr[nt * 32] + hs * v;
;             acc[mt][nt][i] = z; s1 += z; s2 += z * z;
;           }
;           s1 = row16_sum(s1); s2 = row16_sum(s2);
;           if ((lane & 15) == 0) { f32x2 sv = {s1, s2}; *(f32x2*)(redw + (mt * 32 + (i & 3) + 8 * (i >> 2)) * 2) = sv; }
	ds_read2_b32 v[154:155], v168 offset1:32
	ds_read2_b32 v[158:159], v168 offset0:64 offset1:96
	v_mov_b32_e32 v157, v18
	v_pk_add_f32 v[160:161], v[156:157], 0 op_sel_hi:[1,0]
	v_mov_b32_e32 v156, v34
	v_pk_add_f32 v[156:157], v[156:157], 0 op_sel_hi:[1,0]
	s_waitcnt lgkmcnt(0)
	v_mov_b32_e32 v170, v154
	v_mov_b32_e32 v171, v158
	s_mov_b32 s2, s67
	v_mov_b32_e32 v176, v155
	v_mov_b32_e32 v177, v158
	v_pk_fma_f32 v[154:155], v[170:171], s[2:3], v[160:161] op_sel_hi:[1,0,1]
	v_pk_fma_f32 v[156:157], v[176:177], s[2:3], v[156:157] op_sel_hi:[1,0,1]
	v_pk_mul_f32 v[174:175], v[170:171], s[2:3] op_sel_hi:[1,0]
	v_pk_mul_f32 v[170:171], v[154:155], v[154:155]
	v_pk_mul_f32 v[176:177], v[156:157], v[156:157]
	v_pk_mov_b32 v[160:161], v[160:161], v[170:171] op_sel:[1,0]
	v_pk_mov_b32 v[170:171], v[174:175], v[176:177] op_sel:[1,0]
	v_add_f32_e32 v128, 0, v2
	v_pk_add_f32 v[160:161], v[160:161], v[170:171]
	v_pk_add_f32 v[170:171], v[154:155], v[156:157]
	v_pk_mul_f32 v[174:175], v[154:155], v[156:157]
	v_fmac_f32_e32 v128, 0x3fd744fd, v159
	v_mov_b32_e32 v171, v175
	v_pk_add_f32 v[160:161], v[170:171], v[160:161]
	v_mul_f32_e32 v129, v128, v128
	v_pk_add_f32 v[158:159], v[160:161], v[128:129]
	s_nop 1
	v_mov_b32_dpp v160, v158 quad_perm:[1,0,3,2] row_mask:0xf bank_mask:0xf bound_ctrl:1
	v_mov_b32_dpp v161, v159 quad_perm:[1,0,3,2] row_mask:0xf bank_mask:0xf bound_ctrl:1
	v_pk_add_f32 v[158:159], v[158:159], v[160:161]
	s_nop 1
	v_mov_b32_dpp v160, v158 quad_perm:[2,3,0,1] row_mask:0xf bank_mask:0xf bound_ctrl:1
	v_mov_b32_dpp v161, v159 quad_perm:[2,3,0,1] row_mask:0xf bank_mask:0xf bound_ctrl:1
	v_pk_add_f32 v[158:159], v[158:159], v[160:161]
	s_nop 1
	v_mov_b32_dpp v160, v158 row_half_mirror row_mask:0xf bank_mask:0xf bound_ctrl:1
	v_mov_b32_dpp v161, v159 row_half_mirror row_mask:0xf bank_mask:0xf bound_ctrl:1
	v_pk_add_f32 v[158:159], v[158:159], v[160:161]
	s_nop 1
	v_mov_b32_dpp v160, v158 row_mirror row_mask:0xf bank_mask:0xf bound_ctrl:1
	v_mov_b32_dpp v161, v159 row_mirror row_mask:0xf bank_mask:0xf bound_ctrl:1
	s_and_saveexec_b64 s[6:7], vcc
	v_pk_add_f32 v[158:159], v[158:159], v[160:161]
	ds_write_b64 v181, v[158:159] offset:256
	s_or_b64 exec, exec, s[6:7]
	ds_read2_b32 v[158:159], v168 offset0:128 offset1:160
	ds_read2_b32 v[160:161], v168 offset0:192 offset1:224
	v_mov_b32_e32 v18, v51
	v_pk_add_f32 v[168:169], v[18:19], 0 op_sel_hi:[1,0]
	v_mov_b32_e32 v18, v35
	v_pk_add_f32 v[18:19], v[18:19], 0 op_sel_hi:[1,0]
	s_waitcnt lgkmcnt(1)
	v_mov_b32_e32 v34, v158
	s_waitcnt lgkmcnt(0)
	v_mov_b32_e32 v35, v160
	s_mov_b32 s2, s67
	v_mov_b32_e32 v50, v159
	v_mov_b32_e32 v51, v160
	v_pk_mul_f32 v[170:171], v[34:35], s[2:3] op_sel_hi:[1,0]
	v_pk_fma_f32 v[34:35], v[34:35], s[2:3], v[168:169] op_sel_hi:[1,0,1]
	v_pk_fma_f32 v[50:51], v[50:51], s[2:3], v[18:19] op_sel_hi:[1,0,1]
	v_pk_mul_f32 v[158:159], v[34:35], v[34:35]
	v_pk_mul_f32 v[18:19], v[50:51], v[50:51]
	v_pk_mov_b32 v[158:159], v[168:169], v[158:159] op_sel:[1,0]
	v_pk_mov_b32 v[18:19], v[170:171], v[18:19] op_sel:[1,0]
	v_add_f32_e32 v2, 0, v3
	v_pk_add_f32 v[18:19], v[158:159], v[18:19]
	v_pk_add_f32 v[158:159], v[34:35], v[50:51]
	v_pk_mul_f32 v[168:169], v[34:35], v[50:51]
	v_fmac_f32_e32 v2, 0x3fd744fd, v161
	v_mov_b32_e32 v159, v169
	v_pk_add_f32 v[18:19], v[158:159], v[18:19]
	v_mul_f32_e32 v3, v2, v2
	v_pk_add_f32 v[18:19], v[18:19], v[2:3]
	s_nop 1
	v_mov_b32_dpp v158, v18 quad_perm:[1,0,3,2] row_mask:0xf bank_mask:0xf bound_ctrl:1
	v_mov_b32_dpp v159, v19 quad_perm:[1,0,3,2] row_mask:0xf bank_mask:0xf bound_ctrl:1
	v_pk_add_f32 v[18:19], v[18:19], v[158:159]
	s_nop 1
	v_mov_b32_dpp v158, v18 quad_perm:[2,3,0,1] row_mask:0xf bank_mask:0xf bound_ctrl:1
	v_mov_b32_dpp v159, v19 quad_perm:[2,3,0,1] row_mask:0xf bank_mask:0xf bound_ctrl:1
	v_pk_add_f32 v[18:19], v[18:19], v[158:159]
	s_nop 1
	v_mov_b32_dpp v158, v18 row_half_mirror row_mask:0xf bank_mask:0xf bound_ctrl:1
	v_mov_b32_dpp v159, v19 row_half_mirror row_mask:0xf bank_mask:0xf bound_ctrl:1
	v_pk_add_f32 v[18:19], v[18:19], v[158:159]
	s_nop 1
	v_mov_b32_dpp v158, v18 row_mirror row_mask:0xf bank_mask:0xf bound_ctrl:1
	v_mov_b32_dpp v159, v19 row_mirror row_mask:0xf bank_mask:0xf bound_ctrl:1
	s_and_saveexec_b64 s[6:7], vcc
	v_pk_add_f32 v[18:19], v[18:19], v[158:159]
	ds_write_b64 v181, v[18:19] offset:264
	s_or_b64 exec, exec, s[6:7]
	ds_read2_b32 v[158:159], v153 offset1:32
	ds_read2_b32 v[168:169], v153 offset0:64 offset1:96
	v_mov_b32_e32 v160, v52
	v_mov_b32_e32 v161, v20
	v_pk_add_f32 v[170:171], v[160:161], 0 op_sel_hi:[1,0]
	v_mov_b32_e32 v160, v36
	v_pk_add_f32 v[160:161], v[160:161], 0 op_sel_hi:[1,0]
	s_waitcnt lgkmcnt(1)
	v_mov_b32_e32 v174, v158
	s_waitcnt lgkmcnt(0)
;   DI void operator()(f32x16 (&acc)[2][4], int grow0, int gcol0, int lane, int w, char* lds) {
;     ...
;       for (int qq = 0; qq < 2; ++qq)
; #pragma unroll
;         for (int e = 0; e < 4; ++e) {
;           const int i = 4 * (2 * (ps & 1) + qq) + e;
;           const float* xr = (const float*)(xs + (8 * qq + 4 * hh + e) * 512) + l31;
;           float s1 = 0.f, s2 = 0.f;
; #pragma unroll
;           for (int nt = 0; nt < 4; ++nt) {
;             float v = (acc[mt][nt][i] + bia[nt]) * csc[nt];
;             float z = ALPHA * xr[nt * 32] + hs * v;
;             acc[mt][nt][i] = z; s1 += z; s2 += z * z;
;           }
;           s1 = row16_sum(s1); s2 = row16_sum(s2);
;           if ((lane & 15) == 0) { f32x2 sv = {s1, s2}; *(f32x2*)(redw + (mt * 32 + (i & 3) + 8 * (i >> 2)) * 2) = sv; }
	v_mov_b32_e32 v175, v168
	s_mov_b32 s2, s67
	v_mov_b32_e32 v178, v159
	v_mov_b32_e32 v179, v168
	v_pk_fma_f32 v[158:159], v[174:175], s[2:3], v[170:171] op_sel_hi:[1,0,1]
	v_pk_fma_f32 v[160:161], v[178:179], s[2:3], v[160:161] op_sel_hi:[1,0,1]
	v_pk_mul_f32 v[176:177], v[174:175], s[2:3] op_sel_hi:[1,0]
	v_pk_mul_f32 v[174:175], v[158:159], v[158:159]
	v_pk_mul_f32 v[178:179], v[160:161], v[160:161]
	v_pk_mov_b32 v[170:171], v[170:171], v[174:175] op_sel:[1,0]
	v_pk_mov_b32 v[174:175], v[176:177], v[178:179] op_sel:[1,0]
	v_add_f32_e32 v18, 0, v4
	v_pk_add_f32 v[170:171], v[170:171], v[174:175]
	v_pk_add_f32 v[174:175], v[158:159], v[160:161]
	v_pk_mul_f32 v[176:177], v[158:159], v[160:161]
	v_fmac_f32_e32 v18, 0x3fd744fd, v169
	v_mov_b32_e32 v175, v177
	v_pk_add_f32 v[170:171], v[174:175], v[170:171]
	v_mul_f32_e32 v19, v18, v18
	v_pk_add_f32 v[168:169], v[170:171], v[18:19]
	s_nop 1
	v_mov_b32_dpp v170, v168 quad_perm:[1,0,3,2] row_mask:0xf bank_mask:0xf bound_ctrl:1
	v_mov_b32_dpp v171, v169 quad_perm:[1,0,3,2] row_mask:0xf bank_mask:0xf bound_ctrl:1
	v_pk_add_f32 v[168:169], v[168:169], v[170:171]
	s_nop 1
	v_mov_b32_dpp v170, v168 quad_perm:[2,3,0,1] row_mask:0xf bank_mask:0xf bound_ctrl:1
	v_mov_b32_dpp v171, v169 quad_perm:[2,3,0,1] row_mask:0xf bank_mask:0xf bound_ctrl:1
	v_pk_add_f32 v[168:169], v[168:169], v[170:171]
	s_nop 1
	v_mov_b32_dpp v170, v168 row_half_mirror row_mask:0xf bank_mask:0xf bound_ctrl:1
	v_mov_b32_dpp v171, v169 row_half_mirror row_mask:0xf bank_mask:0xf bound_ctrl:1
	v_pk_add_f32 v[168:169], v[168:169], v[170:171]
	s_nop 1
	v_mov_b32_dpp v170, v168 row_mirror row_mask:0xf bank_mask:0xf bound_ctrl:1
	v_mov_b32_dpp v171, v169 row_mirror row_mask:0xf bank_mask:0xf bound_ctrl:1
	s_and_saveexec_b64 s[6:7], vcc
	v_pk_add_f32 v[168:169], v[168:169], v[170:171]
	ds_write_b64 v181, v[168:169] offset:272
	s_or_b64 exec, exec, s[6:7]
	ds_read2_b32 v[168:169], v151 offset1:32
	ds_read2_b32 v[170:171], v151 offset0:64 offset1:96
	v_mov_b32_e32 v20, v53
	v_pk_add_f32 v[174:175], v[20:21], 0 op_sel_hi:[1,0]
	v_mov_b32_e32 v20, v37
	v_pk_add_f32 v[20:21], v[20:21], 0 op_sel_hi:[1,0]
	s_waitcnt lgkmcnt(1)
	v_mov_b32_e32 v36, v168
	s_waitcnt lgkmcnt(0)
	v_mov_b32_e32 v37, v170
	s_mov_b32 s2, s67
	v_mov_b32_e32 v52, v169
	v_mov_b32_e32 v53, v170
	v_pk_mul_f32 v[176:177], v[36:37], s[2:3] op_sel_hi:[1,0]
	v_pk_fma_f32 v[36:37], v[36:37], s[2:3], v[174:175] op_sel_hi:[1,0,1]
	v_pk_fma_f32 v[52:53], v[52:53], s[2:3], v[20:21] op_sel_hi:[1,0,1]
	v_pk_mul_f32 v[168:169], v[36:37], v[36:37]
	v_pk_mul_f32 v[20:21], v[52:53], v[52:53]
	v_pk_mov_b32 v[168:169], v[174:175], v[168:169] op_sel:[1,0]
	v_pk_mov_b32 v[20:21], v[176:177], v[20:21] op_sel:[1,0]
	v_add_f32_e32 v4, 0, v5
	v_pk_add_f32 v[20:21], v[168:169], v[20:21]
	v_pk_add_f32 v[168:169], v[36:37], v[52:53]
	v_pk_mul_f32 v[174:175], v[36:37], v[52:53]
	v_fmac_f32_e32 v4, 0x3fd744fd, v171
	v_mov_b32_e32 v169, v175
	v_pk_add_f32 v[20:21], v[168:169], v[20:21]
	v_mul_f32_e32 v5, v4, v4
	v_pk_add_f32 v[20:21], v[20:21], v[4:5]
	s_nop 1
	v_mov_b32_dpp v168, v20 quad_perm:[1,0,3,2] row_mask:0xf bank_mask:0xf bound_ctrl:1
	v_mov_b32_dpp v169, v21 quad_perm:[1,0,3,2] row_mask:0xf bank_mask:0xf bound_ctrl:1
	v_pk_add_f32 v[20:21], v[20:21], v[168:169]
	s_nop 1
	v_mov_b32_dpp v168, v20 quad_perm:[2,3,0,1] row_mask:0xf bank_mask:0xf bound_ctrl:1
	v_mov_b32_dpp v169, v21 quad_perm:[2,3,0,1] row_mask:0xf bank_mask:0xf bound_ctrl:1
	v_pk_add_f32 v[20:21], v[20:21], v[168:169]
	s_nop 1
	v_mov_b32_dpp v168, v20 row_half_mirror row_mask:0xf bank_mask:0xf bound_ctrl:1
	v_mov_b32_dpp v169, v21 row_half_mirror row_mask:0xf bank_mask:0xf bound_ctrl:1
	v_pk_add_f32 v[20:21], v[20:21], v[168:169]
	s_nop 1
	v_mov_b32_dpp v168, v20 row_mirror row_mask:0xf bank_mask:0xf bound_ctrl:1
	v_mov_b32_dpp v169, v21 row_mirror row_mask:0xf bank_mask:0xf bound_ctrl:1
	s_and_saveexec_b64 s[6:7], vcc
	v_pk_add_f32 v[20:21], v[20:21], v[168:169]
	ds_write_b64 v181, v[20:21] offset:280
	s_or_b64 exec, exec, s[6:7]
	ds_read2_b32 v[168:169], v67 offset1:32
	ds_read2_b32 v[174:175], v67 offset0:64 offset1:96
	v_mov_b32_e32 v170, v54
	v_mov_b32_e32 v171, v22
	v_pk_add_f32 v[176:177], v[170:171], 0 op_sel_hi:[1,0]
	v_mov_b32_e32 v170, v38
	v_pk_add_f32 v[170:171], v[170:171], 0 op_sel_hi:[1,0]
	s_waitcnt lgkmcnt(1)
	v_mov_b32_e32 v178, v168
	s_waitcnt lgkmcnt(0)
	v_mov_b32_e32 v179, v174
	s_mov_b32 s2, s67
	v_mov_b32_e32 v190, v169
	v_mov_b32_e32 v191, v174
	v_pk_fma_f32 v[168:169], v[178:179], s[2:3], v[176:177] op_sel_hi:[1,0,1]
	v_pk_fma_f32 v[170:171], v[190:191], s[2:3], v[170:171] op_sel_hi:[1,0,1]
	v_pk_mul_f32 v[182:183], v[178:179], s[2:3] op_sel_hi:[1,0]
	v_pk_mul_f32 v[178:179], v[168:169], v[168:169]
	v_pk_mul_f32 v[190:191], v[170:171], v[170:171]
	v_pk_mov_b32 v[176:177], v[176:177], v[178:179] op_sel:[1,0]
	v_pk_mov_b32 v[178:179], v[182:183], v[190:191] op_sel:[1,0]
	v_add_f32_e32 v20, 0, v6
	v_pk_add_f32 v[176:177], v[176:177], v[178:179]
	v_pk_add_f32 v[178:179], v[168:169], v[170:171]
	v_pk_mul_f32 v[182:183], v[168:169], v[170:171]
	v_fmac_f32_e32 v20, 0x3fd744fd, v175
	v_mov_b32_e32 v179, v183
	v_pk_add_f32 v[176:177], v[178:179], v[176:177]
	v_mul_f32_e32 v21, v20, v20
	v_pk_add_f32 v[174:175], v[176:177], v[20:21]
	s_nop 1
	v_mov_b32_dpp v176, v174 quad_perm:[1,0,3,2] row_mask:0xf bank_mask:0xf bound_ctrl:1
	v_mov_b32_dpp v177, v175 quad_perm:[1,0,3,2] row_mask:0xf bank_mask:0xf bound_ctrl:1
	v_pk_add_f32 v[174:175], v[174:175], v[176:177]
	s_nop 1
	v_mov_b32_dpp v176, v174 quad_perm:[2,3,0,1] row_mask:0xf bank_mask:0xf bound_ctrl:1
	v_mov_b32_dpp v177, v175 quad_perm:[2,3,0,1] row_mask:0xf bank_mask:0xf bound_ctrl:1
	v_pk_add_f32 v[174:175], v[174:175], v[176:177]
	s_nop 1
	v_mov_b32_dpp v176, v174 row_half_mirror row_mask:0xf bank_mask:0xf bound_ctrl:1
	v_mov_b32_dpp v177, v175 row_half_mirror row_mask:0xf bank_mask:0xf bound_ctrl:1
	v_pk_add_f32 v[174:175], v[174:175], v[176:177]
	s_nop 1
	v_mov_b32_dpp v176, v174 row_mirror row_mask:0xf bank_mask:0xf bound_ctrl:1
	v_mov_b32_dpp v177, v175 row_mirror row_mask:0xf bank_mask:0xf bound_ctrl:1
	s_and_saveexec_b64 s[6:7], vcc
	v_pk_add_f32 v[174:175], v[174:175], v[176:177]
	ds_write_b64 v181, v[174:175] offset:320
	s_or_b64 exec, exec, s[6:7]
	ds_read2_b32 v[174:175], v67 offset0:128 offset1:160
	ds_read2_b32 v[176:177], v67 offset0:192 offset1:224
	v_mov_b32_e32 v22, v55
	v_pk_add_f32 v[178:179], v[22:23], 0 op_sel_hi:[1,0]
	v_mov_b32_e32 v22, v39
	v_pk_add_f32 v[22:23], v[22:23], 0 op_sel_hi:[1,0]
	s_waitcnt lgkmcnt(1)
;   DI void operator()(f32x16 (&acc)[2][4], int grow0, int gcol0, int lane, int w, char* lds) {
;     ...
;       for (int qq = 0; qq < 2; ++qq)
; #pragma unroll
;         for (int e = 0; e < 4; ++e) {
;           const int i = 4 * (2 * (ps & 1) + qq) + e;
;           const float* xr = (const float*)(xs + (8 * qq + 4 * hh + e) * 512) + l31;
;           float s1 = 0.f, s2 = 0.f;
; #pragma unroll
;           for (int nt = 0; nt < 4; ++nt) {
;             float v = (acc[mt][nt][i] + bia[nt]) * csc[nt];
;             float z = ALPHA * xr[nt * 32] + hs * v;
;             acc[mt][nt][i] = z; s1 += z; s2 += z * z;
;           }
;           s1 = row16_sum(s1); s2 = row16_sum(s2);
;           if ((lane & 15) == 0) { f32x2 sv = {s1, s2}; *(f32x2*)(redw + (mt * 32 + (i & 3) + 8 * (i >> 2)) * 2) = sv; }
	v_mov_b32_e32 v38, v174
	s_waitcnt lgkmcnt(0)
	v_mov_b32_e32 v39, v176
	s_mov_b32 s2, s67
	v_mov_b32_e32 v54, v175
	v_mov_b32_e32 v55, v176
	v_pk_mul_f32 v[182:183], v[38:39], s[2:3] op_sel_hi:[1,0]
	v_pk_fma_f32 v[38:39], v[38:39], s[2:3], v[178:179] op_sel_hi:[1,0,1]
	v_pk_fma_f32 v[54:55], v[54:55], s[2:3], v[22:23] op_sel_hi:[1,0,1]
	v_pk_mul_f32 v[174:175], v[38:39], v[38:39]
	v_pk_mul_f32 v[22:23], v[54:55], v[54:55]
	v_pk_mov_b32 v[174:175], v[178:179], v[174:175] op_sel:[1,0]
	v_pk_mov_b32 v[22:23], v[182:183], v[22:23] op_sel:[1,0]
	v_add_f32_e32 v6, 0, v7
	v_pk_add_f32 v[22:23], v[174:175], v[22:23]
	v_pk_add_f32 v[174:175], v[38:39], v[54:55]
	v_pk_mul_f32 v[178:179], v[38:39], v[54:55]
	v_fmac_f32_e32 v6, 0x3fd744fd, v177
	v_mov_b32_e32 v175, v179
	v_pk_add_f32 v[22:23], v[174:175], v[22:23]
	v_mul_f32_e32 v7, v6, v6
	v_pk_add_f32 v[22:23], v[22:23], v[6:7]
	s_nop 1
	v_mov_b32_dpp v174, v22 quad_perm:[1,0,3,2] row_mask:0xf bank_mask:0xf bound_ctrl:1
	v_mov_b32_dpp v175, v23 quad_perm:[1,0,3,2] row_mask:0xf bank_mask:0xf bound_ctrl:1
	v_pk_add_f32 v[22:23], v[22:23], v[174:175]
	s_nop 1
	v_mov_b32_dpp v174, v22 quad_perm:[2,3,0,1] row_mask:0xf bank_mask:0xf bound_ctrl:1
	v_mov_b32_dpp v175, v23 quad_perm:[2,3,0,1] row_mask:0xf bank_mask:0xf bound_ctrl:1
	v_pk_add_f32 v[22:23], v[22:23], v[174:175]
	s_nop 1
	v_mov_b32_dpp v174, v22 row_half_mirror row_mask:0xf bank_mask:0xf bound_ctrl:1
	v_mov_b32_dpp v175, v23 row_half_mirror row_mask:0xf bank_mask:0xf bound_ctrl:1
	v_pk_add_f32 v[22:23], v[22:23], v[174:175]
	s_nop 1
	v_mov_b32_dpp v174, v22 row_mirror row_mask:0xf bank_mask:0xf bound_ctrl:1
	v_mov_b32_dpp v175, v23 row_mirror row_mask:0xf bank_mask:0xf bound_ctrl:1
	s_and_saveexec_b64 s[6:7], vcc
	v_pk_add_f32 v[22:23], v[22:23], v[174:175]
	ds_write_b64 v181, v[22:23] offset:328
	s_or_b64 exec, exec, s[6:7]
	ds_read2_b32 v[174:175], v69 offset1:32
	ds_read2_b32 v[178:179], v69 offset0:64 offset1:96
	v_mov_b32_e32 v176, v56
	v_mov_b32_e32 v177, v24
	v_pk_add_f32 v[182:183], v[176:177], 0 op_sel_hi:[1,0]
	v_mov_b32_e32 v176, v40
	v_pk_add_f32 v[176:177], v[176:177], 0 op_sel_hi:[1,0]
	s_waitcnt lgkmcnt(1)
	v_mov_b32_e32 v190, v174
	s_waitcnt lgkmcnt(0)
	v_mov_b32_e32 v191, v178
	s_mov_b32 s2, s67
	v_mov_b32_e32 v194, v175
	v_mov_b32_e32 v195, v178
	v_pk_fma_f32 v[174:175], v[190:191], s[2:3], v[182:183] op_sel_hi:[1,0,1]
	v_pk_fma_f32 v[176:177], v[194:195], s[2:3], v[176:177] op_sel_hi:[1,0,1]
	v_pk_mul_f32 v[192:193], v[190:191], s[2:3] op_sel_hi:[1,0]
	v_pk_mul_f32 v[190:191], v[174:175], v[174:175]
	v_pk_mul_f32 v[194:195], v[176:177], v[176:177]
	v_pk_mov_b32 v[182:183], v[182:183], v[190:191] op_sel:[1,0]
	v_pk_mov_b32 v[190:191], v[192:193], v[194:195] op_sel:[1,0]
	v_add_f32_e32 v22, 0, v8
	v_pk_add_f32 v[182:183], v[182:183], v[190:191]
	v_pk_add_f32 v[190:191], v[174:175], v[176:177]
	v_pk_mul_f32 v[192:193], v[174:175], v[176:177]
	v_fmac_f32_e32 v22, 0x3fd744fd, v179
	v_mov_b32_e32 v191, v193
	v_pk_add_f32 v[182:183], v[190:191], v[182:183]
	v_mul_f32_e32 v23, v22, v22
	v_pk_add_f32 v[178:179], v[182:183], v[22:23]
	s_nop 1
	v_mov_b32_dpp v182, v178 quad_perm:[1,0,3,2] row_mask:0xf bank_mask:0xf bound_ctrl:1
	v_mov_b32_dpp v183, v179 quad_perm:[1,0,3,2] row_mask:0xf bank_mask:0xf bound_ctrl:1
	v_pk_add_f32 v[178:179], v[178:179], v[182:183]
	s_nop 1
	v_mov_b32_dpp v182, v178 quad_perm:[2,3,0,1] row_mask:0xf bank_mask:0xf bound_ctrl:1
	v_mov_b32_dpp v183, v179 quad_perm:[2,3,0,1] row_mask:0xf bank_mask:0xf bound_ctrl:1
	v_pk_add_f32 v[178:179], v[178:179], v[182:183]
	s_nop 1
	v_mov_b32_dpp v182, v178 row_half_mirror row_mask:0xf bank_mask:0xf bound_ctrl:1
	v_mov_b32_dpp v183, v179 row_half_mirror row_mask:0xf bank_mask:0xf bound_ctrl:1
	v_pk_add_f32 v[178:179], v[178:179], v[182:183]
	s_nop 1
	v_mov_b32_dpp v182, v178 row_mirror row_mask:0xf bank_mask:0xf bound_ctrl:1
	v_mov_b32_dpp v183, v179 row_mirror row_mask:0xf bank_mask:0xf bound_ctrl:1
	s_and_saveexec_b64 s[6:7], vcc
	v_pk_add_f32 v[178:179], v[178:179], v[182:183]
	ds_write_b64 v181, v[178:179] offset:336
	s_or_b64 exec, exec, s[6:7]
	ds_read2_b32 v[178:179], v71 offset1:32
	ds_read2_b32 v[182:183], v71 offset0:64 offset1:96
	v_mov_b32_e32 v24, v57
	v_pk_add_f32 v[190:191], v[24:25], 0 op_sel_hi:[1,0]
	v_mov_b32_e32 v24, v41
	v_pk_add_f32 v[24:25], v[24:25], 0 op_sel_hi:[1,0]
	s_waitcnt lgkmcnt(1)
	v_mov_b32_e32 v40, v178
	s_waitcnt lgkmcnt(0)
	v_mov_b32_e32 v41, v182
	s_mov_b32 s2, s67
	v_mov_b32_e32 v56, v179
	v_mov_b32_e32 v57, v182
	v_pk_mul_f32 v[192:193], v[40:41], s[2:3] op_sel_hi:[1,0]
	v_pk_fma_f32 v[40:41], v[40:41], s[2:3], v[190:191] op_sel_hi:[1,0,1]
	v_pk_fma_f32 v[56:57], v[56:57], s[2:3], v[24:25] op_sel_hi:[1,0,1]
	v_pk_mul_f32 v[178:179], v[40:41], v[40:41]
	v_pk_mul_f32 v[24:25], v[56:57], v[56:57]
	v_pk_mov_b32 v[178:179], v[190:191], v[178:179] op_sel:[1,0]
	v_pk_mov_b32 v[24:25], v[192:193], v[24:25] op_sel:[1,0]
	v_add_f32_e32 v8, 0, v9
	v_pk_add_f32 v[24:25], v[178:179], v[24:25]
	v_pk_add_f32 v[178:179], v[40:41], v[56:57]
	v_pk_mul_f32 v[190:191], v[40:41], v[56:57]
	v_fmac_f32_e32 v8, 0x3fd744fd, v183
	v_mov_b32_e32 v179, v191
	v_pk_add_f32 v[24:25], v[178:179], v[24:25]
	v_mul_f32_e32 v9, v8, v8
	v_pk_add_f32 v[24:25], v[24:25], v[8:9]
	s_nop 1
	v_mov_b32_dpp v178, v24 quad_perm:[1,0,3,2] row_mask:0xf bank_mask:0xf bound_ctrl:1
	v_mov_b32_dpp v179, v25 quad_perm:[1,0,3,2] row_mask:0xf bank_mask:0xf bound_ctrl:1
	v_pk_add_f32 v[24:25], v[24:25], v[178:179]
	s_nop 1
	v_mov_b32_dpp v178, v24 quad_perm:[2,3,0,1] row_mask:0xf bank_mask:0xf bound_ctrl:1
	v_mov_b32_dpp v179, v25 quad_perm:[2,3,0,1] row_mask:0xf bank_mask:0xf bound_ctrl:1
	v_pk_add_f32 v[24:25], v[24:25], v[178:179]
	s_nop 1
	v_mov_b32_dpp v178, v24 row_half_mirror row_mask:0xf bank_mask:0xf bound_ctrl:1
	v_mov_b32_dpp v179, v25 row_half_mirror row_mask:0xf bank_mask:0xf bound_ctrl:1
	v_pk_add_f32 v[24:25], v[24:25], v[178:179]
	s_nop 1
	v_mov_b32_dpp v178, v24 row_mirror row_mask:0xf bank_mask:0xf bound_ctrl:1
	v_mov_b32_dpp v179, v25 row_mirror row_mask:0xf bank_mask:0xf bound_ctrl:1
	s_and_saveexec_b64 s[6:7], vcc
	v_pk_add_f32 v[24:25], v[24:25], v[178:179]
	ds_write_b64 v181, v[24:25] offset:344
	s_or_b64 exec, exec, s[6:7]
	s_waitcnt vmcnt(0)
;   DI void operator()(f32x16 (&acc)[2][4], int grow0, int gcol0, int lane, int w, char* lds) {
;     ...
;       for (int qq = 0; qq < 2; ++qq)
; #pragma unroll
;         for (int e = 0; e < 4; ++e) {
;           const int i = 4 * (2 * (ps & 1) + qq) + e;
;           const float* xr = (const float*)(xs + (8 * qq + 4 * hh + e) * 512) + l31;
;           float s1 = 0.f, s2 = 0.f;
; #pragma unroll
;           for (int nt = 0; nt < 4; ++nt) {
;             float v = (acc[mt][nt][i] + bia[nt]) * csc[nt];
;             float z = ALPHA * xr[nt * 32] + hs * v;
;             acc[mt][nt][i] = z; s1 += z; s2 += z * z;
;           }
;           s1 = row16_sum(s1); s2 = row16_sum(s2);
;           if ((lane & 15) == 0) { f32x2 sv = {s1, s2}; *(f32x2*)(redw + (mt * 32 + (i & 3) + 8 * (i >> 2)) * 2) = sv; }
	ds_read2_b32 v[182:183], v73 offset1:32
	ds_read2_b32 v[192:193], v73 offset0:64 offset1:96
	v_add_f32_e32 v179, 0, v42
	v_mov_b32_e32 v190, v58
	v_mov_b32_e32 v191, v26
	s_waitcnt lgkmcnt(1)
	v_fmac_f32_e32 v179, 0x3fd744fd, v183
	v_pk_add_f32 v[194:195], v[190:191], 0 op_sel_hi:[1,0]
	s_waitcnt lgkmcnt(0)
	v_mov_b32_e32 v183, v192
	s_mov_b32 s2, s67
	v_pk_fma_f32 v[190:191], v[182:183], s[2:3], v[194:195] op_sel_hi:[1,0,1]
	v_mov_b32_e32 v178, v192
	v_pk_mul_f32 v[182:183], v[190:191], v[190:191]
	v_mov_b32_e32 v196, v165
	v_mov_b32_e32 v197, v179
	v_pk_mov_b32 v[182:183], v[194:195], v[182:183] op_sel:[1,0]
	v_add_f32_e32 v24, 0, v10
	v_pk_fma_f32 v[182:183], v[178:179], v[196:197], v[182:183]
	v_fmac_f32_e32 v24, 0x3fd744fd, v193
	v_pk_mov_b32 v[194:195], v[178:179], v[182:183] op_sel:[1,0]
	v_mul_f32_e32 v25, v24, v24
	v_pk_add_f32 v[196:197], v[190:191], v[194:195]
	v_pk_mul_f32 v[194:195], v[190:191], v[194:195]
	s_nop 0
	v_mov_b32_e32 v197, v195
	v_pk_add_f32 v[194:195], v[182:183], v[196:197]
	s_nop 0
	v_pk_add_f32 v[192:193], v[194:195], v[24:25]
	s_nop 1
	v_mov_b32_dpp v194, v192 quad_perm:[1,0,3,2] row_mask:0xf bank_mask:0xf bound_ctrl:1
	v_mov_b32_dpp v195, v193 quad_perm:[1,0,3,2] row_mask:0xf bank_mask:0xf bound_ctrl:1
	v_pk_add_f32 v[192:193], v[192:193], v[194:195]
	s_nop 1
	v_mov_b32_dpp v194, v192 quad_perm:[2,3,0,1] row_mask:0xf bank_mask:0xf bound_ctrl:1
	v_mov_b32_dpp v195, v193 quad_perm:[2,3,0,1] row_mask:0xf bank_mask:0xf bound_ctrl:1
	v_pk_add_f32 v[192:193], v[192:193], v[194:195]
	s_nop 1
	v_mov_b32_dpp v194, v192 row_half_mirror row_mask:0xf bank_mask:0xf bound_ctrl:1
	v_mov_b32_dpp v195, v193 row_half_mirror row_mask:0xf bank_mask:0xf bound_ctrl:1
	v_pk_add_f32 v[192:193], v[192:193], v[194:195]
	s_nop 1
	v_mov_b32_dpp v194, v192 row_mirror row_mask:0xf bank_mask:0xf bound_ctrl:1
	v_mov_b32_dpp v195, v193 row_mirror row_mask:0xf bank_mask:0xf bound_ctrl:1
	s_and_saveexec_b64 s[6:7], vcc
	v_pk_add_f32 v[192:193], v[192:193], v[194:195]
	ds_write_b64 v181, v[192:193] offset:384
	s_or_b64 exec, exec, s[6:7]
	ds_read2_b32 v[192:193], v85 offset1:32
	ds_read2_b32 v[194:195], v85 offset0:64 offset1:96
	v_mov_b32_e32 v26, v59
	v_pk_add_f32 v[196:197], v[26:27], 0 op_sel_hi:[1,0]
	v_mov_b32_e32 v26, v43
	v_pk_add_f32 v[26:27], v[26:27], 0 op_sel_hi:[1,0]
	s_waitcnt lgkmcnt(1)
	v_mov_b32_e32 v42, v192
	s_waitcnt lgkmcnt(0)
	v_mov_b32_e32 v43, v194
	s_mov_b32 s2, s67
	v_mov_b32_e32 v58, v193
	v_mov_b32_e32 v59, v194
	v_pk_mul_f32 v[198:199], v[42:43], s[2:3] op_sel_hi:[1,0]
	v_pk_fma_f32 v[42:43], v[42:43], s[2:3], v[196:197] op_sel_hi:[1,0,1]
	v_pk_fma_f32 v[58:59], v[58:59], s[2:3], v[26:27] op_sel_hi:[1,0,1]
	v_pk_mul_f32 v[192:193], v[42:43], v[42:43]
	v_pk_mul_f32 v[26:27], v[58:59], v[58:59]
	v_pk_mov_b32 v[192:193], v[196:197], v[192:193] op_sel:[1,0]
	v_pk_mov_b32 v[26:27], v[198:199], v[26:27] op_sel:[1,0]
	v_add_f32_e32 v10, 0, v11
	v_pk_add_f32 v[26:27], v[192:193], v[26:27]
	v_pk_add_f32 v[192:193], v[42:43], v[58:59]
	v_pk_mul_f32 v[196:197], v[42:43], v[58:59]
	v_fmac_f32_e32 v10, 0x3fd744fd, v195
	v_mov_b32_e32 v193, v197
	v_pk_add_f32 v[26:27], v[192:193], v[26:27]
	v_mul_f32_e32 v11, v10, v10
	v_pk_add_f32 v[26:27], v[26:27], v[10:11]
	s_nop 1
	v_mov_b32_dpp v192, v26 quad_perm:[1,0,3,2] row_mask:0xf bank_mask:0xf bound_ctrl:1
	v_mov_b32_dpp v193, v27 quad_perm:[1,0,3,2] row_mask:0xf bank_mask:0xf bound_ctrl:1
	v_pk_add_f32 v[26:27], v[26:27], v[192:193]
	s_nop 1
	v_mov_b32_dpp v192, v26 quad_perm:[2,3,0,1] row_mask:0xf bank_mask:0xf bound_ctrl:1
	v_mov_b32_dpp v193, v27 quad_perm:[2,3,0,1] row_mask:0xf bank_mask:0xf bound_ctrl:1
	v_pk_add_f32 v[26:27], v[26:27], v[192:193]
	s_nop 1
	v_mov_b32_dpp v192, v26 row_half_mirror row_mask:0xf bank_mask:0xf bound_ctrl:1
	v_mov_b32_dpp v193, v27 row_half_mirror row_mask:0xf bank_mask:0xf bound_ctrl:1
	v_pk_add_f32 v[26:27], v[26:27], v[192:193]
	s_nop 1
	v_mov_b32_dpp v192, v26 row_mirror row_mask:0xf bank_mask:0xf bound_ctrl:1
	v_mov_b32_dpp v193, v27 row_mirror row_mask:0xf bank_mask:0xf bound_ctrl:1
	s_and_saveexec_b64 s[6:7], vcc
	v_pk_add_f32 v[26:27], v[26:27], v[192:193]
	ds_write_b64 v181, v[26:27] offset:392
	s_or_b64 exec, exec, s[6:7]
	ds_read2_b32 v[192:193], v75 offset1:32
	ds_read2_b32 v[196:197], v75 offset0:64 offset1:96
	v_mov_b32_e32 v194, v60
	v_mov_b32_e32 v195, v28
	v_pk_add_f32 v[198:199], v[194:195], 0 op_sel_hi:[1,0]
	v_mov_b32_e32 v194, v44
	v_pk_add_f32 v[194:195], v[194:195], 0 op_sel_hi:[1,0]
	s_waitcnt lgkmcnt(1)
	v_mov_b32_e32 v202, v192
	s_waitcnt lgkmcnt(0)
	v_mov_b32_e32 v203, v196
	s_mov_b32 s2, s67
	v_mov_b32_e32 v206, v193
	v_mov_b32_e32 v207, v196
	v_pk_fma_f32 v[192:193], v[202:203], s[2:3], v[198:199] op_sel_hi:[1,0,1]
	v_pk_fma_f32 v[194:195], v[206:207], s[2:3], v[194:195] op_sel_hi:[1,0,1]
	v_pk_mul_f32 v[204:205], v[202:203], s[2:3] op_sel_hi:[1,0]
	v_pk_mul_f32 v[202:203], v[192:193], v[192:193]
	v_pk_mul_f32 v[206:207], v[194:195], v[194:195]
	v_pk_mov_b32 v[198:199], v[198:199], v[202:203] op_sel:[1,0]
	v_pk_mov_b32 v[202:203], v[204:205], v[206:207] op_sel:[1,0]
	v_add_f32_e32 v26, 0, v12
	v_pk_add_f32 v[198:199], v[198:199], v[202:203]
	v_pk_add_f32 v[202:203], v[192:193], v[194:195]
	v_pk_mul_f32 v[204:205], v[192:193], v[194:195]
	v_fmac_f32_e32 v26, 0x3fd744fd, v197
	v_mov_b32_e32 v203, v205
	v_pk_add_f32 v[198:199], v[202:203], v[198:199]
	v_mul_f32_e32 v27, v26, v26
	v_pk_add_f32 v[196:197], v[198:199], v[26:27]
	s_nop 1
	v_mov_b32_dpp v198, v196 quad_perm:[1,0,3,2] row_mask:0xf bank_mask:0xf bound_ctrl:1
	v_mov_b32_dpp v199, v197 quad_perm:[1,0,3,2] row_mask:0xf bank_mask:0xf bound_ctrl:1
	v_pk_add_f32 v[196:197], v[196:197], v[198:199]
	s_nop 1
	v_mov_b32_dpp v198, v196 quad_perm:[2,3,0,1] row_mask:0xf bank_mask:0xf bound_ctrl:1
	v_mov_b32_dpp v199, v197 quad_perm:[2,3,0,1] row_mask:0xf bank_mask:0xf bound_ctrl:1
	v_pk_add_f32 v[196:197], v[196:197], v[198:199]
	s_nop 1
	v_mov_b32_dpp v198, v196 row_half_mirror row_mask:0xf bank_mask:0xf bound_ctrl:1
	v_mov_b32_dpp v199, v197 row_half_mirror row_mask:0xf bank_mask:0xf bound_ctrl:1
	v_pk_add_f32 v[196:197], v[196:197], v[198:199]
	s_nop 1
	v_mov_b32_dpp v198, v196 row_mirror row_mask:0xf bank_mask:0xf bound_ctrl:1
	v_mov_b32_dpp v199, v197 row_mirror row_mask:0xf bank_mask:0xf bound_ctrl:1
	s_and_saveexec_b64 s[6:7], vcc
	v_pk_add_f32 v[196:197], v[196:197], v[198:199]
	ds_write_b64 v181, v[196:197] offset:400
	s_or_b64 exec, exec, s[6:7]
	ds_read2_b32 v[196:197], v87 offset1:32
	ds_read2_b32 v[198:199], v87 offset0:64 offset1:96
	v_mov_b32_e32 v28, v61
	v_pk_add_f32 v[202:203], v[28:29], 0 op_sel_hi:[1,0]
	v_mov_b32_e32 v28, v45
	v_pk_add_f32 v[28:29], v[28:29], 0 op_sel_hi:[1,0]
	s_waitcnt lgkmcnt(1)
;   DI void operator()(f32x16 (&acc)[2][4], int grow0, int gcol0, int lane, int w, char* lds) {
;     ...
;       for (int qq = 0; qq < 2; ++qq)
; #pragma unroll
;         for (int e = 0; e < 4; ++e) {
;           const int i = 4 * (2 * (ps & 1) + qq) + e;
;           const float* xr = (const float*)(xs + (8 * qq + 4 * hh + e) * 512) + l31;
;           float s1 = 0.f, s2 = 0.f;
; #pragma unroll
;           for (int nt = 0; nt < 4; ++nt) {
;             float v = (acc[mt][nt][i] + bia[nt]) * csc[nt];
;             float z = ALPHA * xr[nt * 32] + hs * v;
;             acc[mt][nt][i] = z; s1 += z; s2 += z * z;
;           }
;           s1 = row16_sum(s1); s2 = row16_sum(s2);
;           if ((lane & 15) == 0) { f32x2 sv = {s1, s2}; *(f32x2*)(redw + (mt * 32 + (i & 3) + 8 * (i >> 2)) * 2) = sv; }
	v_mov_b32_e32 v44, v196
	s_waitcnt lgkmcnt(0)
	v_mov_b32_e32 v45, v198
	s_mov_b32 s2, s67
	v_mov_b32_e32 v60, v197
	v_mov_b32_e32 v61, v198
	v_pk_mul_f32 v[204:205], v[44:45], s[2:3] op_sel_hi:[1,0]
	v_pk_fma_f32 v[44:45], v[44:45], s[2:3], v[202:203] op_sel_hi:[1,0,1]
	v_pk_fma_f32 v[60:61], v[60:61], s[2:3], v[28:29] op_sel_hi:[1,0,1]
	v_pk_mul_f32 v[196:197], v[44:45], v[44:45]
	v_pk_mul_f32 v[28:29], v[60:61], v[60:61]
	v_pk_mov_b32 v[196:197], v[202:203], v[196:197] op_sel:[1,0]
	v_pk_mov_b32 v[28:29], v[204:205], v[28:29] op_sel:[1,0]
	v_add_f32_e32 v12, 0, v13
	v_pk_add_f32 v[28:29], v[196:197], v[28:29]
	v_pk_add_f32 v[196:197], v[44:45], v[60:61]
	v_pk_mul_f32 v[202:203], v[44:45], v[60:61]
	v_fmac_f32_e32 v12, 0x3fd744fd, v199
	v_mov_b32_e32 v197, v203
	v_pk_add_f32 v[28:29], v[196:197], v[28:29]
	v_mul_f32_e32 v13, v12, v12
	v_pk_add_f32 v[28:29], v[28:29], v[12:13]
	s_nop 1
	v_mov_b32_dpp v196, v28 quad_perm:[1,0,3,2] row_mask:0xf bank_mask:0xf bound_ctrl:1
	v_mov_b32_dpp v197, v29 quad_perm:[1,0,3,2] row_mask:0xf bank_mask:0xf bound_ctrl:1
	v_pk_add_f32 v[28:29], v[28:29], v[196:197]
	s_nop 1
	v_mov_b32_dpp v196, v28 quad_perm:[2,3,0,1] row_mask:0xf bank_mask:0xf bound_ctrl:1
	v_mov_b32_dpp v197, v29 quad_perm:[2,3,0,1] row_mask:0xf bank_mask:0xf bound_ctrl:1
	v_pk_add_f32 v[28:29], v[28:29], v[196:197]
	s_nop 1
	v_mov_b32_dpp v196, v28 row_half_mirror row_mask:0xf bank_mask:0xf bound_ctrl:1
	v_mov_b32_dpp v197, v29 row_half_mirror row_mask:0xf bank_mask:0xf bound_ctrl:1
	v_pk_add_f32 v[28:29], v[28:29], v[196:197]
	s_nop 1
	v_mov_b32_dpp v196, v28 row_mirror row_mask:0xf bank_mask:0xf bound_ctrl:1
	v_mov_b32_dpp v197, v29 row_mirror row_mask:0xf bank_mask:0xf bound_ctrl:1
	s_and_saveexec_b64 s[6:7], vcc
	v_pk_add_f32 v[28:29], v[28:29], v[196:197]
	ds_write_b64 v181, v[28:29] offset:408
	s_or_b64 exec, exec, s[6:7]
	ds_read2_b32 v[196:197], v77 offset1:32
	ds_read2_b32 v[202:203], v77 offset0:64 offset1:96
	v_mov_b32_e32 v198, v62
	v_mov_b32_e32 v199, v30
	v_pk_add_f32 v[204:205], v[198:199], 0 op_sel_hi:[1,0]
	v_mov_b32_e32 v198, v46
	v_pk_add_f32 v[198:199], v[198:199], 0 op_sel_hi:[1,0]
	s_waitcnt lgkmcnt(1)
	v_mov_b32_e32 v206, v196
	s_waitcnt lgkmcnt(0)
	v_mov_b32_e32 v207, v202
	s_mov_b32 s2, s67
	v_mov_b32_e32 v212, v197
	v_mov_b32_e32 v213, v202
	v_pk_fma_f32 v[196:197], v[206:207], s[2:3], v[204:205] op_sel_hi:[1,0,1]
	v_pk_fma_f32 v[198:199], v[212:213], s[2:3], v[198:199] op_sel_hi:[1,0,1]
	v_pk_mul_f32 v[208:209], v[206:207], s[2:3] op_sel_hi:[1,0]
	v_pk_mul_f32 v[206:207], v[196:197], v[196:197]
	v_pk_mul_f32 v[212:213], v[198:199], v[198:199]
	v_pk_mov_b32 v[204:205], v[204:205], v[206:207] op_sel:[1,0]
	v_pk_mov_b32 v[206:207], v[208:209], v[212:213] op_sel:[1,0]
	v_add_f32_e32 v28, 0, v14
	v_pk_add_f32 v[204:205], v[204:205], v[206:207]
	v_pk_add_f32 v[206:207], v[196:197], v[198:199]
	v_pk_mul_f32 v[208:209], v[196:197], v[198:199]
	v_fmac_f32_e32 v28, 0x3fd744fd, v203
	v_mov_b32_e32 v207, v209
	v_pk_add_f32 v[204:205], v[206:207], v[204:205]
	v_mul_f32_e32 v29, v28, v28
	v_pk_add_f32 v[202:203], v[204:205], v[28:29]
	s_nop 1
	v_mov_b32_dpp v204, v202 quad_perm:[1,0,3,2] row_mask:0xf bank_mask:0xf bound_ctrl:1
	v_mov_b32_dpp v205, v203 quad_perm:[1,0,3,2] row_mask:0xf bank_mask:0xf bound_ctrl:1
	v_pk_add_f32 v[202:203], v[202:203], v[204:205]
	s_nop 1
	v_mov_b32_dpp v204, v202 quad_perm:[2,3,0,1] row_mask:0xf bank_mask:0xf bound_ctrl:1
	v_mov_b32_dpp v205, v203 quad_perm:[2,3,0,1] row_mask:0xf bank_mask:0xf bound_ctrl:1
	v_pk_add_f32 v[202:203], v[202:203], v[204:205]
	s_nop 1
	v_mov_b32_dpp v204, v202 row_half_mirror row_mask:0xf bank_mask:0xf bound_ctrl:1
	v_mov_b32_dpp v205, v203 row_half_mirror row_mask:0xf bank_mask:0xf bound_ctrl:1
	v_pk_add_f32 v[202:203], v[202:203], v[204:205]
	s_nop 1
	v_mov_b32_dpp v204, v202 row_mirror row_mask:0xf bank_mask:0xf bound_ctrl:1
	v_mov_b32_dpp v205, v203 row_mirror row_mask:0xf bank_mask:0xf bound_ctrl:1
	s_and_saveexec_b64 s[6:7], vcc
	v_pk_add_f32 v[202:203], v[202:203], v[204:205]
	ds_write_b64 v181, v[202:203] offset:448
	s_or_b64 exec, exec, s[6:7]
	ds_read2_b32 v[202:203], v91 offset1:32
	ds_read2_b32 v[204:205], v91 offset0:64 offset1:96
	v_mov_b32_e32 v30, v63
	v_pk_add_f32 v[206:207], v[30:31], 0 op_sel_hi:[1,0]
	v_mov_b32_e32 v30, v47
	v_pk_add_f32 v[30:31], v[30:31], 0 op_sel_hi:[1,0]
	s_waitcnt lgkmcnt(1)
	v_mov_b32_e32 v46, v202
	s_waitcnt lgkmcnt(0)
	v_mov_b32_e32 v47, v204
	s_mov_b32 s2, s67
	v_mov_b32_e32 v62, v203
	v_mov_b32_e32 v63, v204
	v_pk_mul_f32 v[208:209], v[46:47], s[2:3] op_sel_hi:[1,0]
	v_pk_fma_f32 v[46:47], v[46:47], s[2:3], v[206:207] op_sel_hi:[1,0,1]
	v_pk_fma_f32 v[62:63], v[62:63], s[2:3], v[30:31] op_sel_hi:[1,0,1]
	v_pk_mul_f32 v[202:203], v[46:47], v[46:47]
	v_pk_mul_f32 v[30:31], v[62:63], v[62:63]
	v_pk_mov_b32 v[202:203], v[206:207], v[202:203] op_sel:[1,0]
	v_pk_mov_b32 v[30:31], v[208:209], v[30:31] op_sel:[1,0]
	v_add_f32_e32 v14, 0, v15
	v_pk_add_f32 v[30:31], v[202:203], v[30:31]
	v_pk_add_f32 v[202:203], v[46:47], v[62:63]
	v_pk_mul_f32 v[206:207], v[46:47], v[62:63]
	v_fmac_f32_e32 v14, 0x3fd744fd, v205
	v_mov_b32_e32 v203, v207
	v_pk_add_f32 v[30:31], v[202:203], v[30:31]
	v_mul_f32_e32 v15, v14, v14
	v_pk_add_f32 v[30:31], v[30:31], v[14:15]
	s_nop 1
	v_mov_b32_dpp v202, v30 quad_perm:[1,0,3,2] row_mask:0xf bank_mask:0xf bound_ctrl:1
	v_mov_b32_dpp v203, v31 quad_perm:[1,0,3,2] row_mask:0xf bank_mask:0xf bound_ctrl:1
	v_pk_add_f32 v[30:31], v[30:31], v[202:203]
	s_nop 1
	v_mov_b32_dpp v202, v30 quad_perm:[2,3,0,1] row_mask:0xf bank_mask:0xf bound_ctrl:1
	v_mov_b32_dpp v203, v31 quad_perm:[2,3,0,1] row_mask:0xf bank_mask:0xf bound_ctrl:1
	v_pk_add_f32 v[30:31], v[30:31], v[202:203]
	s_nop 1
	v_mov_b32_dpp v202, v30 row_half_mirror row_mask:0xf bank_mask:0xf bound_ctrl:1
	v_mov_b32_dpp v203, v31 row_half_mirror row_mask:0xf bank_mask:0xf bound_ctrl:1
	v_pk_add_f32 v[30:31], v[30:31], v[202:203]
	s_nop 1
	v_mov_b32_dpp v202, v30 row_mirror row_mask:0xf bank_mask:0xf bound_ctrl:1
	v_mov_b32_dpp v203, v31 row_mirror row_mask:0xf bank_mask:0xf bound_ctrl:1
	s_and_saveexec_b64 s[6:7], vcc
	v_pk_add_f32 v[30:31], v[30:31], v[202:203]
	ds_write_b64 v181, v[30:31] offset:456
	s_or_b64 exec, exec, s[6:7]
	ds_read2_b32 v[202:203], v79 offset1:32
	ds_read2_b32 v[206:207], v79 offset0:64 offset1:96
	v_mov_b32_e32 v204, v64
	v_mov_b32_e32 v205, v32
	v_pk_add_f32 v[208:209], v[204:205], 0 op_sel_hi:[1,0]
	v_mov_b32_e32 v204, v48
	v_pk_add_f32 v[204:205], v[204:205], 0 op_sel_hi:[1,0]
	s_waitcnt lgkmcnt(1)
; DI void ag_st64(u64_t* p, u64_t v) { __hip_atomic_store(p, v, __ATOMIC_RELAXED, __HIP_MEMORY_SCOPE_AGENT); }
;   DI void operator()(f32x16 (&acc)[2][4], int grow0, int gcol0, int lane, int w, char* lds) {
;     ...
;           for (int nt = 0; nt < 4; ++nt) {
;             float v = (acc[mt][nt][i] + bia[nt]) * csc[nt];
;             float z = ALPHA * xr[nt * 32] + hs * v;
;             acc[mt][nt][i] = z; s1 += z; s2 += z * z;
;           }
;           s1 = row16_sum(s1); s2 = row16_sum(s2);
;           if ((lane & 15) == 0) { f32x2 sv = {s1, s2}; *(f32x2*)(redw + (mt * 32 + (i & 3) + 8 * (i >> 2)) * 2) = sv; }
;         }
;     }
;     __syncthreads();
;     u64_t* myslots = xstat + ((size_t)pm * 256) * 4;
;     if (tid < 256) {
;       float s1 = (red[tid * 2] + red[(256 + tid) * 2]) + (red[(512 + tid) * 2] + red[(768 + tid) * 2]);
;       float s2 = (red[tid * 2 + 1] + red[(256 + tid) * 2 + 1]) + (red[(512 + tid) * 2 + 1] + red[(768 + tid) * 2 + 1]);
;       ag_st64(myslots + tid * 4 + pn, ((u64_t)__float_as_uint(s2) << 32) | (u64_t)__float_as_uint(s1));
	v_mov_b32_e32 v212, v202
	s_waitcnt lgkmcnt(0)
	v_mov_b32_e32 v213, v206
	s_mov_b32 s2, s67
	v_mov_b32_e32 v226, v203
	v_mov_b32_e32 v227, v206
	v_pk_fma_f32 v[202:203], v[212:213], s[2:3], v[208:209] op_sel_hi:[1,0,1]
	v_pk_fma_f32 v[204:205], v[226:227], s[2:3], v[204:205] op_sel_hi:[1,0,1]
	v_pk_mul_f32 v[214:215], v[212:213], s[2:3] op_sel_hi:[1,0]
	v_pk_mul_f32 v[212:213], v[202:203], v[202:203]
	v_pk_mul_f32 v[226:227], v[204:205], v[204:205]
	v_pk_mov_b32 v[208:209], v[208:209], v[212:213] op_sel:[1,0]
	v_pk_mov_b32 v[212:213], v[214:215], v[226:227] op_sel:[1,0]
	v_add_f32_e32 v30, 0, v16
	v_pk_add_f32 v[208:209], v[208:209], v[212:213]
	v_pk_add_f32 v[212:213], v[202:203], v[204:205]
	v_pk_mul_f32 v[214:215], v[202:203], v[204:205]
	v_fmac_f32_e32 v30, 0x3fd744fd, v207
	v_mov_b32_e32 v213, v215
	v_pk_add_f32 v[208:209], v[212:213], v[208:209]
	v_mul_f32_e32 v31, v30, v30
	v_pk_add_f32 v[206:207], v[208:209], v[30:31]
	s_nop 1
	v_mov_b32_dpp v208, v206 quad_perm:[1,0,3,2] row_mask:0xf bank_mask:0xf bound_ctrl:1
	v_mov_b32_dpp v209, v207 quad_perm:[1,0,3,2] row_mask:0xf bank_mask:0xf bound_ctrl:1
	v_pk_add_f32 v[206:207], v[206:207], v[208:209]
	s_nop 1
	v_mov_b32_dpp v208, v206 quad_perm:[2,3,0,1] row_mask:0xf bank_mask:0xf bound_ctrl:1
	v_mov_b32_dpp v209, v207 quad_perm:[2,3,0,1] row_mask:0xf bank_mask:0xf bound_ctrl:1
	v_pk_add_f32 v[206:207], v[206:207], v[208:209]
	s_nop 1
	v_mov_b32_dpp v208, v206 row_half_mirror row_mask:0xf bank_mask:0xf bound_ctrl:1
	v_mov_b32_dpp v209, v207 row_half_mirror row_mask:0xf bank_mask:0xf bound_ctrl:1
	v_pk_add_f32 v[206:207], v[206:207], v[208:209]
	s_nop 1
	v_mov_b32_dpp v208, v206 row_mirror row_mask:0xf bank_mask:0xf bound_ctrl:1
	v_mov_b32_dpp v209, v207 row_mirror row_mask:0xf bank_mask:0xf bound_ctrl:1
	s_and_saveexec_b64 s[6:7], vcc
	v_pk_add_f32 v[206:207], v[206:207], v[208:209]
	ds_write_b64 v181, v[206:207] offset:464
	s_or_b64 exec, exec, s[6:7]
	ds_read2_b32 v[206:207], v93 offset1:32
	ds_read2_b32 v[208:209], v93 offset0:64 offset1:96
	v_mov_b32_e32 v32, v65
	v_pk_add_f32 v[64:65], v[32:33], 0 op_sel_hi:[1,0]
	v_mov_b32_e32 v32, v49
	v_pk_add_f32 v[48:49], v[32:33], 0 op_sel_hi:[1,0]
	s_waitcnt lgkmcnt(1)
	v_mov_b32_e32 v32, v206
	s_waitcnt lgkmcnt(0)
	v_mov_b32_e32 v33, v208
	s_mov_b32 s2, s67
	v_mov_b32_e32 v206, v207
	v_mov_b32_e32 v207, v208
	v_pk_mul_f32 v[212:213], v[32:33], s[2:3] op_sel_hi:[1,0]
	v_pk_fma_f32 v[32:33], v[32:33], s[2:3], v[64:65] op_sel_hi:[1,0,1]
	v_pk_fma_f32 v[48:49], v[206:207], s[2:3], v[48:49] op_sel_hi:[1,0,1]
	v_pk_mul_f32 v[214:215], v[32:33], v[32:33]
	v_pk_mul_f32 v[206:207], v[48:49], v[48:49]
	v_pk_mov_b32 v[64:65], v[64:65], v[214:215] op_sel:[1,0]
	v_pk_mov_b32 v[206:207], v[212:213], v[206:207] op_sel:[1,0]
	v_add_f32_e32 v16, 0, v17
	v_pk_add_f32 v[64:65], v[64:65], v[206:207]
	v_pk_add_f32 v[206:207], v[32:33], v[48:49]
	v_pk_mul_f32 v[212:213], v[32:33], v[48:49]
	v_fmac_f32_e32 v16, 0x3fd744fd, v209
	v_mov_b32_e32 v207, v213
	v_pk_add_f32 v[64:65], v[206:207], v[64:65]
	v_mul_f32_e32 v17, v16, v16
	v_pk_add_f32 v[64:65], v[64:65], v[16:17]
	s_nop 1
	v_mov_b32_dpp v206, v64 quad_perm:[1,0,3,2] row_mask:0xf bank_mask:0xf bound_ctrl:1
	v_mov_b32_dpp v207, v65 quad_perm:[1,0,3,2] row_mask:0xf bank_mask:0xf bound_ctrl:1
	v_pk_add_f32 v[64:65], v[64:65], v[206:207]
	s_nop 1
	v_mov_b32_dpp v206, v64 quad_perm:[2,3,0,1] row_mask:0xf bank_mask:0xf bound_ctrl:1
	v_mov_b32_dpp v207, v65 quad_perm:[2,3,0,1] row_mask:0xf bank_mask:0xf bound_ctrl:1
	v_pk_add_f32 v[64:65], v[64:65], v[206:207]
	s_nop 1
	v_mov_b32_dpp v206, v64 row_half_mirror row_mask:0xf bank_mask:0xf bound_ctrl:1
	v_mov_b32_dpp v207, v65 row_half_mirror row_mask:0xf bank_mask:0xf bound_ctrl:1
	v_pk_add_f32 v[64:65], v[64:65], v[206:207]
	s_nop 1
	v_mov_b32_dpp v206, v64 row_mirror row_mask:0xf bank_mask:0xf bound_ctrl:1
	v_mov_b32_dpp v207, v65 row_mirror row_mask:0xf bank_mask:0xf bound_ctrl:1
	s_and_saveexec_b64 s[6:7], vcc
	v_pk_add_f32 v[64:65], v[64:65], v[206:207]
	ds_write_b64 v181, v[64:65] offset:472
	s_or_b64 exec, exec, s[6:7]
	v_ashrrev_i32_e32 v206, 8, v163
	v_ashrrev_i32_e32 v207, 31, v206
	v_lshlrev_b64 v[64:65], 13, v[206:207]
	v_lshl_add_u64 v[64:65], s[8:9], 0, v[64:65]
	v_cmp_gt_i32_e64 s[40:41], s60, v164
	v_ashrrev_i32_e32 v201, 31, v200
	s_waitcnt lgkmcnt(0)
	s_barrier
	s_and_saveexec_b64 s[6:7], s[40:41]
	s_cbranch_execz .LBB0_240
	v_lshl_add_u32 v0, v164, 3, v221
	ds_read2st64_b64 v[212:215], v0 offset1:4
	ds_read2st64_b64 v[226:229], v0 offset0:8 offset1:12
	v_ashrrev_i32_e32 v208, 8, v184
	v_ashrrev_i32_e32 v209, 31, v208
	s_waitcnt lgkmcnt(1)
	v_mov_b32_e32 v230, v212
	s_waitcnt lgkmcnt(0)
	v_mov_b32_e32 v231, v226
	v_mov_b32_e32 v232, v214
	v_mov_b32_e32 v233, v228
	v_mov_b32_e32 v226, v213
	v_mov_b32_e32 v228, v215
	v_pk_add_f32 v[230:231], v[230:231], v[232:233]
	v_pk_add_f32 v[212:213], v[226:227], v[228:229]
	v_pk_add_f32 v[230:231], v[230:231], v[230:231] op_sel:[0,1] op_sel_hi:[1,0]
	v_pk_add_f32 v[212:213], v[212:213], v[212:213] op_sel:[0,1] op_sel_hi:[1,0]
	v_lshl_add_u64 v[214:215], v[200:201], 3, v[64:65]
	v_lshl_add_u64 v[208:209], v[208:209], 3, v[214:215]
	v_mov_b32_e32 v231, v212
	global_store_dwordx2 v[208:209], v[230:231], off sc1

; DI f32x16 mfma(bf16x8 a, bf16x8 b, f32x16 c) { return __builtin_amdgcn_mfma_f32_32x32x16_bf16(a, b, c, 0, 0, 0); }
; template <int BK> DI int swz(int row) { constexpr int CPR = BK / 8; return (row / (16 / CPR)) % CPR; }
; DI void wait_vm0() { asm volatile("s_waitcnt vmcnt(0)" ::: "memory"); }
;   DI void pre(int grow0, int gcol0, int lane, int w, char* lds) { xpass(0, grow0, gcol0, lane, w, lds); }
;     ...
;   for (int kt = 0; kt < nk; ++kt) {
;     char* cur = lds + (kt & 1) * STG; char* nxt = lds + ((kt + 1) & 1) * STG;
;     const bool more = kt + 1 < nk;
;     const bf16_t* An = Ag + (kt + 1) * BK; const bf16_t* Bn = Bg + (kt + 1) * BK;
;     if (!more) epi.pre(row0 + wm * 64, col0 + wn * (32 * NTW), lane, w, lds);
;     bf16x8 fa[2][2], fb[2][NTW];
; #pragma unroll
;     for (int mt = 0; mt < 2; ++mt) { int row = wm * 64 + mt * 32 + l31; fa[0][mt] = *(const bf16x8*)(cur + row * (BK * 2) + ((hh ^ swz<BK>(row)) << 4)); }
; #pragma unroll
;     for (int nt = 0; nt < NTW; ++nt) { int row = wn * (32 * NTW) + nt * 32 + l31; fb[0][nt] = *(const bf16x8*)(cur + ABYTES + row * (BK * 2) + ((hh ^ swz<BK>(row)) << 4)); }
; #pragma unroll
;     for (int kk = 0; kk < NKK; ++kk) {
;       if (kk + 1 < NKK) {
;         const int ch = (kk + 1) * 2 + hh;
; #pragma unroll
;         for (int mt = 0; mt < 2; ++mt) { int row = wm * 64 + mt * 32 + l31; fa[(kk + 1) & 1][mt] = *(const bf16x8*)(cur + row * (BK * 2) + ((ch ^ swz<BK>(row)) << 4)); }
; #pragma unroll
;         for (int nt = 0; nt < NTW; ++nt) { int row = wn * (32 * NTW) + nt * 32 + l31; fb[(kk + 1) & 1][nt] = *(const bf16x8*)(cur + ABYTES + row * (BK * 2) + ((ch ^ swz<BK>(row)) << 4)); }
;       }
;       if (more) {
; #pragma unroll
;         for (int q = 0; q < PPK; ++q) {
;           const int pi = kk * PPK + q;
;           if (pi < NPA) stage_piece<BM, BK>(An, lda, nxt, tid, pi, wv);
;           else if (pi < NP) stage_piece<BN, BK>(Bn, ldb, nxt + ABYTES, tid, pi - NPA, wv);
;         }
;       }
;       __builtin_amdgcn_s_setprio(1);
; #pragma unroll
;       for (int mt = 0; mt < 2; ++mt)
; #pragma unroll
;         for (int nt = 0; nt < NTW; ++nt) acc[mt][nt] = mfma(fa[kk & 1][mt], fb[kk & 1][nt], acc[mt][nt]);
;       __builtin_amdgcn_s_setprio(0);
;       __builtin_amdgcn_sched_barrier(0);
;     }
;     wait_vm0();
;     __syncthreads();
.LBB0_284:
	s_and_b32 s35, s7, 0x10000
	s_xor_b32 s100, s35, 0x10000
	v_add3_u32 v190, s100, v140, v161
	v_add3_u32 v194, s100, v142, v163
	ds_read_b128 v[190:193], v190
	v_add3_u32 v198, s100, v143, v159
	ds_read_b128 v[194:197], v194
	v_add3_u32 v202, s100, v152, v160
	ds_read_b128 v[198:201], v198 offset:32768
	v_add3_u32 v206, s100, v153, v157
	ds_read_b128 v[202:205], v202 offset:32768
	v_add3_u32 v210, s100, v156, v158
	ds_read_b128 v[206:209], v206 offset:32768
	ds_read_b128 v[210:213], v210 offset:32768
	s_waitcnt lgkmcnt(6)
	s_mov_b32 m0, s34
	v_lshl_add_u64 v[228:229], v[214:215], 0, s[28:29]
	v_mfma_f32_32x32x16_bf16 v[114:129], v[166:169], v[174:177], v[114:129]
	global_load_lds_dwordx4 v[228:229], off
	s_add_i32 m0, s34, 0x2000
	v_lshl_add_u64 v[228:229], v[214:215], 0, s[24:25]
	v_mfma_f32_32x32x16_bf16 v[98:113], v[166:169], v[178:181], v[98:113]
	v_mfma_f32_32x32x16_bf16 v[82:97], v[166:169], v[182:185], v[82:97]
	global_load_lds_dwordx4 v[228:229], off
	s_add_i32 m0, s34, 0x4000
	v_lshl_add_u64 v[228:229], v[214:215], 0, s[26:27]
	v_mfma_f32_32x32x16_bf16 v[66:81], v[166:169], v[186:189], v[66:81]
	v_mfma_f32_32x32x16_bf16 v[50:65], v[170:173], v[174:177], v[50:65]
	global_load_lds_dwordx4 v[228:229], off
	s_add_i32 m0, s34, 0x6000
	v_lshl_add_u64 v[228:229], v[214:215], 0, s[38:39]
	v_mfma_f32_32x32x16_bf16 v[34:49], v[170:173], v[178:181], v[34:49]
	v_mfma_f32_32x32x16_bf16 v[18:33], v[170:173], v[182:185], v[18:33]
	global_load_lds_dwordx4 v[228:229], off
	v_mfma_f32_32x32x16_bf16 v[2:17], v[170:173], v[186:189], v[2:17]
	v_add3_u32 v166, s100, v140, v149
	v_add3_u32 v170, s100, v142, v150
	ds_read_b128 v[166:169], v166
	v_add3_u32 v174, s100, v143, v147
	ds_read_b128 v[170:173], v170
	v_add3_u32 v178, s100, v152, v148
	ds_read_b128 v[174:177], v174 offset:32768
	v_add3_u32 v182, s100, v153, v145
	ds_read_b128 v[178:181], v178 offset:32768
	v_add3_u32 v186, s100, v156, v146
	ds_read_b128 v[182:185], v182 offset:32768
	ds_read_b128 v[186:189], v186 offset:32768
	s_waitcnt lgkmcnt(6)
	v_mfma_f32_32x32x16_bf16 v[114:129], v[190:193], v[198:201], v[114:129]
	v_mfma_f32_32x32x16_bf16 v[98:113], v[190:193], v[202:205], v[98:113]
	v_mfma_f32_32x32x16_bf16 v[82:97], v[190:193], v[206:209], v[82:97]
	v_mfma_f32_32x32x16_bf16 v[66:81], v[190:193], v[210:213], v[66:81]
	v_mfma_f32_32x32x16_bf16 v[50:65], v[194:197], v[198:201], v[50:65]
	v_mfma_f32_32x32x16_bf16 v[34:49], v[194:197], v[202:205], v[34:49]
	v_mfma_f32_32x32x16_bf16 v[18:33], v[194:197], v[206:209], v[18:33]
	v_mfma_f32_32x32x16_bf16 v[2:17], v[194:197], v[210:213], v[2:17]
	v_add3_u32 v190, s100, v140, v138
	v_add3_u32 v194, s100, v142, v139
	ds_read_b128 v[190:193], v190
	v_add3_u32 v198, s100, v143, v136
	ds_read_b128 v[194:197], v194
	v_add3_u32 v202, s100, v152, v137
	ds_read_b128 v[198:201], v198 offset:32768
	v_add3_u32 v206, s100, v153, v134
	ds_read_b128 v[202:205], v202 offset:32768
	v_add3_u32 v210, s100, v156, v135
	ds_read_b128 v[206:209], v206 offset:32768
	ds_read_b128 v[210:213], v210 offset:32768
	s_waitcnt lgkmcnt(6)
	v_mfma_f32_32x32x16_bf16 v[114:129], v[166:169], v[174:177], v[114:129]
	v_mfma_f32_32x32x16_bf16 v[98:113], v[166:169], v[178:181], v[98:113]
	v_mfma_f32_32x32x16_bf16 v[82:97], v[166:169], v[182:185], v[82:97]
	v_mfma_f32_32x32x16_bf16 v[66:81], v[166:169], v[186:189], v[66:81]
	v_mfma_f32_32x32x16_bf16 v[50:65], v[170:173], v[174:177], v[50:65]
	v_mfma_f32_32x32x16_bf16 v[34:49], v[170:173], v[178:181], v[34:49]
	v_mfma_f32_32x32x16_bf16 v[18:33], v[170:173], v[182:185], v[18:33]
	v_mfma_f32_32x32x16_bf16 v[2:17], v[170:173], v[186:189], v[2:17]
	s_add_u32 s30, s30, 0x80
	s_addc_u32 s31, s31, 0
	s_add_i32 s7, s7, 0x10000
	s_waitcnt vmcnt(0) lgkmcnt(0)
	s_barrier
	s_cmpk_eq_i32 s30, 0x780
	s_cbranch_scc1 .Lk284_exit
	s_add_i32 s34, s100, s3
	v_lshl_add_u64 v[214:215], v[130:131], 0, s[30:31]
	v_lshl_add_u64 v[226:227], v[132:133], 0, s[30:31]
	s_add_i32 m0, s34, 0x8000
	v_lshl_add_u64 v[228:229], v[226:227], 0, s[28:29]
	v_mfma_f32_32x32x16_bf16 v[114:129], v[190:193], v[198:201], v[114:129]
	global_load_lds_dwordx4 v[228:229], off
	v_add3_u32 v166, s35, v140, v141
	v_add3_u32 v170, s35, v142, v144
	ds_read_b128 v[166:169], v166
	v_add3_u32 v174, s35, v143, v151
	ds_read_b128 v[170:173], v170
	v_add3_u32 v178, s35, v152, v154
	ds_read_b128 v[174:177], v174 offset:32768
	v_add3_u32 v182, s35, v153, v155
	ds_read_b128 v[178:181], v178 offset:32768
	v_add3_u32 v186, s35, v156, v164
	ds_read_b128 v[182:185], v182 offset:32768
	ds_read_b128 v[186:189], v186 offset:32768
	s_add_i32 m0, s34, 0xa000
	v_lshl_add_u64 v[228:229], v[226:227], 0, s[24:25]
	v_mfma_f32_32x32x16_bf16 v[98:113], v[190:193], v[202:205], v[98:113]
	v_mfma_f32_32x32x16_bf16 v[82:97], v[190:193], v[206:209], v[82:97]
	global_load_lds_dwordx4 v[228:229], off
	s_add_i32 m0, s34, 0xc000
	v_lshl_add_u64 v[228:229], v[226:227], 0, s[26:27]
	v_mfma_f32_32x32x16_bf16 v[66:81], v[190:193], v[210:213], v[66:81]
	v_mfma_f32_32x32x16_bf16 v[50:65], v[194:197], v[198:201], v[50:65]
	global_load_lds_dwordx4 v[228:229], off
	s_add_i32 m0, s34, 0xe000
	v_lshl_add_u64 v[228:229], v[226:227], 0, s[38:39]
	v_mfma_f32_32x32x16_bf16 v[34:49], v[194:197], v[202:205], v[34:49]
	v_mfma_f32_32x32x16_bf16 v[18:33], v[194:197], v[206:209], v[18:33]
	global_load_lds_dwordx4 v[228:229], off
	v_mfma_f32_32x32x16_bf16 v[2:17], v[194:197], v[210:213], v[2:17]
	s_branch .LBB0_284
; DI f32x16 mfma(bf16x8 a, bf16x8 b, f32x16 c) { return __builtin_amdgcn_mfma_f32_32x32x16_bf16(a, b, c, 0, 0, 0); }
; template <int BK> DI int swz(int row) { constexpr int CPR = BK / 8; return (row / (16 / CPR)) % CPR; }
; DI void wait_vm0() { asm volatile("s_waitcnt vmcnt(0)" ::: "memory"); }
;   DI void pre(int grow0, int gcol0, int lane, int w, char* lds) { xpass(0, grow0, gcol0, lane, w, lds); }
;     ...
;     if (!more) epi.pre(row0 + wm * 64, col0 + wn * (32 * NTW), lane, w, lds);
;     bf16x8 fa[2][2], fb[2][NTW];
; #pragma unroll
;     for (int mt = 0; mt < 2; ++mt) { int row = wm * 64 + mt * 32 + l31; fa[0][mt] = *(const bf16x8*)(cur + row * (BK * 2) + ((hh ^ swz<BK>(row)) << 4)); }
; #pragma unroll
;     for (int nt = 0; nt < NTW; ++nt) { int row = wn * (32 * NTW) + nt * 32 + l31; fb[0][nt] = *(const bf16x8*)(cur + ABYTES + row * (BK * 2) + ((hh ^ swz<BK>(row)) << 4)); }
; #pragma unroll
;     for (int kk = 0; kk < NKK; ++kk) {
;       if (kk + 1 < NKK) {
;         const int ch = (kk + 1) * 2 + hh;
; #pragma unroll
;         for (int mt = 0; mt < 2; ++mt) { int row = wm * 64 + mt * 32 + l31; fa[(kk + 1) & 1][mt] = *(const bf16x8*)(cur + row * (BK * 2) + ((ch ^ swz<BK>(row)) << 4)); }
; #pragma unroll
;         for (int nt = 0; nt < NTW; ++nt) { int row = wn * (32 * NTW) + nt * 32 + l31; fb[(kk + 1) & 1][nt] = *(const bf16x8*)(cur + ABYTES + row * (BK * 2) + ((ch ^ swz<BK>(row)) << 4)); }
;       }
;       if (more) {
; #pragma unroll
;         for (int q = 0; q < PPK; ++q) {
;           const int pi = kk * PPK + q;
;           if (pi < NPA) stage_piece<BM, BK>(An, lda, nxt, tid, pi, wv);
;           else if (pi < NP) stage_piece<BN, BK>(Bn, ldb, nxt + ABYTES, tid, pi - NPA, wv);
;         }
;       }
;       __builtin_amdgcn_s_setprio(1);
; #pragma unroll
;       for (int mt = 0; mt < 2; ++mt)
; #pragma unroll
;         for (int nt = 0; nt < NTW; ++nt) acc[mt][nt] = mfma(fa[kk & 1][mt], fb[kk & 1][nt], acc[mt][nt]);
;       __builtin_amdgcn_s_setprio(0);
;       __builtin_amdgcn_sched_barrier(0);
;     }
;     wait_vm0();
;     __syncthreads();
.Lk284_exit:
	v_add3_u32 v166, s35, v140, v141
	v_add3_u32 v170, s35, v142, v144
	ds_read_b128 v[166:169], v166
	v_add3_u32 v174, s35, v143, v151
	ds_read_b128 v[170:173], v170
	v_add3_u32 v178, s35, v152, v154
	ds_read_b128 v[174:177], v174 offset:32768
	v_add3_u32 v182, s35, v153, v155
	ds_read_b128 v[178:181], v178 offset:32768
	v_add3_u32 v186, s35, v156, v164
	ds_read_b128 v[182:185], v182 offset:32768
	ds_read_b128 v[186:189], v186 offset:32768
	v_mfma_f32_32x32x16_bf16 v[114:129], v[190:193], v[198:201], v[114:129]
	v_mfma_f32_32x32x16_bf16 v[98:113], v[190:193], v[202:205], v[98:113]
	v_mfma_f32_32x32x16_bf16 v[82:97], v[190:193], v[206:209], v[82:97]
	v_mfma_f32_32x32x16_bf16 v[66:81], v[190:193], v[210:213], v[66:81]
	v_mfma_f32_32x32x16_bf16 v[50:65], v[194:197], v[198:201], v[50:65]
	v_mfma_f32_32x32x16_bf16 v[34:49], v[194:197], v[202:205], v[34:49]
	v_mfma_f32_32x32x16_bf16 v[18:33], v[194:197], v[206:209], v[18:33]
	v_mfma_f32_32x32x16_bf16 v[2:17], v[194:197], v[210:213], v[2:17]
	s_waitcnt lgkmcnt(0)
	v_add_u32_e32 v0, 0x10000, v140
	v_add_u32_e32 v198, 0x10000, v142
	v_add_u32_e32 v130, v0, v141
	v_add_u32_e32 v140, v198, v144
	v_add_u32_e32 v199, 0x18000, v143
	v_add_u32_e32 v200, 0x18000, v152
	ds_read_b128 v[130:133], v130
	ds_read_b128 v[166:169], v140
	v_add_u32_e32 v140, v199, v151
	v_add_u32_e32 v144, v200, v154
	v_add_u32_e32 v201, 0x18000, v153
	ds_read_b128 v[140:143], v140
	ds_read_b128 v[170:173], v144
	v_add_u32_e32 v144, v201, v155
	v_add_u32_e32 v202, 0x18000, v156
	v_add_u32_e32 v151, v202, v164
	ds_read_b128 v[152:155], v144
	ds_read_b128 v[174:177], v151
	v_add_u32_e32 v144, v0, v161
	v_add_u32_e32 v151, v198, v163
	ds_read_b128 v[178:181], v144
	ds_read_b128 v[182:185], v151
	v_add_u32_e32 v144, v199, v159
	v_add_u32_e32 v151, v200, v160
	ds_read_b128 v[186:189], v144
	ds_read_b128 v[190:193], v151
	v_add_u32_e32 v144, v201, v157
	v_add_u32_e32 v151, v202, v158
	ds_read_b128 v[156:159], v144
	ds_read_b128 v[194:197], v151
	s_add_i32 s44, s44, s94
	s_cmpk_gt_i32 s44, 0xff
	s_cselect_b64 s[30:31], -1, 0
	s_cmpk_lt_i32 s44, 0x100
	s_setprio 1
	s_waitcnt lgkmcnt(9)
	v_mfma_f32_32x32x16_bf16 v[114:129], v[130:133], v[140:143], v[114:129]
	s_waitcnt lgkmcnt(8)
	v_mfma_f32_32x32x16_bf16 v[98:113], v[130:133], v[170:173], v[98:113]
	s_waitcnt lgkmcnt(7)
	v_mfma_f32_32x32x16_bf16 v[82:97], v[130:133], v[152:155], v[82:97]
	s_waitcnt lgkmcnt(6)
	v_mfma_f32_32x32x16_bf16 v[66:81], v[130:133], v[174:177], v[66:81]
	v_mfma_f32_32x32x16_bf16 v[50:65], v[166:169], v[140:143], v[50:65]
	v_mfma_f32_32x32x16_bf16 v[34:49], v[166:169], v[170:173], v[34:49]
	v_mfma_f32_32x32x16_bf16 v[18:33], v[166:169], v[152:155], v[18:33]
	v_mfma_f32_32x32x16_bf16 v[2:17], v[166:169], v[174:177], v[2:17]
	s_setprio 0
	v_add_u32_e32 v130, v0, v149
	v_add_u32_e32 v140, v198, v150
	v_add_u32_e32 v144, v199, v147
	ds_read_b128 v[130:133], v130
	ds_read_b128 v[140:143], v140
	v_add_u32_e32 v147, v200, v148
	ds_read_b128 v[148:151], v144
	ds_read_b128 v[152:155], v147
	v_add_u32_e32 v144, v201, v145
	v_add_u32_e32 v160, v202, v146
	ds_read_b128 v[144:147], v144
	ds_read_b128 v[166:169], v160
	s_setprio 1
	s_waitcnt lgkmcnt(9)
	v_mfma_f32_32x32x16_bf16 v[114:129], v[178:181], v[186:189], v[114:129]
	s_waitcnt lgkmcnt(8)
	v_mfma_f32_32x32x16_bf16 v[98:113], v[178:181], v[190:193], v[98:113]
	s_waitcnt lgkmcnt(7)
	v_mfma_f32_32x32x16_bf16 v[82:97], v[178:181], v[156:159], v[82:97]
	s_waitcnt lgkmcnt(6)
	v_mfma_f32_32x32x16_bf16 v[66:81], v[178:181], v[194:197], v[66:81]
	v_mfma_f32_32x32x16_bf16 v[50:65], v[182:185], v[186:189], v[50:65]
	v_mfma_f32_32x32x16_bf16 v[34:49], v[182:185], v[190:193], v[34:49]
	v_mfma_f32_32x32x16_bf16 v[18:33], v[182:185], v[156:159], v[18:33]
	v_mfma_f32_32x32x16_bf16 v[2:17], v[182:185], v[194:197], v[2:17]
	s_setprio 0
	v_add_u32_e32 v0, v0, v138
	v_add_u32_e32 v138, v198, v139
	ds_read_b128 v[156:159], v0
	ds_read_b128 v[170:173], v138
	v_add_u32_e32 v0, v199, v136
	v_add_u32_e32 v160, v200, v137
	ds_read_b128 v[136:139], v0
	ds_read_b128 v[174:177], v160
	v_add_u32_e32 v0, v201, v134
	v_add_u32_e32 v134, v202, v135
	ds_read_b128 v[178:181], v0
	ds_read_b128 v[182:185], v134
	s_setprio 1
	s_waitcnt lgkmcnt(9)
	v_mfma_f32_32x32x16_bf16 v[114:129], v[130:133], v[148:151], v[114:129]
	s_waitcnt lgkmcnt(8)
	v_mfma_f32_32x32x16_bf16 v[98:113], v[130:133], v[152:155], v[98:113]
	s_waitcnt lgkmcnt(7)
	v_mfma_f32_32x32x16_bf16 v[82:97], v[130:133], v[144:147], v[82:97]
	s_waitcnt lgkmcnt(6)
	v_mfma_f32_32x32x16_bf16 v[66:81], v[130:133], v[166:169], v[66:81]
	v_mfma_f32_32x32x16_bf16 v[50:65], v[140:143], v[148:151], v[50:65]
	v_mfma_f32_32x32x16_bf16 v[34:49], v[140:143], v[152:155], v[34:49]
	v_mfma_f32_32x32x16_bf16 v[18:33], v[140:143], v[144:147], v[18:33]
	v_mfma_f32_32x32x16_bf16 v[2:17], v[140:143], v[166:169], v[2:17]
	s_setprio 0
	s_setprio 1
	s_waitcnt lgkmcnt(3)
	v_mfma_f32_32x32x16_bf16 v[114:129], v[156:159], v[136:139], v[114:129]
	s_waitcnt lgkmcnt(2)
	v_mfma_f32_32x32x16_bf16 v[98:113], v[156:159], v[174:177], v[98:113]
	s_waitcnt lgkmcnt(1)
	v_mfma_f32_32x32x16_bf16 v[82:97], v[156:159], v[178:181], v[82:97]
	s_waitcnt lgkmcnt(0)
	v_mfma_f32_32x32x16_bf16 v[66:81], v[156:159], v[182:185], v[66:81]
	v_mfma_f32_32x32x16_bf16 v[50:65], v[170:173], v[136:139], v[50:65]
	v_mfma_f32_32x32x16_bf16 v[34:49], v[170:173], v[174:177], v[34:49]
	v_mfma_f32_32x32x16_bf16 v[18:33], v[170:173], v[178:181], v[18:33]
	v_mfma_f32_32x32x16_bf16 v[2:17], v[170:173], v[182:185], v[2:17]
	s_setprio 0
	s_waitcnt vmcnt(0)
	s_barrier
; DI int launder(int x) { asm volatile("" : "+v"(x)); return x; }
;   DI void pre(int grow0, int gcol0, int lane, int w, char* lds) { xpass(0, grow0, gcol0, lane, w, lds); }
;     ...
;   if (has_next) { const int tid3 = launder(threadIdx.x); stage_tile<BM, BK>(A + (size_t)row0n * lda, lda, lds, tid3); stage_tile<BN, BK>(Bt + (size_t)col0n * ldb, ldb, lds + ABYTES, tid3); }
; template <class Epi>
; DI void gemm_phase256(const bf16_t* A, int lda, const bf16_t* Bt, int K, int nN, char* lds, Epi& epi, int vb) {
;     ...
;   for (int t = vb; t < ntiles; t += gridDim.x) {
;     const int x = t & 7, L = t >> 3; const int pm = 8 * x + (L & 7), pn = L >> 3;
;     const int t2 = t + gridDim.x; const bool hn = t2 < ntiles;
;     const int x2 = t2 & 7, L2 = t2 >> 3; const int pm2 = 8 * x2 + (L2 & 7), pn2 = L2 >> 3;
;     gemm_tile<4, 64>(A, lda, Bt, K, K, pm * 256, pn * 256, lds, epi, pre, hn, pm2 * 256, pn2 * 256);
;     pre = hn;
	s_cbranch_scc0 .LBB0_280
	v_mov_b32_e32 v132, v216
	s_lshl_b32 s3, s44, 3
	v_ashrrev_i32_e32 v0, 31, v132
	v_lshrrev_b32_e32 v130, 29, v0
	v_lshrrev_b32_e32 v0, 28, v0
	v_add_u32_e32 v0, v132, v0
	v_ashrrev_i32_e32 v0, 4, v0
	s_and_b32 s3, s3, 56
	s_bfe_u32 s7, s44, 0x30003
	v_lshrrev_b32_e32 v133, 29, v0
	s_or_b32 s3, s3, s7
	s_lshl_b32 s7, s44, 2
	v_add_u32_e32 v130, v132, v130
	v_add_u32_e32 v133, v0, v133
	s_and_b32 s34, s7, 0xffffff00
	s_lshl_b32 s3, s3, 19
	v_and_b32_e32 v131, 0xffffff8, v130
	v_and_b32_e32 v133, 0xffffff8, v133
	s_add_u32 s46, s12, s3
	v_sub_u32_e32 v131, v132, v131
	v_sub_u32_e32 v0, v0, v133
	v_lshlrev_b32_e32 v130, 8, v130
	v_readfirstlane_b32 s3, v132
	s_addc_u32 s47, s13, 0
	v_xor_b32_e32 v0, v0, v131
	v_and_b32_e32 v130, 0xfffff800, v130
	s_lshl_b32 s3, s3, 4
	v_lshl_add_u32 v0, v0, 4, v130
	s_and_b32 s3, s3, 0xfffffc00
	v_lshl_add_u64 v[130:131], s[46:47], 0, v[0:1]
	s_mov_b32 m0, s3
	v_lshl_add_u64 v[132:133], v[130:131], 0, s[58:59]
	global_load_lds_dwordx4 v0, s[46:47]
	s_add_i32 m0, s3, 0x2000
	s_ashr_i32 s35, s34, 31
	global_load_lds_dwordx4 v[132:133], off
	v_lshl_add_u64 v[132:133], v[130:131], 0, s[48:49]
	s_add_i32 m0, s3, 0x4000
	s_lshl_b64 s[34:35], s[34:35], 11
	global_load_lds_dwordx4 v[132:133], off
	s_add_i32 m0, s3, 0x6000
	s_add_u32 s34, s40, s34
	v_lshl_add_u64 v[130:131], v[130:131], 0, s[50:51]
	s_addc_u32 s35, s41, s35
	global_load_lds_dwordx4 v[130:131], off
	v_lshl_add_u64 v[130:131], s[34:35], 0, v[0:1]
	s_add_i32 m0, s3, 0x8000
	v_lshl_add_u64 v[132:133], v[130:131], 0, s[58:59]
	global_load_lds_dwordx4 v0, s[34:35]
	s_add_i32 m0, s3, 0xa000
	s_nop 0
	global_load_lds_dwordx4 v[132:133], off
	v_lshl_add_u64 v[132:133], v[130:131], 0, s[48:49]
	s_add_i32 m0, s3, 0xc000
	v_lshl_add_u64 v[130:131], v[130:131], 0, s[50:51]
	global_load_lds_dwordx4 v[132:133], off
	s_add_i32 m0, s3, 0xe000
	s_nop 0
	global_load_lds_dwordx4 v[130:131], off
	s_branch .LBB0_280

; DI f32x16 mfma(bf16x8 a, bf16x8 b, f32x16 c) { return __builtin_amdgcn_mfma_f32_32x32x16_bf16(a, b, c, 0, 0, 0); }
; template <int BK> DI int swz(int row) { constexpr int CPR = BK / 8; return (row / (16 / CPR)) % CPR; }
; DI void wait_vm0() { asm volatile("s_waitcnt vmcnt(0)" ::: "memory"); }
;   DI void pre(int grow0, int gcol0, int lane, int w, char* lds) { xpass(0, grow0, gcol0, lane, w, lds); }
;     ...
;   for (int kt = 0; kt < nk; ++kt) {
;     char* cur = lds + (kt & 1) * STG; char* nxt = lds + ((kt + 1) & 1) * STG;
;     const bool more = kt + 1 < nk;
;     const bf16_t* An = Ag + (kt + 1) * BK; const bf16_t* Bn = Bg + (kt + 1) * BK;
;     if (!more) epi.pre(row0 + wm * 64, col0 + wn * (32 * NTW), lane, w, lds);
;     bf16x8 fa[2][2], fb[2][NTW];
; #pragma unroll
;     for (int mt = 0; mt < 2; ++mt) { int row = wm * 64 + mt * 32 + l31; fa[0][mt] = *(const bf16x8*)(cur + row * (BK * 2) + ((hh ^ swz<BK>(row)) << 4)); }
; #pragma unroll
;     for (int nt = 0; nt < NTW; ++nt) { int row = wn * (32 * NTW) + nt * 32 + l31; fb[0][nt] = *(const bf16x8*)(cur + ABYTES + row * (BK * 2) + ((hh ^ swz<BK>(row)) << 4)); }
; #pragma unroll
;     for (int kk = 0; kk < NKK; ++kk) {
;       if (kk + 1 < NKK) {
;         const int ch = (kk + 1) * 2 + hh;
; #pragma unroll
;         for (int mt = 0; mt < 2; ++mt) { int row = wm * 64 + mt * 32 + l31; fa[(kk + 1) & 1][mt] = *(const bf16x8*)(cur + row * (BK * 2) + ((ch ^ swz<BK>(row)) << 4)); }
; #pragma unroll
;         for (int nt = 0; nt < NTW; ++nt) { int row = wn * (32 * NTW) + nt * 32 + l31; fb[(kk + 1) & 1][nt] = *(const bf16x8*)(cur + ABYTES + row * (BK * 2) + ((ch ^ swz<BK>(row)) << 4)); }
;       }
;       if (more) {
; #pragma unroll
;         for (int q = 0; q < PPK; ++q) {
;           const int pi = kk * PPK + q;
;           if (pi < NPA) stage_piece<BM, BK>(An, lda, nxt, tid, pi, wv);
;           else if (pi < NP) stage_piece<BN, BK>(Bn, ldb, nxt + ABYTES, tid, pi - NPA, wv);
;         }
;       }
;       __builtin_amdgcn_s_setprio(1);
; #pragma unroll
;       for (int mt = 0; mt < 2; ++mt)
; #pragma unroll
;         for (int nt = 0; nt < NTW; ++nt) acc[mt][nt] = mfma(fa[kk & 1][mt], fb[kk & 1][nt], acc[mt][nt]);
;       __builtin_amdgcn_s_setprio(0);
;       __builtin_amdgcn_sched_barrier(0);
;     }
;     wait_vm0();
;     __syncthreads();
.LBB0_292:
	s_and_b32 s30, s3, 0x10000
	s_xor_b32 s100, s30, 0x10000
	v_add3_u32 v194, s100, v136, v164
	v_add3_u32 v198, s100, v144, v166
	ds_read_b128 v[194:197], v194
	v_add3_u32 v202, s100, v145, v161
	ds_read_b128 v[198:201], v198
	v_add3_u32 v206, s100, v152, v163
	ds_read_b128 v[202:205], v202 offset:32768
	v_add3_u32 v210, s100, v155, v159
	ds_read_b128 v[206:209], v206 offset:32768
	v_add3_u32 v226, s100, v158, v160
	ds_read_b128 v[210:213], v210 offset:32768
	ds_read_b128 v[226:229], v226 offset:32768
	s_waitcnt lgkmcnt(6)
	s_mov_b32 m0, s31
	v_lshl_add_u64 v[232:233], v[214:215], 0, s[28:29]
	v_mfma_f32_32x32x16_bf16 v[114:129], v[170:173], v[178:181], v[114:129]
	global_load_lds_dwordx4 v[232:233], off
	s_add_i32 m0, s31, 0x2000
	v_lshl_add_u64 v[232:233], v[214:215], 0, s[36:37]
	v_mfma_f32_32x32x16_bf16 v[98:113], v[170:173], v[182:185], v[98:113]
	v_mfma_f32_32x32x16_bf16 v[82:97], v[170:173], v[186:189], v[82:97]
	global_load_lds_dwordx4 v[232:233], off
	s_add_i32 m0, s31, 0x4000
	v_lshl_add_u64 v[232:233], v[214:215], 0, s[40:41]
	v_mfma_f32_32x32x16_bf16 v[66:81], v[170:173], v[190:193], v[66:81]
	v_mfma_f32_32x32x16_bf16 v[50:65], v[174:177], v[178:181], v[50:65]
	global_load_lds_dwordx4 v[232:233], off
	s_add_i32 m0, s31, 0x6000
	v_lshl_add_u64 v[232:233], v[214:215], 0, s[42:43]
	v_mfma_f32_32x32x16_bf16 v[34:49], v[174:177], v[182:185], v[34:49]
	v_mfma_f32_32x32x16_bf16 v[18:33], v[174:177], v[186:189], v[18:33]
	global_load_lds_dwordx4 v[232:233], off
	v_mfma_f32_32x32x16_bf16 v[2:17], v[174:177], v[190:193], v[2:17]
	v_add3_u32 v170, s100, v136, v153
	v_add3_u32 v174, s100, v144, v154
	ds_read_b128 v[170:173], v170
	v_add3_u32 v178, s100, v145, v149
	ds_read_b128 v[174:177], v174
	v_add3_u32 v182, s100, v152, v150
	ds_read_b128 v[178:181], v178 offset:32768
	v_add3_u32 v186, s100, v155, v147
	ds_read_b128 v[182:185], v182 offset:32768
	v_add3_u32 v190, s100, v158, v148
	ds_read_b128 v[186:189], v186 offset:32768
	ds_read_b128 v[190:193], v190 offset:32768
	s_waitcnt lgkmcnt(6)
	v_mfma_f32_32x32x16_bf16 v[114:129], v[194:197], v[202:205], v[114:129]
	v_mfma_f32_32x32x16_bf16 v[98:113], v[194:197], v[206:209], v[98:113]
	v_mfma_f32_32x32x16_bf16 v[82:97], v[194:197], v[210:213], v[82:97]
	v_mfma_f32_32x32x16_bf16 v[66:81], v[194:197], v[226:229], v[66:81]
	v_mfma_f32_32x32x16_bf16 v[50:65], v[198:201], v[202:205], v[50:65]
	v_mfma_f32_32x32x16_bf16 v[34:49], v[198:201], v[206:209], v[34:49]
	v_mfma_f32_32x32x16_bf16 v[18:33], v[198:201], v[210:213], v[18:33]
	v_mfma_f32_32x32x16_bf16 v[2:17], v[198:201], v[226:229], v[2:17]
	v_add3_u32 v194, s100, v136, v141
	v_add3_u32 v198, s100, v144, v142
	ds_read_b128 v[194:197], v194
	v_add3_u32 v202, s100, v145, v139
	ds_read_b128 v[198:201], v198
	v_add3_u32 v206, s100, v152, v140
	ds_read_b128 v[202:205], v202 offset:32768
	v_add3_u32 v210, s100, v155, v137
	ds_read_b128 v[206:209], v206 offset:32768
	v_add3_u32 v226, s100, v158, v138
	ds_read_b128 v[210:213], v210 offset:32768
	ds_read_b128 v[226:229], v226 offset:32768
	s_waitcnt lgkmcnt(6)
	v_mfma_f32_32x32x16_bf16 v[114:129], v[170:173], v[178:181], v[114:129]
	v_mfma_f32_32x32x16_bf16 v[98:113], v[170:173], v[182:185], v[98:113]
	v_mfma_f32_32x32x16_bf16 v[82:97], v[170:173], v[186:189], v[82:97]
	v_mfma_f32_32x32x16_bf16 v[66:81], v[170:173], v[190:193], v[66:81]
	v_mfma_f32_32x32x16_bf16 v[50:65], v[174:177], v[178:181], v[50:65]
	v_mfma_f32_32x32x16_bf16 v[34:49], v[174:177], v[182:185], v[34:49]
	v_mfma_f32_32x32x16_bf16 v[18:33], v[174:177], v[186:189], v[18:33]
	v_mfma_f32_32x32x16_bf16 v[2:17], v[174:177], v[190:193], v[2:17]
	s_add_u32 s6, s6, 0x80
	s_addc_u32 s7, s7, 0
	s_add_i32 s3, s3, 0x10000
	s_waitcnt vmcnt(0) lgkmcnt(0)
	s_barrier
	s_cmpk_lg_i32 s6, 0x1580
	s_cbranch_scc0 .Lk292_exit
	s_add_i32 s31, s100, s2
	v_lshl_add_u64 v[214:215], v[132:133], 0, s[6:7]
	v_lshl_add_u64 v[230:231], v[130:131], 0, s[6:7]
	s_add_i32 m0, s31, 0x8000
	v_lshl_add_u64 v[232:233], v[230:231], 0, s[28:29]
	v_mfma_f32_32x32x16_bf16 v[114:129], v[194:197], v[202:205], v[114:129]
	global_load_lds_dwordx4 v[232:233], off
	v_add3_u32 v170, s30, v136, v143
	v_add3_u32 v174, s30, v144, v146
	ds_read_b128 v[170:173], v170
	v_add3_u32 v178, s30, v145, v151
	ds_read_b128 v[174:177], v174
	v_add3_u32 v182, s30, v152, v156
	ds_read_b128 v[178:181], v178 offset:32768
	v_add3_u32 v186, s30, v155, v157
	ds_read_b128 v[182:185], v182 offset:32768
	v_add3_u32 v190, s30, v158, v167
	ds_read_b128 v[186:189], v186 offset:32768
	ds_read_b128 v[190:193], v190 offset:32768
	s_add_i32 m0, s31, 0xa000
	v_lshl_add_u64 v[232:233], v[230:231], 0, s[36:37]
	v_mfma_f32_32x32x16_bf16 v[98:113], v[194:197], v[206:209], v[98:113]
	v_mfma_f32_32x32x16_bf16 v[82:97], v[194:197], v[210:213], v[82:97]
	global_load_lds_dwordx4 v[232:233], off
	s_add_i32 m0, s31, 0xc000
	v_lshl_add_u64 v[232:233], v[230:231], 0, s[40:41]
	v_mfma_f32_32x32x16_bf16 v[66:81], v[194:197], v[226:229], v[66:81]
	v_mfma_f32_32x32x16_bf16 v[50:65], v[198:201], v[202:205], v[50:65]
	global_load_lds_dwordx4 v[232:233], off
	s_add_i32 m0, s31, 0xe000
	v_lshl_add_u64 v[232:233], v[230:231], 0, s[42:43]
	v_mfma_f32_32x32x16_bf16 v[34:49], v[198:201], v[206:209], v[34:49]
	v_mfma_f32_32x32x16_bf16 v[18:33], v[198:201], v[210:213], v[18:33]
	global_load_lds_dwordx4 v[232:233], off
	v_mfma_f32_32x32x16_bf16 v[2:17], v[198:201], v[226:229], v[2:17]
	s_branch .LBB0_292
; DI void wait_vm0() { asm volatile("s_waitcnt vmcnt(0)" ::: "memory"); }
;     ...
;     if (!more) epi.pre(row0 + wm * 64, col0 + wn * (32 * NTW), lane, w, lds);
;     bf16x8 fa[2][2], fb[2][NTW];
; #pragma unroll
;     for (int mt = 0; mt < 2; ++mt) { int row = wm * 64 + mt * 32 + l31; fa[0][mt] = *(const bf16x8*)(cur + row * (BK * 2) + ((hh ^ swz<BK>(row)) << 4)); }
; #pragma unroll
;     for (int nt = 0; nt < NTW; ++nt) { int row = wn * (32 * NTW) + nt * 32 + l31; fb[0][nt] = *(const bf16x8*)(cur + ABYTES + row * (BK * 2) + ((hh ^ swz<BK>(row)) << 4)); }
; #pragma unroll
;     for (int kk = 0; kk < NKK; ++kk) {
;       if (kk + 1 < NKK) {
;         const int ch = (kk + 1) * 2 + hh;
; #pragma unroll
;         for (int mt = 0; mt < 2; ++mt) { int row = wm * 64 + mt * 32 + l31; fa[(kk + 1) & 1][mt] = *(const bf16x8*)(cur + row * (BK * 2) + ((ch ^ swz<BK>(row)) << 4)); }
; #pragma unroll
;         for (int nt = 0; nt < NTW; ++nt) { int row = wn * (32 * NTW) + nt * 32 + l31; fb[(kk + 1) & 1][nt] = *(const bf16x8*)(cur + ABYTES + row * (BK * 2) + ((ch ^ swz<BK>(row)) << 4)); }
;       }
;       if (more) {
; #pragma unroll
;         for (int q = 0; q < PPK; ++q) {
;           const int pi = kk * PPK + q;
;           if (pi < NPA) stage_piece<BM, BK>(An, lda, nxt, tid, pi, wv);
;           else if (pi < NP) stage_piece<BN, BK>(Bn, ldb, nxt + ABYTES, tid, pi - NPA, wv);
;         }
;       }
;       __builtin_amdgcn_s_setprio(1);
; #pragma unroll
;       for (int mt = 0; mt < 2; ++mt)
; #pragma unroll
;         for (int nt = 0; nt < NTW; ++nt) acc[mt][nt] = mfma(fa[kk & 1][mt], fb[kk & 1][nt], acc[mt][nt]);
;       __builtin_amdgcn_s_setprio(0);
;       __builtin_amdgcn_sched_barrier(0);
;     }
;     wait_vm0();
;     __syncthreads();
;   DI void xpass(int ps, int grow0, int gcol0, int lane, int w, char* lds) const {
;     char* xs = lds + (ps & 1) * 65536 + __builtin_amdgcn_readfirstlane(w) * 8192;
;     const float* xsrc = Xin + (size_t)(grow0 + (ps >> 1) * 32 + (ps & 1) * 16 + (lane >> 5)) * D_ + gcol0 + (lane & 31) * 4;
; #pragma unroll
;     for (int pc = 0; pc < 8; ++pc)
;       __builtin_amdgcn_global_load_lds((const unsigned*)(xsrc + (size_t)(2 * pc) * D_), (__attribute__((address_space(3))) unsigned*)(xs + pc * 1024), 16, 0, 0);
;   }
;   DI void pre(int grow0, int gcol0, int lane, int w, char* lds) { xpass(0, grow0, gcol0, lane, w, lds); }
.Lk292_exit:
	v_add3_u32 v170, s30, v136, v143
	v_add3_u32 v174, s30, v144, v146
	ds_read_b128 v[170:173], v170
	v_add3_u32 v178, s30, v145, v151
	ds_read_b128 v[174:177], v174
	v_add3_u32 v182, s30, v152, v156
	ds_read_b128 v[178:181], v178 offset:32768
	v_add3_u32 v186, s30, v155, v157
	ds_read_b128 v[182:185], v182 offset:32768
	v_add3_u32 v190, s30, v158, v167
	ds_read_b128 v[186:189], v186 offset:32768
	ds_read_b128 v[190:193], v190 offset:32768
	v_mfma_f32_32x32x16_bf16 v[114:129], v[194:197], v[202:205], v[114:129]
	v_mfma_f32_32x32x16_bf16 v[98:113], v[194:197], v[206:209], v[98:113]
	v_mfma_f32_32x32x16_bf16 v[82:97], v[194:197], v[210:213], v[82:97]
	v_mfma_f32_32x32x16_bf16 v[66:81], v[194:197], v[226:229], v[66:81]
	v_mfma_f32_32x32x16_bf16 v[50:65], v[198:201], v[202:205], v[50:65]
	v_mfma_f32_32x32x16_bf16 v[34:49], v[198:201], v[206:209], v[34:49]
	v_mfma_f32_32x32x16_bf16 v[18:33], v[198:201], v[210:213], v[18:33]
	v_mfma_f32_32x32x16_bf16 v[2:17], v[198:201], v[226:229], v[2:17]
	s_waitcnt lgkmcnt(0)
	v_readlane_b32 s3, v253, 9
	v_readlane_b32 s6, v253, 27
	v_readlane_b32 s54, v255, 29
	v_or_b32_e32 v130, s3, v135
	v_add_u32_e32 v130, v130, v169
	v_ashrrev_i32_e32 v131, 31, v130
	v_lshlrev_b64 v[130:131], 12, v[130:131]
	v_add_u32_e32 v132, s6, v168
	v_readlane_b32 s55, v255, 30
	v_ashrrev_i32_e32 v133, 31, v132
	v_readfirstlane_b32 s2, v134
	v_lshl_add_u64 v[130:131], s[54:55], 0, v[130:131]
	v_lshlrev_b32_e32 v0, 4, v0
	s_lshl_b32 s2, s2, 13
	v_lshl_add_u64 v[130:131], v[132:133], 2, v[130:131]
	v_and_b32_e32 v0, 0x1f0, v0
	v_lshl_add_u64 v[130:131], v[130:131], 0, v[0:1]
	s_mov_b32 m0, s2
	s_mov_b64 s[34:35], 0x2000
	global_load_lds_dwordx4 v[130:131], off
	v_lshl_add_u64 v[132:133], v[130:131], 0, s[34:35]
	s_or_b32 m0, s2, 0x400
	s_mov_b64 s[36:37], 0x4000
	global_load_lds_dwordx4 v[132:133], off
	v_lshl_add_u64 v[132:133], v[130:131], 0, s[36:37]
	s_or_b32 m0, s2, 0x800
	s_mov_b64 s[40:41], 0x6000
	global_load_lds_dwordx4 v[132:133], off
	v_lshl_add_u64 v[132:133], v[130:131], 0, s[40:41]
	s_or_b32 m0, s2, 0xc00
	s_mov_b64 s[42:43], 0x8000
	global_load_lds_dwordx4 v[132:133], off
	v_lshl_add_u64 v[132:133], v[130:131], 0, s[42:43]
	s_or_b32 m0, s2, 0x1000
	s_mov_b64 s[44:45], 0xa000
	global_load_lds_dwordx4 v[132:133], off
	v_lshl_add_u64 v[132:133], v[130:131], 0, s[44:45]
	s_or_b32 m0, s2, 0x1400
	s_mov_b64 s[46:47], 0xc000
	global_load_lds_dwordx4 v[132:133], off
	v_lshl_add_u64 v[132:133], v[130:131], 0, s[46:47]
	s_or_b32 m0, s2, 0x1800
	s_mov_b64 s[52:53], 0xe000
	global_load_lds_dwordx4 v[132:133], off
	v_lshl_add_u64 v[130:131], v[130:131], 0, s[52:53]
	s_or_b32 m0, s2, 0x1c00
	v_add_u32_e32 v0, s30, v136
	global_load_lds_dwordx4 v[130:131], off
	v_add_u32_e32 v134, s30, v144
	v_add_u32_e32 v130, v0, v143
	v_add_u32_e32 v135, v134, v146
	ds_read_b128 v[130:133], v130
	ds_read_b128 v[168:171], v135
	v_add_u32_e32 v135, s30, v145
	v_add_u32_e32 v136, v135, v151
	v_add_u32_e32 v143, s30, v152
	v_add_u32_e32 v144, v143, v156
	ds_read_b128 v[172:175], v136 offset:32768
	ds_read_b128 v[176:179], v144 offset:32768
	v_add_u32_e32 v136, s30, v155
	v_add_u32_e32 v144, v136, v157
	v_add_u32_e32 v208, s30, v158
	v_add_u32_e32 v145, v208, v167
	ds_read_b128 v[180:183], v144 offset:32768
	ds_read_b128 v[184:187], v145 offset:32768
	v_add_u32_e32 v144, v0, v164
	v_add_u32_e32 v145, v134, v166
	ds_read_b128 v[188:191], v144
	ds_read_b128 v[192:195], v145
	v_add_u32_e32 v144, v135, v161
	v_add_u32_e32 v145, v143, v163
	ds_read_b128 v[196:199], v144 offset:32768
	ds_read_b128 v[200:203], v145 offset:32768
	v_add_u32_e32 v144, v136, v159
	v_add_u32_e32 v145, v208, v160
	ds_read_b128 v[156:159], v144 offset:32768
	ds_read_b128 v[204:207], v145 offset:32768
	v_readlane_b32 s7, v253, 28
	s_setprio 1
	s_waitcnt lgkmcnt(0)
	v_mfma_f32_32x32x16_bf16 v[114:129], v[130:133], v[172:175], v[114:129]
	v_mfma_f32_32x32x16_bf16 v[98:113], v[130:133], v[176:179], v[98:113]
	v_mfma_f32_32x32x16_bf16 v[82:97], v[130:133], v[180:183], v[82:97]
	v_mfma_f32_32x32x16_bf16 v[66:81], v[130:133], v[184:187], v[66:81]
	v_mfma_f32_32x32x16_bf16 v[50:65], v[168:171], v[172:175], v[50:65]
	v_mfma_f32_32x32x16_bf16 v[34:49], v[168:171], v[176:179], v[34:49]
	v_mfma_f32_32x32x16_bf16 v[18:33], v[168:171], v[180:183], v[18:33]
	v_mfma_f32_32x32x16_bf16 v[2:17], v[168:171], v[184:187], v[2:17]
	s_setprio 0
	v_add_u32_e32 v130, v0, v153
	v_add_u32_e32 v144, v134, v154
	ds_read_b128 v[130:133], v130
	ds_read_b128 v[152:155], v144
	v_add_u32_e32 v144, v135, v149
	v_add_u32_e32 v145, v143, v150
	ds_read_b128 v[166:169], v144 offset:32768
	ds_read_b128 v[170:173], v145 offset:32768
	v_add_u32_e32 v144, v136, v147
	v_add_u32_e32 v148, v208, v148
	ds_read_b128 v[144:147], v144 offset:32768
	ds_read_b128 v[148:151], v148 offset:32768
	s_setprio 1
	v_mfma_f32_32x32x16_bf16 v[114:129], v[188:191], v[196:199], v[114:129]
	v_mfma_f32_32x32x16_bf16 v[98:113], v[188:191], v[200:203], v[98:113]
	v_mfma_f32_32x32x16_bf16 v[82:97], v[188:191], v[156:159], v[82:97]
	v_mfma_f32_32x32x16_bf16 v[66:81], v[188:191], v[204:207], v[66:81]
	v_mfma_f32_32x32x16_bf16 v[50:65], v[192:195], v[196:199], v[50:65]
	v_mfma_f32_32x32x16_bf16 v[34:49], v[192:195], v[200:203], v[34:49]
	v_mfma_f32_32x32x16_bf16 v[18:33], v[192:195], v[156:159], v[18:33]
	v_mfma_f32_32x32x16_bf16 v[2:17], v[192:195], v[204:207], v[2:17]
	s_setprio 0
	v_add_u32_e32 v0, v0, v141
	v_add_u32_e32 v134, v134, v142
	ds_read_b128 v[156:159], v0
	ds_read_b128 v[174:177], v134
	v_add_u32_e32 v0, v135, v139
	v_add_u32_e32 v134, v143, v140
	ds_read_b128 v[140:143], v0 offset:32768
	ds_read_b128 v[178:181], v134 offset:32768
	v_add_u32_e32 v0, v136, v137
	v_add_u32_e32 v138, v208, v138
	ds_read_b128 v[134:137], v0 offset:32768
	ds_read_b128 v[182:185], v138 offset:32768
	s_setprio 1
	s_waitcnt lgkmcnt(9)
;   DI void xpass(int ps, int grow0, int gcol0, int lane, int w, char* lds) const {
;     char* xs = lds + (ps & 1) * 65536 + __builtin_amdgcn_readfirstlane(w) * 8192;
;     const float* xsrc = Xin + (size_t)(grow0 + (ps >> 1) * 32 + (ps & 1) * 16 + (lane >> 5)) * D_ + gcol0 + (lane & 31) * 4;
; #pragma unroll
;     for (int pc = 0; pc < 8; ++pc)
;       __builtin_amdgcn_global_load_lds((const unsigned*)(xsrc + (size_t)(2 * pc) * D_), (__attribute__((address_space(3))) unsigned*)(xs + pc * 1024), 16, 0, 0);
;   }
;   DI void operator()(f32x16 (&acc)[2][4], int grow0, int gcol0, int lane, int w, char* lds) {
;     ...
;     for (int ps = 0; ps < 4; ++ps) {
;       const int mt = ps >> 1;
;       if (ps + 1 < 4) {
;         if (ps >= 1) asm volatile("s_waitcnt lgkmcnt(0)" ::: "memory");
;         xpass(ps + 1, grow0, gcol0, lane, w, lds);
;         if (ps >= 1) asm volatile("s_waitcnt vmcnt(8)" ::: "memory");
;       } else asm volatile("s_waitcnt vmcnt(0)" ::: "memory");
;       const char* xs = lds + (ps & 1) * 65536 + w * 8192;
; #pragma unroll
;       for (int qq = 0; qq < 2; ++qq)
; #pragma unroll
;         for (int e = 0; e < 4; ++e) {
;           const int i = 4 * (2 * (ps & 1) + qq) + e;
;           const float* xr = (const float*)(xs + (8 * qq + 4 * hh + e) * 512) + l31;
;           float s1 = 0.f, s2 = 0.f;
; #pragma unroll
;           for (int nt = 0; nt < 4; ++nt) {
;             float v = (acc[mt][nt][i] + bia[nt]) * csc[nt];
;             float z = ALPHA * xr[nt * 32] + hs * v;
;             acc[mt][nt][i] = z; s1 += z; s2 += z * z;
;           }
;           s1 = row16_sum(s1); s2 = row16_sum(s2);
;           if ((lane & 15) == 0) { f32x2 sv = {s1, s2}; *(f32x2*)(redw + (mt * 32 + (i & 3) + 8 * (i >> 2)) * 2) = sv; }
	v_mfma_f32_32x32x16_bf16 v[114:129], v[130:133], v[166:169], v[114:129]
	s_waitcnt lgkmcnt(8)
	v_mfma_f32_32x32x16_bf16 v[98:113], v[130:133], v[170:173], v[98:113]
	s_waitcnt lgkmcnt(7)
	v_mfma_f32_32x32x16_bf16 v[82:97], v[130:133], v[144:147], v[82:97]
	s_waitcnt lgkmcnt(6)
	v_mfma_f32_32x32x16_bf16 v[66:81], v[130:133], v[148:151], v[66:81]
	v_mfma_f32_32x32x16_bf16 v[50:65], v[152:155], v[166:169], v[50:65]
	v_mfma_f32_32x32x16_bf16 v[34:49], v[152:155], v[170:173], v[34:49]
	v_mfma_f32_32x32x16_bf16 v[18:33], v[152:155], v[144:147], v[18:33]
	v_mfma_f32_32x32x16_bf16 v[2:17], v[152:155], v[148:151], v[2:17]
	s_setprio 0
	s_setprio 1
	s_waitcnt lgkmcnt(3)
	v_mfma_f32_32x32x16_bf16 v[114:129], v[156:159], v[140:143], v[114:129]
	s_waitcnt lgkmcnt(2)
	v_mfma_f32_32x32x16_bf16 v[98:113], v[156:159], v[178:181], v[98:113]
	s_waitcnt lgkmcnt(1)
	v_mfma_f32_32x32x16_bf16 v[82:97], v[156:159], v[134:137], v[82:97]
	s_waitcnt lgkmcnt(0)
	v_mfma_f32_32x32x16_bf16 v[66:81], v[156:159], v[182:185], v[66:81]
	v_mfma_f32_32x32x16_bf16 v[50:65], v[174:177], v[140:143], v[50:65]
	v_mfma_f32_32x32x16_bf16 v[34:49], v[174:177], v[178:181], v[34:49]
	v_mfma_f32_32x32x16_bf16 v[18:33], v[174:177], v[134:137], v[18:33]
	v_mfma_f32_32x32x16_bf16 v[2:17], v[174:177], v[182:185], v[2:17]
	s_setprio 0
	v_mov_b32_e32 v210, v216
	s_waitcnt vmcnt(0)
	s_barrier
	v_add_f32_e32 v114, 0, v114
	v_ashrrev_i32_e32 v169, 6, v210
	v_lshrrev_b32_e32 v0, 30, v169
	v_add_u32_e32 v0, v169, v0
	v_ashrrev_i32_e32 v134, 2, v0
	v_mul_i32_i24_e32 v0, 4, v134
	v_sub_u32_e32 v0, v169, v0
	v_lshlrev_b32_e32 v135, 6, v0
	v_add_u32_e32 v164, s3, v135
	v_bfe_u32 v0, v210, 5, 1
	v_or_b32_e32 v176, v164, v0
	v_or_b32_e32 v130, 16, v176
	v_ashrrev_i32_e32 v131, 31, v130
	v_lshl_add_u32 v154, v134, 7, s6
	v_lshlrev_b32_e32 v168, 2, v210
	v_lshlrev_b64 v[130:131], 12, v[130:131]
	v_ashrrev_i32_e32 v155, 31, v154
	v_and_b32_e32 v0, 0x7c, v168
	v_readfirstlane_b32 s2, v169
	v_lshl_add_u64 v[130:131], s[54:55], 0, v[130:131]
	s_lshl_b32 s2, s2, 13
	v_lshl_add_u64 v[130:131], v[154:155], 2, v[130:131]
	v_lshlrev_b32_e32 v0, 2, v0
	s_add_i32 m0, s2, 0x10000
	v_lshl_add_u64 v[130:131], v[130:131], 0, v[0:1]
	global_load_lds_dwordx4 v[130:131], off
	v_lshl_add_u64 v[132:133], v[130:131], 0, s[34:35]
	s_add_i32 m0, s2, 0x10400
	v_and_b32_e32 v211, 0xc0, v135
	global_load_lds_dwordx4 v[132:133], off
	v_lshl_add_u64 v[132:133], v[130:131], 0, s[36:37]
	s_add_i32 m0, s2, 0x10800
	v_mov_b32_e32 v144, v98
	global_load_lds_dwordx4 v[132:133], off
	v_lshl_add_u64 v[132:133], v[130:131], 0, s[40:41]
	s_add_i32 m0, s2, 0x10c00
	v_mov_b32_e32 v145, v82
	global_load_lds_dwordx4 v[132:133], off
	v_lshl_add_u64 v[132:133], v[130:131], 0, s[42:43]
	s_add_i32 m0, s2, 0x11000
	v_mul_f32_e32 v141, 0.5, v114
	global_load_lds_dwordx4 v[132:133], off
	v_lshl_add_u64 v[132:133], v[130:131], 0, s[44:45]
	s_add_i32 m0, s2, 0x11400
	v_pk_add_f32 v[144:145], v[144:145], 0 op_sel_hi:[1,0]
	global_load_lds_dwordx4 v[132:133], off
	v_lshl_add_u64 v[132:133], v[130:131], 0, s[46:47]
	s_add_i32 m0, s2, 0x11800
	v_lshl_add_u64 v[130:131], v[130:131], 0, s[52:53]
	global_load_lds_dwordx4 v[132:133], off
	s_add_i32 m0, s2, 0x11c00
	v_bfe_u32 v132, v210, 4, 1
	global_load_lds_dwordx4 v[130:131], off
	v_and_b32_e32 v130, 31, v210
	v_lshlrev_b32_e32 v131, 1, v134
	v_bfe_u32 v134, v210, 3, 3
	v_and_or_b32 v131, v131, 2, v132
	v_and_b32_e32 v132, 4, v134
	v_lshlrev_b32_e32 v130, 2, v130
	v_or_b32_e32 v133, v211, v132
	v_lshl_or_b32 v138, v169, 13, v130
	v_lshlrev_b32_e32 v172, 9, v132
	v_lshlrev_b32_e32 v135, 3, v133
	v_or_b32_e32 v132, v138, v172
	v_and_b32_e32 v133, 15, v210
	v_lshl_or_b32 v139, v131, 11, v221
	s_waitcnt vmcnt(8)
	ds_read2_b32 v[130:131], v132 offset1:32
	v_cmp_eq_u32_e32 vcc, 0, v133
	ds_read2_b32 v[132:133], v132 offset0:64 offset1:96
	v_mov_b32_e32 v140, v82
	v_mov_b32_e32 v136, v1
	s_waitcnt lgkmcnt(0)
	v_mul_f32_e32 v137, 0x3fd744fd, v130
	v_mov_b32_e32 v130, v131
	v_mov_b32_e32 v131, v132
	s_mov_b32 s2, s67
	v_pk_add_f32 v[160:161], v[140:141], v[136:137]
	v_pk_mul_f32 v[130:131], v[130:131], s[2:3] op_sel_hi:[1,0]
	v_pk_mul_f32 v[136:137], v[144:145], 0.5 op_sel_hi:[1,0]
	v_pk_fma_f32 v[158:159], v[144:145], 0.5, v[130:131] op_sel_hi:[1,0,1]
	v_mov_b32_e32 v136, v161
	v_mov_b32_e32 v144, v1
	v_mov_b32_e32 v145, v131
	v_add_f32_e32 v142, 0, v66
	v_mov_b32_e32 v143, v133
	v_pk_mul_f32 v[140:141], v[158:159], v[158:159]
	v_pk_add_f32 v[136:137], v[136:137], v[144:145]
	v_mul_f32_e32 v66, 0x3fd744fd, v133
	v_mov_b32_e32 v163, v161
	v_pk_mov_b32 v[130:131], v[130:131], v[140:141] op_sel:[1,0]
	v_pk_add_f32 v[140:141], v[158:159], v[136:137]
	v_pk_mul_f32 v[136:137], v[158:159], v[136:137]
	v_pk_fma_f32 v[166:167], v[142:143], s[66:67], v[66:67] op_sel_hi:[1,1,0]
	v_pk_fma_f32 v[130:131], v[160:161], v[162:163], v[130:131]
	v_mov_b32_e32 v141, v137
	v_pk_mul_f32 v[132:133], v[166:167], v[166:167]
	v_pk_add_f32 v[130:131], v[140:141], v[130:131]
	v_mov_b32_e32 v167, v132
	v_pk_add_f32 v[130:131], v[130:131], v[166:167]
	v_add_u32_e32 v160, v139, v135
	s_nop 0
	v_mov_b32_dpp v132, v130 quad_perm:[1,0,3,2] row_mask:0xf bank_mask:0xf bound_ctrl:1
	v_mov_b32_dpp v133, v131 quad_perm:[1,0,3,2] row_mask:0xf bank_mask:0xf bound_ctrl:1
	v_pk_add_f32 v[130:131], v[130:131], v[132:133]
	s_nop 1
	v_mov_b32_dpp v132, v130 quad_perm:[2,3,0,1] row_mask:0xf bank_mask:0xf bound_ctrl:1
	v_mov_b32_dpp v133, v131 quad_perm:[2,3,0,1] row_mask:0xf bank_mask:0xf bound_ctrl:1
	v_pk_add_f32 v[130:131], v[130:131], v[132:133]
	s_nop 1
	v_mov_b32_dpp v132, v130 row_half_mirror row_mask:0xf bank_mask:0xf bound_ctrl:1
	v_mov_b32_dpp v133, v131 row_half_mirror row_mask:0xf bank_mask:0xf bound_ctrl:1
	v_pk_add_f32 v[130:131], v[130:131], v[132:133]
	s_nop 1
	v_mov_b32_dpp v132, v130 row_mirror row_mask:0xf bank_mask:0xf bound_ctrl:1
	v_mov_b32_dpp v133, v131 row_mirror row_mask:0xf bank_mask:0xf bound_ctrl:1
	s_and_saveexec_b64 s[6:7], vcc
	v_pk_add_f32 v[130:131], v[130:131], v[132:133]
	ds_write_b64 v160, v[130:131]
	s_or_b64 exec, exec, s[6:7]
	v_add_u32_e32 v167, v138, v172
	ds_read2_b32 v[130:131], v167 offset0:128 offset1:160
	ds_read2_b32 v[132:133], v167 offset0:192 offset1:224
	v_add_f32_e32 v82, 0, v115
	v_mul_f32_e32 v115, 0.5, v82
	v_mov_b32_e32 v82, v99
	s_waitcnt lgkmcnt(1)
;   DI void operator()(f32x16 (&acc)[2][4], int grow0, int gcol0, int lane, int w, char* lds) {
;     ...
; #pragma unroll
;       for (int qq = 0; qq < 2; ++qq)
; #pragma unroll
;         for (int e = 0; e < 4; ++e) {
;           const int i = 4 * (2 * (ps & 1) + qq) + e;
;           const float* xr = (const float*)(xs + (8 * qq + 4 * hh + e) * 512) + l31;
;           float s1 = 0.f, s2 = 0.f;
; #pragma unroll
;           for (int nt = 0; nt < 4; ++nt) {
;             float v = (acc[mt][nt][i] + bia[nt]) * csc[nt];
;             float z = ALPHA * xr[nt * 32] + hs * v;
;             acc[mt][nt][i] = z; s1 += z; s2 += z * z;
;           }
;           s1 = row16_sum(s1); s2 = row16_sum(s2);
;           if ((lane & 15) == 0) { f32x2 sv = {s1, s2}; *(f32x2*)(redw + (mt * 32 + (i & 3) + 8 * (i >> 2)) * 2) = sv; }
	v_mul_f32_e32 v137, 0x3fd744fd, v130
	v_pk_add_f32 v[98:99], v[82:83], 0 op_sel_hi:[1,0]
	v_mov_b32_e32 v114, v83
	v_mov_b32_e32 v136, v1
	v_mov_b32_e32 v82, v131
	s_waitcnt lgkmcnt(0)
	v_mov_b32_e32 v83, v132
	s_mov_b32 s2, s67
	v_pk_add_f32 v[170:171], v[114:115], v[136:137]
	v_pk_mul_f32 v[82:83], v[82:83], s[2:3] op_sel_hi:[1,0]
	v_pk_mul_f32 v[114:115], v[98:99], 0.5 op_sel_hi:[1,0]
	v_pk_fma_f32 v[148:149], v[98:99], 0.5, v[82:83] op_sel_hi:[1,0,1]
	v_mov_b32_e32 v114, v171
	v_mov_b32_e32 v130, v1
	v_mov_b32_e32 v131, v83
	v_pk_mul_f32 v[98:99], v[148:149], v[148:149]
	v_pk_add_f32 v[114:115], v[114:115], v[130:131]
	v_mov_b32_e32 v163, v171
	v_pk_mov_b32 v[82:83], v[82:83], v[98:99] op_sel:[1,0]
	v_pk_add_f32 v[98:99], v[148:149], v[114:115]
	v_pk_mul_f32 v[114:115], v[148:149], v[114:115]
	v_pk_fma_f32 v[82:83], v[170:171], v[162:163], v[82:83]
	v_mov_b32_e32 v99, v115
	v_add_f32_e32 v66, 0, v67
	v_mov_b32_e32 v67, v133
	v_pk_add_f32 v[82:83], v[98:99], v[82:83]
	v_mul_f32_e32 v98, 0x3fd744fd, v133
	v_pk_fma_f32 v[142:143], v[66:67], s[66:67], v[98:99] op_sel_hi:[1,1,0]
	s_nop 0
	v_pk_mul_f32 v[66:67], v[142:143], v[142:143]
	s_nop 0
	v_mov_b32_e32 v143, v66
	v_pk_add_f32 v[66:67], v[82:83], v[142:143]
	s_nop 1
	v_mov_b32_dpp v82, v66 quad_perm:[1,0,3,2] row_mask:0xf bank_mask:0xf bound_ctrl:1
	v_mov_b32_dpp v83, v67 quad_perm:[1,0,3,2] row_mask:0xf bank_mask:0xf bound_ctrl:1
	v_pk_add_f32 v[66:67], v[66:67], v[82:83]
	s_nop 1
	v_mov_b32_dpp v82, v66 quad_perm:[2,3,0,1] row_mask:0xf bank_mask:0xf bound_ctrl:1
	v_mov_b32_dpp v83, v67 quad_perm:[2,3,0,1] row_mask:0xf bank_mask:0xf bound_ctrl:1
	v_pk_add_f32 v[66:67], v[66:67], v[82:83]
	s_nop 1
	v_mov_b32_dpp v82, v66 row_half_mirror row_mask:0xf bank_mask:0xf bound_ctrl:1
	v_mov_b32_dpp v83, v67 row_half_mirror row_mask:0xf bank_mask:0xf bound_ctrl:1
	v_pk_add_f32 v[66:67], v[66:67], v[82:83]
	s_nop 1
	v_mov_b32_dpp v82, v66 row_mirror row_mask:0xf bank_mask:0xf bound_ctrl:1
	v_mov_b32_dpp v83, v67 row_mirror row_mask:0xf bank_mask:0xf bound_ctrl:1
	s_and_saveexec_b64 s[6:7], vcc
	v_pk_add_f32 v[66:67], v[66:67], v[82:83]
	ds_write_b64 v160, v[66:67] offset:8
	s_or_b64 exec, exec, s[6:7]
	v_add_u32_e32 v143, 0x400, v167
	ds_read2_b32 v[66:67], v143 offset1:32
	ds_read2_b32 v[82:83], v143 offset0:64 offset1:96
	v_add_f32_e32 v99, 0, v116
	v_mov_b32_e32 v132, v100
	v_mov_b32_e32 v133, v84
	v_mul_f32_e32 v115, 0.5, v99
	s_waitcnt lgkmcnt(1)
	v_mul_f32_e32 v131, 0x3fd744fd, v66
	v_pk_add_f32 v[132:133], v[132:133], 0 op_sel_hi:[1,0]
	v_mov_b32_e32 v114, v84
	v_mov_b32_e32 v130, v1
	v_mov_b32_e32 v66, v67
	s_waitcnt lgkmcnt(0)
	v_mov_b32_e32 v67, v82
	s_mov_b32 s2, s67
	v_pk_add_f32 v[144:145], v[114:115], v[130:131]
	v_pk_mul_f32 v[114:115], v[66:67], s[2:3] op_sel_hi:[1,0]
	v_pk_mul_f32 v[130:131], v[132:133], 0.5 op_sel_hi:[1,0]
	v_pk_fma_f32 v[66:67], v[132:133], 0.5, v[114:115] op_sel_hi:[1,0,1]
	v_mov_b32_e32 v130, v145
	v_mov_b32_e32 v136, v1
	v_mov_b32_e32 v137, v115
	v_add_f32_e32 v98, 0, v68
	v_mov_b32_e32 v99, v83
	v_pk_mul_f32 v[132:133], v[66:67], v[66:67]
	v_pk_add_f32 v[130:131], v[130:131], v[136:137]
	v_mul_f32_e32 v68, 0x3fd744fd, v83
	v_mov_b32_e32 v163, v145
	v_pk_mov_b32 v[114:115], v[114:115], v[132:133] op_sel:[1,0]
	v_pk_add_f32 v[132:133], v[66:67], v[130:131]
	v_pk_mul_f32 v[130:131], v[66:67], v[130:131]
	v_pk_fma_f32 v[82:83], v[98:99], s[66:67], v[68:69] op_sel_hi:[1,1,0]
	v_pk_fma_f32 v[114:115], v[144:145], v[162:163], v[114:115]
	v_mov_b32_e32 v133, v131
	v_pk_mul_f32 v[98:99], v[82:83], v[82:83]
	v_pk_add_f32 v[114:115], v[132:133], v[114:115]
	v_mov_b32_e32 v83, v98
	v_pk_add_f32 v[98:99], v[114:115], v[82:83]
	s_nop 1
	v_mov_b32_dpp v114, v98 quad_perm:[1,0,3,2] row_mask:0xf bank_mask:0xf bound_ctrl:1
	v_mov_b32_dpp v115, v99 quad_perm:[1,0,3,2] row_mask:0xf bank_mask:0xf bound_ctrl:1
	v_pk_add_f32 v[98:99], v[98:99], v[114:115]
	s_nop 1
	v_mov_b32_dpp v114, v98 quad_perm:[2,3,0,1] row_mask:0xf bank_mask:0xf bound_ctrl:1
	v_mov_b32_dpp v115, v99 quad_perm:[2,3,0,1] row_mask:0xf bank_mask:0xf bound_ctrl:1
	v_pk_add_f32 v[98:99], v[98:99], v[114:115]
	s_nop 1
	v_mov_b32_dpp v114, v98 row_half_mirror row_mask:0xf bank_mask:0xf bound_ctrl:1
	v_mov_b32_dpp v115, v99 row_half_mirror row_mask:0xf bank_mask:0xf bound_ctrl:1
	v_pk_add_f32 v[98:99], v[98:99], v[114:115]
	s_nop 1
	v_mov_b32_dpp v114, v98 row_mirror row_mask:0xf bank_mask:0xf bound_ctrl:1
	v_mov_b32_dpp v115, v99 row_mirror row_mask:0xf bank_mask:0xf bound_ctrl:1
	s_and_saveexec_b64 s[6:7], vcc
	v_pk_add_f32 v[98:99], v[98:99], v[114:115]
	ds_write_b64 v160, v[98:99] offset:16
	s_or_b64 exec, exec, s[6:7]
	v_lshlrev_b32_e32 v139, 9, v134
	v_or_b32_e32 v152, 0x600, v139
	v_add_u32_e32 v144, v138, v152
	ds_read2_b32 v[114:115], v144 offset1:32
	ds_read2_b32 v[130:131], v144 offset0:64 offset1:96
	v_add_f32_e32 v68, 0, v117
	v_add_f32_e32 v116, 0, v69
	v_mul_f32_e32 v69, 0.5, v68
	s_waitcnt lgkmcnt(1)
	v_mul_f32_e32 v99, 0x3fd744fd, v114
	v_mov_b32_e32 v84, v101
	v_mov_b32_e32 v68, v85
	v_mov_b32_e32 v98, v1
	v_pk_add_f32 v[100:101], v[84:85], 0 op_sel_hi:[1,0]
	v_pk_add_f32 v[98:99], v[68:69], v[98:99]
	v_mov_b32_e32 v68, v115
	s_waitcnt lgkmcnt(0)
;   DI void operator()(f32x16 (&acc)[2][4], int grow0, int gcol0, int lane, int w, char* lds) {
;     ...
; #pragma unroll
;       for (int qq = 0; qq < 2; ++qq)
; #pragma unroll
;         for (int e = 0; e < 4; ++e) {
;           const int i = 4 * (2 * (ps & 1) + qq) + e;
;           const float* xr = (const float*)(xs + (8 * qq + 4 * hh + e) * 512) + l31;
;           float s1 = 0.f, s2 = 0.f;
; #pragma unroll
;           for (int nt = 0; nt < 4; ++nt) {
;             float v = (acc[mt][nt][i] + bia[nt]) * csc[nt];
;             float z = ALPHA * xr[nt * 32] + hs * v;
;             acc[mt][nt][i] = z; s1 += z; s2 += z * z;
;           }
;           s1 = row16_sum(s1); s2 = row16_sum(s2);
;           if ((lane & 15) == 0) { f32x2 sv = {s1, s2}; *(f32x2*)(redw + (mt * 32 + (i & 3) + 8 * (i >> 2)) * 2) = sv; }
	v_mov_b32_e32 v69, v130
	s_mov_b32 s2, s67
	v_pk_mul_f32 v[84:85], v[68:69], s[2:3] op_sel_hi:[1,0]
	v_pk_mul_f32 v[114:115], v[100:101], 0.5 op_sel_hi:[1,0]
	v_pk_fma_f32 v[68:69], v[100:101], 0.5, v[84:85] op_sel_hi:[1,0,1]
	v_mov_b32_e32 v114, v99
	v_mov_b32_e32 v132, v1
	v_mov_b32_e32 v133, v85
	v_pk_mul_f32 v[100:101], v[68:69], v[68:69]
	v_pk_add_f32 v[114:115], v[114:115], v[132:133]
	v_mov_b32_e32 v163, v99
	v_pk_mov_b32 v[84:85], v[84:85], v[100:101] op_sel:[1,0]
	v_pk_add_f32 v[100:101], v[68:69], v[114:115]
	v_pk_mul_f32 v[114:115], v[68:69], v[114:115]
	v_pk_fma_f32 v[84:85], v[98:99], v[162:163], v[84:85]
	v_mov_b32_e32 v101, v115
	v_mov_b32_e32 v117, v131
	v_pk_add_f32 v[100:101], v[100:101], v[84:85]
	v_mul_f32_e32 v84, 0x3fd744fd, v131
	v_pk_fma_f32 v[84:85], v[116:117], s[66:67], v[84:85] op_sel_hi:[1,1,0]
	s_nop 0
	v_pk_mul_f32 v[114:115], v[84:85], v[84:85]
	s_nop 0
	v_mov_b32_e32 v85, v114
	v_pk_add_f32 v[100:101], v[100:101], v[84:85]
	s_nop 1
	v_mov_b32_dpp v114, v100 quad_perm:[1,0,3,2] row_mask:0xf bank_mask:0xf bound_ctrl:1
	v_mov_b32_dpp v115, v101 quad_perm:[1,0,3,2] row_mask:0xf bank_mask:0xf bound_ctrl:1
	v_pk_add_f32 v[100:101], v[100:101], v[114:115]
	s_nop 1
	v_mov_b32_dpp v114, v100 quad_perm:[2,3,0,1] row_mask:0xf bank_mask:0xf bound_ctrl:1
	v_mov_b32_dpp v115, v101 quad_perm:[2,3,0,1] row_mask:0xf bank_mask:0xf bound_ctrl:1
	v_pk_add_f32 v[100:101], v[100:101], v[114:115]
	s_nop 1
	v_mov_b32_dpp v114, v100 row_half_mirror row_mask:0xf bank_mask:0xf bound_ctrl:1
	v_mov_b32_dpp v115, v101 row_half_mirror row_mask:0xf bank_mask:0xf bound_ctrl:1
	v_pk_add_f32 v[100:101], v[100:101], v[114:115]
	s_nop 1
	v_mov_b32_dpp v114, v100 row_mirror row_mask:0xf bank_mask:0xf bound_ctrl:1
	v_mov_b32_dpp v115, v101 row_mirror row_mask:0xf bank_mask:0xf bound_ctrl:1
	s_and_saveexec_b64 s[6:7], vcc
	v_pk_add_f32 v[100:101], v[100:101], v[114:115]
	ds_write_b64 v160, v[100:101] offset:24
	s_or_b64 exec, exec, s[6:7]
	v_add_u32_e32 v83, 0x1000, v167
	ds_read2_b32 v[100:101], v83 offset1:32
	ds_read2_b32 v[114:115], v83 offset0:64 offset1:96
	v_add_f32_e32 v85, 0, v118
	v_mov_b32_e32 v134, v102
	v_mov_b32_e32 v135, v86
	v_mul_f32_e32 v117, 0.5, v85
	s_waitcnt lgkmcnt(1)
	v_mul_f32_e32 v133, 0x3fd744fd, v100
	v_pk_add_f32 v[134:135], v[134:135], 0 op_sel_hi:[1,0]
	v_mov_b32_e32 v116, v86
	v_mov_b32_e32 v132, v1
	v_mov_b32_e32 v100, v101
	s_waitcnt lgkmcnt(0)
	v_mov_b32_e32 v101, v114
	s_mov_b32 s2, s67
	v_pk_add_f32 v[116:117], v[116:117], v[132:133]
	v_pk_mul_f32 v[132:133], v[100:101], s[2:3] op_sel_hi:[1,0]
	v_pk_mul_f32 v[136:137], v[134:135], 0.5 op_sel_hi:[1,0]
	v_pk_fma_f32 v[100:101], v[134:135], 0.5, v[132:133] op_sel_hi:[1,0,1]
	v_mov_b32_e32 v136, v117
	v_mov_b32_e32 v140, v1
	v_mov_b32_e32 v141, v133
	v_add_f32_e32 v130, 0, v70
	v_mov_b32_e32 v131, v115
	v_pk_mul_f32 v[134:135], v[100:101], v[100:101]
	v_pk_add_f32 v[136:137], v[136:137], v[140:141]
	v_mul_f32_e32 v70, 0x3fd744fd, v115
	v_mov_b32_e32 v163, v117
	v_pk_mov_b32 v[132:133], v[132:133], v[134:135] op_sel:[1,0]
	v_pk_add_f32 v[134:135], v[100:101], v[136:137]
	v_pk_mul_f32 v[136:137], v[100:101], v[136:137]
	v_pk_fma_f32 v[114:115], v[130:131], s[66:67], v[70:71] op_sel_hi:[1,1,0]
	v_pk_fma_f32 v[132:133], v[116:117], v[162:163], v[132:133]
	v_mov_b32_e32 v135, v137
	v_pk_mul_f32 v[130:131], v[114:115], v[114:115]
	v_pk_add_f32 v[132:133], v[134:135], v[132:133]
	v_mov_b32_e32 v115, v130
	v_pk_add_f32 v[130:131], v[132:133], v[114:115]
	s_nop 1
	v_mov_b32_dpp v132, v130 quad_perm:[1,0,3,2] row_mask:0xf bank_mask:0xf bound_ctrl:1
	v_mov_b32_dpp v133, v131 quad_perm:[1,0,3,2] row_mask:0xf bank_mask:0xf bound_ctrl:1
	v_pk_add_f32 v[130:131], v[130:131], v[132:133]
	s_nop 1
	v_mov_b32_dpp v132, v130 quad_perm:[2,3,0,1] row_mask:0xf bank_mask:0xf bound_ctrl:1
	v_mov_b32_dpp v133, v131 quad_perm:[2,3,0,1] row_mask:0xf bank_mask:0xf bound_ctrl:1
	v_pk_add_f32 v[130:131], v[130:131], v[132:133]
	s_nop 1
	v_mov_b32_dpp v132, v130 row_half_mirror row_mask:0xf bank_mask:0xf bound_ctrl:1
	v_mov_b32_dpp v133, v131 row_half_mirror row_mask:0xf bank_mask:0xf bound_ctrl:1
	v_pk_add_f32 v[130:131], v[130:131], v[132:133]
	s_nop 1
	v_mov_b32_dpp v132, v130 row_mirror row_mask:0xf bank_mask:0xf bound_ctrl:1
	v_mov_b32_dpp v133, v131 row_mirror row_mask:0xf bank_mask:0xf bound_ctrl:1
	s_and_saveexec_b64 s[6:7], vcc
	v_pk_add_f32 v[130:131], v[130:131], v[132:133]
	ds_write_b64 v160, v[130:131] offset:64
	s_or_b64 exec, exec, s[6:7]
	ds_read2_b32 v[130:131], v83 offset0:128 offset1:160
	ds_read2_b32 v[132:133], v83 offset0:192 offset1:224
	v_add_f32_e32 v70, 0, v119
	v_add_f32_e32 v118, 0, v71
	v_mul_f32_e32 v71, 0.5, v70
	s_waitcnt lgkmcnt(1)
	v_mul_f32_e32 v135, 0x3fd744fd, v130
	v_mov_b32_e32 v86, v103
	v_mov_b32_e32 v70, v87
	v_mov_b32_e32 v134, v1
	v_pk_add_f32 v[136:137], v[86:87], 0 op_sel_hi:[1,0]
	v_pk_add_f32 v[102:103], v[70:71], v[134:135]
	v_mov_b32_e32 v70, v131
	s_waitcnt lgkmcnt(0)
;   DI void operator()(f32x16 (&acc)[2][4], int grow0, int gcol0, int lane, int w, char* lds) {
;     ...
; #pragma unroll
;       for (int qq = 0; qq < 2; ++qq)
; #pragma unroll
;         for (int e = 0; e < 4; ++e) {
;           const int i = 4 * (2 * (ps & 1) + qq) + e;
;           const float* xr = (const float*)(xs + (8 * qq + 4 * hh + e) * 512) + l31;
;           float s1 = 0.f, s2 = 0.f;
; #pragma unroll
;           for (int nt = 0; nt < 4; ++nt) {
;             float v = (acc[mt][nt][i] + bia[nt]) * csc[nt];
;             float z = ALPHA * xr[nt * 32] + hs * v;
;             acc[mt][nt][i] = z; s1 += z; s2 += z * z;
;           }
;           s1 = row16_sum(s1); s2 = row16_sum(s2);
;           if ((lane & 15) == 0) { f32x2 sv = {s1, s2}; *(f32x2*)(redw + (mt * 32 + (i & 3) + 8 * (i >> 2)) * 2) = sv; }
	v_mov_b32_e32 v71, v132
	s_mov_b32 s2, s67
	v_pk_mul_f32 v[86:87], v[70:71], s[2:3] op_sel_hi:[1,0]
	v_pk_mul_f32 v[130:131], v[136:137], 0.5 op_sel_hi:[1,0]
	v_pk_fma_f32 v[70:71], v[136:137], 0.5, v[86:87] op_sel_hi:[1,0,1]
	v_mov_b32_e32 v130, v103
	v_mov_b32_e32 v136, v1
	v_mov_b32_e32 v137, v87
	v_pk_mul_f32 v[134:135], v[70:71], v[70:71]
	v_pk_add_f32 v[130:131], v[130:131], v[136:137]
	v_mov_b32_e32 v163, v103
	v_pk_mov_b32 v[86:87], v[86:87], v[134:135] op_sel:[1,0]
	v_pk_add_f32 v[134:135], v[70:71], v[130:131]
	v_pk_mul_f32 v[130:131], v[70:71], v[130:131]
	v_pk_fma_f32 v[86:87], v[102:103], v[162:163], v[86:87]
	v_mov_b32_e32 v135, v131
	v_mov_b32_e32 v119, v133
	v_pk_add_f32 v[130:131], v[134:135], v[86:87]
	v_mul_f32_e32 v86, 0x3fd744fd, v133
	v_pk_fma_f32 v[86:87], v[118:119], s[66:67], v[86:87] op_sel_hi:[1,1,0]
	s_nop 0
	v_pk_mul_f32 v[118:119], v[86:87], v[86:87]
	s_nop 0
	v_mov_b32_e32 v87, v118
	v_pk_add_f32 v[118:119], v[130:131], v[86:87]
	s_nop 1
	v_mov_b32_dpp v130, v118 quad_perm:[1,0,3,2] row_mask:0xf bank_mask:0xf bound_ctrl:1
	v_mov_b32_dpp v131, v119 quad_perm:[1,0,3,2] row_mask:0xf bank_mask:0xf bound_ctrl:1
	v_pk_add_f32 v[118:119], v[118:119], v[130:131]
	s_nop 1
	v_mov_b32_dpp v130, v118 quad_perm:[2,3,0,1] row_mask:0xf bank_mask:0xf bound_ctrl:1
	v_mov_b32_dpp v131, v119 quad_perm:[2,3,0,1] row_mask:0xf bank_mask:0xf bound_ctrl:1
	v_pk_add_f32 v[118:119], v[118:119], v[130:131]
	s_nop 1
	v_mov_b32_dpp v130, v118 row_half_mirror row_mask:0xf bank_mask:0xf bound_ctrl:1
	v_mov_b32_dpp v131, v119 row_half_mirror row_mask:0xf bank_mask:0xf bound_ctrl:1
	v_pk_add_f32 v[118:119], v[118:119], v[130:131]
	s_nop 1
	v_mov_b32_dpp v130, v118 row_mirror row_mask:0xf bank_mask:0xf bound_ctrl:1
	v_mov_b32_dpp v131, v119 row_mirror row_mask:0xf bank_mask:0xf bound_ctrl:1
	s_and_saveexec_b64 s[6:7], vcc
	v_pk_add_f32 v[118:119], v[118:119], v[130:131]
	ds_write_b64 v160, v[118:119] offset:72
	s_or_b64 exec, exec, s[6:7]
	v_add_u32_e32 v85, 0x1400, v167
	ds_read2_b32 v[118:119], v85 offset1:32
	ds_read2_b32 v[130:131], v85 offset0:64 offset1:96
	v_add_f32_e32 v87, 0, v120
	v_mov_b32_e32 v140, v104
	v_mov_b32_e32 v141, v88
	v_mul_f32_e32 v133, 0.5, v87
	s_waitcnt lgkmcnt(1)
	v_mul_f32_e32 v137, 0x3fd744fd, v118
	v_pk_add_f32 v[140:141], v[140:141], 0 op_sel_hi:[1,0]
	v_mov_b32_e32 v132, v88
	v_mov_b32_e32 v136, v1
	v_mov_b32_e32 v118, v119
	s_waitcnt lgkmcnt(0)
	v_mov_b32_e32 v119, v130
	s_mov_b32 s2, s67
	v_pk_add_f32 v[132:133], v[132:133], v[136:137]
	v_pk_mul_f32 v[136:137], v[118:119], s[2:3] op_sel_hi:[1,0]
	v_pk_mul_f32 v[146:147], v[140:141], 0.5 op_sel_hi:[1,0]
	v_pk_fma_f32 v[118:119], v[140:141], 0.5, v[136:137] op_sel_hi:[1,0,1]
	v_mov_b32_e32 v146, v133
	v_mov_b32_e32 v150, v1
	v_mov_b32_e32 v151, v137
	v_add_f32_e32 v134, 0, v72
	v_mov_b32_e32 v135, v131
	v_pk_mul_f32 v[140:141], v[118:119], v[118:119]
	v_pk_add_f32 v[146:147], v[146:147], v[150:151]
	v_mul_f32_e32 v72, 0x3fd744fd, v131
	v_mov_b32_e32 v163, v133
	v_pk_mov_b32 v[136:137], v[136:137], v[140:141] op_sel:[1,0]
	v_pk_add_f32 v[140:141], v[118:119], v[146:147]
	v_pk_mul_f32 v[146:147], v[118:119], v[146:147]
	v_pk_fma_f32 v[130:131], v[134:135], s[66:67], v[72:73] op_sel_hi:[1,1,0]
	v_pk_fma_f32 v[136:137], v[132:133], v[162:163], v[136:137]
	v_mov_b32_e32 v141, v147
	v_pk_mul_f32 v[134:135], v[130:131], v[130:131]
	v_pk_add_f32 v[136:137], v[140:141], v[136:137]
	v_mov_b32_e32 v131, v134
	v_pk_add_f32 v[134:135], v[136:137], v[130:131]
	s_nop 1
	v_mov_b32_dpp v136, v134 quad_perm:[1,0,3,2] row_mask:0xf bank_mask:0xf bound_ctrl:1
	v_mov_b32_dpp v137, v135 quad_perm:[1,0,3,2] row_mask:0xf bank_mask:0xf bound_ctrl:1
	v_pk_add_f32 v[134:135], v[134:135], v[136:137]
	s_nop 1
	v_mov_b32_dpp v136, v134 quad_perm:[2,3,0,1] row_mask:0xf bank_mask:0xf bound_ctrl:1
	v_mov_b32_dpp v137, v135 quad_perm:[2,3,0,1] row_mask:0xf bank_mask:0xf bound_ctrl:1
	v_pk_add_f32 v[134:135], v[134:135], v[136:137]
	s_nop 1
	v_mov_b32_dpp v136, v134 row_half_mirror row_mask:0xf bank_mask:0xf bound_ctrl:1
	v_mov_b32_dpp v137, v135 row_half_mirror row_mask:0xf bank_mask:0xf bound_ctrl:1
	v_pk_add_f32 v[134:135], v[134:135], v[136:137]
	s_nop 1
	v_mov_b32_dpp v136, v134 row_mirror row_mask:0xf bank_mask:0xf bound_ctrl:1
	v_mov_b32_dpp v137, v135 row_mirror row_mask:0xf bank_mask:0xf bound_ctrl:1
	s_and_saveexec_b64 s[6:7], vcc
	v_pk_add_f32 v[134:135], v[134:135], v[136:137]
	ds_write_b64 v160, v[134:135] offset:80
	s_or_b64 exec, exec, s[6:7]
	v_or_b32_e32 v115, 0x1600, v139
	v_add_u32_e32 v87, v138, v115
	ds_read2_b32 v[134:135], v87 offset1:32
	ds_read2_b32 v[136:137], v87 offset0:64 offset1:96
	v_add_f32_e32 v72, 0, v121
	v_add_f32_e32 v120, 0, v73
	v_mul_f32_e32 v73, 0.5, v72
	s_waitcnt lgkmcnt(1)
	v_mul_f32_e32 v141, 0x3fd744fd, v134
	v_mov_b32_e32 v88, v105
	v_mov_b32_e32 v72, v89
	v_mov_b32_e32 v140, v1
	v_pk_add_f32 v[146:147], v[88:89], 0 op_sel_hi:[1,0]
	v_pk_add_f32 v[104:105], v[72:73], v[140:141]
	v_mov_b32_e32 v72, v135
	s_waitcnt lgkmcnt(0)
;   DI void xpass(int ps, int grow0, int gcol0, int lane, int w, char* lds) const {
;     char* xs = lds + (ps & 1) * 65536 + __builtin_amdgcn_readfirstlane(w) * 8192;
;     const float* xsrc = Xin + (size_t)(grow0 + (ps >> 1) * 32 + (ps & 1) * 16 + (lane >> 5)) * D_ + gcol0 + (lane & 31) * 4;
; #pragma unroll
;     for (int pc = 0; pc < 8; ++pc)
;       __builtin_amdgcn_global_load_lds((const unsigned*)(xsrc + (size_t)(2 * pc) * D_), (__attribute__((address_space(3))) unsigned*)(xs + pc * 1024), 16, 0, 0);
;   }
;   DI void operator()(f32x16 (&acc)[2][4], int grow0, int gcol0, int lane, int w, char* lds) {
;     ...
;     for (int ps = 0; ps < 4; ++ps) {
;       const int mt = ps >> 1;
;       if (ps + 1 < 4) {
;         if (ps >= 1) asm volatile("s_waitcnt lgkmcnt(0)" ::: "memory");
;         xpass(ps + 1, grow0, gcol0, lane, w, lds);
;         if (ps >= 1) asm volatile("s_waitcnt vmcnt(8)" ::: "memory");
;       } else asm volatile("s_waitcnt vmcnt(0)" ::: "memory");
;       const char* xs = lds + (ps & 1) * 65536 + w * 8192;
; #pragma unroll
;       for (int qq = 0; qq < 2; ++qq)
; #pragma unroll
;         for (int e = 0; e < 4; ++e) {
;           const int i = 4 * (2 * (ps & 1) + qq) + e;
;           const float* xr = (const float*)(xs + (8 * qq + 4 * hh + e) * 512) + l31;
;           float s1 = 0.f, s2 = 0.f;
; #pragma unroll
;           for (int nt = 0; nt < 4; ++nt) {
;             float v = (acc[mt][nt][i] + bia[nt]) * csc[nt];
;             float z = ALPHA * xr[nt * 32] + hs * v;
;             acc[mt][nt][i] = z; s1 += z; s2 += z * z;
;           }
;           s1 = row16_sum(s1); s2 = row16_sum(s2);
;           if ((lane & 15) == 0) { f32x2 sv = {s1, s2}; *(f32x2*)(redw + (mt * 32 + (i & 3) + 8 * (i >> 2)) * 2) = sv; }
	v_mov_b32_e32 v73, v136
	s_mov_b32 s2, s67
	v_pk_mul_f32 v[88:89], v[72:73], s[2:3] op_sel_hi:[1,0]
	v_pk_mul_f32 v[134:135], v[146:147], 0.5 op_sel_hi:[1,0]
	v_pk_fma_f32 v[72:73], v[146:147], 0.5, v[88:89] op_sel_hi:[1,0,1]
	v_mov_b32_e32 v134, v105
	v_mov_b32_e32 v146, v1
	v_mov_b32_e32 v147, v89
	v_pk_mul_f32 v[140:141], v[72:73], v[72:73]
	v_pk_add_f32 v[134:135], v[134:135], v[146:147]
	v_mov_b32_e32 v163, v105
	v_pk_mov_b32 v[88:89], v[88:89], v[140:141] op_sel:[1,0]
	v_pk_add_f32 v[140:141], v[72:73], v[134:135]
	v_pk_mul_f32 v[134:135], v[72:73], v[134:135]
	v_pk_fma_f32 v[88:89], v[104:105], v[162:163], v[88:89]
	v_mov_b32_e32 v141, v135
	v_mov_b32_e32 v121, v137
	v_pk_add_f32 v[134:135], v[140:141], v[88:89]
	v_mul_f32_e32 v88, 0x3fd744fd, v137
	v_pk_fma_f32 v[88:89], v[120:121], s[66:67], v[88:89] op_sel_hi:[1,1,0]
	s_nop 0
	v_pk_mul_f32 v[120:121], v[88:89], v[88:89]
	s_nop 0
	v_mov_b32_e32 v89, v120
	v_pk_add_f32 v[120:121], v[134:135], v[88:89]
	s_nop 1
	v_mov_b32_dpp v134, v120 quad_perm:[1,0,3,2] row_mask:0xf bank_mask:0xf bound_ctrl:1
	v_mov_b32_dpp v135, v121 quad_perm:[1,0,3,2] row_mask:0xf bank_mask:0xf bound_ctrl:1
	v_pk_add_f32 v[120:121], v[120:121], v[134:135]
	s_nop 1
	v_mov_b32_dpp v134, v120 quad_perm:[2,3,0,1] row_mask:0xf bank_mask:0xf bound_ctrl:1
	v_mov_b32_dpp v135, v121 quad_perm:[2,3,0,1] row_mask:0xf bank_mask:0xf bound_ctrl:1
	v_pk_add_f32 v[120:121], v[120:121], v[134:135]
	s_nop 1
	v_mov_b32_dpp v134, v120 row_half_mirror row_mask:0xf bank_mask:0xf bound_ctrl:1
	v_mov_b32_dpp v135, v121 row_half_mirror row_mask:0xf bank_mask:0xf bound_ctrl:1
	v_pk_add_f32 v[120:121], v[120:121], v[134:135]
	s_nop 1
	v_mov_b32_dpp v134, v120 row_mirror row_mask:0xf bank_mask:0xf bound_ctrl:1
	v_mov_b32_dpp v135, v121 row_mirror row_mask:0xf bank_mask:0xf bound_ctrl:1
	s_and_saveexec_b64 s[6:7], vcc
	v_pk_add_f32 v[120:121], v[120:121], v[134:135]
	ds_write_b64 v160, v[120:121] offset:88
	s_or_b64 exec, exec, s[6:7]
	v_or_b32_e32 v120, 32, v176
	v_ashrrev_i32_e32 v121, 31, v120
	v_readlane_b32 s6, v255, 29
	v_lshlrev_b64 v[120:121], 12, v[120:121]
	v_readlane_b32 s7, v255, 30
	v_readfirstlane_b32 s2, v169
	s_lshl_b32 s2, s2, 13
	v_lshl_add_u64 v[120:121], s[6:7], 0, v[120:121]
	v_lshl_add_u64 v[120:121], v[154:155], 2, v[120:121]
	s_waitcnt lgkmcnt(0)
	v_lshl_add_u64 v[120:121], v[120:121], 0, v[0:1]
	s_mov_b32 m0, s2
	s_mov_b64 s[6:7], 0x2000
	global_load_lds_dwordx4 v[120:121], off
	v_lshl_add_u64 v[134:135], v[120:121], 0, s[6:7]
	s_or_b32 m0, s2, 0x400
	s_mov_b64 s[6:7], 0x4000
	global_load_lds_dwordx4 v[134:135], off
	v_lshl_add_u64 v[134:135], v[120:121], 0, s[6:7]
	s_or_b32 m0, s2, 0x800
	s_mov_b64 s[6:7], 0x6000
	global_load_lds_dwordx4 v[134:135], off
	v_lshl_add_u64 v[134:135], v[120:121], 0, s[6:7]
	s_or_b32 m0, s2, 0xc00
	s_mov_b64 s[6:7], 0x8000
	global_load_lds_dwordx4 v[134:135], off
	v_lshl_add_u64 v[134:135], v[120:121], 0, s[6:7]
	s_or_b32 m0, s2, 0x1000
	s_mov_b64 s[6:7], 0xa000
	global_load_lds_dwordx4 v[134:135], off
	v_lshl_add_u64 v[134:135], v[120:121], 0, s[6:7]
	s_or_b32 m0, s2, 0x1400
	s_mov_b64 s[6:7], 0xc000
	global_load_lds_dwordx4 v[134:135], off
	v_lshl_add_u64 v[134:135], v[120:121], 0, s[6:7]
	s_or_b32 m0, s2, 0x1800
	s_mov_b64 s[6:7], 0xe000
	global_load_lds_dwordx4 v[134:135], off
	v_lshl_add_u64 v[120:121], v[120:121], 0, s[6:7]
	s_or_b32 m0, s2, 0x1c00
	v_add_u32_e32 v116, 0x10000, v138
	global_load_lds_dwordx4 v[120:121], off
	s_waitcnt vmcnt(8)
	v_add_u32_e32 v89, v116, v172
	ds_read2_b32 v[120:121], v89 offset1:32
	ds_read2_b32 v[134:135], v89 offset0:64 offset1:96
	v_add_f32_e32 v98, 0, v122
	v_mov_b32_e32 v146, v106
	v_mov_b32_e32 v147, v90
	s_waitcnt lgkmcnt(0)
	v_mul_f32_e32 v137, 0x3fd744fd, v120
	v_mul_f32_e32 v139, 0.5, v98
	v_pk_add_f32 v[146:147], v[146:147], 0 op_sel_hi:[1,0]
	v_mov_b32_e32 v138, v90
	v_mov_b32_e32 v136, v1
	v_mov_b32_e32 v120, v121
	v_mov_b32_e32 v121, v134
	s_mov_b32 s2, s67
	v_pk_add_f32 v[136:137], v[138:139], v[136:137]
	v_pk_mul_f32 v[138:139], v[120:121], s[2:3] op_sel_hi:[1,0]
	v_pk_mul_f32 v[150:151], v[146:147], 0.5 op_sel_hi:[1,0]
	v_pk_fma_f32 v[120:121], v[146:147], 0.5, v[138:139] op_sel_hi:[1,0,1]
	v_mov_b32_e32 v150, v137
	v_mov_b32_e32 v156, v1
	v_mov_b32_e32 v157, v139
	v_add_f32_e32 v140, 0, v74
	v_mov_b32_e32 v141, v135
	v_pk_mul_f32 v[146:147], v[120:121], v[120:121]
	v_pk_add_f32 v[150:151], v[150:151], v[156:157]
	v_mul_f32_e32 v74, 0x3fd744fd, v135
	v_mov_b32_e32 v163, v137
	v_pk_mov_b32 v[138:139], v[138:139], v[146:147] op_sel:[1,0]
	v_pk_add_f32 v[146:147], v[120:121], v[150:151]
	v_pk_mul_f32 v[150:151], v[120:121], v[150:151]
	v_pk_fma_f32 v[134:135], v[140:141], s[66:67], v[74:75] op_sel_hi:[1,1,0]
	v_pk_fma_f32 v[138:139], v[136:137], v[162:163], v[138:139]
	v_mov_b32_e32 v147, v151
	v_pk_mul_f32 v[140:141], v[134:135], v[134:135]
	v_pk_add_f32 v[138:139], v[146:147], v[138:139]
	v_mov_b32_e32 v135, v140
	v_pk_add_f32 v[138:139], v[138:139], v[134:135]
	s_nop 1
	v_mov_b32_dpp v140, v138 quad_perm:[1,0,3,2] row_mask:0xf bank_mask:0xf bound_ctrl:1
	v_mov_b32_dpp v141, v139 quad_perm:[1,0,3,2] row_mask:0xf bank_mask:0xf bound_ctrl:1
	v_pk_add_f32 v[138:139], v[138:139], v[140:141]
	s_nop 1
	v_mov_b32_dpp v140, v138 quad_perm:[2,3,0,1] row_mask:0xf bank_mask:0xf bound_ctrl:1
	v_mov_b32_dpp v141, v139 quad_perm:[2,3,0,1] row_mask:0xf bank_mask:0xf bound_ctrl:1
	v_pk_add_f32 v[138:139], v[138:139], v[140:141]
	s_nop 1
	v_mov_b32_dpp v140, v138 row_half_mirror row_mask:0xf bank_mask:0xf bound_ctrl:1
	v_mov_b32_dpp v141, v139 row_half_mirror row_mask:0xf bank_mask:0xf bound_ctrl:1
	v_pk_add_f32 v[138:139], v[138:139], v[140:141]
	s_nop 1
	v_mov_b32_dpp v140, v138 row_mirror row_mask:0xf bank_mask:0xf bound_ctrl:1
	v_mov_b32_dpp v141, v139 row_mirror row_mask:0xf bank_mask:0xf bound_ctrl:1
	s_and_saveexec_b64 s[6:7], vcc
	v_pk_add_f32 v[138:139], v[138:139], v[140:141]
	ds_write_b64 v160, v[138:139] offset:128
	s_or_b64 exec, exec, s[6:7]
	v_or_b32_e32 v74, 0x200, v172
	v_add_u32_e32 v98, v116, v74
	ds_read2_b32 v[138:139], v98 offset1:32
	ds_read2_b32 v[140:141], v98 offset0:64 offset1:96
	v_add_f32_e32 v74, 0, v123
	v_add_f32_e32 v122, 0, v75
	v_mul_f32_e32 v75, 0.5, v74
	s_waitcnt lgkmcnt(1)
;   DI void operator()(f32x16 (&acc)[2][4], int grow0, int gcol0, int lane, int w, char* lds) {
;     ...
; #pragma unroll
;       for (int qq = 0; qq < 2; ++qq)
; #pragma unroll
;         for (int e = 0; e < 4; ++e) {
;           const int i = 4 * (2 * (ps & 1) + qq) + e;
;           const float* xr = (const float*)(xs + (8 * qq + 4 * hh + e) * 512) + l31;
;           float s1 = 0.f, s2 = 0.f;
; #pragma unroll
;           for (int nt = 0; nt < 4; ++nt) {
;             float v = (acc[mt][nt][i] + bia[nt]) * csc[nt];
;             float z = ALPHA * xr[nt * 32] + hs * v;
;             acc[mt][nt][i] = z; s1 += z; s2 += z * z;
;           }
;           s1 = row16_sum(s1); s2 = row16_sum(s2);
;           if ((lane & 15) == 0) { f32x2 sv = {s1, s2}; *(f32x2*)(redw + (mt * 32 + (i & 3) + 8 * (i >> 2)) * 2) = sv; }
	v_mul_f32_e32 v147, 0x3fd744fd, v138
	v_mov_b32_e32 v90, v107
	v_mov_b32_e32 v74, v91
	v_mov_b32_e32 v146, v1
	v_pk_add_f32 v[150:151], v[90:91], 0 op_sel_hi:[1,0]
	v_pk_add_f32 v[106:107], v[74:75], v[146:147]
	v_mov_b32_e32 v74, v139
	s_waitcnt lgkmcnt(0)
	v_mov_b32_e32 v75, v140
	s_mov_b32 s2, s67
	v_pk_mul_f32 v[90:91], v[74:75], s[2:3] op_sel_hi:[1,0]
	v_pk_mul_f32 v[138:139], v[150:151], 0.5 op_sel_hi:[1,0]
	v_pk_fma_f32 v[74:75], v[150:151], 0.5, v[90:91] op_sel_hi:[1,0,1]
	v_mov_b32_e32 v138, v107
	v_mov_b32_e32 v150, v1
	v_mov_b32_e32 v151, v91
	v_pk_mul_f32 v[146:147], v[74:75], v[74:75]
	v_pk_add_f32 v[138:139], v[138:139], v[150:151]
	v_mov_b32_e32 v163, v107
	v_pk_mov_b32 v[90:91], v[90:91], v[146:147] op_sel:[1,0]
	v_pk_add_f32 v[146:147], v[74:75], v[138:139]
	v_pk_mul_f32 v[138:139], v[74:75], v[138:139]
	v_pk_fma_f32 v[90:91], v[106:107], v[162:163], v[90:91]
	v_mov_b32_e32 v147, v139
	v_mov_b32_e32 v123, v141
	v_pk_add_f32 v[138:139], v[146:147], v[90:91]
	v_mul_f32_e32 v90, 0x3fd744fd, v141
	v_pk_fma_f32 v[90:91], v[122:123], s[66:67], v[90:91] op_sel_hi:[1,1,0]
	s_nop 0
	v_pk_mul_f32 v[122:123], v[90:91], v[90:91]
	s_nop 0
	v_mov_b32_e32 v91, v122
	v_pk_add_f32 v[122:123], v[138:139], v[90:91]
	s_nop 1
	v_mov_b32_dpp v138, v122 quad_perm:[1,0,3,2] row_mask:0xf bank_mask:0xf bound_ctrl:1
	v_mov_b32_dpp v139, v123 quad_perm:[1,0,3,2] row_mask:0xf bank_mask:0xf bound_ctrl:1
	v_pk_add_f32 v[122:123], v[122:123], v[138:139]
	s_nop 1
	v_mov_b32_dpp v138, v122 quad_perm:[2,3,0,1] row_mask:0xf bank_mask:0xf bound_ctrl:1
	v_mov_b32_dpp v139, v123 quad_perm:[2,3,0,1] row_mask:0xf bank_mask:0xf bound_ctrl:1
	v_pk_add_f32 v[122:123], v[122:123], v[138:139]
	s_nop 1
	v_mov_b32_dpp v138, v122 row_half_mirror row_mask:0xf bank_mask:0xf bound_ctrl:1
	v_mov_b32_dpp v139, v123 row_half_mirror row_mask:0xf bank_mask:0xf bound_ctrl:1
	v_pk_add_f32 v[122:123], v[122:123], v[138:139]
	s_nop 1
	v_mov_b32_dpp v138, v122 row_mirror row_mask:0xf bank_mask:0xf bound_ctrl:1
	v_mov_b32_dpp v139, v123 row_mirror row_mask:0xf bank_mask:0xf bound_ctrl:1
	s_and_saveexec_b64 s[6:7], vcc
	v_pk_add_f32 v[122:123], v[122:123], v[138:139]
	ds_write_b64 v160, v[122:123] offset:136
	s_or_b64 exec, exec, s[6:7]
	v_or_b32_e32 v91, 0x400, v172
	v_add_u32_e32 v102, v116, v91
	ds_read2_b32 v[122:123], v102 offset1:32
	ds_read2_b32 v[138:139], v102 offset0:64 offset1:96
	v_add_f32_e32 v91, 0, v124
	v_mov_b32_e32 v156, v108
	v_mov_b32_e32 v157, v92
	v_mul_f32_e32 v141, 0.5, v91
	s_waitcnt lgkmcnt(1)
	v_mul_f32_e32 v151, 0x3fd744fd, v122
	v_pk_add_f32 v[156:157], v[156:157], 0 op_sel_hi:[1,0]
	v_mov_b32_e32 v140, v92
	v_mov_b32_e32 v150, v1
	v_mov_b32_e32 v122, v123
	s_waitcnt lgkmcnt(0)
	v_mov_b32_e32 v123, v138
	s_mov_b32 s2, s67
	v_pk_add_f32 v[140:141], v[140:141], v[150:151]
	v_pk_mul_f32 v[150:151], v[122:123], s[2:3] op_sel_hi:[1,0]
	v_pk_mul_f32 v[174:175], v[156:157], 0.5 op_sel_hi:[1,0]
	v_pk_fma_f32 v[122:123], v[156:157], 0.5, v[150:151] op_sel_hi:[1,0,1]
	v_mov_b32_e32 v174, v141
	v_mov_b32_e32 v178, v1
	v_mov_b32_e32 v179, v151
	v_add_f32_e32 v146, 0, v76
	v_mov_b32_e32 v147, v139
	v_pk_mul_f32 v[156:157], v[122:123], v[122:123]
	v_pk_add_f32 v[174:175], v[174:175], v[178:179]
	v_mul_f32_e32 v76, 0x3fd744fd, v139
	v_mov_b32_e32 v163, v141
	v_pk_mov_b32 v[150:151], v[150:151], v[156:157] op_sel:[1,0]
	v_pk_add_f32 v[156:157], v[122:123], v[174:175]
	v_pk_mul_f32 v[174:175], v[122:123], v[174:175]
	v_pk_fma_f32 v[138:139], v[146:147], s[66:67], v[76:77] op_sel_hi:[1,1,0]
	v_pk_fma_f32 v[150:151], v[140:141], v[162:163], v[150:151]
	v_mov_b32_e32 v157, v175
	v_pk_mul_f32 v[146:147], v[138:139], v[138:139]
	v_pk_add_f32 v[150:151], v[156:157], v[150:151]
	v_mov_b32_e32 v139, v146
	v_pk_add_f32 v[146:147], v[150:151], v[138:139]
	s_nop 1
	v_mov_b32_dpp v150, v146 quad_perm:[1,0,3,2] row_mask:0xf bank_mask:0xf bound_ctrl:1
	v_mov_b32_dpp v151, v147 quad_perm:[1,0,3,2] row_mask:0xf bank_mask:0xf bound_ctrl:1
	v_pk_add_f32 v[146:147], v[146:147], v[150:151]
	s_nop 1
	v_mov_b32_dpp v150, v146 quad_perm:[2,3,0,1] row_mask:0xf bank_mask:0xf bound_ctrl:1
	v_mov_b32_dpp v151, v147 quad_perm:[2,3,0,1] row_mask:0xf bank_mask:0xf bound_ctrl:1
	v_pk_add_f32 v[146:147], v[146:147], v[150:151]
	s_nop 1
	v_mov_b32_dpp v150, v146 row_half_mirror row_mask:0xf bank_mask:0xf bound_ctrl:1
	v_mov_b32_dpp v151, v147 row_half_mirror row_mask:0xf bank_mask:0xf bound_ctrl:1
	v_pk_add_f32 v[146:147], v[146:147], v[150:151]
	s_nop 1
	v_mov_b32_dpp v150, v146 row_mirror row_mask:0xf bank_mask:0xf bound_ctrl:1
	v_mov_b32_dpp v151, v147 row_mirror row_mask:0xf bank_mask:0xf bound_ctrl:1
	s_and_saveexec_b64 s[6:7], vcc
	v_pk_add_f32 v[146:147], v[146:147], v[150:151]
	ds_write_b64 v160, v[146:147] offset:144
	s_or_b64 exec, exec, s[6:7]
	v_add_u32_e32 v104, v116, v152
	ds_read2_b32 v[146:147], v104 offset1:32
	ds_read2_b32 v[150:151], v104 offset0:64 offset1:96
	v_add_f32_e32 v76, 0, v125
	v_add_f32_e32 v124, 0, v77
	v_mul_f32_e32 v77, 0.5, v76
	s_waitcnt lgkmcnt(1)
	v_mul_f32_e32 v153, 0x3fd744fd, v146
	v_mov_b32_e32 v92, v109
	v_mov_b32_e32 v76, v93
	v_mov_b32_e32 v152, v1
	v_pk_add_f32 v[156:157], v[92:93], 0 op_sel_hi:[1,0]
	v_pk_add_f32 v[108:109], v[76:77], v[152:153]
	v_mov_b32_e32 v76, v147
	s_waitcnt lgkmcnt(0)
;   DI void operator()(f32x16 (&acc)[2][4], int grow0, int gcol0, int lane, int w, char* lds) {
;     ...
; #pragma unroll
;       for (int qq = 0; qq < 2; ++qq)
; #pragma unroll
;         for (int e = 0; e < 4; ++e) {
;           const int i = 4 * (2 * (ps & 1) + qq) + e;
;           const float* xr = (const float*)(xs + (8 * qq + 4 * hh + e) * 512) + l31;
;           float s1 = 0.f, s2 = 0.f;
; #pragma unroll
;           for (int nt = 0; nt < 4; ++nt) {
;             float v = (acc[mt][nt][i] + bia[nt]) * csc[nt];
;             float z = ALPHA * xr[nt * 32] + hs * v;
;             acc[mt][nt][i] = z; s1 += z; s2 += z * z;
;           }
;           s1 = row16_sum(s1); s2 = row16_sum(s2);
;           if ((lane & 15) == 0) { f32x2 sv = {s1, s2}; *(f32x2*)(redw + (mt * 32 + (i & 3) + 8 * (i >> 2)) * 2) = sv; }
	v_mov_b32_e32 v77, v150
	s_mov_b32 s2, s67
	v_pk_mul_f32 v[92:93], v[76:77], s[2:3] op_sel_hi:[1,0]
	v_pk_mul_f32 v[146:147], v[156:157], 0.5 op_sel_hi:[1,0]
	v_pk_fma_f32 v[76:77], v[156:157], 0.5, v[92:93] op_sel_hi:[1,0,1]
	v_mov_b32_e32 v146, v109
	v_mov_b32_e32 v156, v1
	v_mov_b32_e32 v157, v93
	v_pk_mul_f32 v[152:153], v[76:77], v[76:77]
	v_pk_add_f32 v[146:147], v[146:147], v[156:157]
	v_mov_b32_e32 v163, v109
	v_pk_mov_b32 v[92:93], v[92:93], v[152:153] op_sel:[1,0]
	v_pk_add_f32 v[152:153], v[76:77], v[146:147]
	v_pk_mul_f32 v[146:147], v[76:77], v[146:147]
	v_pk_fma_f32 v[92:93], v[108:109], v[162:163], v[92:93]
	v_mov_b32_e32 v153, v147
	v_mov_b32_e32 v125, v151
	v_pk_add_f32 v[146:147], v[152:153], v[92:93]
	v_mul_f32_e32 v92, 0x3fd744fd, v151
	v_pk_fma_f32 v[92:93], v[124:125], s[66:67], v[92:93] op_sel_hi:[1,1,0]
	s_nop 0
	v_pk_mul_f32 v[124:125], v[92:93], v[92:93]
	s_nop 0
	v_mov_b32_e32 v93, v124
	v_pk_add_f32 v[124:125], v[146:147], v[92:93]
	s_nop 1
	v_mov_b32_dpp v146, v124 quad_perm:[1,0,3,2] row_mask:0xf bank_mask:0xf bound_ctrl:1
	v_mov_b32_dpp v147, v125 quad_perm:[1,0,3,2] row_mask:0xf bank_mask:0xf bound_ctrl:1
	v_pk_add_f32 v[124:125], v[124:125], v[146:147]
	s_nop 1
	v_mov_b32_dpp v146, v124 quad_perm:[2,3,0,1] row_mask:0xf bank_mask:0xf bound_ctrl:1
	v_mov_b32_dpp v147, v125 quad_perm:[2,3,0,1] row_mask:0xf bank_mask:0xf bound_ctrl:1
	v_pk_add_f32 v[124:125], v[124:125], v[146:147]
	s_nop 1
	v_mov_b32_dpp v146, v124 row_half_mirror row_mask:0xf bank_mask:0xf bound_ctrl:1
	v_mov_b32_dpp v147, v125 row_half_mirror row_mask:0xf bank_mask:0xf bound_ctrl:1
	v_pk_add_f32 v[124:125], v[124:125], v[146:147]
	s_nop 1
	v_mov_b32_dpp v146, v124 row_mirror row_mask:0xf bank_mask:0xf bound_ctrl:1
	v_mov_b32_dpp v147, v125 row_mirror row_mask:0xf bank_mask:0xf bound_ctrl:1
	s_and_saveexec_b64 s[6:7], vcc
	v_pk_add_f32 v[124:125], v[124:125], v[146:147]
	ds_write_b64 v160, v[124:125] offset:152
	s_or_b64 exec, exec, s[6:7]
	v_or_b32_e32 v91, 0x1000, v172
	v_add_u32_e32 v93, v116, v91
	ds_read2_b32 v[124:125], v93 offset1:32
	ds_read2_b32 v[146:147], v93 offset0:64 offset1:96
	v_add_f32_e32 v91, 0, v126
	v_mov_b32_e32 v174, v110
	v_mov_b32_e32 v175, v94
	v_mul_f32_e32 v151, 0.5, v91
	s_waitcnt lgkmcnt(1)
	v_mul_f32_e32 v157, 0x3fd744fd, v124
	v_pk_add_f32 v[174:175], v[174:175], 0 op_sel_hi:[1,0]
	v_mov_b32_e32 v150, v94
	v_mov_b32_e32 v156, v1
	v_mov_b32_e32 v124, v125
	s_waitcnt lgkmcnt(0)
	v_mov_b32_e32 v125, v146
	s_mov_b32 s2, s67
	v_pk_add_f32 v[150:151], v[150:151], v[156:157]
	v_pk_mul_f32 v[156:157], v[124:125], s[2:3] op_sel_hi:[1,0]
	v_pk_mul_f32 v[178:179], v[174:175], 0.5 op_sel_hi:[1,0]
	v_pk_fma_f32 v[124:125], v[174:175], 0.5, v[156:157] op_sel_hi:[1,0,1]
	v_mov_b32_e32 v178, v151
	v_mov_b32_e32 v180, v1
	v_mov_b32_e32 v181, v157
	v_add_f32_e32 v152, 0, v78
	v_mov_b32_e32 v153, v147
	v_pk_mul_f32 v[174:175], v[124:125], v[124:125]
	v_pk_add_f32 v[178:179], v[178:179], v[180:181]
	v_mul_f32_e32 v78, 0x3fd744fd, v147
	v_mov_b32_e32 v163, v151
	v_pk_mov_b32 v[156:157], v[156:157], v[174:175] op_sel:[1,0]
	v_pk_add_f32 v[174:175], v[124:125], v[178:179]
	v_pk_mul_f32 v[178:179], v[124:125], v[178:179]
	v_pk_fma_f32 v[146:147], v[152:153], s[66:67], v[78:79] op_sel_hi:[1,1,0]
	v_pk_fma_f32 v[156:157], v[150:151], v[162:163], v[156:157]
	v_mov_b32_e32 v175, v179
	v_pk_mul_f32 v[152:153], v[146:147], v[146:147]
	v_pk_add_f32 v[156:157], v[174:175], v[156:157]
	v_mov_b32_e32 v147, v152
	v_pk_add_f32 v[152:153], v[156:157], v[146:147]
	s_nop 1
	v_mov_b32_dpp v156, v152 quad_perm:[1,0,3,2] row_mask:0xf bank_mask:0xf bound_ctrl:1
	v_mov_b32_dpp v157, v153 quad_perm:[1,0,3,2] row_mask:0xf bank_mask:0xf bound_ctrl:1
	v_pk_add_f32 v[152:153], v[152:153], v[156:157]
	s_nop 1
	v_mov_b32_dpp v156, v152 quad_perm:[2,3,0,1] row_mask:0xf bank_mask:0xf bound_ctrl:1
	v_mov_b32_dpp v157, v153 quad_perm:[2,3,0,1] row_mask:0xf bank_mask:0xf bound_ctrl:1
	v_pk_add_f32 v[152:153], v[152:153], v[156:157]
	s_nop 1
	v_mov_b32_dpp v156, v152 row_half_mirror row_mask:0xf bank_mask:0xf bound_ctrl:1
	v_mov_b32_dpp v157, v153 row_half_mirror row_mask:0xf bank_mask:0xf bound_ctrl:1
	v_pk_add_f32 v[152:153], v[152:153], v[156:157]
	s_nop 1
	v_mov_b32_dpp v156, v152 row_mirror row_mask:0xf bank_mask:0xf bound_ctrl:1
	v_mov_b32_dpp v157, v153 row_mirror row_mask:0xf bank_mask:0xf bound_ctrl:1
	s_and_saveexec_b64 s[6:7], vcc
	v_pk_add_f32 v[152:153], v[152:153], v[156:157]
	ds_write_b64 v160, v[152:153] offset:192
	s_or_b64 exec, exec, s[6:7]
	v_or_b32_e32 v78, 0x1200, v172
	v_add_u32_e32 v106, v116, v78
	ds_read2_b32 v[152:153], v106 offset1:32
	ds_read2_b32 v[156:157], v106 offset0:64 offset1:96
	v_add_f32_e32 v78, 0, v127
	v_add_f32_e32 v126, 0, v79
	v_mul_f32_e32 v79, 0.5, v78
	s_waitcnt lgkmcnt(1)
	v_mul_f32_e32 v175, 0x3fd744fd, v152
	v_mov_b32_e32 v94, v111
	v_mov_b32_e32 v78, v95
	v_mov_b32_e32 v174, v1
	v_pk_add_f32 v[178:179], v[94:95], 0 op_sel_hi:[1,0]
	v_pk_add_f32 v[110:111], v[78:79], v[174:175]
	v_mov_b32_e32 v78, v153
	s_waitcnt lgkmcnt(0)
;   DI void operator()(f32x16 (&acc)[2][4], int grow0, int gcol0, int lane, int w, char* lds) {
;     ...
; #pragma unroll
;       for (int qq = 0; qq < 2; ++qq)
; #pragma unroll
;         for (int e = 0; e < 4; ++e) {
;           const int i = 4 * (2 * (ps & 1) + qq) + e;
;           const float* xr = (const float*)(xs + (8 * qq + 4 * hh + e) * 512) + l31;
;           float s1 = 0.f, s2 = 0.f;
; #pragma unroll
;           for (int nt = 0; nt < 4; ++nt) {
;             float v = (acc[mt][nt][i] + bia[nt]) * csc[nt];
;             float z = ALPHA * xr[nt * 32] + hs * v;
;             acc[mt][nt][i] = z; s1 += z; s2 += z * z;
;           }
;           s1 = row16_sum(s1); s2 = row16_sum(s2);
;           if ((lane & 15) == 0) { f32x2 sv = {s1, s2}; *(f32x2*)(redw + (mt * 32 + (i & 3) + 8 * (i >> 2)) * 2) = sv; }
	v_mov_b32_e32 v79, v156
	s_mov_b32 s2, s67
	v_pk_mul_f32 v[94:95], v[78:79], s[2:3] op_sel_hi:[1,0]
	v_pk_mul_f32 v[152:153], v[178:179], 0.5 op_sel_hi:[1,0]
	v_pk_fma_f32 v[78:79], v[178:179], 0.5, v[94:95] op_sel_hi:[1,0,1]
	v_mov_b32_e32 v152, v111
	v_mov_b32_e32 v178, v1
	v_mov_b32_e32 v179, v95
	v_pk_mul_f32 v[174:175], v[78:79], v[78:79]
	v_pk_add_f32 v[152:153], v[152:153], v[178:179]
	v_mov_b32_e32 v163, v111
	v_pk_mov_b32 v[94:95], v[94:95], v[174:175] op_sel:[1,0]
	v_pk_add_f32 v[174:175], v[78:79], v[152:153]
	v_pk_mul_f32 v[152:153], v[78:79], v[152:153]
	v_pk_fma_f32 v[94:95], v[110:111], v[162:163], v[94:95]
	v_mov_b32_e32 v175, v153
	v_mov_b32_e32 v127, v157
	v_pk_add_f32 v[152:153], v[174:175], v[94:95]
	v_mul_f32_e32 v94, 0x3fd744fd, v157
	v_pk_fma_f32 v[94:95], v[126:127], s[66:67], v[94:95] op_sel_hi:[1,1,0]
	s_nop 0
	v_pk_mul_f32 v[126:127], v[94:95], v[94:95]
	s_nop 0
	v_mov_b32_e32 v95, v126
	v_pk_add_f32 v[126:127], v[152:153], v[94:95]
	s_nop 1
	v_mov_b32_dpp v152, v126 quad_perm:[1,0,3,2] row_mask:0xf bank_mask:0xf bound_ctrl:1
	v_mov_b32_dpp v153, v127 quad_perm:[1,0,3,2] row_mask:0xf bank_mask:0xf bound_ctrl:1
	v_pk_add_f32 v[126:127], v[126:127], v[152:153]
	s_nop 1
	v_mov_b32_dpp v152, v126 quad_perm:[2,3,0,1] row_mask:0xf bank_mask:0xf bound_ctrl:1
	v_mov_b32_dpp v153, v127 quad_perm:[2,3,0,1] row_mask:0xf bank_mask:0xf bound_ctrl:1
	v_pk_add_f32 v[126:127], v[126:127], v[152:153]
	s_nop 1
	v_mov_b32_dpp v152, v126 row_half_mirror row_mask:0xf bank_mask:0xf bound_ctrl:1
	v_mov_b32_dpp v153, v127 row_half_mirror row_mask:0xf bank_mask:0xf bound_ctrl:1
	v_pk_add_f32 v[126:127], v[126:127], v[152:153]
	s_nop 1
	v_mov_b32_dpp v152, v126 row_mirror row_mask:0xf bank_mask:0xf bound_ctrl:1
	v_mov_b32_dpp v153, v127 row_mirror row_mask:0xf bank_mask:0xf bound_ctrl:1
	s_and_saveexec_b64 s[6:7], vcc
	v_pk_add_f32 v[126:127], v[126:127], v[152:153]
	ds_write_b64 v160, v[126:127] offset:200
	s_or_b64 exec, exec, s[6:7]
	v_or_b32_e32 v91, 0x1400, v172
	v_add_u32_e32 v95, v116, v91
	ds_read2_b32 v[126:127], v95 offset1:32
	ds_read2_b32 v[152:153], v95 offset0:64 offset1:96
	v_add_f32_e32 v91, 0, v128
	v_mov_b32_e32 v178, v112
	v_mov_b32_e32 v179, v96
	v_mul_f32_e32 v157, 0.5, v91
	s_waitcnt lgkmcnt(1)
	v_mul_f32_e32 v175, 0x3fd744fd, v126
	v_pk_add_f32 v[178:179], v[178:179], 0 op_sel_hi:[1,0]
	v_mov_b32_e32 v156, v96
	v_mov_b32_e32 v174, v1
	v_mov_b32_e32 v126, v127
	s_waitcnt lgkmcnt(0)
	v_mov_b32_e32 v127, v152
	s_mov_b32 s2, s67
	v_pk_add_f32 v[156:157], v[156:157], v[174:175]
	v_pk_mul_f32 v[174:175], v[126:127], s[2:3] op_sel_hi:[1,0]
	v_pk_mul_f32 v[180:181], v[178:179], 0.5 op_sel_hi:[1,0]
	v_pk_fma_f32 v[126:127], v[178:179], 0.5, v[174:175] op_sel_hi:[1,0,1]
	v_mov_b32_e32 v180, v157
	v_mov_b32_e32 v182, v1
	v_mov_b32_e32 v183, v175
	v_add_f32_e32 v172, 0, v80
	v_mov_b32_e32 v173, v153
	v_pk_mul_f32 v[178:179], v[126:127], v[126:127]
	v_pk_add_f32 v[180:181], v[180:181], v[182:183]
	v_mul_f32_e32 v80, 0x3fd744fd, v153
	v_mov_b32_e32 v163, v157
	v_pk_mov_b32 v[174:175], v[174:175], v[178:179] op_sel:[1,0]
	v_pk_add_f32 v[178:179], v[126:127], v[180:181]
	v_pk_mul_f32 v[180:181], v[126:127], v[180:181]
	v_pk_fma_f32 v[152:153], v[172:173], s[66:67], v[80:81] op_sel_hi:[1,1,0]
	v_pk_fma_f32 v[174:175], v[156:157], v[162:163], v[174:175]
	v_mov_b32_e32 v179, v181
	v_pk_mul_f32 v[172:173], v[152:153], v[152:153]
	v_pk_add_f32 v[174:175], v[178:179], v[174:175]
	v_mov_b32_e32 v153, v172
	v_pk_add_f32 v[172:173], v[174:175], v[152:153]
	s_nop 1
	v_mov_b32_dpp v174, v172 quad_perm:[1,0,3,2] row_mask:0xf bank_mask:0xf bound_ctrl:1
	v_mov_b32_dpp v175, v173 quad_perm:[1,0,3,2] row_mask:0xf bank_mask:0xf bound_ctrl:1
	v_pk_add_f32 v[172:173], v[172:173], v[174:175]
	s_nop 1
	v_mov_b32_dpp v174, v172 quad_perm:[2,3,0,1] row_mask:0xf bank_mask:0xf bound_ctrl:1
	v_mov_b32_dpp v175, v173 quad_perm:[2,3,0,1] row_mask:0xf bank_mask:0xf bound_ctrl:1
	v_pk_add_f32 v[172:173], v[172:173], v[174:175]
	s_nop 1
	v_mov_b32_dpp v174, v172 row_half_mirror row_mask:0xf bank_mask:0xf bound_ctrl:1
	v_mov_b32_dpp v175, v173 row_half_mirror row_mask:0xf bank_mask:0xf bound_ctrl:1
	v_pk_add_f32 v[172:173], v[172:173], v[174:175]
	s_nop 1
	v_mov_b32_dpp v174, v172 row_mirror row_mask:0xf bank_mask:0xf bound_ctrl:1
	v_mov_b32_dpp v175, v173 row_mirror row_mask:0xf bank_mask:0xf bound_ctrl:1
	s_and_saveexec_b64 s[6:7], vcc
	v_pk_add_f32 v[172:173], v[172:173], v[174:175]
	ds_write_b64 v160, v[172:173] offset:208
	s_or_b64 exec, exec, s[6:7]
	v_add_u32_e32 v91, v116, v115
	v_add_f32_e32 v80, 0, v129
	ds_read2_b32 v[128:129], v91 offset1:32
	ds_read2_b32 v[178:179], v91 offset0:64 offset1:96
	v_mov_b32_e32 v96, v113
	v_mul_f32_e32 v175, 0.5, v80
	v_add_f32_e32 v180, 0, v81
	s_waitcnt lgkmcnt(1)
	v_mul_f32_e32 v173, 0x3fd744fd, v128
	v_pk_add_f32 v[80:81], v[96:97], 0 op_sel_hi:[1,0]
	v_mov_b32_e32 v174, v97
	v_mov_b32_e32 v172, v1
	v_mov_b32_e32 v96, v129
	s_waitcnt lgkmcnt(0)
;   DI void xpass(int ps, int grow0, int gcol0, int lane, int w, char* lds) const {
;     char* xs = lds + (ps & 1) * 65536 + __builtin_amdgcn_readfirstlane(w) * 8192;
;     const float* xsrc = Xin + (size_t)(grow0 + (ps >> 1) * 32 + (ps & 1) * 16 + (lane >> 5)) * D_ + gcol0 + (lane & 31) * 4;
; #pragma unroll
;     for (int pc = 0; pc < 8; ++pc)
;       __builtin_amdgcn_global_load_lds((const unsigned*)(xsrc + (size_t)(2 * pc) * D_), (__attribute__((address_space(3))) unsigned*)(xs + pc * 1024), 16, 0, 0);
;   }
;   DI void operator()(f32x16 (&acc)[2][4], int grow0, int gcol0, int lane, int w, char* lds) {
;     ...
;     for (int ps = 0; ps < 4; ++ps) {
;       const int mt = ps >> 1;
;       if (ps + 1 < 4) {
;         if (ps >= 1) asm volatile("s_waitcnt lgkmcnt(0)" ::: "memory");
;         xpass(ps + 1, grow0, gcol0, lane, w, lds);
;         if (ps >= 1) asm volatile("s_waitcnt vmcnt(8)" ::: "memory");
;       } else asm volatile("s_waitcnt vmcnt(0)" ::: "memory");
;       const char* xs = lds + (ps & 1) * 65536 + w * 8192;
; #pragma unroll
;       for (int qq = 0; qq < 2; ++qq)
; #pragma unroll
;         for (int e = 0; e < 4; ++e) {
;           const int i = 4 * (2 * (ps & 1) + qq) + e;
;           const float* xr = (const float*)(xs + (8 * qq + 4 * hh + e) * 512) + l31;
;           float s1 = 0.f, s2 = 0.f;
; #pragma unroll
;           for (int nt = 0; nt < 4; ++nt) {
;             float v = (acc[mt][nt][i] + bia[nt]) * csc[nt];
;             float z = ALPHA * xr[nt * 32] + hs * v;
;             acc[mt][nt][i] = z; s1 += z; s2 += z * z;
;           }
;           s1 = row16_sum(s1); s2 = row16_sum(s2);
;           if ((lane & 15) == 0) { f32x2 sv = {s1, s2}; *(f32x2*)(redw + (mt * 32 + (i & 3) + 8 * (i >> 2)) * 2) = sv; }
	v_mov_b32_e32 v97, v178
	s_mov_b32 s2, s67
	v_pk_add_f32 v[112:113], v[174:175], v[172:173]
	v_pk_mul_f32 v[96:97], v[96:97], s[2:3] op_sel_hi:[1,0]
	v_pk_mul_f32 v[128:129], v[80:81], 0.5 op_sel_hi:[1,0]
	v_pk_fma_f32 v[80:81], v[80:81], 0.5, v[96:97] op_sel_hi:[1,0,1]
	v_mov_b32_e32 v128, v113
	v_mov_b32_e32 v174, v1
	v_mov_b32_e32 v175, v97
	v_pk_mul_f32 v[172:173], v[80:81], v[80:81]
	v_pk_add_f32 v[128:129], v[128:129], v[174:175]
	v_mov_b32_e32 v163, v113
	v_pk_mov_b32 v[96:97], v[96:97], v[172:173] op_sel:[1,0]
	v_pk_add_f32 v[172:173], v[80:81], v[128:129]
	v_pk_mul_f32 v[128:129], v[80:81], v[128:129]
	v_pk_fma_f32 v[96:97], v[112:113], v[162:163], v[96:97]
	v_mov_b32_e32 v173, v129
	v_mov_b32_e32 v181, v179
	v_pk_add_f32 v[128:129], v[172:173], v[96:97]
	v_mul_f32_e32 v96, 0x3fd744fd, v179
	v_pk_fma_f32 v[96:97], v[180:181], s[66:67], v[96:97] op_sel_hi:[1,1,0]
	s_nop 0
	v_pk_mul_f32 v[172:173], v[96:97], v[96:97]
	s_nop 0
	v_mov_b32_e32 v97, v172
	v_pk_add_f32 v[128:129], v[128:129], v[96:97]
	s_nop 1
	v_mov_b32_dpp v172, v128 quad_perm:[1,0,3,2] row_mask:0xf bank_mask:0xf bound_ctrl:1
	v_mov_b32_dpp v173, v129 quad_perm:[1,0,3,2] row_mask:0xf bank_mask:0xf bound_ctrl:1
	v_pk_add_f32 v[128:129], v[128:129], v[172:173]
	s_nop 1
	v_mov_b32_dpp v172, v128 quad_perm:[2,3,0,1] row_mask:0xf bank_mask:0xf bound_ctrl:1
	v_mov_b32_dpp v173, v129 quad_perm:[2,3,0,1] row_mask:0xf bank_mask:0xf bound_ctrl:1
	v_pk_add_f32 v[128:129], v[128:129], v[172:173]
	s_nop 1
	v_mov_b32_dpp v172, v128 row_half_mirror row_mask:0xf bank_mask:0xf bound_ctrl:1
	v_mov_b32_dpp v173, v129 row_half_mirror row_mask:0xf bank_mask:0xf bound_ctrl:1
	v_pk_add_f32 v[128:129], v[128:129], v[172:173]
	s_nop 1
	v_mov_b32_dpp v172, v128 row_mirror row_mask:0xf bank_mask:0xf bound_ctrl:1
	v_mov_b32_dpp v173, v129 row_mirror row_mask:0xf bank_mask:0xf bound_ctrl:1
	s_and_saveexec_b64 s[6:7], vcc
	v_pk_add_f32 v[128:129], v[128:129], v[172:173]
	ds_write_b64 v160, v[128:129] offset:216
	s_or_b64 exec, exec, s[6:7]
	v_or_b32_e32 v128, 48, v176
	v_ashrrev_i32_e32 v129, 31, v128
	v_readlane_b32 s6, v255, 29
	v_lshlrev_b64 v[128:129], 12, v[128:129]
	v_readlane_b32 s7, v255, 30
	v_readfirstlane_b32 s2, v169
	s_lshl_b32 s2, s2, 13
	v_lshl_add_u64 v[128:129], s[6:7], 0, v[128:129]
	v_lshl_add_u64 v[128:129], v[154:155], 2, v[128:129]
	s_waitcnt lgkmcnt(0)
	s_add_i32 m0, s2, 0x10000
	v_lshl_add_u64 v[128:129], v[128:129], 0, v[0:1]
	s_mov_b64 s[6:7], 0x2000
	global_load_lds_dwordx4 v[128:129], off
	v_lshl_add_u64 v[172:173], v[128:129], 0, s[6:7]
	s_add_i32 m0, s2, 0x10400
	s_mov_b64 s[6:7], 0x4000
	global_load_lds_dwordx4 v[172:173], off
	v_lshl_add_u64 v[172:173], v[128:129], 0, s[6:7]
	s_add_i32 m0, s2, 0x10800
	s_mov_b64 s[6:7], 0x6000
	global_load_lds_dwordx4 v[172:173], off
	v_lshl_add_u64 v[172:173], v[128:129], 0, s[6:7]
	s_add_i32 m0, s2, 0x10c00
	s_mov_b64 s[6:7], 0x8000
	global_load_lds_dwordx4 v[172:173], off
	v_lshl_add_u64 v[172:173], v[128:129], 0, s[6:7]
	s_add_i32 m0, s2, 0x11000
	s_mov_b64 s[6:7], 0xa000
	global_load_lds_dwordx4 v[172:173], off
	v_lshl_add_u64 v[172:173], v[128:129], 0, s[6:7]
	s_add_i32 m0, s2, 0x11400
	s_mov_b64 s[6:7], 0xc000
	global_load_lds_dwordx4 v[172:173], off
	v_lshl_add_u64 v[172:173], v[128:129], 0, s[6:7]
	s_add_i32 m0, s2, 0x11800
	s_mov_b64 s[6:7], 0xe000
	global_load_lds_dwordx4 v[172:173], off
	v_lshl_add_u64 v[128:129], v[128:129], 0, s[6:7]
	s_add_i32 m0, s2, 0x11c00
	v_add_f32_e32 v0, 0, v50
	global_load_lds_dwordx4 v[128:129], off
	s_waitcnt vmcnt(8)
	ds_read2_b32 v[128:129], v167 offset1:32
	ds_read2_b32 v[172:173], v167 offset0:64 offset1:96
	v_mov_b32_e32 v180, v34
	v_mov_b32_e32 v181, v18
	v_mul_f32_e32 v177, 0.5, v0
	s_waitcnt lgkmcnt(0)
	v_mul_f32_e32 v175, 0x3fd744fd, v128
	v_pk_add_f32 v[180:181], v[180:181], 0 op_sel_hi:[1,0]
	v_mov_b32_e32 v176, v18
	v_mov_b32_e32 v174, v1
	v_mov_b32_e32 v128, v129
	v_mov_b32_e32 v129, v172
	s_mov_b32 s2, s67
	v_pk_add_f32 v[174:175], v[176:177], v[174:175]
	v_pk_mul_f32 v[176:177], v[128:129], s[2:3] op_sel_hi:[1,0]
	v_pk_mul_f32 v[182:183], v[180:181], 0.5 op_sel_hi:[1,0]
	v_pk_fma_f32 v[128:129], v[180:181], 0.5, v[176:177] op_sel_hi:[1,0,1]
	v_mov_b32_e32 v182, v175
	v_mov_b32_e32 v184, v1
	v_mov_b32_e32 v185, v177
	v_add_f32_e32 v178, 0, v2
	v_mov_b32_e32 v179, v173
	v_pk_mul_f32 v[180:181], v[128:129], v[128:129]
	v_pk_add_f32 v[182:183], v[182:183], v[184:185]
	v_mul_f32_e32 v0, 0x3fd744fd, v173
	v_mov_b32_e32 v163, v175
	v_pk_mov_b32 v[176:177], v[176:177], v[180:181] op_sel:[1,0]
	v_pk_add_f32 v[180:181], v[128:129], v[182:183]
	v_pk_mul_f32 v[182:183], v[128:129], v[182:183]
	v_pk_fma_f32 v[172:173], v[178:179], s[66:67], v[0:1] op_sel_hi:[1,1,0]
	v_pk_fma_f32 v[176:177], v[174:175], v[162:163], v[176:177]
	v_mov_b32_e32 v181, v183
	v_pk_mul_f32 v[178:179], v[172:173], v[172:173]
	v_pk_add_f32 v[176:177], v[180:181], v[176:177]
	v_mov_b32_e32 v173, v178
	v_pk_add_f32 v[176:177], v[176:177], v[172:173]
	s_nop 1
	v_mov_b32_dpp v178, v176 quad_perm:[1,0,3,2] row_mask:0xf bank_mask:0xf bound_ctrl:1
	v_mov_b32_dpp v179, v177 quad_perm:[1,0,3,2] row_mask:0xf bank_mask:0xf bound_ctrl:1
	v_pk_add_f32 v[176:177], v[176:177], v[178:179]
	s_nop 1
	v_mov_b32_dpp v178, v176 quad_perm:[2,3,0,1] row_mask:0xf bank_mask:0xf bound_ctrl:1
	v_mov_b32_dpp v179, v177 quad_perm:[2,3,0,1] row_mask:0xf bank_mask:0xf bound_ctrl:1
	v_pk_add_f32 v[176:177], v[176:177], v[178:179]
	s_nop 1
	v_mov_b32_dpp v178, v176 row_half_mirror row_mask:0xf bank_mask:0xf bound_ctrl:1
	v_mov_b32_dpp v179, v177 row_half_mirror row_mask:0xf bank_mask:0xf bound_ctrl:1
	v_pk_add_f32 v[176:177], v[176:177], v[178:179]
	s_nop 1
	v_mov_b32_dpp v178, v176 row_mirror row_mask:0xf bank_mask:0xf bound_ctrl:1
	v_mov_b32_dpp v179, v177 row_mirror row_mask:0xf bank_mask:0xf bound_ctrl:1
	s_and_saveexec_b64 s[6:7], vcc
	v_pk_add_f32 v[176:177], v[176:177], v[178:179]
	ds_write_b64 v160, v[176:177] offset:256
	s_or_b64 exec, exec, s[6:7]
	ds_read2_b32 v[176:177], v167 offset0:128 offset1:160
	ds_read2_b32 v[178:179], v167 offset0:192 offset1:224
	v_add_f32_e32 v0, 0, v51
	v_add_f32_e32 v50, 0, v3
	v_mul_f32_e32 v3, 0.5, v0
	s_waitcnt lgkmcnt(1)
;   DI void operator()(f32x16 (&acc)[2][4], int grow0, int gcol0, int lane, int w, char* lds) {
;     ...
; #pragma unroll
;       for (int qq = 0; qq < 2; ++qq)
; #pragma unroll
;         for (int e = 0; e < 4; ++e) {
;           const int i = 4 * (2 * (ps & 1) + qq) + e;
;           const float* xr = (const float*)(xs + (8 * qq + 4 * hh + e) * 512) + l31;
;           float s1 = 0.f, s2 = 0.f;
; #pragma unroll
;           for (int nt = 0; nt < 4; ++nt) {
;             float v = (acc[mt][nt][i] + bia[nt]) * csc[nt];
;             float z = ALPHA * xr[nt * 32] + hs * v;
;             acc[mt][nt][i] = z; s1 += z; s2 += z * z;
;           }
;           s1 = row16_sum(s1); s2 = row16_sum(s2);
;           if ((lane & 15) == 0) { f32x2 sv = {s1, s2}; *(f32x2*)(redw + (mt * 32 + (i & 3) + 8 * (i >> 2)) * 2) = sv; }
	v_mul_f32_e32 v181, 0x3fd744fd, v176
	v_mov_b32_e32 v18, v35
	v_mov_b32_e32 v2, v19
	v_mov_b32_e32 v180, v1
	v_pk_add_f32 v[182:183], v[18:19], 0 op_sel_hi:[1,0]
	v_pk_add_f32 v[34:35], v[2:3], v[180:181]
	v_mov_b32_e32 v2, v177
	s_waitcnt lgkmcnt(0)
	v_mov_b32_e32 v3, v178
	s_mov_b32 s2, s67
	v_pk_mul_f32 v[18:19], v[2:3], s[2:3] op_sel_hi:[1,0]
	v_pk_mul_f32 v[176:177], v[182:183], 0.5 op_sel_hi:[1,0]
	v_pk_fma_f32 v[2:3], v[182:183], 0.5, v[18:19] op_sel_hi:[1,0,1]
	v_mov_b32_e32 v176, v35
	v_mov_b32_e32 v182, v1
	v_mov_b32_e32 v183, v19
	v_pk_mul_f32 v[180:181], v[2:3], v[2:3]
	v_pk_add_f32 v[176:177], v[176:177], v[182:183]
	v_mov_b32_e32 v163, v35
	v_pk_mov_b32 v[18:19], v[18:19], v[180:181] op_sel:[1,0]
	v_pk_add_f32 v[180:181], v[2:3], v[176:177]
	v_pk_mul_f32 v[176:177], v[2:3], v[176:177]
	v_mov_b32_e32 v51, v179
	v_pk_fma_f32 v[18:19], v[34:35], v[162:163], v[18:19]
	v_mov_b32_e32 v181, v177
	v_mul_f32_e32 v0, 0x3fd744fd, v179
	v_pk_add_f32 v[176:177], v[180:181], v[18:19]
	v_pk_fma_f32 v[18:19], v[50:51], s[66:67], v[0:1] op_sel_hi:[1,1,0]
	s_nop 0
	v_pk_mul_f32 v[50:51], v[18:19], v[18:19]
	s_nop 0
	v_mov_b32_e32 v19, v50
	v_pk_add_f32 v[50:51], v[176:177], v[18:19]
	s_nop 1
	v_mov_b32_dpp v176, v50 quad_perm:[1,0,3,2] row_mask:0xf bank_mask:0xf bound_ctrl:1
	v_mov_b32_dpp v177, v51 quad_perm:[1,0,3,2] row_mask:0xf bank_mask:0xf bound_ctrl:1
	v_pk_add_f32 v[50:51], v[50:51], v[176:177]
	s_nop 1
	v_mov_b32_dpp v176, v50 quad_perm:[2,3,0,1] row_mask:0xf bank_mask:0xf bound_ctrl:1
	v_mov_b32_dpp v177, v51 quad_perm:[2,3,0,1] row_mask:0xf bank_mask:0xf bound_ctrl:1
	v_pk_add_f32 v[50:51], v[50:51], v[176:177]
	s_nop 1
	v_mov_b32_dpp v176, v50 row_half_mirror row_mask:0xf bank_mask:0xf bound_ctrl:1
	v_mov_b32_dpp v177, v51 row_half_mirror row_mask:0xf bank_mask:0xf bound_ctrl:1
	v_pk_add_f32 v[50:51], v[50:51], v[176:177]
	s_nop 1
	v_mov_b32_dpp v176, v50 row_mirror row_mask:0xf bank_mask:0xf bound_ctrl:1
	v_mov_b32_dpp v177, v51 row_mirror row_mask:0xf bank_mask:0xf bound_ctrl:1
	s_and_saveexec_b64 s[6:7], vcc
	v_pk_add_f32 v[50:51], v[50:51], v[176:177]
	ds_write_b64 v160, v[50:51] offset:264
	s_or_b64 exec, exec, s[6:7]
	ds_read2_b32 v[50:51], v143 offset1:32
	ds_read2_b32 v[176:177], v143 offset0:64 offset1:96
	v_add_f32_e32 v0, 0, v52
	v_mov_b32_e32 v184, v36
	v_mov_b32_e32 v185, v20
	v_mul_f32_e32 v179, 0.5, v0
	s_waitcnt lgkmcnt(1)
	v_mul_f32_e32 v183, 0x3fd744fd, v50
	v_pk_add_f32 v[184:185], v[184:185], 0 op_sel_hi:[1,0]
	v_mov_b32_e32 v178, v20
	v_mov_b32_e32 v182, v1
	v_mov_b32_e32 v50, v51
	s_waitcnt lgkmcnt(0)
	v_mov_b32_e32 v51, v176
	s_mov_b32 s2, s67
	v_pk_add_f32 v[178:179], v[178:179], v[182:183]
	v_pk_mul_f32 v[182:183], v[50:51], s[2:3] op_sel_hi:[1,0]
	v_pk_mul_f32 v[186:187], v[184:185], 0.5 op_sel_hi:[1,0]
	v_pk_fma_f32 v[50:51], v[184:185], 0.5, v[182:183] op_sel_hi:[1,0,1]
	v_mov_b32_e32 v186, v179
	v_mov_b32_e32 v188, v1
	v_mov_b32_e32 v189, v183
	v_add_f32_e32 v180, 0, v4
	v_mov_b32_e32 v181, v177
	v_pk_mul_f32 v[184:185], v[50:51], v[50:51]
	v_pk_add_f32 v[186:187], v[186:187], v[188:189]
	v_mul_f32_e32 v0, 0x3fd744fd, v177
	v_mov_b32_e32 v163, v179
	v_pk_mov_b32 v[182:183], v[182:183], v[184:185] op_sel:[1,0]
	v_pk_add_f32 v[184:185], v[50:51], v[186:187]
	v_pk_mul_f32 v[186:187], v[50:51], v[186:187]
	v_pk_fma_f32 v[176:177], v[180:181], s[66:67], v[0:1] op_sel_hi:[1,1,0]
	v_pk_fma_f32 v[182:183], v[178:179], v[162:163], v[182:183]
	v_mov_b32_e32 v185, v187
	v_pk_mul_f32 v[180:181], v[176:177], v[176:177]
	v_pk_add_f32 v[182:183], v[184:185], v[182:183]
	v_mov_b32_e32 v177, v180
	v_pk_add_f32 v[180:181], v[182:183], v[176:177]
	s_nop 1
	v_mov_b32_dpp v182, v180 quad_perm:[1,0,3,2] row_mask:0xf bank_mask:0xf bound_ctrl:1
	v_mov_b32_dpp v183, v181 quad_perm:[1,0,3,2] row_mask:0xf bank_mask:0xf bound_ctrl:1
	v_pk_add_f32 v[180:181], v[180:181], v[182:183]
	s_nop 1
	v_mov_b32_dpp v182, v180 quad_perm:[2,3,0,1] row_mask:0xf bank_mask:0xf bound_ctrl:1
	v_mov_b32_dpp v183, v181 quad_perm:[2,3,0,1] row_mask:0xf bank_mask:0xf bound_ctrl:1
	v_pk_add_f32 v[180:181], v[180:181], v[182:183]
	s_nop 1
	v_mov_b32_dpp v182, v180 row_half_mirror row_mask:0xf bank_mask:0xf bound_ctrl:1
	v_mov_b32_dpp v183, v181 row_half_mirror row_mask:0xf bank_mask:0xf bound_ctrl:1
	v_pk_add_f32 v[180:181], v[180:181], v[182:183]
	s_nop 1
	v_mov_b32_dpp v182, v180 row_mirror row_mask:0xf bank_mask:0xf bound_ctrl:1
	v_mov_b32_dpp v183, v181 row_mirror row_mask:0xf bank_mask:0xf bound_ctrl:1
	s_and_saveexec_b64 s[6:7], vcc
	v_pk_add_f32 v[180:181], v[180:181], v[182:183]
	ds_write_b64 v160, v[180:181] offset:272
	s_or_b64 exec, exec, s[6:7]
	ds_read2_b32 v[180:181], v144 offset1:32
	ds_read2_b32 v[182:183], v144 offset0:64 offset1:96
	v_add_f32_e32 v0, 0, v53
	v_add_f32_e32 v52, 0, v5
	v_mul_f32_e32 v5, 0.5, v0
	s_waitcnt lgkmcnt(1)
	v_mul_f32_e32 v185, 0x3fd744fd, v180
	v_mov_b32_e32 v20, v37
	v_mov_b32_e32 v4, v21
	v_mov_b32_e32 v184, v1
	v_pk_add_f32 v[186:187], v[20:21], 0 op_sel_hi:[1,0]
	v_pk_add_f32 v[36:37], v[4:5], v[184:185]
	v_mov_b32_e32 v4, v181
	s_waitcnt lgkmcnt(0)
;   DI void operator()(f32x16 (&acc)[2][4], int grow0, int gcol0, int lane, int w, char* lds) {
;     ...
; #pragma unroll
;       for (int qq = 0; qq < 2; ++qq)
; #pragma unroll
;         for (int e = 0; e < 4; ++e) {
;           const int i = 4 * (2 * (ps & 1) + qq) + e;
;           const float* xr = (const float*)(xs + (8 * qq + 4 * hh + e) * 512) + l31;
;           float s1 = 0.f, s2 = 0.f;
; #pragma unroll
;           for (int nt = 0; nt < 4; ++nt) {
;             float v = (acc[mt][nt][i] + bia[nt]) * csc[nt];
;             float z = ALPHA * xr[nt * 32] + hs * v;
;             acc[mt][nt][i] = z; s1 += z; s2 += z * z;
;           }
;           s1 = row16_sum(s1); s2 = row16_sum(s2);
;           if ((lane & 15) == 0) { f32x2 sv = {s1, s2}; *(f32x2*)(redw + (mt * 32 + (i & 3) + 8 * (i >> 2)) * 2) = sv; }
	v_mov_b32_e32 v5, v182
	s_mov_b32 s2, s67
	v_pk_mul_f32 v[20:21], v[4:5], s[2:3] op_sel_hi:[1,0]
	v_pk_mul_f32 v[180:181], v[186:187], 0.5 op_sel_hi:[1,0]
	v_pk_fma_f32 v[4:5], v[186:187], 0.5, v[20:21] op_sel_hi:[1,0,1]
	v_mov_b32_e32 v180, v37
	v_mov_b32_e32 v186, v1
	v_mov_b32_e32 v187, v21
	v_pk_mul_f32 v[184:185], v[4:5], v[4:5]
	v_pk_add_f32 v[180:181], v[180:181], v[186:187]
	v_mov_b32_e32 v163, v37
	v_pk_mov_b32 v[20:21], v[20:21], v[184:185] op_sel:[1,0]
	v_pk_add_f32 v[184:185], v[4:5], v[180:181]
	v_pk_mul_f32 v[180:181], v[4:5], v[180:181]
	v_mov_b32_e32 v53, v183
	v_pk_fma_f32 v[20:21], v[36:37], v[162:163], v[20:21]
	v_mov_b32_e32 v185, v181
	v_mul_f32_e32 v0, 0x3fd744fd, v183
	v_pk_add_f32 v[180:181], v[184:185], v[20:21]
	v_pk_fma_f32 v[20:21], v[52:53], s[66:67], v[0:1] op_sel_hi:[1,1,0]
	s_nop 0
	v_pk_mul_f32 v[52:53], v[20:21], v[20:21]
	s_nop 0
	v_mov_b32_e32 v21, v52
	v_pk_add_f32 v[52:53], v[180:181], v[20:21]
	s_nop 1
	v_mov_b32_dpp v180, v52 quad_perm:[1,0,3,2] row_mask:0xf bank_mask:0xf bound_ctrl:1
	v_mov_b32_dpp v181, v53 quad_perm:[1,0,3,2] row_mask:0xf bank_mask:0xf bound_ctrl:1
	v_pk_add_f32 v[52:53], v[52:53], v[180:181]
	s_nop 1
	v_mov_b32_dpp v180, v52 quad_perm:[2,3,0,1] row_mask:0xf bank_mask:0xf bound_ctrl:1
	v_mov_b32_dpp v181, v53 quad_perm:[2,3,0,1] row_mask:0xf bank_mask:0xf bound_ctrl:1
	v_pk_add_f32 v[52:53], v[52:53], v[180:181]
	s_nop 1
	v_mov_b32_dpp v180, v52 row_half_mirror row_mask:0xf bank_mask:0xf bound_ctrl:1
	v_mov_b32_dpp v181, v53 row_half_mirror row_mask:0xf bank_mask:0xf bound_ctrl:1
	v_pk_add_f32 v[52:53], v[52:53], v[180:181]
	s_nop 1
	v_mov_b32_dpp v180, v52 row_mirror row_mask:0xf bank_mask:0xf bound_ctrl:1
	v_mov_b32_dpp v181, v53 row_mirror row_mask:0xf bank_mask:0xf bound_ctrl:1
	s_and_saveexec_b64 s[6:7], vcc
	v_pk_add_f32 v[52:53], v[52:53], v[180:181]
	ds_write_b64 v160, v[52:53] offset:280
	s_or_b64 exec, exec, s[6:7]
	ds_read2_b32 v[52:53], v83 offset1:32
	ds_read2_b32 v[180:181], v83 offset0:64 offset1:96
	v_add_f32_e32 v0, 0, v54
	v_mov_b32_e32 v188, v38
	v_mov_b32_e32 v189, v22
	v_mul_f32_e32 v183, 0.5, v0
	s_waitcnt lgkmcnt(1)
	v_mul_f32_e32 v187, 0x3fd744fd, v52
	v_pk_add_f32 v[188:189], v[188:189], 0 op_sel_hi:[1,0]
	v_mov_b32_e32 v182, v22
	v_mov_b32_e32 v186, v1
	v_mov_b32_e32 v52, v53
	s_waitcnt lgkmcnt(0)
	v_mov_b32_e32 v53, v180
	s_mov_b32 s2, s67
	v_pk_add_f32 v[182:183], v[182:183], v[186:187]
	v_pk_mul_f32 v[186:187], v[52:53], s[2:3] op_sel_hi:[1,0]
	v_pk_mul_f32 v[190:191], v[188:189], 0.5 op_sel_hi:[1,0]
	v_pk_fma_f32 v[52:53], v[188:189], 0.5, v[186:187] op_sel_hi:[1,0,1]
	v_mov_b32_e32 v190, v183
	v_mov_b32_e32 v192, v1
	v_mov_b32_e32 v193, v187
	v_add_f32_e32 v184, 0, v6
	v_mov_b32_e32 v185, v181
	v_pk_mul_f32 v[188:189], v[52:53], v[52:53]
	v_pk_add_f32 v[190:191], v[190:191], v[192:193]
	v_mul_f32_e32 v0, 0x3fd744fd, v181
	v_mov_b32_e32 v163, v183
	v_pk_mov_b32 v[186:187], v[186:187], v[188:189] op_sel:[1,0]
	v_pk_add_f32 v[188:189], v[52:53], v[190:191]
	v_pk_mul_f32 v[190:191], v[52:53], v[190:191]
	v_pk_fma_f32 v[180:181], v[184:185], s[66:67], v[0:1] op_sel_hi:[1,1,0]
	v_pk_fma_f32 v[186:187], v[182:183], v[162:163], v[186:187]
	v_mov_b32_e32 v189, v191
	v_pk_mul_f32 v[184:185], v[180:181], v[180:181]
	v_pk_add_f32 v[186:187], v[188:189], v[186:187]
	v_mov_b32_e32 v181, v184
	v_pk_add_f32 v[184:185], v[186:187], v[180:181]
	s_nop 1
	v_mov_b32_dpp v186, v184 quad_perm:[1,0,3,2] row_mask:0xf bank_mask:0xf bound_ctrl:1
	v_mov_b32_dpp v187, v185 quad_perm:[1,0,3,2] row_mask:0xf bank_mask:0xf bound_ctrl:1
	v_pk_add_f32 v[184:185], v[184:185], v[186:187]
	s_nop 1
	v_mov_b32_dpp v186, v184 quad_perm:[2,3,0,1] row_mask:0xf bank_mask:0xf bound_ctrl:1
	v_mov_b32_dpp v187, v185 quad_perm:[2,3,0,1] row_mask:0xf bank_mask:0xf bound_ctrl:1
	v_pk_add_f32 v[184:185], v[184:185], v[186:187]
	s_nop 1
	v_mov_b32_dpp v186, v184 row_half_mirror row_mask:0xf bank_mask:0xf bound_ctrl:1
	v_mov_b32_dpp v187, v185 row_half_mirror row_mask:0xf bank_mask:0xf bound_ctrl:1
	v_pk_add_f32 v[184:185], v[184:185], v[186:187]
	s_nop 1
	v_mov_b32_dpp v186, v184 row_mirror row_mask:0xf bank_mask:0xf bound_ctrl:1
	v_mov_b32_dpp v187, v185 row_mirror row_mask:0xf bank_mask:0xf bound_ctrl:1
	s_and_saveexec_b64 s[6:7], vcc
	v_pk_add_f32 v[184:185], v[184:185], v[186:187]
	ds_write_b64 v160, v[184:185] offset:320
	s_or_b64 exec, exec, s[6:7]
	ds_read2_b32 v[184:185], v83 offset0:128 offset1:160
	ds_read2_b32 v[186:187], v83 offset0:192 offset1:224
	v_add_f32_e32 v0, 0, v55
	v_add_f32_e32 v54, 0, v7
	v_mul_f32_e32 v7, 0.5, v0
	s_waitcnt lgkmcnt(1)
	v_mul_f32_e32 v189, 0x3fd744fd, v184
	v_mov_b32_e32 v22, v39
	v_mov_b32_e32 v6, v23
	v_mov_b32_e32 v188, v1
	v_pk_add_f32 v[190:191], v[22:23], 0 op_sel_hi:[1,0]
	v_pk_add_f32 v[38:39], v[6:7], v[188:189]
	v_mov_b32_e32 v6, v185
	s_waitcnt lgkmcnt(0)
;   DI void operator()(f32x16 (&acc)[2][4], int grow0, int gcol0, int lane, int w, char* lds) {
;     ...
; #pragma unroll
;       for (int qq = 0; qq < 2; ++qq)
; #pragma unroll
;         for (int e = 0; e < 4; ++e) {
;           const int i = 4 * (2 * (ps & 1) + qq) + e;
;           const float* xr = (const float*)(xs + (8 * qq + 4 * hh + e) * 512) + l31;
;           float s1 = 0.f, s2 = 0.f;
; #pragma unroll
;           for (int nt = 0; nt < 4; ++nt) {
;             float v = (acc[mt][nt][i] + bia[nt]) * csc[nt];
;             float z = ALPHA * xr[nt * 32] + hs * v;
;             acc[mt][nt][i] = z; s1 += z; s2 += z * z;
;           }
;           s1 = row16_sum(s1); s2 = row16_sum(s2);
;           if ((lane & 15) == 0) { f32x2 sv = {s1, s2}; *(f32x2*)(redw + (mt * 32 + (i & 3) + 8 * (i >> 2)) * 2) = sv; }
	v_mov_b32_e32 v7, v186
	s_mov_b32 s2, s67
	v_pk_mul_f32 v[22:23], v[6:7], s[2:3] op_sel_hi:[1,0]
	v_pk_mul_f32 v[184:185], v[190:191], 0.5 op_sel_hi:[1,0]
	v_pk_fma_f32 v[6:7], v[190:191], 0.5, v[22:23] op_sel_hi:[1,0,1]
	v_mov_b32_e32 v184, v39
	v_mov_b32_e32 v190, v1
	v_mov_b32_e32 v191, v23
	v_pk_mul_f32 v[188:189], v[6:7], v[6:7]
	v_pk_add_f32 v[184:185], v[184:185], v[190:191]
	v_mov_b32_e32 v163, v39
	v_pk_mov_b32 v[22:23], v[22:23], v[188:189] op_sel:[1,0]
	v_pk_add_f32 v[188:189], v[6:7], v[184:185]
	v_pk_mul_f32 v[184:185], v[6:7], v[184:185]
	v_mov_b32_e32 v55, v187
	v_pk_fma_f32 v[22:23], v[38:39], v[162:163], v[22:23]
	v_mov_b32_e32 v189, v185
	v_mul_f32_e32 v0, 0x3fd744fd, v187
	v_pk_add_f32 v[184:185], v[188:189], v[22:23]
	v_pk_fma_f32 v[22:23], v[54:55], s[66:67], v[0:1] op_sel_hi:[1,1,0]
	s_nop 0
	v_pk_mul_f32 v[54:55], v[22:23], v[22:23]
	s_nop 0
	v_mov_b32_e32 v23, v54
	v_pk_add_f32 v[54:55], v[184:185], v[22:23]
	s_nop 1
	v_mov_b32_dpp v184, v54 quad_perm:[1,0,3,2] row_mask:0xf bank_mask:0xf bound_ctrl:1
	v_mov_b32_dpp v185, v55 quad_perm:[1,0,3,2] row_mask:0xf bank_mask:0xf bound_ctrl:1
	v_pk_add_f32 v[54:55], v[54:55], v[184:185]
	s_nop 1
	v_mov_b32_dpp v184, v54 quad_perm:[2,3,0,1] row_mask:0xf bank_mask:0xf bound_ctrl:1
	v_mov_b32_dpp v185, v55 quad_perm:[2,3,0,1] row_mask:0xf bank_mask:0xf bound_ctrl:1
	v_pk_add_f32 v[54:55], v[54:55], v[184:185]
	s_nop 1
	v_mov_b32_dpp v184, v54 row_half_mirror row_mask:0xf bank_mask:0xf bound_ctrl:1
	v_mov_b32_dpp v185, v55 row_half_mirror row_mask:0xf bank_mask:0xf bound_ctrl:1
	v_pk_add_f32 v[54:55], v[54:55], v[184:185]
	s_nop 1
	v_mov_b32_dpp v184, v54 row_mirror row_mask:0xf bank_mask:0xf bound_ctrl:1
	v_mov_b32_dpp v185, v55 row_mirror row_mask:0xf bank_mask:0xf bound_ctrl:1
	s_and_saveexec_b64 s[6:7], vcc
	v_pk_add_f32 v[54:55], v[54:55], v[184:185]
	ds_write_b64 v160, v[54:55] offset:328
	s_or_b64 exec, exec, s[6:7]
	ds_read2_b32 v[54:55], v85 offset1:32
	ds_read2_b32 v[184:185], v85 offset0:64 offset1:96
	v_add_f32_e32 v0, 0, v56
	v_mov_b32_e32 v192, v40
	v_mov_b32_e32 v193, v24
	v_mul_f32_e32 v187, 0.5, v0
	s_waitcnt lgkmcnt(1)
	v_mul_f32_e32 v191, 0x3fd744fd, v54
	v_pk_add_f32 v[192:193], v[192:193], 0 op_sel_hi:[1,0]
	v_mov_b32_e32 v186, v24
	v_mov_b32_e32 v190, v1
	v_mov_b32_e32 v54, v55
	s_waitcnt lgkmcnt(0)
	v_mov_b32_e32 v55, v184
	s_mov_b32 s2, s67
	v_pk_add_f32 v[186:187], v[186:187], v[190:191]
	v_pk_mul_f32 v[190:191], v[54:55], s[2:3] op_sel_hi:[1,0]
	v_pk_mul_f32 v[194:195], v[192:193], 0.5 op_sel_hi:[1,0]
	v_pk_fma_f32 v[54:55], v[192:193], 0.5, v[190:191] op_sel_hi:[1,0,1]
	v_mov_b32_e32 v194, v187
	v_mov_b32_e32 v196, v1
	v_mov_b32_e32 v197, v191
	v_add_f32_e32 v188, 0, v8
	v_mov_b32_e32 v189, v185
	v_pk_mul_f32 v[192:193], v[54:55], v[54:55]
	v_pk_add_f32 v[194:195], v[194:195], v[196:197]
	v_mul_f32_e32 v0, 0x3fd744fd, v185
	v_mov_b32_e32 v163, v187
	v_pk_mov_b32 v[190:191], v[190:191], v[192:193] op_sel:[1,0]
	v_pk_add_f32 v[192:193], v[54:55], v[194:195]
	v_pk_mul_f32 v[194:195], v[54:55], v[194:195]
	v_pk_fma_f32 v[184:185], v[188:189], s[66:67], v[0:1] op_sel_hi:[1,1,0]
	v_pk_fma_f32 v[190:191], v[186:187], v[162:163], v[190:191]
	v_mov_b32_e32 v193, v195
	v_pk_mul_f32 v[188:189], v[184:185], v[184:185]
	v_pk_add_f32 v[190:191], v[192:193], v[190:191]
	v_mov_b32_e32 v185, v188
	v_pk_add_f32 v[188:189], v[190:191], v[184:185]
	s_nop 1
	v_mov_b32_dpp v190, v188 quad_perm:[1,0,3,2] row_mask:0xf bank_mask:0xf bound_ctrl:1
	v_mov_b32_dpp v191, v189 quad_perm:[1,0,3,2] row_mask:0xf bank_mask:0xf bound_ctrl:1
	v_pk_add_f32 v[188:189], v[188:189], v[190:191]
	s_nop 1
	v_mov_b32_dpp v190, v188 quad_perm:[2,3,0,1] row_mask:0xf bank_mask:0xf bound_ctrl:1
	v_mov_b32_dpp v191, v189 quad_perm:[2,3,0,1] row_mask:0xf bank_mask:0xf bound_ctrl:1
	v_pk_add_f32 v[188:189], v[188:189], v[190:191]
	s_nop 1
	v_mov_b32_dpp v190, v188 row_half_mirror row_mask:0xf bank_mask:0xf bound_ctrl:1
	v_mov_b32_dpp v191, v189 row_half_mirror row_mask:0xf bank_mask:0xf bound_ctrl:1
	v_pk_add_f32 v[188:189], v[188:189], v[190:191]
	s_nop 1
	v_mov_b32_dpp v190, v188 row_mirror row_mask:0xf bank_mask:0xf bound_ctrl:1
	v_mov_b32_dpp v191, v189 row_mirror row_mask:0xf bank_mask:0xf bound_ctrl:1
	s_and_saveexec_b64 s[6:7], vcc
	v_pk_add_f32 v[188:189], v[188:189], v[190:191]
	ds_write_b64 v160, v[188:189] offset:336
	s_or_b64 exec, exec, s[6:7]
	ds_read2_b32 v[188:189], v87 offset1:32
	ds_read2_b32 v[190:191], v87 offset0:64 offset1:96
	v_add_f32_e32 v0, 0, v57
	v_add_f32_e32 v56, 0, v9
	v_mul_f32_e32 v9, 0.5, v0
	s_waitcnt lgkmcnt(1)
	v_mul_f32_e32 v193, 0x3fd744fd, v188
	v_mov_b32_e32 v24, v41
	v_mov_b32_e32 v8, v25
	v_mov_b32_e32 v192, v1
	v_pk_add_f32 v[194:195], v[24:25], 0 op_sel_hi:[1,0]
	v_pk_add_f32 v[40:41], v[8:9], v[192:193]
	v_mov_b32_e32 v8, v189
	s_waitcnt lgkmcnt(0)
;   DI void operator()(f32x16 (&acc)[2][4], int grow0, int gcol0, int lane, int w, char* lds) {
;     ...
; #pragma unroll
;       for (int qq = 0; qq < 2; ++qq)
; #pragma unroll
;         for (int e = 0; e < 4; ++e) {
;           const int i = 4 * (2 * (ps & 1) + qq) + e;
;           const float* xr = (const float*)(xs + (8 * qq + 4 * hh + e) * 512) + l31;
;           float s1 = 0.f, s2 = 0.f;
; #pragma unroll
;           for (int nt = 0; nt < 4; ++nt) {
;             float v = (acc[mt][nt][i] + bia[nt]) * csc[nt];
;             float z = ALPHA * xr[nt * 32] + hs * v;
;             acc[mt][nt][i] = z; s1 += z; s2 += z * z;
;           }
;           s1 = row16_sum(s1); s2 = row16_sum(s2);
;           if ((lane & 15) == 0) { f32x2 sv = {s1, s2}; *(f32x2*)(redw + (mt * 32 + (i & 3) + 8 * (i >> 2)) * 2) = sv; }
;         }
	v_mov_b32_e32 v9, v190
	s_mov_b32 s2, s67
	v_pk_mul_f32 v[24:25], v[8:9], s[2:3] op_sel_hi:[1,0]
	v_pk_mul_f32 v[188:189], v[194:195], 0.5 op_sel_hi:[1,0]
	v_pk_fma_f32 v[8:9], v[194:195], 0.5, v[24:25] op_sel_hi:[1,0,1]
	v_mov_b32_e32 v188, v41
	v_mov_b32_e32 v194, v1
	v_mov_b32_e32 v195, v25
	v_pk_mul_f32 v[192:193], v[8:9], v[8:9]
	v_pk_add_f32 v[188:189], v[188:189], v[194:195]
	v_mov_b32_e32 v163, v41
	v_pk_mov_b32 v[24:25], v[24:25], v[192:193] op_sel:[1,0]
	v_pk_add_f32 v[192:193], v[8:9], v[188:189]
	v_pk_mul_f32 v[188:189], v[8:9], v[188:189]
	v_mov_b32_e32 v57, v191
	v_pk_fma_f32 v[24:25], v[40:41], v[162:163], v[24:25]
	v_mov_b32_e32 v193, v189
	v_mul_f32_e32 v0, 0x3fd744fd, v191
	v_pk_add_f32 v[188:189], v[192:193], v[24:25]
	v_pk_fma_f32 v[24:25], v[56:57], s[66:67], v[0:1] op_sel_hi:[1,1,0]
	s_nop 0
	v_pk_mul_f32 v[56:57], v[24:25], v[24:25]
	s_nop 0
	v_mov_b32_e32 v25, v56
	v_pk_add_f32 v[56:57], v[188:189], v[24:25]
	s_nop 1
	v_mov_b32_dpp v188, v56 quad_perm:[1,0,3,2] row_mask:0xf bank_mask:0xf bound_ctrl:1
	v_mov_b32_dpp v189, v57 quad_perm:[1,0,3,2] row_mask:0xf bank_mask:0xf bound_ctrl:1
	v_pk_add_f32 v[56:57], v[56:57], v[188:189]
	s_nop 1
	v_mov_b32_dpp v188, v56 quad_perm:[2,3,0,1] row_mask:0xf bank_mask:0xf bound_ctrl:1
	v_mov_b32_dpp v189, v57 quad_perm:[2,3,0,1] row_mask:0xf bank_mask:0xf bound_ctrl:1
	v_pk_add_f32 v[56:57], v[56:57], v[188:189]
	s_nop 1
	v_mov_b32_dpp v188, v56 row_half_mirror row_mask:0xf bank_mask:0xf bound_ctrl:1
	v_mov_b32_dpp v189, v57 row_half_mirror row_mask:0xf bank_mask:0xf bound_ctrl:1
	v_pk_add_f32 v[56:57], v[56:57], v[188:189]
	s_nop 1
	v_mov_b32_dpp v188, v56 row_mirror row_mask:0xf bank_mask:0xf bound_ctrl:1
	v_mov_b32_dpp v189, v57 row_mirror row_mask:0xf bank_mask:0xf bound_ctrl:1
	s_and_saveexec_b64 s[6:7], vcc
	v_pk_add_f32 v[56:57], v[56:57], v[188:189]
	ds_write_b64 v160, v[56:57] offset:344
	s_or_b64 exec, exec, s[6:7]
	s_waitcnt vmcnt(0)
	ds_read2_b32 v[56:57], v89 offset1:32
	ds_read2_b32 v[190:191], v89 offset0:64 offset1:96
	v_add_f32_e32 v0, 0, v58
	v_mul_f32_e32 v189, 0.5, v0
	v_mov_b32_e32 v188, v26
	s_waitcnt lgkmcnt(1)
	v_mul_f32_e32 v193, 0x3fd744fd, v56
	v_add_f32_e32 v56, 0, v42
	v_mul_f32_e32 v0, 0x3fd744fd, v57
	v_mov_b32_e32 v192, v1
	v_pk_fma_f32 v[56:57], v[56:57], s[66:67], v[0:1] op_sel_hi:[1,1,0]
	v_pk_add_f32 v[192:193], v[188:189], v[192:193]
	s_waitcnt lgkmcnt(0)
	v_mov_b32_e32 v188, v190
	v_mov_b32_e32 v189, v56
	v_mov_b32_e32 v196, v165
	v_mov_b32_e32 v197, v56
	v_mov_b32_e32 v163, v193
	v_pk_mul_f32 v[196:197], v[188:189], v[196:197]
	v_pk_mul_f32 v[198:199], v[192:193], v[162:163]
	v_mov_b32_e32 v200, v1
	v_pk_mov_b32 v[198:199], v[192:193], v[198:199] op_sel:[1,0]
	v_mov_b32_e32 v201, v196
	v_add_f32_e32 v194, 0, v10
	v_mov_b32_e32 v195, v191
	v_pk_fma_f32 v[188:189], v[192:193], v[162:163], v[196:197]
	v_pk_add_f32 v[196:197], v[198:199], v[200:201]
	v_mul_f32_e32 v0, 0x3fd744fd, v191
	v_pk_add_f32 v[198:199], v[56:57], v[196:197]
	v_pk_mul_f32 v[196:197], v[188:189], v[196:197] op_sel_hi:[0,1]
	v_pk_fma_f32 v[190:191], v[194:195], s[66:67], v[0:1] op_sel_hi:[1,1,0]
	v_mov_b32_e32 v199, v197
	v_pk_mul_f32 v[194:195], v[190:191], v[190:191]
	v_pk_add_f32 v[196:197], v[188:189], v[198:199]
	v_mov_b32_e32 v191, v194
	v_pk_add_f32 v[194:195], v[196:197], v[190:191]
	s_nop 1
	v_mov_b32_dpp v196, v194 quad_perm:[1,0,3,2] row_mask:0xf bank_mask:0xf bound_ctrl:1
	v_mov_b32_dpp v197, v195 quad_perm:[1,0,3,2] row_mask:0xf bank_mask:0xf bound_ctrl:1
	v_pk_add_f32 v[194:195], v[194:195], v[196:197]
	s_nop 1
	v_mov_b32_dpp v196, v194 quad_perm:[2,3,0,1] row_mask:0xf bank_mask:0xf bound_ctrl:1
	v_mov_b32_dpp v197, v195 quad_perm:[2,3,0,1] row_mask:0xf bank_mask:0xf bound_ctrl:1
	v_pk_add_f32 v[194:195], v[194:195], v[196:197]
	s_nop 1
	v_mov_b32_dpp v196, v194 row_half_mirror row_mask:0xf bank_mask:0xf bound_ctrl:1
	v_mov_b32_dpp v197, v195 row_half_mirror row_mask:0xf bank_mask:0xf bound_ctrl:1
	v_pk_add_f32 v[194:195], v[194:195], v[196:197]
	s_nop 1
	v_mov_b32_dpp v196, v194 row_mirror row_mask:0xf bank_mask:0xf bound_ctrl:1
	v_mov_b32_dpp v197, v195 row_mirror row_mask:0xf bank_mask:0xf bound_ctrl:1
	s_and_saveexec_b64 s[6:7], vcc
	v_pk_add_f32 v[194:195], v[194:195], v[196:197]
	ds_write_b64 v160, v[194:195] offset:384
	s_or_b64 exec, exec, s[6:7]
	ds_read2_b32 v[194:195], v98 offset1:32
	ds_read2_b32 v[196:197], v98 offset0:64 offset1:96
	v_add_f32_e32 v0, 0, v59
	v_add_f32_e32 v58, 0, v11
	v_mul_f32_e32 v11, 0.5, v0
	s_waitcnt lgkmcnt(1)
	v_mul_f32_e32 v199, 0x3fd744fd, v194
	v_mov_b32_e32 v26, v43
	v_mov_b32_e32 v10, v27
	v_mov_b32_e32 v198, v1
	v_pk_add_f32 v[200:201], v[26:27], 0 op_sel_hi:[1,0]
	v_pk_add_f32 v[42:43], v[10:11], v[198:199]
	v_mov_b32_e32 v10, v195
	s_waitcnt lgkmcnt(0)
;   DI void operator()(f32x16 (&acc)[2][4], int grow0, int gcol0, int lane, int w, char* lds) {
;     ...
; #pragma unroll
;       for (int qq = 0; qq < 2; ++qq)
; #pragma unroll
;         for (int e = 0; e < 4; ++e) {
;           const int i = 4 * (2 * (ps & 1) + qq) + e;
;           const float* xr = (const float*)(xs + (8 * qq + 4 * hh + e) * 512) + l31;
;           float s1 = 0.f, s2 = 0.f;
; #pragma unroll
;           for (int nt = 0; nt < 4; ++nt) {
;             float v = (acc[mt][nt][i] + bia[nt]) * csc[nt];
;             float z = ALPHA * xr[nt * 32] + hs * v;
;             acc[mt][nt][i] = z; s1 += z; s2 += z * z;
;           }
;           s1 = row16_sum(s1); s2 = row16_sum(s2);
;           if ((lane & 15) == 0) { f32x2 sv = {s1, s2}; *(f32x2*)(redw + (mt * 32 + (i & 3) + 8 * (i >> 2)) * 2) = sv; }
;         }
	v_mov_b32_e32 v11, v196
	s_mov_b32 s2, s67
	v_pk_mul_f32 v[26:27], v[10:11], s[2:3] op_sel_hi:[1,0]
	v_pk_mul_f32 v[194:195], v[200:201], 0.5 op_sel_hi:[1,0]
	v_pk_fma_f32 v[10:11], v[200:201], 0.5, v[26:27] op_sel_hi:[1,0,1]
	v_mov_b32_e32 v194, v43
	v_mov_b32_e32 v200, v1
	v_mov_b32_e32 v201, v27
	v_pk_mul_f32 v[198:199], v[10:11], v[10:11]
	v_pk_add_f32 v[194:195], v[194:195], v[200:201]
	v_mov_b32_e32 v163, v43
	v_pk_mov_b32 v[26:27], v[26:27], v[198:199] op_sel:[1,0]
	v_pk_add_f32 v[198:199], v[10:11], v[194:195]
	v_pk_mul_f32 v[194:195], v[10:11], v[194:195]
	v_mov_b32_e32 v59, v197
	v_pk_fma_f32 v[26:27], v[42:43], v[162:163], v[26:27]
	v_mov_b32_e32 v199, v195
	v_mul_f32_e32 v0, 0x3fd744fd, v197
	v_pk_add_f32 v[194:195], v[198:199], v[26:27]
	v_pk_fma_f32 v[26:27], v[58:59], s[66:67], v[0:1] op_sel_hi:[1,1,0]
	s_nop 0
	v_pk_mul_f32 v[58:59], v[26:27], v[26:27]
	s_nop 0
	v_mov_b32_e32 v27, v58
	v_pk_add_f32 v[58:59], v[194:195], v[26:27]
	s_nop 1
	v_mov_b32_dpp v194, v58 quad_perm:[1,0,3,2] row_mask:0xf bank_mask:0xf bound_ctrl:1
	v_mov_b32_dpp v195, v59 quad_perm:[1,0,3,2] row_mask:0xf bank_mask:0xf bound_ctrl:1
	v_pk_add_f32 v[58:59], v[58:59], v[194:195]
	s_nop 1
	v_mov_b32_dpp v194, v58 quad_perm:[2,3,0,1] row_mask:0xf bank_mask:0xf bound_ctrl:1
	v_mov_b32_dpp v195, v59 quad_perm:[2,3,0,1] row_mask:0xf bank_mask:0xf bound_ctrl:1
	v_pk_add_f32 v[58:59], v[58:59], v[194:195]
	s_nop 1
	v_mov_b32_dpp v194, v58 row_half_mirror row_mask:0xf bank_mask:0xf bound_ctrl:1
	v_mov_b32_dpp v195, v59 row_half_mirror row_mask:0xf bank_mask:0xf bound_ctrl:1
	v_pk_add_f32 v[58:59], v[58:59], v[194:195]
	s_nop 1
	v_mov_b32_dpp v194, v58 row_mirror row_mask:0xf bank_mask:0xf bound_ctrl:1
	v_mov_b32_dpp v195, v59 row_mirror row_mask:0xf bank_mask:0xf bound_ctrl:1
	s_and_saveexec_b64 s[6:7], vcc
	v_pk_add_f32 v[58:59], v[58:59], v[194:195]
	ds_write_b64 v160, v[58:59] offset:392
	s_or_b64 exec, exec, s[6:7]
	ds_read2_b32 v[58:59], v102 offset1:32
	ds_read2_b32 v[194:195], v102 offset0:64 offset1:96
	v_add_f32_e32 v0, 0, v60
	v_mov_b32_e32 v202, v44
	v_mov_b32_e32 v203, v28
	v_mul_f32_e32 v197, 0.5, v0
	s_waitcnt lgkmcnt(1)
	v_mul_f32_e32 v201, 0x3fd744fd, v58
	v_pk_add_f32 v[202:203], v[202:203], 0 op_sel_hi:[1,0]
	v_mov_b32_e32 v196, v28
	v_mov_b32_e32 v200, v1
	v_mov_b32_e32 v58, v59
	s_waitcnt lgkmcnt(0)
	v_mov_b32_e32 v59, v194
	s_mov_b32 s2, s67
	v_pk_add_f32 v[196:197], v[196:197], v[200:201]
	v_pk_mul_f32 v[200:201], v[58:59], s[2:3] op_sel_hi:[1,0]
	v_pk_mul_f32 v[204:205], v[202:203], 0.5 op_sel_hi:[1,0]
	v_pk_fma_f32 v[58:59], v[202:203], 0.5, v[200:201] op_sel_hi:[1,0,1]
	v_mov_b32_e32 v204, v197
	v_mov_b32_e32 v206, v1
	v_mov_b32_e32 v207, v201
	v_add_f32_e32 v198, 0, v12
	v_mov_b32_e32 v199, v195
	v_pk_mul_f32 v[202:203], v[58:59], v[58:59]
	v_pk_add_f32 v[204:205], v[204:205], v[206:207]
	v_mul_f32_e32 v0, 0x3fd744fd, v195
	v_mov_b32_e32 v163, v197
	v_pk_mov_b32 v[200:201], v[200:201], v[202:203] op_sel:[1,0]
	v_pk_add_f32 v[202:203], v[58:59], v[204:205]
	v_pk_mul_f32 v[204:205], v[58:59], v[204:205]
	v_pk_fma_f32 v[194:195], v[198:199], s[66:67], v[0:1] op_sel_hi:[1,1,0]
	v_pk_fma_f32 v[200:201], v[196:197], v[162:163], v[200:201]
	v_mov_b32_e32 v203, v205
	v_pk_mul_f32 v[198:199], v[194:195], v[194:195]
	v_pk_add_f32 v[200:201], v[202:203], v[200:201]
	v_mov_b32_e32 v195, v198
	v_pk_add_f32 v[198:199], v[200:201], v[194:195]
	s_nop 1
	v_mov_b32_dpp v200, v198 quad_perm:[1,0,3,2] row_mask:0xf bank_mask:0xf bound_ctrl:1
	v_mov_b32_dpp v201, v199 quad_perm:[1,0,3,2] row_mask:0xf bank_mask:0xf bound_ctrl:1
	v_pk_add_f32 v[198:199], v[198:199], v[200:201]
	s_nop 1
	v_mov_b32_dpp v200, v198 quad_perm:[2,3,0,1] row_mask:0xf bank_mask:0xf bound_ctrl:1
	v_mov_b32_dpp v201, v199 quad_perm:[2,3,0,1] row_mask:0xf bank_mask:0xf bound_ctrl:1
	v_pk_add_f32 v[198:199], v[198:199], v[200:201]
	s_nop 1
	v_mov_b32_dpp v200, v198 row_half_mirror row_mask:0xf bank_mask:0xf bound_ctrl:1
	v_mov_b32_dpp v201, v199 row_half_mirror row_mask:0xf bank_mask:0xf bound_ctrl:1
	v_pk_add_f32 v[198:199], v[198:199], v[200:201]
	s_nop 1
	v_mov_b32_dpp v200, v198 row_mirror row_mask:0xf bank_mask:0xf bound_ctrl:1
	v_mov_b32_dpp v201, v199 row_mirror row_mask:0xf bank_mask:0xf bound_ctrl:1
	s_and_saveexec_b64 s[6:7], vcc
	v_pk_add_f32 v[198:199], v[198:199], v[200:201]
	ds_write_b64 v160, v[198:199] offset:400
	s_or_b64 exec, exec, s[6:7]
	ds_read2_b32 v[198:199], v104 offset1:32
	ds_read2_b32 v[200:201], v104 offset0:64 offset1:96
	v_add_f32_e32 v0, 0, v61
	v_add_f32_e32 v60, 0, v13
	v_mul_f32_e32 v13, 0.5, v0
	s_waitcnt lgkmcnt(1)
	v_mul_f32_e32 v203, 0x3fd744fd, v198
	v_mov_b32_e32 v28, v45
	v_mov_b32_e32 v12, v29
	v_mov_b32_e32 v202, v1
	v_pk_add_f32 v[204:205], v[28:29], 0 op_sel_hi:[1,0]
	v_pk_add_f32 v[44:45], v[12:13], v[202:203]
	v_mov_b32_e32 v12, v199
	s_waitcnt lgkmcnt(0)
;   DI void operator()(f32x16 (&acc)[2][4], int grow0, int gcol0, int lane, int w, char* lds) {
;     ...
; #pragma unroll
;       for (int qq = 0; qq < 2; ++qq)
; #pragma unroll
;         for (int e = 0; e < 4; ++e) {
;           const int i = 4 * (2 * (ps & 1) + qq) + e;
;           const float* xr = (const float*)(xs + (8 * qq + 4 * hh + e) * 512) + l31;
;           float s1 = 0.f, s2 = 0.f;
; #pragma unroll
;           for (int nt = 0; nt < 4; ++nt) {
;             float v = (acc[mt][nt][i] + bia[nt]) * csc[nt];
;             float z = ALPHA * xr[nt * 32] + hs * v;
;             acc[mt][nt][i] = z; s1 += z; s2 += z * z;
;           }
;           s1 = row16_sum(s1); s2 = row16_sum(s2);
;           if ((lane & 15) == 0) { f32x2 sv = {s1, s2}; *(f32x2*)(redw + (mt * 32 + (i & 3) + 8 * (i >> 2)) * 2) = sv; }
;         }
	v_mov_b32_e32 v13, v200
	s_mov_b32 s2, s67
	v_pk_mul_f32 v[28:29], v[12:13], s[2:3] op_sel_hi:[1,0]
	v_pk_mul_f32 v[198:199], v[204:205], 0.5 op_sel_hi:[1,0]
	v_pk_fma_f32 v[12:13], v[204:205], 0.5, v[28:29] op_sel_hi:[1,0,1]
	v_mov_b32_e32 v198, v45
	v_mov_b32_e32 v204, v1
	v_mov_b32_e32 v205, v29
	v_pk_mul_f32 v[202:203], v[12:13], v[12:13]
	v_pk_add_f32 v[198:199], v[198:199], v[204:205]
	v_mov_b32_e32 v163, v45
	v_pk_mov_b32 v[28:29], v[28:29], v[202:203] op_sel:[1,0]
	v_pk_add_f32 v[202:203], v[12:13], v[198:199]
	v_pk_mul_f32 v[198:199], v[12:13], v[198:199]
	v_mov_b32_e32 v61, v201
	v_pk_fma_f32 v[28:29], v[44:45], v[162:163], v[28:29]
	v_mov_b32_e32 v203, v199
	v_mul_f32_e32 v0, 0x3fd744fd, v201
	v_pk_add_f32 v[198:199], v[202:203], v[28:29]
	v_pk_fma_f32 v[28:29], v[60:61], s[66:67], v[0:1] op_sel_hi:[1,1,0]
	s_nop 0
	v_pk_mul_f32 v[60:61], v[28:29], v[28:29]
	s_nop 0
	v_mov_b32_e32 v29, v60
	v_pk_add_f32 v[60:61], v[198:199], v[28:29]
	s_nop 1
	v_mov_b32_dpp v198, v60 quad_perm:[1,0,3,2] row_mask:0xf bank_mask:0xf bound_ctrl:1
	v_mov_b32_dpp v199, v61 quad_perm:[1,0,3,2] row_mask:0xf bank_mask:0xf bound_ctrl:1
	v_pk_add_f32 v[60:61], v[60:61], v[198:199]
	s_nop 1
	v_mov_b32_dpp v198, v60 quad_perm:[2,3,0,1] row_mask:0xf bank_mask:0xf bound_ctrl:1
	v_mov_b32_dpp v199, v61 quad_perm:[2,3,0,1] row_mask:0xf bank_mask:0xf bound_ctrl:1
	v_pk_add_f32 v[60:61], v[60:61], v[198:199]
	s_nop 1
	v_mov_b32_dpp v198, v60 row_half_mirror row_mask:0xf bank_mask:0xf bound_ctrl:1
	v_mov_b32_dpp v199, v61 row_half_mirror row_mask:0xf bank_mask:0xf bound_ctrl:1
	v_pk_add_f32 v[60:61], v[60:61], v[198:199]
	s_nop 1
	v_mov_b32_dpp v198, v60 row_mirror row_mask:0xf bank_mask:0xf bound_ctrl:1
	v_mov_b32_dpp v199, v61 row_mirror row_mask:0xf bank_mask:0xf bound_ctrl:1
	s_and_saveexec_b64 s[6:7], vcc
	v_pk_add_f32 v[60:61], v[60:61], v[198:199]
	ds_write_b64 v160, v[60:61] offset:408
	s_or_b64 exec, exec, s[6:7]
	ds_read2_b32 v[60:61], v93 offset1:32
	ds_read2_b32 v[198:199], v93 offset0:64 offset1:96
	v_add_f32_e32 v0, 0, v62
	v_mov_b32_e32 v206, v46
	v_mov_b32_e32 v207, v30
	v_mul_f32_e32 v201, 0.5, v0
	s_waitcnt lgkmcnt(1)
	v_mul_f32_e32 v205, 0x3fd744fd, v60
	v_pk_add_f32 v[206:207], v[206:207], 0 op_sel_hi:[1,0]
	v_mov_b32_e32 v200, v30
	v_mov_b32_e32 v204, v1
	v_mov_b32_e32 v60, v61
	s_waitcnt lgkmcnt(0)
	v_mov_b32_e32 v61, v198
	s_mov_b32 s2, s67
	v_pk_add_f32 v[200:201], v[200:201], v[204:205]
	v_pk_mul_f32 v[204:205], v[60:61], s[2:3] op_sel_hi:[1,0]
	v_pk_mul_f32 v[208:209], v[206:207], 0.5 op_sel_hi:[1,0]
	v_pk_fma_f32 v[60:61], v[206:207], 0.5, v[204:205] op_sel_hi:[1,0,1]
	v_mov_b32_e32 v208, v201
	v_mov_b32_e32 v212, v1
	v_mov_b32_e32 v213, v205
	v_add_f32_e32 v202, 0, v14
	v_mov_b32_e32 v203, v199
	v_pk_mul_f32 v[206:207], v[60:61], v[60:61]
	v_pk_add_f32 v[208:209], v[208:209], v[212:213]
	v_mul_f32_e32 v0, 0x3fd744fd, v199
	v_mov_b32_e32 v163, v201
	v_pk_mov_b32 v[204:205], v[204:205], v[206:207] op_sel:[1,0]
	v_pk_add_f32 v[206:207], v[60:61], v[208:209]
	v_pk_mul_f32 v[208:209], v[60:61], v[208:209]
	v_pk_fma_f32 v[198:199], v[202:203], s[66:67], v[0:1] op_sel_hi:[1,1,0]
	v_pk_fma_f32 v[204:205], v[200:201], v[162:163], v[204:205]
	v_mov_b32_e32 v207, v209
	v_pk_mul_f32 v[202:203], v[198:199], v[198:199]
	v_pk_add_f32 v[204:205], v[206:207], v[204:205]
	v_mov_b32_e32 v199, v202
	v_pk_add_f32 v[202:203], v[204:205], v[198:199]
	s_nop 1
	v_mov_b32_dpp v204, v202 quad_perm:[1,0,3,2] row_mask:0xf bank_mask:0xf bound_ctrl:1
	v_mov_b32_dpp v205, v203 quad_perm:[1,0,3,2] row_mask:0xf bank_mask:0xf bound_ctrl:1
	v_pk_add_f32 v[202:203], v[202:203], v[204:205]
	s_nop 1
	v_mov_b32_dpp v204, v202 quad_perm:[2,3,0,1] row_mask:0xf bank_mask:0xf bound_ctrl:1
	v_mov_b32_dpp v205, v203 quad_perm:[2,3,0,1] row_mask:0xf bank_mask:0xf bound_ctrl:1
	v_pk_add_f32 v[202:203], v[202:203], v[204:205]
	s_nop 1
	v_mov_b32_dpp v204, v202 row_half_mirror row_mask:0xf bank_mask:0xf bound_ctrl:1
	v_mov_b32_dpp v205, v203 row_half_mirror row_mask:0xf bank_mask:0xf bound_ctrl:1
	v_pk_add_f32 v[202:203], v[202:203], v[204:205]
	s_nop 1
	v_mov_b32_dpp v204, v202 row_mirror row_mask:0xf bank_mask:0xf bound_ctrl:1
	v_mov_b32_dpp v205, v203 row_mirror row_mask:0xf bank_mask:0xf bound_ctrl:1
	s_and_saveexec_b64 s[6:7], vcc
	v_pk_add_f32 v[202:203], v[202:203], v[204:205]
	ds_write_b64 v160, v[202:203] offset:448
	s_or_b64 exec, exec, s[6:7]
	ds_read2_b32 v[202:203], v106 offset1:32
	ds_read2_b32 v[204:205], v106 offset0:64 offset1:96
	v_add_f32_e32 v0, 0, v63
	v_add_f32_e32 v62, 0, v15
	v_mul_f32_e32 v15, 0.5, v0
	s_waitcnt lgkmcnt(1)
	v_mul_f32_e32 v207, 0x3fd744fd, v202
	v_mov_b32_e32 v30, v47
	v_mov_b32_e32 v14, v31
	v_mov_b32_e32 v206, v1
	v_pk_add_f32 v[208:209], v[30:31], 0 op_sel_hi:[1,0]
	v_pk_add_f32 v[46:47], v[14:15], v[206:207]
	v_mov_b32_e32 v14, v203
	s_waitcnt lgkmcnt(0)
;   DI void operator()(f32x16 (&acc)[2][4], int grow0, int gcol0, int lane, int w, char* lds) {
;     ...
; #pragma unroll
;       for (int qq = 0; qq < 2; ++qq)
; #pragma unroll
;         for (int e = 0; e < 4; ++e) {
;           const int i = 4 * (2 * (ps & 1) + qq) + e;
;           const float* xr = (const float*)(xs + (8 * qq + 4 * hh + e) * 512) + l31;
;           float s1 = 0.f, s2 = 0.f;
; #pragma unroll
;           for (int nt = 0; nt < 4; ++nt) {
;             float v = (acc[mt][nt][i] + bia[nt]) * csc[nt];
;             float z = ALPHA * xr[nt * 32] + hs * v;
;             acc[mt][nt][i] = z; s1 += z; s2 += z * z;
;           }
;           s1 = row16_sum(s1); s2 = row16_sum(s2);
;           if ((lane & 15) == 0) { f32x2 sv = {s1, s2}; *(f32x2*)(redw + (mt * 32 + (i & 3) + 8 * (i >> 2)) * 2) = sv; }
;         }
;     }
;     __syncthreads();
;     u64_t* myslots = xstat + ((size_t)pm * 256) * 4;
	v_mov_b32_e32 v15, v204
	s_mov_b32 s2, s67
	v_pk_mul_f32 v[30:31], v[14:15], s[2:3] op_sel_hi:[1,0]
	v_pk_mul_f32 v[202:203], v[208:209], 0.5 op_sel_hi:[1,0]
	v_pk_fma_f32 v[14:15], v[208:209], 0.5, v[30:31] op_sel_hi:[1,0,1]
	v_mov_b32_e32 v202, v47
	v_mov_b32_e32 v208, v1
	v_mov_b32_e32 v209, v31
	v_pk_mul_f32 v[206:207], v[14:15], v[14:15]
	v_pk_add_f32 v[202:203], v[202:203], v[208:209]
	v_mov_b32_e32 v163, v47
	v_pk_mov_b32 v[30:31], v[30:31], v[206:207] op_sel:[1,0]
	v_pk_add_f32 v[206:207], v[14:15], v[202:203]
	v_pk_mul_f32 v[202:203], v[14:15], v[202:203]
	v_mov_b32_e32 v63, v205
	v_pk_fma_f32 v[30:31], v[46:47], v[162:163], v[30:31]
	v_mov_b32_e32 v207, v203
	v_mul_f32_e32 v0, 0x3fd744fd, v205
	v_pk_add_f32 v[202:203], v[206:207], v[30:31]
	v_pk_fma_f32 v[30:31], v[62:63], s[66:67], v[0:1] op_sel_hi:[1,1,0]
	s_nop 0
	v_pk_mul_f32 v[62:63], v[30:31], v[30:31]
	s_nop 0
	v_mov_b32_e32 v31, v62
	v_pk_add_f32 v[62:63], v[202:203], v[30:31]
	s_nop 1
	v_mov_b32_dpp v202, v62 quad_perm:[1,0,3,2] row_mask:0xf bank_mask:0xf bound_ctrl:1
	v_mov_b32_dpp v203, v63 quad_perm:[1,0,3,2] row_mask:0xf bank_mask:0xf bound_ctrl:1
	v_pk_add_f32 v[62:63], v[62:63], v[202:203]
	s_nop 1
	v_mov_b32_dpp v202, v62 quad_perm:[2,3,0,1] row_mask:0xf bank_mask:0xf bound_ctrl:1
	v_mov_b32_dpp v203, v63 quad_perm:[2,3,0,1] row_mask:0xf bank_mask:0xf bound_ctrl:1
	v_pk_add_f32 v[62:63], v[62:63], v[202:203]
	s_nop 1
	v_mov_b32_dpp v202, v62 row_half_mirror row_mask:0xf bank_mask:0xf bound_ctrl:1
	v_mov_b32_dpp v203, v63 row_half_mirror row_mask:0xf bank_mask:0xf bound_ctrl:1
	v_pk_add_f32 v[62:63], v[62:63], v[202:203]
	s_nop 1
	v_mov_b32_dpp v202, v62 row_mirror row_mask:0xf bank_mask:0xf bound_ctrl:1
	v_mov_b32_dpp v203, v63 row_mirror row_mask:0xf bank_mask:0xf bound_ctrl:1
	s_and_saveexec_b64 s[6:7], vcc
	v_pk_add_f32 v[62:63], v[62:63], v[202:203]
	ds_write_b64 v160, v[62:63] offset:456
	s_or_b64 exec, exec, s[6:7]
	ds_read2_b32 v[62:63], v95 offset1:32
	ds_read2_b32 v[202:203], v95 offset0:64 offset1:96
	v_add_f32_e32 v0, 0, v64
	v_mov_b32_e32 v212, v48
	v_mov_b32_e32 v213, v32
	v_mul_f32_e32 v205, 0.5, v0
	s_waitcnt lgkmcnt(1)
	v_mul_f32_e32 v209, 0x3fd744fd, v62
	v_pk_add_f32 v[212:213], v[212:213], 0 op_sel_hi:[1,0]
	v_mov_b32_e32 v204, v32
	v_mov_b32_e32 v208, v1
	v_mov_b32_e32 v62, v63
	s_waitcnt lgkmcnt(0)
	v_mov_b32_e32 v63, v202
	s_mov_b32 s2, s67
	v_pk_add_f32 v[204:205], v[204:205], v[208:209]
	v_pk_mul_f32 v[208:209], v[62:63], s[2:3] op_sel_hi:[1,0]
	v_pk_mul_f32 v[214:215], v[212:213], 0.5 op_sel_hi:[1,0]
	v_pk_fma_f32 v[62:63], v[212:213], 0.5, v[208:209] op_sel_hi:[1,0,1]
	v_mov_b32_e32 v214, v205
	v_mov_b32_e32 v226, v1
	v_mov_b32_e32 v227, v209
	v_add_f32_e32 v206, 0, v16
	v_mov_b32_e32 v207, v203
	v_pk_mul_f32 v[212:213], v[62:63], v[62:63]
	v_pk_add_f32 v[214:215], v[214:215], v[226:227]
	v_mul_f32_e32 v0, 0x3fd744fd, v203
	v_mov_b32_e32 v163, v205
	v_pk_mov_b32 v[208:209], v[208:209], v[212:213] op_sel:[1,0]
	v_pk_add_f32 v[212:213], v[62:63], v[214:215]
	v_pk_mul_f32 v[214:215], v[62:63], v[214:215]
	v_pk_fma_f32 v[202:203], v[206:207], s[66:67], v[0:1] op_sel_hi:[1,1,0]
	v_pk_fma_f32 v[208:209], v[204:205], v[162:163], v[208:209]
	v_mov_b32_e32 v213, v215
	v_pk_mul_f32 v[206:207], v[202:203], v[202:203]
	v_pk_add_f32 v[208:209], v[212:213], v[208:209]
	v_mov_b32_e32 v203, v206
	v_pk_add_f32 v[206:207], v[208:209], v[202:203]
	s_nop 1
	v_mov_b32_dpp v208, v206 quad_perm:[1,0,3,2] row_mask:0xf bank_mask:0xf bound_ctrl:1
	v_mov_b32_dpp v209, v207 quad_perm:[1,0,3,2] row_mask:0xf bank_mask:0xf bound_ctrl:1
	v_pk_add_f32 v[206:207], v[206:207], v[208:209]
	s_nop 1
	v_mov_b32_dpp v208, v206 quad_perm:[2,3,0,1] row_mask:0xf bank_mask:0xf bound_ctrl:1
	v_mov_b32_dpp v209, v207 quad_perm:[2,3,0,1] row_mask:0xf bank_mask:0xf bound_ctrl:1
	v_pk_add_f32 v[206:207], v[206:207], v[208:209]
	s_nop 1
	v_mov_b32_dpp v208, v206 row_half_mirror row_mask:0xf bank_mask:0xf bound_ctrl:1
	v_mov_b32_dpp v209, v207 row_half_mirror row_mask:0xf bank_mask:0xf bound_ctrl:1
	v_pk_add_f32 v[206:207], v[206:207], v[208:209]
	s_nop 1
	v_mov_b32_dpp v208, v206 row_mirror row_mask:0xf bank_mask:0xf bound_ctrl:1
	v_mov_b32_dpp v209, v207 row_mirror row_mask:0xf bank_mask:0xf bound_ctrl:1
	s_and_saveexec_b64 s[6:7], vcc
	v_pk_add_f32 v[206:207], v[206:207], v[208:209]
	ds_write_b64 v160, v[206:207] offset:464
	s_or_b64 exec, exec, s[6:7]
	v_add_f32_e32 v0, 0, v65
	ds_read2_b32 v[64:65], v91 offset1:32
	ds_read2_b32 v[212:213], v91 offset0:64 offset1:96
	v_mov_b32_e32 v32, v49
	v_mul_f32_e32 v209, 0.5, v0
	v_add_f32_e32 v214, 0, v17
	s_waitcnt lgkmcnt(1)
	v_mul_f32_e32 v207, 0x3fd744fd, v64
	v_pk_add_f32 v[16:17], v[32:33], 0 op_sel_hi:[1,0]
	v_mov_b32_e32 v208, v33
	v_mov_b32_e32 v206, v1
	v_mov_b32_e32 v32, v65
	s_waitcnt lgkmcnt(0)
	v_mov_b32_e32 v33, v212
	s_mov_b32 s2, s67
	v_pk_add_f32 v[48:49], v[208:209], v[206:207]
	v_pk_mul_f32 v[32:33], v[32:33], s[2:3] op_sel_hi:[1,0]
	v_pk_mul_f32 v[64:65], v[16:17], 0.5 op_sel_hi:[1,0]
	v_pk_fma_f32 v[16:17], v[16:17], 0.5, v[32:33] op_sel_hi:[1,0,1]
	v_mov_b32_e32 v64, v49
	v_mov_b32_e32 v208, v1
	v_mov_b32_e32 v209, v33
	v_pk_mul_f32 v[206:207], v[16:17], v[16:17]
	v_pk_add_f32 v[64:65], v[64:65], v[208:209]
	v_mov_b32_e32 v163, v49
	v_pk_mov_b32 v[32:33], v[32:33], v[206:207] op_sel:[1,0]
	v_pk_add_f32 v[206:207], v[16:17], v[64:65]
	v_pk_mul_f32 v[64:65], v[16:17], v[64:65]
	v_mov_b32_e32 v215, v213
	v_pk_fma_f32 v[32:33], v[48:49], v[162:163], v[32:33]
	v_mov_b32_e32 v207, v65
	v_mul_f32_e32 v0, 0x3fd744fd, v213
	v_pk_add_f32 v[64:65], v[206:207], v[32:33]
	v_pk_fma_f32 v[32:33], v[214:215], s[66:67], v[0:1] op_sel_hi:[1,1,0]
	s_nop 0
	v_pk_mul_f32 v[206:207], v[32:33], v[32:33]
	s_nop 0
	v_mov_b32_e32 v33, v206
	v_pk_add_f32 v[64:65], v[64:65], v[32:33]
	s_nop 1
	v_mov_b32_dpp v206, v64 quad_perm:[1,0,3,2] row_mask:0xf bank_mask:0xf bound_ctrl:1
	v_mov_b32_dpp v207, v65 quad_perm:[1,0,3,2] row_mask:0xf bank_mask:0xf bound_ctrl:1
	v_pk_add_f32 v[64:65], v[64:65], v[206:207]
	s_nop 1
	v_mov_b32_dpp v206, v64 quad_perm:[2,3,0,1] row_mask:0xf bank_mask:0xf bound_ctrl:1
	v_mov_b32_dpp v207, v65 quad_perm:[2,3,0,1] row_mask:0xf bank_mask:0xf bound_ctrl:1
	v_pk_add_f32 v[64:65], v[64:65], v[206:207]
	s_nop 1
	v_mov_b32_dpp v206, v64 row_half_mirror row_mask:0xf bank_mask:0xf bound_ctrl:1
	v_mov_b32_dpp v207, v65 row_half_mirror row_mask:0xf bank_mask:0xf bound_ctrl:1
	v_pk_add_f32 v[64:65], v[64:65], v[206:207]
	s_nop 1
	v_mov_b32_dpp v206, v64 row_mirror row_mask:0xf bank_mask:0xf bound_ctrl:1
	v_mov_b32_dpp v207, v65 row_mirror row_mask:0xf bank_mask:0xf bound_ctrl:1
	s_and_saveexec_b64 s[6:7], vcc
	v_pk_add_f32 v[64:65], v[64:65], v[206:207]
	ds_write_b64 v160, v[64:65] offset:472
	s_or_b64 exec, exec, s[6:7]
	v_ashrrev_i32_e32 v206, 8, v164
	v_ashrrev_i32_e32 v207, 31, v206
	v_lshlrev_b64 v[64:65], 13, v[206:207]
	v_lshl_add_u64 v[64:65], s[8:9], 0, v[64:65]
	v_cmp_gt_i32_e64 s[40:41], s60, v210
	v_ashrrev_i32_e32 v169, 31, v168
	s_waitcnt lgkmcnt(0)
	s_barrier
; DI void ag_st64(u64_t* p, u64_t v) { __hip_atomic_store(p, v, __ATOMIC_RELAXED, __HIP_MEMORY_SCOPE_AGENT); }
;   DI void operator()(f32x16 (&acc)[2][4], int grow0, int gcol0, int lane, int w, char* lds) {
;     ...
;     if (tid < 256) {
;       float s1 = (red[tid * 2] + red[(256 + tid) * 2]) + (red[(512 + tid) * 2] + red[(768 + tid) * 2]);
;       float s2 = (red[tid * 2 + 1] + red[(256 + tid) * 2 + 1]) + (red[(512 + tid) * 2 + 1] + red[(768 + tid) * 2 + 1]);
;       ag_st64(myslots + tid * 4 + pn, ((u64_t)__float_as_uint(s2) << 32) | (u64_t)__float_as_uint(s1));
	s_and_saveexec_b64 s[6:7], s[40:41]
	s_cbranch_execz .LBB0_359
	v_lshl_add_u32 v0, v210, 3, v221
	ds_read2st64_b64 v[212:215], v0 offset1:4
	ds_read2st64_b64 v[226:229], v0 offset0:8 offset1:12
	v_ashrrev_i32_e32 v208, 8, v154
	v_ashrrev_i32_e32 v209, 31, v208
	s_waitcnt lgkmcnt(1)
	v_mov_b32_e32 v230, v212
	s_waitcnt lgkmcnt(0)
	v_mov_b32_e32 v231, v226
	v_mov_b32_e32 v232, v214
	v_mov_b32_e32 v233, v228
	v_mov_b32_e32 v226, v213
	v_mov_b32_e32 v228, v215
	v_pk_add_f32 v[230:231], v[230:231], v[232:233]
	v_pk_add_f32 v[212:213], v[226:227], v[228:229]
	v_pk_add_f32 v[230:231], v[230:231], v[230:231] op_sel:[0,1] op_sel_hi:[1,0]
	v_pk_add_f32 v[212:213], v[212:213], v[212:213] op_sel:[0,1] op_sel_hi:[1,0]
	v_lshl_add_u64 v[214:215], v[168:169], 3, v[64:65]
	v_lshl_add_u64 v[208:209], v[208:209], 3, v[214:215]
	v_mov_b32_e32 v231, v212
	global_store_dwordx2 v[208:209], v[230:231], off sc1

; DI f32x16 mfma(bf16x8 a, bf16x8 b, f32x16 c) { return __builtin_amdgcn_mfma_f32_32x32x16_bf16(a, b, c, 0, 0, 0); }
; template <int BK> DI int swz(int row) { constexpr int CPR = BK / 8; return (row / (16 / CPR)) % CPR; }
;   DI void pre(int grow0, int gcol0, int lane, int w, char* lds) { xpass(0, grow0, gcol0, lane, w, lds); }
;     ...
;   for (int kt = 0; kt < nk; ++kt) {
;     char* cur = lds + (kt & 1) * STG; char* nxt = lds + ((kt + 1) & 1) * STG;
;     const bool more = kt + 1 < nk;
;     const bf16_t* An = Ag + (kt + 1) * BK; const bf16_t* Bn = Bg + (kt + 1) * BK;
;     if (!more) epi.pre(row0 + wm * 64, col0 + wn * (32 * NTW), lane, w, lds);
;     bf16x8 fa[2][2], fb[2][NTW];
; #pragma unroll
;     for (int mt = 0; mt < 2; ++mt) { int row = wm * 64 + mt * 32 + l31; fa[0][mt] = *(const bf16x8*)(cur + row * (BK * 2) + ((hh ^ swz<BK>(row)) << 4)); }
; #pragma unroll
;     for (int nt = 0; nt < NTW; ++nt) { int row = wn * (32 * NTW) + nt * 32 + l31; fb[0][nt] = *(const bf16x8*)(cur + ABYTES + row * (BK * 2) + ((hh ^ swz<BK>(row)) << 4)); }
; #pragma unroll
;     for (int kk = 0; kk < NKK; ++kk) {
;       if (kk + 1 < NKK) {
;         const int ch = (kk + 1) * 2 + hh;
; #pragma unroll
;         for (int mt = 0; mt < 2; ++mt) { int row = wm * 64 + mt * 32 + l31; fa[(kk + 1) & 1][mt] = *(const bf16x8*)(cur + row * (BK * 2) + ((ch ^ swz<BK>(row)) << 4)); }
; #pragma unroll
;         for (int nt = 0; nt < NTW; ++nt) { int row = wn * (32 * NTW) + nt * 32 + l31; fb[(kk + 1) & 1][nt] = *(const bf16x8*)(cur + ABYTES + row * (BK * 2) + ((ch ^ swz<BK>(row)) << 4)); }
;       }
;       if (more) {
; #pragma unroll
;         for (int q = 0; q < PPK; ++q) {
;           const int pi = kk * PPK + q;
;           if (pi < NPA) stage_piece<BM, BK>(An, lda, nxt, tid, pi, wv);
;           else if (pi < NP) stage_piece<BN, BK>(Bn, ldb, nxt + ABYTES, tid, pi - NPA, wv);
;         }
;       }
;       __builtin_amdgcn_s_setprio(1);
; #pragma unroll
;       for (int mt = 0; mt < 2; ++mt)
; #pragma unroll
;         for (int nt = 0; nt < NTW; ++nt) acc[mt][nt] = mfma(fa[kk & 1][mt], fb[kk & 1][nt], acc[mt][nt]);
;       __builtin_amdgcn_s_setprio(0);
;       __builtin_amdgcn_sched_barrier(0);
;     }
.LBB0_382:
	s_and_b32 s42, s7, 0x10000
	s_xor_b32 s100, s42, 0x10000
	v_add3_u32 v190, s100, v140, v161
	v_add3_u32 v194, s100, v142, v163
	ds_read_b128 v[190:193], v190
	v_add3_u32 v198, s100, v143, v159
	ds_read_b128 v[194:197], v194
	v_add3_u32 v202, s100, v152, v160
	ds_read_b128 v[198:201], v198 offset:32768
	v_add3_u32 v206, s100, v153, v157
	ds_read_b128 v[202:205], v202 offset:32768
	v_add3_u32 v210, s100, v156, v158
	ds_read_b128 v[206:209], v206 offset:32768
	ds_read_b128 v[210:213], v210 offset:32768
	s_waitcnt lgkmcnt(6)
	s_mov_b32 m0, s37
	v_lshl_add_u64 v[228:229], v[214:215], 0, s[28:29]
	v_mfma_f32_32x32x16_bf16 v[114:129], v[166:169], v[174:177], v[114:129]
	global_load_lds_dwordx4 v[228:229], off
	s_add_i32 m0, s37, 0x2000
	v_lshl_add_u64 v[228:229], v[214:215], 0, s[24:25]
	v_mfma_f32_32x32x16_bf16 v[98:113], v[166:169], v[178:181], v[98:113]
	v_mfma_f32_32x32x16_bf16 v[82:97], v[166:169], v[182:185], v[82:97]
	global_load_lds_dwordx4 v[228:229], off
	s_add_i32 m0, s37, 0x4000
	v_lshl_add_u64 v[228:229], v[214:215], 0, s[26:27]
	v_mfma_f32_32x32x16_bf16 v[66:81], v[166:169], v[186:189], v[66:81]
	v_mfma_f32_32x32x16_bf16 v[50:65], v[170:173], v[174:177], v[50:65]
	global_load_lds_dwordx4 v[228:229], off
	s_add_i32 m0, s37, 0x6000
	v_lshl_add_u64 v[228:229], v[214:215], 0, s[38:39]
	v_mfma_f32_32x32x16_bf16 v[34:49], v[170:173], v[178:181], v[34:49]
	v_mfma_f32_32x32x16_bf16 v[18:33], v[170:173], v[182:185], v[18:33]
	global_load_lds_dwordx4 v[228:229], off
	v_mfma_f32_32x32x16_bf16 v[2:17], v[170:173], v[186:189], v[2:17]
	v_add3_u32 v166, s100, v140, v149
	v_add3_u32 v170, s100, v142, v150
	ds_read_b128 v[166:169], v166
	v_add3_u32 v174, s100, v143, v147
	ds_read_b128 v[170:173], v170
	v_add3_u32 v178, s100, v152, v148
	ds_read_b128 v[174:177], v174 offset:32768
	v_add3_u32 v182, s100, v153, v145
	ds_read_b128 v[178:181], v178 offset:32768
	v_add3_u32 v186, s100, v156, v146
	ds_read_b128 v[182:185], v182 offset:32768
	ds_read_b128 v[186:189], v186 offset:32768
	s_waitcnt lgkmcnt(6)
	v_mfma_f32_32x32x16_bf16 v[114:129], v[190:193], v[198:201], v[114:129]
	v_mfma_f32_32x32x16_bf16 v[98:113], v[190:193], v[202:205], v[98:113]
	v_mfma_f32_32x32x16_bf16 v[82:97], v[190:193], v[206:209], v[82:97]
	v_mfma_f32_32x32x16_bf16 v[66:81], v[190:193], v[210:213], v[66:81]
	v_mfma_f32_32x32x16_bf16 v[50:65], v[194:197], v[198:201], v[50:65]
	v_mfma_f32_32x32x16_bf16 v[34:49], v[194:197], v[202:205], v[34:49]
	v_mfma_f32_32x32x16_bf16 v[18:33], v[194:197], v[206:209], v[18:33]
	v_mfma_f32_32x32x16_bf16 v[2:17], v[194:197], v[210:213], v[2:17]
	v_add3_u32 v190, s100, v140, v138
	v_add3_u32 v194, s100, v142, v139
	ds_read_b128 v[190:193], v190
	v_add3_u32 v198, s100, v143, v136
	ds_read_b128 v[194:197], v194
	v_add3_u32 v202, s100, v152, v137
	ds_read_b128 v[198:201], v198 offset:32768
	v_add3_u32 v206, s100, v153, v134
	ds_read_b128 v[202:205], v202 offset:32768
	v_add3_u32 v210, s100, v156, v135
	ds_read_b128 v[206:209], v206 offset:32768
	ds_read_b128 v[210:213], v210 offset:32768
	s_waitcnt lgkmcnt(6)
	v_mfma_f32_32x32x16_bf16 v[114:129], v[166:169], v[174:177], v[114:129]
	v_mfma_f32_32x32x16_bf16 v[98:113], v[166:169], v[178:181], v[98:113]
	v_mfma_f32_32x32x16_bf16 v[82:97], v[166:169], v[182:185], v[82:97]
	v_mfma_f32_32x32x16_bf16 v[66:81], v[166:169], v[186:189], v[66:81]
	v_mfma_f32_32x32x16_bf16 v[50:65], v[170:173], v[174:177], v[50:65]
	v_mfma_f32_32x32x16_bf16 v[34:49], v[170:173], v[178:181], v[34:49]
	v_mfma_f32_32x32x16_bf16 v[18:33], v[170:173], v[182:185], v[18:33]
	v_mfma_f32_32x32x16_bf16 v[2:17], v[170:173], v[186:189], v[2:17]
	s_add_u32 s30, s30, 0x80
	s_addc_u32 s31, s31, 0
	s_add_i32 s7, s7, 0x10000
	s_waitcnt vmcnt(0) lgkmcnt(0)
	s_barrier
	s_cmpk_eq_i32 s30, 0x780
	s_cbranch_scc1 .Lk382_exit
	s_add_i32 s37, s100, s3
	v_lshl_add_u64 v[214:215], v[130:131], 0, s[30:31]
	v_lshl_add_u64 v[226:227], v[132:133], 0, s[30:31]
	s_add_i32 m0, s37, 0x8000
	v_lshl_add_u64 v[228:229], v[226:227], 0, s[28:29]
	v_mfma_f32_32x32x16_bf16 v[114:129], v[190:193], v[198:201], v[114:129]
	global_load_lds_dwordx4 v[228:229], off
	v_add3_u32 v166, s42, v140, v141
	v_add3_u32 v170, s42, v142, v144
	ds_read_b128 v[166:169], v166
	v_add3_u32 v174, s42, v143, v151
	ds_read_b128 v[170:173], v170
	v_add3_u32 v178, s42, v152, v154
	ds_read_b128 v[174:177], v174 offset:32768
	v_add3_u32 v182, s42, v153, v155
	ds_read_b128 v[178:181], v178 offset:32768
	v_add3_u32 v186, s42, v156, v164
	ds_read_b128 v[182:185], v182 offset:32768
	ds_read_b128 v[186:189], v186 offset:32768
	s_add_i32 m0, s37, 0xa000
	v_lshl_add_u64 v[228:229], v[226:227], 0, s[24:25]
	v_mfma_f32_32x32x16_bf16 v[98:113], v[190:193], v[202:205], v[98:113]
	v_mfma_f32_32x32x16_bf16 v[82:97], v[190:193], v[206:209], v[82:97]
	global_load_lds_dwordx4 v[228:229], off
	s_add_i32 m0, s37, 0xc000
	v_lshl_add_u64 v[228:229], v[226:227], 0, s[26:27]
	v_mfma_f32_32x32x16_bf16 v[66:81], v[190:193], v[210:213], v[66:81]
	v_mfma_f32_32x32x16_bf16 v[50:65], v[194:197], v[198:201], v[50:65]
	global_load_lds_dwordx4 v[228:229], off
	s_add_i32 m0, s37, 0xe000
	v_lshl_add_u64 v[228:229], v[226:227], 0, s[38:39]
	v_mfma_f32_32x32x16_bf16 v[34:49], v[194:197], v[202:205], v[34:49]
	v_mfma_f32_32x32x16_bf16 v[18:33], v[194:197], v[206:209], v[18:33]
	global_load_lds_dwordx4 v[228:229], off
	v_mfma_f32_32x32x16_bf16 v[2:17], v[194:197], v[210:213], v[2:17]
	s_branch .LBB0_382
; DI f32x16 mfma(bf16x8 a, bf16x8 b, f32x16 c) { return __builtin_amdgcn_mfma_f32_32x32x16_bf16(a, b, c, 0, 0, 0); }
; template <int BK> DI int swz(int row) { constexpr int CPR = BK / 8; return (row / (16 / CPR)) % CPR; }
; DI void wait_vm0() { asm volatile("s_waitcnt vmcnt(0)" ::: "memory"); }
;   DI void pre(int grow0, int gcol0, int lane, int w, char* lds) { xpass(0, grow0, gcol0, lane, w, lds); }
;     ...
;   for (int kt = 0; kt < nk; ++kt) {
;     char* cur = lds + (kt & 1) * STG; char* nxt = lds + ((kt + 1) & 1) * STG;
;     const bool more = kt + 1 < nk;
;     const bf16_t* An = Ag + (kt + 1) * BK; const bf16_t* Bn = Bg + (kt + 1) * BK;
;     if (!more) epi.pre(row0 + wm * 64, col0 + wn * (32 * NTW), lane, w, lds);
;     bf16x8 fa[2][2], fb[2][NTW];
; #pragma unroll
;     for (int mt = 0; mt < 2; ++mt) { int row = wm * 64 + mt * 32 + l31; fa[0][mt] = *(const bf16x8*)(cur + row * (BK * 2) + ((hh ^ swz<BK>(row)) << 4)); }
; #pragma unroll
;     for (int nt = 0; nt < NTW; ++nt) { int row = wn * (32 * NTW) + nt * 32 + l31; fb[0][nt] = *(const bf16x8*)(cur + ABYTES + row * (BK * 2) + ((hh ^ swz<BK>(row)) << 4)); }
; #pragma unroll
;     for (int kk = 0; kk < NKK; ++kk) {
;       if (kk + 1 < NKK) {
;         const int ch = (kk + 1) * 2 + hh;
; #pragma unroll
;         for (int mt = 0; mt < 2; ++mt) { int row = wm * 64 + mt * 32 + l31; fa[(kk + 1) & 1][mt] = *(const bf16x8*)(cur + row * (BK * 2) + ((ch ^ swz<BK>(row)) << 4)); }
; #pragma unroll
;         for (int nt = 0; nt < NTW; ++nt) { int row = wn * (32 * NTW) + nt * 32 + l31; fb[(kk + 1) & 1][nt] = *(const bf16x8*)(cur + ABYTES + row * (BK * 2) + ((ch ^ swz<BK>(row)) << 4)); }
;       }
;       if (more) {
; #pragma unroll
;         for (int q = 0; q < PPK; ++q) {
;           const int pi = kk * PPK + q;
;           if (pi < NPA) stage_piece<BM, BK>(An, lda, nxt, tid, pi, wv);
;           else if (pi < NP) stage_piece<BN, BK>(Bn, ldb, nxt + ABYTES, tid, pi - NPA, wv);
;         }
;       }
;       __builtin_amdgcn_s_setprio(1);
; #pragma unroll
;       for (int mt = 0; mt < 2; ++mt)
; #pragma unroll
;         for (int nt = 0; nt < NTW; ++nt) acc[mt][nt] = mfma(fa[kk & 1][mt], fb[kk & 1][nt], acc[mt][nt]);
;       __builtin_amdgcn_s_setprio(0);
;       __builtin_amdgcn_sched_barrier(0);
;     }
;     wait_vm0();
;     __syncthreads();
;   }
.Lk382_exit:
	v_add3_u32 v166, s42, v140, v141
	v_add3_u32 v170, s42, v142, v144
	ds_read_b128 v[166:169], v166
	v_add3_u32 v174, s42, v143, v151
	ds_read_b128 v[170:173], v170
	v_add3_u32 v178, s42, v152, v154
	ds_read_b128 v[174:177], v174 offset:32768
	v_add3_u32 v182, s42, v153, v155
	ds_read_b128 v[178:181], v178 offset:32768
	v_add3_u32 v186, s42, v156, v164
	ds_read_b128 v[182:185], v182 offset:32768
	ds_read_b128 v[186:189], v186 offset:32768
	v_mfma_f32_32x32x16_bf16 v[114:129], v[190:193], v[198:201], v[114:129]
	v_mfma_f32_32x32x16_bf16 v[98:113], v[190:193], v[202:205], v[98:113]
	v_mfma_f32_32x32x16_bf16 v[82:97], v[190:193], v[206:209], v[82:97]
	v_mfma_f32_32x32x16_bf16 v[66:81], v[190:193], v[210:213], v[66:81]
	v_mfma_f32_32x32x16_bf16 v[50:65], v[194:197], v[198:201], v[50:65]
	v_mfma_f32_32x32x16_bf16 v[34:49], v[194:197], v[202:205], v[34:49]
	v_mfma_f32_32x32x16_bf16 v[18:33], v[194:197], v[206:209], v[18:33]
	v_mfma_f32_32x32x16_bf16 v[2:17], v[194:197], v[210:213], v[2:17]
	s_waitcnt lgkmcnt(0)
	v_add_u32_e32 v0, 0x10000, v140
	v_add_u32_e32 v198, 0x10000, v142
	v_add_u32_e32 v130, v0, v141
	v_add_u32_e32 v140, v198, v144
	v_add_u32_e32 v199, 0x18000, v143
	v_add_u32_e32 v200, 0x18000, v152
	ds_read_b128 v[130:133], v130
	ds_read_b128 v[166:169], v140
	v_add_u32_e32 v140, v199, v151
	v_add_u32_e32 v144, v200, v154
	v_add_u32_e32 v201, 0x18000, v153
	ds_read_b128 v[140:143], v140
	ds_read_b128 v[170:173], v144
	v_add_u32_e32 v144, v201, v155
	v_add_u32_e32 v202, 0x18000, v156
	v_add_u32_e32 v151, v202, v164
	ds_read_b128 v[152:155], v144
	ds_read_b128 v[174:177], v151
	v_add_u32_e32 v144, v0, v161
	v_add_u32_e32 v151, v198, v163
	ds_read_b128 v[178:181], v144
	ds_read_b128 v[182:185], v151
	v_add_u32_e32 v144, v199, v159
	v_add_u32_e32 v151, v200, v160
	ds_read_b128 v[186:189], v144
	ds_read_b128 v[190:193], v151
	v_add_u32_e32 v144, v201, v157
	v_add_u32_e32 v151, v202, v158
	ds_read_b128 v[156:159], v144
	ds_read_b128 v[194:197], v151
	s_add_i32 s36, s36, s94
	s_cmpk_gt_i32 s36, 0x4ff
	s_cselect_b64 s[42:43], -1, 0
	s_cmpk_lt_i32 s36, 0x500
	s_setprio 1
	s_waitcnt lgkmcnt(9)
	v_mfma_f32_32x32x16_bf16 v[114:129], v[130:133], v[140:143], v[114:129]
	s_waitcnt lgkmcnt(8)
	v_mfma_f32_32x32x16_bf16 v[98:113], v[130:133], v[170:173], v[98:113]
	s_waitcnt lgkmcnt(7)
	v_mfma_f32_32x32x16_bf16 v[82:97], v[130:133], v[152:155], v[82:97]
	s_waitcnt lgkmcnt(6)
	v_mfma_f32_32x32x16_bf16 v[66:81], v[130:133], v[174:177], v[66:81]
	v_mfma_f32_32x32x16_bf16 v[50:65], v[166:169], v[140:143], v[50:65]
	v_mfma_f32_32x32x16_bf16 v[34:49], v[166:169], v[170:173], v[34:49]
	v_mfma_f32_32x32x16_bf16 v[18:33], v[166:169], v[152:155], v[18:33]
	v_mfma_f32_32x32x16_bf16 v[2:17], v[166:169], v[174:177], v[2:17]
	s_setprio 0
	v_add_u32_e32 v130, v0, v149
	v_add_u32_e32 v140, v198, v150
	v_add_u32_e32 v144, v199, v147
	ds_read_b128 v[130:133], v130
	ds_read_b128 v[140:143], v140
	v_add_u32_e32 v147, v200, v148
	ds_read_b128 v[148:151], v144
	ds_read_b128 v[152:155], v147
	v_add_u32_e32 v144, v201, v145
	v_add_u32_e32 v160, v202, v146
	ds_read_b128 v[144:147], v144
	ds_read_b128 v[166:169], v160
	s_setprio 1
	s_waitcnt lgkmcnt(9)
	v_mfma_f32_32x32x16_bf16 v[114:129], v[178:181], v[186:189], v[114:129]
	s_waitcnt lgkmcnt(8)
	v_mfma_f32_32x32x16_bf16 v[98:113], v[178:181], v[190:193], v[98:113]
	s_waitcnt lgkmcnt(7)
	v_mfma_f32_32x32x16_bf16 v[82:97], v[178:181], v[156:159], v[82:97]
	s_waitcnt lgkmcnt(6)
	v_mfma_f32_32x32x16_bf16 v[66:81], v[178:181], v[194:197], v[66:81]
	v_mfma_f32_32x32x16_bf16 v[50:65], v[182:185], v[186:189], v[50:65]
	v_mfma_f32_32x32x16_bf16 v[34:49], v[182:185], v[190:193], v[34:49]
	v_mfma_f32_32x32x16_bf16 v[18:33], v[182:185], v[156:159], v[18:33]
	v_mfma_f32_32x32x16_bf16 v[2:17], v[182:185], v[194:197], v[2:17]
	s_setprio 0
	v_add_u32_e32 v0, v0, v138
	v_add_u32_e32 v138, v198, v139
	ds_read_b128 v[156:159], v0
	ds_read_b128 v[170:173], v138
	v_add_u32_e32 v0, v199, v136
	v_add_u32_e32 v160, v200, v137
	ds_read_b128 v[136:139], v0
	ds_read_b128 v[174:177], v160
	v_add_u32_e32 v0, v201, v134
	v_add_u32_e32 v134, v202, v135
	ds_read_b128 v[178:181], v0
	ds_read_b128 v[182:185], v134
	s_setprio 1
	s_waitcnt lgkmcnt(9)
	v_mfma_f32_32x32x16_bf16 v[114:129], v[130:133], v[148:151], v[114:129]
	s_waitcnt lgkmcnt(8)
	v_mfma_f32_32x32x16_bf16 v[98:113], v[130:133], v[152:155], v[98:113]
	s_waitcnt lgkmcnt(7)
	v_mfma_f32_32x32x16_bf16 v[82:97], v[130:133], v[144:147], v[82:97]
	s_waitcnt lgkmcnt(6)
	v_mfma_f32_32x32x16_bf16 v[66:81], v[130:133], v[166:169], v[66:81]
	v_mfma_f32_32x32x16_bf16 v[50:65], v[140:143], v[148:151], v[50:65]
	v_mfma_f32_32x32x16_bf16 v[34:49], v[140:143], v[152:155], v[34:49]
	v_mfma_f32_32x32x16_bf16 v[18:33], v[140:143], v[144:147], v[18:33]
	v_mfma_f32_32x32x16_bf16 v[2:17], v[140:143], v[166:169], v[2:17]
	s_setprio 0
	s_setprio 1
	s_waitcnt lgkmcnt(3)
	v_mfma_f32_32x32x16_bf16 v[114:129], v[156:159], v[136:139], v[114:129]
	s_waitcnt lgkmcnt(2)
	v_mfma_f32_32x32x16_bf16 v[98:113], v[156:159], v[174:177], v[98:113]
	s_waitcnt lgkmcnt(1)
	v_mfma_f32_32x32x16_bf16 v[82:97], v[156:159], v[178:181], v[82:97]
	s_waitcnt lgkmcnt(0)
	v_mfma_f32_32x32x16_bf16 v[66:81], v[156:159], v[182:185], v[66:81]
	v_mfma_f32_32x32x16_bf16 v[50:65], v[170:173], v[136:139], v[50:65]
	v_mfma_f32_32x32x16_bf16 v[34:49], v[170:173], v[174:177], v[34:49]
	v_mfma_f32_32x32x16_bf16 v[18:33], v[170:173], v[178:181], v[18:33]
	v_mfma_f32_32x32x16_bf16 v[2:17], v[170:173], v[182:185], v[2:17]
	s_setprio 0
	s_waitcnt vmcnt(0)
	s_barrier
; DI int launder(int x) { asm volatile("" : "+v"(x)); return x; }
;   DI void pre(int grow0, int gcol0, int lane, int w, char* lds) { xpass(0, grow0, gcol0, lane, w, lds); }
;     ...
;   if (has_next) { const int tid3 = launder(threadIdx.x); stage_tile<BM, BK>(A + (size_t)row0n * lda, lda, lds, tid3); stage_tile<BN, BK>(Bt + (size_t)col0n * ldb, ldb, lds + ABYTES, tid3); }
; template <class Epi>
; DI void gemm_phase256(const bf16_t* A, int lda, const bf16_t* Bt, int K, int nN, char* lds, Epi& epi, int vb) {
;     ...
;     const int x = t & 7, L = t >> 3; const int pm = 8 * x + (L & 7), pn = L >> 3;
;     const int t2 = t + gridDim.x; const bool hn = t2 < ntiles;
;     const int x2 = t2 & 7, L2 = t2 >> 3; const int pm2 = 8 * x2 + (L2 & 7), pn2 = L2 >> 3;
;     gemm_tile<4, 64>(A, lda, Bt, K, K, pm * 256, pn * 256, lds, epi, pre, hn, pm2 * 256, pn2 * 256);
	s_cbranch_scc0 .LBB0_378
	v_mov_b32_e32 v132, v216
	s_lshl_b32 s3, s36, 3
	v_ashrrev_i32_e32 v0, 31, v132
	v_lshrrev_b32_e32 v130, 29, v0
	v_lshrrev_b32_e32 v0, 28, v0
	v_add_u32_e32 v0, v132, v0
	v_ashrrev_i32_e32 v0, 4, v0
	s_and_b32 s3, s3, 56
	s_bfe_u32 s7, s36, 0x30003
	v_lshrrev_b32_e32 v133, 29, v0
	s_or_b32 s3, s3, s7
	s_lshl_b32 s7, s36, 2
	v_add_u32_e32 v130, v132, v130
	v_add_u32_e32 v133, v0, v133
	s_and_b32 s30, s7, 0xffffff00
	s_lshl_b32 s3, s3, 19
	v_and_b32_e32 v131, 0xffffff8, v130
	v_and_b32_e32 v133, 0xffffff8, v133
	s_add_u32 s44, s12, s3
	v_sub_u32_e32 v131, v132, v131
	v_sub_u32_e32 v0, v0, v133
	v_lshlrev_b32_e32 v130, 8, v130
	v_readfirstlane_b32 s3, v132
	s_addc_u32 s45, s13, 0
	v_xor_b32_e32 v0, v0, v131
	v_and_b32_e32 v130, 0xfffff800, v130
	s_lshl_b32 s3, s3, 4
	v_lshl_add_u32 v0, v0, 4, v130
	s_and_b32 s3, s3, 0xfffffc00
	v_lshl_add_u64 v[130:131], s[44:45], 0, v[0:1]
	s_mov_b32 m0, s3
	v_lshl_add_u64 v[132:133], v[130:131], 0, s[58:59]
	global_load_lds_dwordx4 v0, s[44:45]
	s_add_i32 m0, s3, 0x2000
	s_ashr_i32 s31, s30, 31
	global_load_lds_dwordx4 v[132:133], off
	v_lshl_add_u64 v[132:133], v[130:131], 0, s[48:49]
	s_add_i32 m0, s3, 0x4000
	s_lshl_b64 s[30:31], s[30:31], 11
	global_load_lds_dwordx4 v[132:133], off
	s_add_i32 m0, s3, 0x6000
	s_add_u32 s30, s40, s30
	v_lshl_add_u64 v[130:131], v[130:131], 0, s[50:51]
	s_addc_u32 s31, s41, s31
	global_load_lds_dwordx4 v[130:131], off
	v_lshl_add_u64 v[130:131], s[30:31], 0, v[0:1]
	s_add_i32 m0, s3, 0x8000
	v_lshl_add_u64 v[132:133], v[130:131], 0, s[58:59]
	global_load_lds_dwordx4 v0, s[30:31]
	s_add_i32 m0, s3, 0xa000
	s_nop 0
	global_load_lds_dwordx4 v[132:133], off
	v_lshl_add_u64 v[132:133], v[130:131], 0, s[48:49]
	s_add_i32 m0, s3, 0xc000
	v_lshl_add_u64 v[130:131], v[130:131], 0, s[50:51]
	global_load_lds_dwordx4 v[132:133], off
	s_add_i32 m0, s3, 0xe000
	s_nop 0
	global_load_lds_dwordx4 v[130:131], off
	s_branch .LBB0_378

; DI f32x16 mfma(bf16x8 a, bf16x8 b, f32x16 c) { return __builtin_amdgcn_mfma_f32_32x32x16_bf16(a, b, c, 0, 0, 0); }
; template <int BK> DI int swz(int row) { constexpr int CPR = BK / 8; return (row / (16 / CPR)) % CPR; }
;   DI void pre(int grow0, int gcol0, int lane, int w, char* lds) { xpass(0, grow0, gcol0, lane, w, lds); }
;     ...
;   for (int kt = 0; kt < nk; ++kt) {
;     char* cur = lds + (kt & 1) * STG; char* nxt = lds + ((kt + 1) & 1) * STG;
;     const bool more = kt + 1 < nk;
;     const bf16_t* An = Ag + (kt + 1) * BK; const bf16_t* Bn = Bg + (kt + 1) * BK;
;     if (!more) epi.pre(row0 + wm * 64, col0 + wn * (32 * NTW), lane, w, lds);
;     bf16x8 fa[2][2], fb[2][NTW];
; #pragma unroll
;     for (int mt = 0; mt < 2; ++mt) { int row = wm * 64 + mt * 32 + l31; fa[0][mt] = *(const bf16x8*)(cur + row * (BK * 2) + ((hh ^ swz<BK>(row)) << 4)); }
; #pragma unroll
;     for (int nt = 0; nt < NTW; ++nt) { int row = wn * (32 * NTW) + nt * 32 + l31; fb[0][nt] = *(const bf16x8*)(cur + ABYTES + row * (BK * 2) + ((hh ^ swz<BK>(row)) << 4)); }
; #pragma unroll
;     for (int kk = 0; kk < NKK; ++kk) {
;       if (kk + 1 < NKK) {
;         const int ch = (kk + 1) * 2 + hh;
; #pragma unroll
;         for (int mt = 0; mt < 2; ++mt) { int row = wm * 64 + mt * 32 + l31; fa[(kk + 1) & 1][mt] = *(const bf16x8*)(cur + row * (BK * 2) + ((ch ^ swz<BK>(row)) << 4)); }
; #pragma unroll
;         for (int nt = 0; nt < NTW; ++nt) { int row = wn * (32 * NTW) + nt * 32 + l31; fb[(kk + 1) & 1][nt] = *(const bf16x8*)(cur + ABYTES + row * (BK * 2) + ((ch ^ swz<BK>(row)) << 4)); }
;       }
;       if (more) {
; #pragma unroll
;         for (int q = 0; q < PPK; ++q) {
;           const int pi = kk * PPK + q;
;           if (pi < NPA) stage_piece<BM, BK>(An, lda, nxt, tid, pi, wv);
;           else if (pi < NP) stage_piece<BN, BK>(Bn, ldb, nxt + ABYTES, tid, pi - NPA, wv);
;         }
;       }
;       __builtin_amdgcn_s_setprio(1);
; #pragma unroll
;       for (int mt = 0; mt < 2; ++mt)
; #pragma unroll
;         for (int nt = 0; nt < NTW; ++nt) acc[mt][nt] = mfma(fa[kk & 1][mt], fb[kk & 1][nt], acc[mt][nt]);
;       __builtin_amdgcn_s_setprio(0);
;       __builtin_amdgcn_sched_barrier(0);
;     }
.LBB0_388:
	s_bitcmp1_b32 s3, 0
	s_cselect_b32 s100, 0, 0xc000
	s_cselect_b32 s42, 0xc000, 0
	v_add3_u32 v106, s100, v70, v87
	v_add3_u32 v110, s100, v71, v88
	ds_read_b128 v[106:109], v106
	v_add3_u32 v114, s100, v77, v85
	ds_read_b128 v[110:113], v110
	v_add3_u32 v118, s100, v84, v86
	ds_read_b128 v[114:117], v114 offset:32768
	ds_read_b128 v[118:121], v118 offset:32768
	s_waitcnt lgkmcnt(4)
	s_mov_b32 m0, s37
	v_lshl_add_u64 v[126:127], v[122:123], 0, s[28:29]
	v_mfma_f32_32x32x16_bf16 v[50:65], v[90:93], v[98:101], v[50:65]
	global_load_lds_dwordx4 v[126:127], off
	s_add_i32 m0, s37, 0x2000
	v_lshl_add_u64 v[126:127], v[122:123], 0, s[24:25]
	v_mfma_f32_32x32x16_bf16 v[34:49], v[90:93], v[102:105], v[34:49]
	global_load_lds_dwordx4 v[126:127], off
	s_add_i32 m0, s37, 0x4000
	v_lshl_add_u64 v[126:127], v[122:123], 0, s[26:27]
	v_mfma_f32_32x32x16_bf16 v[18:33], v[94:97], v[98:101], v[18:33]
	global_load_lds_dwordx4 v[126:127], off
	v_mfma_f32_32x32x16_bf16 v[2:17], v[94:97], v[102:105], v[2:17]
	v_add3_u32 v90, s100, v70, v81
	v_add3_u32 v94, s100, v71, v82
	ds_read_b128 v[90:93], v90
	v_add3_u32 v98, s100, v77, v78
	ds_read_b128 v[94:97], v94
	v_add3_u32 v102, s100, v84, v79
	ds_read_b128 v[98:101], v98 offset:32768
	ds_read_b128 v[102:105], v102 offset:32768
	s_waitcnt lgkmcnt(4)
	v_mfma_f32_32x32x16_bf16 v[50:65], v[106:109], v[114:117], v[50:65]
	v_mfma_f32_32x32x16_bf16 v[34:49], v[106:109], v[118:121], v[34:49]
	v_mfma_f32_32x32x16_bf16 v[18:33], v[110:113], v[114:117], v[18:33]
	v_mfma_f32_32x32x16_bf16 v[2:17], v[110:113], v[118:121], v[2:17]
	v_add3_u32 v106, s100, v70, v74
	v_add3_u32 v110, s100, v71, v75
	ds_read_b128 v[106:109], v106
	v_add3_u32 v114, s100, v77, v72
	ds_read_b128 v[110:113], v110
	v_add3_u32 v118, s100, v84, v73
	ds_read_b128 v[114:117], v114 offset:32768
	ds_read_b128 v[118:121], v118 offset:32768
	s_waitcnt lgkmcnt(4)
	v_mfma_f32_32x32x16_bf16 v[50:65], v[90:93], v[98:101], v[50:65]
	v_mfma_f32_32x32x16_bf16 v[34:49], v[90:93], v[102:105], v[34:49]
	v_mfma_f32_32x32x16_bf16 v[18:33], v[94:97], v[98:101], v[18:33]
	v_mfma_f32_32x32x16_bf16 v[2:17], v[94:97], v[102:105], v[2:17]
	s_add_u32 s30, s30, 0x80
	s_addc_u32 s31, s31, 0
	s_add_i32 s3, s3, 1
	s_waitcnt vmcnt(0) lgkmcnt(0)
	s_barrier
	s_cmpk_lg_i32 s30, 0x780
	s_cbranch_scc0 .Lk388_exit
	s_add_i32 s37, s7, s100
	v_lshl_add_u64 v[122:123], v[66:67], 0, s[30:31]
	v_lshl_add_u64 v[124:125], v[68:69], 0, s[30:31]
	s_add_i32 m0, s37, 0x6000
	v_lshl_add_u64 v[126:127], v[122:123], 0, s[38:39]
	v_mfma_f32_32x32x16_bf16 v[50:65], v[106:109], v[114:117], v[50:65]
	global_load_lds_dwordx4 v[126:127], off
	v_add3_u32 v90, s42, v70, v76
	v_add3_u32 v94, s42, v71, v80
	ds_read_b128 v[90:93], v90
	v_add3_u32 v98, s42, v77, v83
	ds_read_b128 v[94:97], v94
	v_add3_u32 v102, s42, v84, v89
	ds_read_b128 v[98:101], v98 offset:32768
	ds_read_b128 v[102:105], v102 offset:32768
	s_add_i32 m0, s37, 0x8000
	v_lshl_add_u64 v[126:127], v[124:125], 0, s[28:29]
	v_mfma_f32_32x32x16_bf16 v[34:49], v[106:109], v[118:121], v[34:49]
	global_load_lds_dwordx4 v[126:127], off
	s_add_i32 m0, s37, 0xa000
	v_lshl_add_u64 v[126:127], v[124:125], 0, s[24:25]
	v_mfma_f32_32x32x16_bf16 v[18:33], v[110:113], v[114:117], v[18:33]
	global_load_lds_dwordx4 v[126:127], off
	v_mfma_f32_32x32x16_bf16 v[2:17], v[110:113], v[118:121], v[2:17]
	s_branch .LBB0_388
.Lk388_exit:
	v_add3_u32 v90, s42, v70, v76
	v_add3_u32 v94, s42, v71, v80
	ds_read_b128 v[90:93], v90
	v_add3_u32 v98, s42, v77, v83
	ds_read_b128 v[94:97], v94
	v_add3_u32 v102, s42, v84, v89
	ds_read_b128 v[98:101], v98 offset:32768
	ds_read_b128 v[102:105], v102 offset:32768
	v_mfma_f32_32x32x16_bf16 v[50:65], v[106:109], v[114:117], v[50:65]
	v_mfma_f32_32x32x16_bf16 v[34:49], v[106:109], v[118:121], v[34:49]
	v_mfma_f32_32x32x16_bf16 v[18:33], v[110:113], v[114:117], v[18:33]
	v_mfma_f32_32x32x16_bf16 v[2:17], v[110:113], v[118:121], v[2:17]
	s_waitcnt lgkmcnt(0)
	v_add_u32_e32 v0, v70, v76
	v_add_u32_e32 v76, v71, v80
	ds_read_b128 v[66:69], v0 offset:49152
	ds_read_b128 v[90:93], v76 offset:49152
	v_add_u32_e32 v0, 0x14000, v77
	v_add_u32_e32 v76, v0, v83
	v_add_u32_e32 v114, 0x14000, v84
	v_add_u32_e32 v77, v114, v89
	ds_read_b128 v[94:97], v76
	ds_read_b128 v[98:101], v77
	v_add_u32_e32 v76, v70, v87
	v_add_u32_e32 v77, v71, v88
	ds_read_b128 v[102:105], v76 offset:49152
	ds_read_b128 v[106:109], v77 offset:49152
	v_add_u32_e32 v76, v0, v85
	v_add_u32_e32 v77, v114, v86
	ds_read_b128 v[84:87], v76
	ds_read_b128 v[110:113], v77
	s_lshl_b32 s2, s2, 8
	s_setprio 1
	s_waitcnt lgkmcnt(5)
	v_mfma_f32_32x32x16_bf16 v[50:65], v[66:69], v[94:97], v[50:65]
	s_waitcnt lgkmcnt(4)
	v_mfma_f32_32x32x16_bf16 v[34:49], v[66:69], v[98:101], v[34:49]
	v_mfma_f32_32x32x16_bf16 v[18:33], v[90:93], v[94:97], v[18:33]
	v_mfma_f32_32x32x16_bf16 v[2:17], v[90:93], v[98:101], v[2:17]
	s_setprio 0
	v_add_u32_e32 v66, v70, v81
	v_add_u32_e32 v76, v71, v82
	ds_read_b128 v[66:69], v66 offset:49152
	ds_read_b128 v[80:83], v76 offset:49152
	v_add_u32_e32 v76, v0, v78
	v_add_u32_e32 v88, v114, v79
	ds_read_b128 v[76:79], v76
	ds_read_b128 v[88:91], v88
	s_setprio 1
	s_waitcnt lgkmcnt(5)
	v_mfma_f32_32x32x16_bf16 v[50:65], v[102:105], v[84:87], v[50:65]
	s_waitcnt lgkmcnt(4)
	v_mfma_f32_32x32x16_bf16 v[34:49], v[102:105], v[110:113], v[34:49]
	v_mfma_f32_32x32x16_bf16 v[18:33], v[106:109], v[84:87], v[18:33]
	v_mfma_f32_32x32x16_bf16 v[2:17], v[106:109], v[110:113], v[2:17]
	s_setprio 0
	v_add_u32_e32 v70, v70, v74
	v_add_u32_e32 v71, v71, v75
	v_add_u32_e32 v0, v0, v72
	ds_read_b128 v[84:87], v70 offset:49152
	ds_read_b128 v[92:95], v71 offset:49152
	v_add_u32_e32 v74, v114, v73
	ds_read_b128 v[70:73], v0
	ds_read_b128 v[96:99], v74
	s_setprio 1
	s_waitcnt lgkmcnt(5)
	v_mfma_f32_32x32x16_bf16 v[50:65], v[66:69], v[76:79], v[50:65]
	s_waitcnt lgkmcnt(4)
	v_mfma_f32_32x32x16_bf16 v[34:49], v[66:69], v[88:91], v[34:49]
	v_mfma_f32_32x32x16_bf16 v[18:33], v[80:83], v[76:79], v[18:33]
	v_mfma_f32_32x32x16_bf16 v[2:17], v[80:83], v[88:91], v[2:17]
	s_setprio 0
	s_setprio 1
	s_waitcnt lgkmcnt(1)
	v_mfma_f32_32x32x16_bf16 v[50:65], v[84:87], v[70:73], v[50:65]
	s_waitcnt lgkmcnt(0)
	v_mfma_f32_32x32x16_bf16 v[34:49], v[84:87], v[96:99], v[34:49]
	v_mfma_f32_32x32x16_bf16 v[18:33], v[92:95], v[70:73], v[18:33]
	v_mfma_f32_32x32x16_bf16 v[2:17], v[92:95], v[96:99], v[2:17]
	s_setprio 0
	v_mov_b32_e32 v0, v216
	s_waitcnt vmcnt(0)
	s_barrier
; DI bf16_t f2bf(float x) { return (bf16_t)(pack2(x, 0.f) & 0xffffu); }
; DI int crow(int i, int hh) { return (i & 3) + 8 * (i >> 2) + 4 * hh; }
;   template <int NTW>
;   DI void operator()(f32x16 (&acc)[2][NTW], int grow0, int gcol0, int lane, int w, char* lds) {
;     const int l31 = lane & 31, hh = lane >> 5;
; #pragma unroll
;     for (int mt = 0; mt < 2; ++mt)
; #pragma unroll
;       for (int pr = 0; pr < NTW / 2; ++pr) {
;         const int col = (gcol0 / 64 + pr) * 32 + l31;
; #pragma unroll
;         for (int i = 0; i < 16; ++i) {
;           float g = acc[mt][2 * pr][i], u = acc[mt][2 * pr + 1][i];
;           float v = g * __builtin_amdgcn_rcpf(1.f + __expf(-g)) * u;
;           int row = grow0 + mt * 32 + crow(i, hh);
;           H[(size_t)row * F_ + col] = f2bf(v);
;         }
;       }
	s_add_i32 s36, s36, s94
	v_ashrrev_i32_e32 v66, 6, v0
	v_lshrrev_b32_e32 v67, 30, v66
	v_add_u32_e32 v67, v66, v67
	v_ashrrev_i32_e32 v67, 2, v67
	v_mul_i32_i24_e32 v68, 4, v67
	v_sub_u32_e32 v68, v66, v68
	v_lshl_add_u32 v66, v67, 6, s6
	v_ashrrev_i32_e32 v66, 1, v66
	v_and_or_b32 v66, v0, 31, v66
	v_lshrrev_b32_e32 v0, 3, v0
	v_and_or_b32 v0, v0, 4, s2
	v_lshl_add_u32 v0, v68, 6, v0
	v_mul_f32_e32 v68, 0xbfb8aa3b, v50
	v_exp_f32_e32 v68, v68
	s_movk_i32 s2, 0x1600
	v_ashrrev_i32_e32 v67, 31, v66
	v_lshl_add_u64 v[66:67], v[66:67], 1, s[76:77]
	v_add_f32_e32 v68, 1.0, v68
	v_rcp_f32_e32 v68, v68
	s_add_i32 s35, s35, s63
	v_mul_f32_e32 v50, v50, v68
	v_mul_lo_u32 v68, v0, s2
	v_mul_f32_e32 v0, 0xbfb8aa3b, v51
	v_exp_f32_e32 v0, v0
	v_mul_f32_e32 v34, v34, v50
	v_ashrrev_i32_e32 v69, 31, v68
	v_cvt_pk_bf16_f32 v34, v34, s0
	v_add_f32_e32 v0, 1.0, v0
	v_rcp_f32_e32 v0, v0
	v_lshl_add_u64 v[66:67], v[66:67], 0, v[68:69]
	s_movk_i32 s2, 0x1000
	global_store_short v[66:67], v34, off
	v_mul_f32_e32 v0, v51, v0
	v_mul_f32_e32 v0, v35, v0
	v_add_co_u32_e32 v34, vcc, s2, v66
	v_cvt_pk_bf16_f32 v0, v0, s0
	s_nop 0
	v_addc_co_u32_e32 v35, vcc, 0, v67, vcc
	global_store_short v[34:35], v0, off offset:1536
	v_mul_f32_e32 v0, 0xbfb8aa3b, v52
	v_exp_f32_e32 v0, v0
	s_movk_i32 s2, 0x2000
	v_add_co_u32_e32 v34, vcc, s2, v66
	v_add_f32_e32 v0, 1.0, v0
	v_rcp_f32_e32 v0, v0
	v_addc_co_u32_e32 v35, vcc, 0, v67, vcc
	s_mov_b32 s2, 0xb000
	v_mul_f32_e32 v0, v52, v0
	v_mul_f32_e32 v0, v36, v0
	v_cvt_pk_bf16_f32 v0, v0, s0
	global_store_short v[34:35], v0, off offset:3072
	v_mul_f32_e32 v0, 0xbfb8aa3b, v53
	v_exp_f32_e32 v0, v0
	v_add_co_u32_e32 v34, vcc, s91, v66
	v_add_f32_e32 v0, 1.0, v0
	v_rcp_f32_e32 v0, v0
	v_addc_co_u32_e32 v35, vcc, 0, v67, vcc
	v_mul_f32_e32 v0, v53, v0
	v_mul_f32_e32 v0, v37, v0
	v_cvt_pk_bf16_f32 v0, v0, s0
	global_store_short v[34:35], v0, off offset:512
	v_mul_f32_e32 v0, 0xbfb8aa3b, v54
	v_exp_f32_e32 v0, v0
	v_add_co_u32_e32 v34, vcc, s2, v66
	s_mov_b32 s2, 0xc000
	v_add_f32_e32 v0, 1.0, v0
	v_rcp_f32_e32 v0, v0
	v_addc_co_u32_e32 v35, vcc, 0, v67, vcc
	v_mul_f32_e32 v0, v54, v0
	v_mul_f32_e32 v0, v38, v0
	v_cvt_pk_bf16_f32 v0, v0, s0
	global_store_short v[34:35], v0, off
	v_mul_f32_e32 v0, 0xbfb8aa3b, v55
	v_exp_f32_e32 v0, v0
	v_add_co_u32_e32 v34, vcc, s2, v66
	s_mov_b32 s2, 0xd000
	v_add_f32_e32 v0, 1.0, v0
	v_rcp_f32_e32 v0, v0
	v_addc_co_u32_e32 v35, vcc, 0, v67, vcc
	v_mul_f32_e32 v0, v55, v0
	v_mul_f32_e32 v0, v39, v0
	v_cvt_pk_bf16_f32 v0, v0, s0
	global_store_short v[34:35], v0, off offset:1536
	v_mul_f32_e32 v0, 0xbfb8aa3b, v56
	v_exp_f32_e32 v0, v0
	v_add_co_u32_e32 v34, vcc, s2, v66
	s_mov_b32 s2, 0xf000
	v_add_f32_e32 v0, 1.0, v0
	v_rcp_f32_e32 v0, v0
	v_addc_co_u32_e32 v35, vcc, 0, v67, vcc
	v_mul_f32_e32 v0, v56, v0
	v_mul_f32_e32 v0, v40, v0
	v_cvt_pk_bf16_f32 v0, v0, s0
	global_store_short v[34:35], v0, off offset:3072
	v_mul_f32_e32 v0, 0xbfb8aa3b, v57
	v_exp_f32_e32 v0, v0
	v_add_co_u32_e32 v34, vcc, s2, v66
	s_mov_b32 s2, 0x16000
	v_add_f32_e32 v0, 1.0, v0
	v_rcp_f32_e32 v0, v0
	v_addc_co_u32_e32 v35, vcc, 0, v67, vcc
	v_mul_f32_e32 v0, v57, v0
	v_mul_f32_e32 v0, v41, v0
	v_cvt_pk_bf16_f32 v0, v0, s0
	global_store_short v[34:35], v0, off offset:512
	v_mul_f32_e32 v0, 0xbfb8aa3b, v58
	v_exp_f32_e32 v0, v0
	v_add_co_u32_e32 v34, vcc, s2, v66
	s_mov_b32 s2, 0x17000
	v_add_f32_e32 v0, 1.0, v0
	v_rcp_f32_e32 v0, v0
	v_addc_co_u32_e32 v35, vcc, 0, v67, vcc
	v_mul_f32_e32 v0, v58, v0
	v_mul_f32_e32 v0, v42, v0
	v_cvt_pk_bf16_f32 v0, v0, s0
	global_store_short v[34:35], v0, off
	v_mul_f32_e32 v0, 0xbfb8aa3b, v59
	v_exp_f32_e32 v0, v0
	v_add_co_u32_e32 v34, vcc, s2, v66
	s_mov_b32 s2, 0x18000
	v_add_f32_e32 v0, 1.0, v0
	v_rcp_f32_e32 v0, v0
	v_addc_co_u32_e32 v35, vcc, 0, v67, vcc
	v_mul_f32_e32 v0, v59, v0
	v_mul_f32_e32 v0, v43, v0
	v_cvt_pk_bf16_f32 v0, v0, s0
	global_store_short v[34:35], v0, off offset:1536
	v_mul_f32_e32 v0, 0xbfb8aa3b, v60
	v_exp_f32_e32 v0, v0
	v_add_co_u32_e32 v34, vcc, s2, v66
	s_mov_b32 s2, 0x1a000
	v_add_f32_e32 v0, 1.0, v0
	v_rcp_f32_e32 v0, v0
	v_addc_co_u32_e32 v35, vcc, 0, v67, vcc
	v_mul_f32_e32 v0, v60, v0
	v_mul_f32_e32 v0, v44, v0
	v_cvt_pk_bf16_f32 v0, v0, s0
	global_store_short v[34:35], v0, off offset:3072
	v_mul_f32_e32 v0, 0xbfb8aa3b, v61
	v_exp_f32_e32 v0, v0
	v_add_co_u32_e32 v34, vcc, s2, v66
	s_mov_b32 s2, 0x21000
	v_add_f32_e32 v0, 1.0, v0
	v_rcp_f32_e32 v0, v0
	v_addc_co_u32_e32 v35, vcc, 0, v67, vcc
	v_mul_f32_e32 v0, v61, v0
	v_mul_f32_e32 v0, v45, v0
	v_cvt_pk_bf16_f32 v0, v0, s0
	global_store_short v[34:35], v0, off offset:512
	v_mul_f32_e32 v0, 0xbfb8aa3b, v62
	v_exp_f32_e32 v0, v0
	v_add_co_u32_e32 v34, vcc, s2, v66
	s_mov_b32 s2, 0x22000
	v_add_f32_e32 v0, 1.0, v0
	v_rcp_f32_e32 v0, v0
	v_addc_co_u32_e32 v35, vcc, 0, v67, vcc
	v_mul_f32_e32 v0, v62, v0
	v_mul_f32_e32 v0, v46, v0
	v_cvt_pk_bf16_f32 v0, v0, s0
	global_store_short v[34:35], v0, off
	v_mul_f32_e32 v0, 0xbfb8aa3b, v63
	v_exp_f32_e32 v0, v0
	v_add_co_u32_e32 v34, vcc, s2, v66
	s_mov_b32 s2, 0x23000
	v_add_f32_e32 v0, 1.0, v0
	v_rcp_f32_e32 v0, v0
	v_addc_co_u32_e32 v35, vcc, 0, v67, vcc
	v_mul_f32_e32 v0, v63, v0
	v_mul_f32_e32 v0, v47, v0
	v_cvt_pk_bf16_f32 v0, v0, s0
	global_store_short v[34:35], v0, off offset:1536
	v_mul_f32_e32 v0, 0xbfb8aa3b, v64
	v_exp_f32_e32 v0, v0
	v_add_co_u32_e32 v34, vcc, s2, v66
	s_mov_b32 s2, 0x25000
	v_add_f32_e32 v0, 1.0, v0
	v_rcp_f32_e32 v0, v0
	v_addc_co_u32_e32 v35, vcc, 0, v67, vcc
	v_mul_f32_e32 v0, v64, v0
	v_mul_f32_e32 v0, v48, v0
	v_cvt_pk_bf16_f32 v0, v0, s0
	global_store_short v[34:35], v0, off offset:3072
	v_mul_f32_e32 v0, 0xbfb8aa3b, v65
	v_exp_f32_e32 v0, v0
; DI bf16_t f2bf(float x) { return (bf16_t)(pack2(x, 0.f) & 0xffffu); }
; DI int crow(int i, int hh) { return (i & 3) + 8 * (i >> 2) + 4 * hh; }
;   template <int NTW>
;   DI void operator()(f32x16 (&acc)[2][NTW], int grow0, int gcol0, int lane, int w, char* lds) {
;     const int l31 = lane & 31, hh = lane >> 5;
; #pragma unroll
;     for (int mt = 0; mt < 2; ++mt)
; #pragma unroll
;       for (int pr = 0; pr < NTW / 2; ++pr) {
;         const int col = (gcol0 / 64 + pr) * 32 + l31;
; #pragma unroll
;         for (int i = 0; i < 16; ++i) {
;           float g = acc[mt][2 * pr][i], u = acc[mt][2 * pr + 1][i];
;           float v = g * __builtin_amdgcn_rcpf(1.f + __expf(-g)) * u;
;           int row = grow0 + mt * 32 + crow(i, hh);
;           H[(size_t)row * F_ + col] = f2bf(v);
;         }
;       }
	v_add_co_u32_e32 v34, vcc, s2, v66
	s_mov_b32 s2, 0x2c000
	v_add_f32_e32 v0, 1.0, v0
	v_rcp_f32_e32 v0, v0
	v_addc_co_u32_e32 v35, vcc, 0, v67, vcc
	v_mul_f32_e32 v0, v65, v0
	v_mul_f32_e32 v0, v49, v0
	v_cvt_pk_bf16_f32 v0, v0, s0
	global_store_short v[34:35], v0, off offset:512
	v_mul_f32_e32 v0, 0xbfb8aa3b, v18
	v_exp_f32_e32 v0, v0
	v_add_co_u32_e32 v34, vcc, s2, v66
	s_mov_b32 s2, 0x2d000
	v_add_f32_e32 v0, 1.0, v0
	v_rcp_f32_e32 v0, v0
	v_addc_co_u32_e32 v35, vcc, 0, v67, vcc
	v_mul_f32_e32 v0, v18, v0
	v_mul_f32_e32 v0, v2, v0
	v_cvt_pk_bf16_f32 v0, v0, s0
	global_store_short v[34:35], v0, off
	v_mul_f32_e32 v0, 0xbfb8aa3b, v19
	v_exp_f32_e32 v0, v0
	v_add_co_u32_e32 v2, vcc, s2, v66
	s_mov_b32 s2, 0x2e000
	v_add_f32_e32 v0, 1.0, v0
	v_rcp_f32_e32 v0, v0
	s_nop 0
	v_mul_f32_e32 v0, v19, v0
	v_mul_f32_e32 v0, v3, v0
	v_cvt_pk_bf16_f32 v0, v0, s0
	v_addc_co_u32_e32 v3, vcc, 0, v67, vcc
	global_store_short v[2:3], v0, off offset:1536
	v_mul_f32_e32 v0, 0xbfb8aa3b, v20
	v_exp_f32_e32 v0, v0
	v_add_co_u32_e32 v2, vcc, s2, v66
	s_mov_b32 s2, 0x30000
	v_add_f32_e32 v0, 1.0, v0
	v_rcp_f32_e32 v0, v0
	v_addc_co_u32_e32 v3, vcc, 0, v67, vcc
	v_mul_f32_e32 v0, v20, v0
	v_mul_f32_e32 v0, v4, v0
	v_cvt_pk_bf16_f32 v0, v0, s0
	global_store_short v[2:3], v0, off offset:3072
	v_mul_f32_e32 v0, 0xbfb8aa3b, v21
	v_exp_f32_e32 v0, v0
	v_add_co_u32_e32 v2, vcc, s2, v66
	s_mov_b32 s2, 0x37000
	v_add_f32_e32 v0, 1.0, v0
	v_rcp_f32_e32 v0, v0
	v_addc_co_u32_e32 v3, vcc, 0, v67, vcc
	v_mul_f32_e32 v0, v21, v0
	v_mul_f32_e32 v0, v5, v0
	v_cvt_pk_bf16_f32 v0, v0, s0
	global_store_short v[2:3], v0, off offset:512
	v_mul_f32_e32 v0, 0xbfb8aa3b, v22
	v_exp_f32_e32 v0, v0
	v_add_co_u32_e32 v2, vcc, s2, v66
	s_mov_b32 s2, 0x38000
	v_add_f32_e32 v0, 1.0, v0
	v_rcp_f32_e32 v0, v0
	v_addc_co_u32_e32 v3, vcc, 0, v67, vcc
	v_mul_f32_e32 v0, v22, v0
	v_mul_f32_e32 v0, v6, v0
	v_cvt_pk_bf16_f32 v0, v0, s0
	global_store_short v[2:3], v0, off
	v_mul_f32_e32 v0, 0xbfb8aa3b, v23
	v_exp_f32_e32 v0, v0
	v_add_co_u32_e32 v2, vcc, s2, v66
	s_mov_b32 s2, 0x39000
	v_add_f32_e32 v0, 1.0, v0
	v_rcp_f32_e32 v0, v0
	v_addc_co_u32_e32 v3, vcc, 0, v67, vcc
	v_mul_f32_e32 v0, v23, v0
	v_mul_f32_e32 v0, v7, v0
	v_cvt_pk_bf16_f32 v0, v0, s0
	global_store_short v[2:3], v0, off offset:1536
	v_mul_f32_e32 v0, 0xbfb8aa3b, v24
	v_exp_f32_e32 v0, v0
	v_add_co_u32_e32 v2, vcc, s2, v66
	s_mov_b32 s2, 0x3b000
	v_add_f32_e32 v0, 1.0, v0
	v_rcp_f32_e32 v0, v0
	v_addc_co_u32_e32 v3, vcc, 0, v67, vcc
	v_mul_f32_e32 v0, v24, v0
	v_mul_f32_e32 v0, v8, v0
	v_cvt_pk_bf16_f32 v0, v0, s0
	global_store_short v[2:3], v0, off offset:3072
	v_mul_f32_e32 v0, 0xbfb8aa3b, v25
	v_exp_f32_e32 v0, v0
	v_add_co_u32_e32 v2, vcc, s2, v66
	s_mov_b32 s2, 0x42000
	v_add_f32_e32 v0, 1.0, v0
	v_rcp_f32_e32 v0, v0
	v_addc_co_u32_e32 v3, vcc, 0, v67, vcc
	v_mul_f32_e32 v0, v25, v0
	v_mul_f32_e32 v0, v9, v0
	v_cvt_pk_bf16_f32 v0, v0, s0
	global_store_short v[2:3], v0, off offset:512
	v_mul_f32_e32 v0, 0xbfb8aa3b, v26
	v_exp_f32_e32 v0, v0
	v_add_co_u32_e32 v2, vcc, s2, v66
	s_mov_b32 s2, 0x43000
	v_add_f32_e32 v0, 1.0, v0
	v_rcp_f32_e32 v0, v0
	v_addc_co_u32_e32 v3, vcc, 0, v67, vcc
	v_mul_f32_e32 v0, v26, v0
	v_mul_f32_e32 v0, v10, v0
	v_cvt_pk_bf16_f32 v0, v0, s0
	global_store_short v[2:3], v0, off
	v_mul_f32_e32 v0, 0xbfb8aa3b, v27
	v_exp_f32_e32 v0, v0
	v_add_co_u32_e32 v2, vcc, s2, v66
	s_mov_b32 s2, 0x44000
	v_add_f32_e32 v0, 1.0, v0
	v_rcp_f32_e32 v0, v0
	v_addc_co_u32_e32 v3, vcc, 0, v67, vcc
	v_mul_f32_e32 v0, v27, v0
	v_mul_f32_e32 v0, v11, v0
	v_cvt_pk_bf16_f32 v0, v0, s0
	global_store_short v[2:3], v0, off offset:1536
	v_mul_f32_e32 v0, 0xbfb8aa3b, v28
	v_exp_f32_e32 v0, v0
	v_add_co_u32_e32 v2, vcc, s2, v66
	s_mov_b32 s2, 0x46000
	v_add_f32_e32 v0, 1.0, v0
	v_rcp_f32_e32 v0, v0
	v_addc_co_u32_e32 v3, vcc, 0, v67, vcc
	v_mul_f32_e32 v0, v28, v0
	v_mul_f32_e32 v0, v12, v0
	v_cvt_pk_bf16_f32 v0, v0, s0
	global_store_short v[2:3], v0, off offset:3072
	v_mul_f32_e32 v0, 0xbfb8aa3b, v29
	v_exp_f32_e32 v0, v0
	v_add_co_u32_e32 v2, vcc, s2, v66
	s_mov_b32 s2, 0x4d000
	v_add_f32_e32 v0, 1.0, v0
	v_rcp_f32_e32 v0, v0
	v_addc_co_u32_e32 v3, vcc, 0, v67, vcc
	v_mul_f32_e32 v0, v29, v0
	v_mul_f32_e32 v0, v13, v0
	v_cvt_pk_bf16_f32 v0, v0, s0
	global_store_short v[2:3], v0, off offset:512
	v_mul_f32_e32 v0, 0xbfb8aa3b, v30
	v_exp_f32_e32 v0, v0
	v_add_co_u32_e32 v2, vcc, s2, v66
	s_mov_b32 s2, 0x4e000
	v_add_f32_e32 v0, 1.0, v0
	v_rcp_f32_e32 v0, v0
	v_addc_co_u32_e32 v3, vcc, 0, v67, vcc
	v_mul_f32_e32 v0, v30, v0
	v_mul_f32_e32 v0, v14, v0
	v_cvt_pk_bf16_f32 v0, v0, s0
	global_store_short v[2:3], v0, off
	v_mul_f32_e32 v0, 0xbfb8aa3b, v31
	v_exp_f32_e32 v0, v0
	v_add_co_u32_e32 v2, vcc, s2, v66
	s_mov_b32 s2, 0x4f000
	v_add_f32_e32 v0, 1.0, v0
	v_rcp_f32_e32 v0, v0
	v_addc_co_u32_e32 v3, vcc, 0, v67, vcc
	v_mul_f32_e32 v0, v31, v0
	v_mul_f32_e32 v0, v15, v0
	v_cvt_pk_bf16_f32 v0, v0, s0
	global_store_short v[2:3], v0, off offset:1536
	v_mul_f32_e32 v0, 0xbfb8aa3b, v32
	v_exp_f32_e32 v0, v0
	v_add_co_u32_e32 v2, vcc, s2, v66
	v_readlane_b32 s2, v254, 39
	v_add_f32_e32 v0, 1.0, v0
	v_rcp_f32_e32 v0, v0
	v_addc_co_u32_e32 v3, vcc, 0, v67, vcc
	s_add_i32 s34, s34, s2
	v_mul_f32_e32 v0, v32, v0
	v_mul_f32_e32 v0, v16, v0
	v_cvt_pk_bf16_f32 v0, v0, s0
	global_store_short v[2:3], v0, off offset:3072
	v_mul_f32_e32 v0, 0xbfb8aa3b, v33
	v_exp_f32_e32 v0, v0
	v_add_co_u32_e32 v2, vcc, 0x51000, v66
	s_cmpk_gt_i32 s36, 0xff
	v_add_f32_e32 v0, 1.0, v0
	v_rcp_f32_e32 v0, v0
	v_addc_co_u32_e32 v3, vcc, 0, v67, vcc
	v_mul_f32_e32 v0, v33, v0
	v_mul_f32_e32 v0, v17, v0
	v_cvt_pk_bf16_f32 v0, v0, s0
	global_store_short v[2:3], v0, off offset:512
	s_cbranch_scc0 .LBB0_387

; DI f32x16 mfma(bf16x8 a, bf16x8 b, f32x16 c) { return __builtin_amdgcn_mfma_f32_32x32x16_bf16(a, b, c, 0, 0, 0); }
; template <int BK> DI int swz(int row) { constexpr int CPR = BK / 8; return (row / (16 / CPR)) % CPR; }
;   DI void pre(int grow0, int gcol0, int lane, int w, char* lds) { xpass(0, grow0, gcol0, lane, w, lds); }
;     ...
;   for (int kt = 0; kt < nk; ++kt) {
;     char* cur = lds + (kt & 1) * STG; char* nxt = lds + ((kt + 1) & 1) * STG;
;     const bool more = kt + 1 < nk;
;     const bf16_t* An = Ag + (kt + 1) * BK; const bf16_t* Bn = Bg + (kt + 1) * BK;
;     if (!more) epi.pre(row0 + wm * 64, col0 + wn * (32 * NTW), lane, w, lds);
;     bf16x8 fa[2][2], fb[2][NTW];
; #pragma unroll
;     for (int mt = 0; mt < 2; ++mt) { int row = wm * 64 + mt * 32 + l31; fa[0][mt] = *(const bf16x8*)(cur + row * (BK * 2) + ((hh ^ swz<BK>(row)) << 4)); }
; #pragma unroll
;     for (int nt = 0; nt < NTW; ++nt) { int row = wn * (32 * NTW) + nt * 32 + l31; fb[0][nt] = *(const bf16x8*)(cur + ABYTES + row * (BK * 2) + ((hh ^ swz<BK>(row)) << 4)); }
; #pragma unroll
;     for (int kk = 0; kk < NKK; ++kk) {
;       if (kk + 1 < NKK) {
;         const int ch = (kk + 1) * 2 + hh;
; #pragma unroll
;         for (int mt = 0; mt < 2; ++mt) { int row = wm * 64 + mt * 32 + l31; fa[(kk + 1) & 1][mt] = *(const bf16x8*)(cur + row * (BK * 2) + ((ch ^ swz<BK>(row)) << 4)); }
; #pragma unroll
;         for (int nt = 0; nt < NTW; ++nt) { int row = wn * (32 * NTW) + nt * 32 + l31; fb[(kk + 1) & 1][nt] = *(const bf16x8*)(cur + ABYTES + row * (BK * 2) + ((ch ^ swz<BK>(row)) << 4)); }
;       }
;       if (more) {
; #pragma unroll
;         for (int q = 0; q < PPK; ++q) {
;           const int pi = kk * PPK + q;
;           if (pi < NPA) stage_piece<BM, BK>(An, lda, nxt, tid, pi, wv);
;           else if (pi < NP) stage_piece<BN, BK>(Bn, ldb, nxt + ABYTES, tid, pi - NPA, wv);
;         }
;       }
;       __builtin_amdgcn_s_setprio(1);
; #pragma unroll
;       for (int mt = 0; mt < 2; ++mt)
; #pragma unroll
;         for (int nt = 0; nt < NTW; ++nt) acc[mt][nt] = mfma(fa[kk & 1][mt], fb[kk & 1][nt], acc[mt][nt]);
;       __builtin_amdgcn_s_setprio(0);
;       __builtin_amdgcn_sched_barrier(0);
;     }
.LBB0_439:
	s_and_b32 s40, s7, 0x10000
	s_xor_b32 s100, s40, 0x10000
	v_add3_u32 v190, s100, v140, v161
	v_add3_u32 v194, s100, v142, v163
	ds_read_b128 v[190:193], v190
	v_add3_u32 v198, s100, v143, v159
	ds_read_b128 v[194:197], v194
	v_add3_u32 v202, s100, v152, v160
	ds_read_b128 v[198:201], v198 offset:32768
	v_add3_u32 v206, s100, v153, v157
	ds_read_b128 v[202:205], v202 offset:32768
	v_add3_u32 v210, s100, v156, v158
	ds_read_b128 v[206:209], v206 offset:32768
	ds_read_b128 v[210:213], v210 offset:32768
	s_waitcnt lgkmcnt(6)
	s_mov_b32 m0, s37
	v_lshl_add_u64 v[228:229], v[214:215], 0, s[28:29]
	v_mfma_f32_32x32x16_bf16 v[114:129], v[166:169], v[174:177], v[114:129]
	global_load_lds_dwordx4 v[228:229], off
	s_add_i32 m0, s37, 0x2000
	v_lshl_add_u64 v[228:229], v[214:215], 0, s[24:25]
	v_mfma_f32_32x32x16_bf16 v[98:113], v[166:169], v[178:181], v[98:113]
	v_mfma_f32_32x32x16_bf16 v[50:65], v[166:169], v[182:185], v[50:65]
	global_load_lds_dwordx4 v[228:229], off
	s_add_i32 m0, s37, 0x4000
	v_lshl_add_u64 v[228:229], v[214:215], 0, s[26:27]
	v_mfma_f32_32x32x16_bf16 v[34:49], v[166:169], v[186:189], v[34:49]
	v_mfma_f32_32x32x16_bf16 v[82:97], v[170:173], v[174:177], v[82:97]
	global_load_lds_dwordx4 v[228:229], off
	s_add_i32 m0, s37, 0x6000
	v_lshl_add_u64 v[228:229], v[214:215], 0, s[38:39]
	v_mfma_f32_32x32x16_bf16 v[66:81], v[170:173], v[178:181], v[66:81]
	v_mfma_f32_32x32x16_bf16 v[18:33], v[170:173], v[182:185], v[18:33]
	global_load_lds_dwordx4 v[228:229], off
	v_mfma_f32_32x32x16_bf16 v[2:17], v[170:173], v[186:189], v[2:17]
	v_add3_u32 v166, s100, v140, v149
	v_add3_u32 v170, s100, v142, v150
	ds_read_b128 v[166:169], v166
	v_add3_u32 v174, s100, v143, v147
	ds_read_b128 v[170:173], v170
	v_add3_u32 v178, s100, v152, v148
	ds_read_b128 v[174:177], v174 offset:32768
	v_add3_u32 v182, s100, v153, v145
	ds_read_b128 v[178:181], v178 offset:32768
	v_add3_u32 v186, s100, v156, v146
	ds_read_b128 v[182:185], v182 offset:32768
	ds_read_b128 v[186:189], v186 offset:32768
	s_waitcnt lgkmcnt(6)
	v_mfma_f32_32x32x16_bf16 v[114:129], v[190:193], v[198:201], v[114:129]
	v_mfma_f32_32x32x16_bf16 v[98:113], v[190:193], v[202:205], v[98:113]
	v_mfma_f32_32x32x16_bf16 v[50:65], v[190:193], v[206:209], v[50:65]
	v_mfma_f32_32x32x16_bf16 v[34:49], v[190:193], v[210:213], v[34:49]
	v_mfma_f32_32x32x16_bf16 v[82:97], v[194:197], v[198:201], v[82:97]
	v_mfma_f32_32x32x16_bf16 v[66:81], v[194:197], v[202:205], v[66:81]
	v_mfma_f32_32x32x16_bf16 v[18:33], v[194:197], v[206:209], v[18:33]
	v_mfma_f32_32x32x16_bf16 v[2:17], v[194:197], v[210:213], v[2:17]
	v_add3_u32 v190, s100, v140, v138
	v_add3_u32 v194, s100, v142, v139
	ds_read_b128 v[190:193], v190
	v_add3_u32 v198, s100, v143, v136
	ds_read_b128 v[194:197], v194
	v_add3_u32 v202, s100, v152, v137
	ds_read_b128 v[198:201], v198 offset:32768
	v_add3_u32 v206, s100, v153, v134
	ds_read_b128 v[202:205], v202 offset:32768
	v_add3_u32 v210, s100, v156, v135
	ds_read_b128 v[206:209], v206 offset:32768
	ds_read_b128 v[210:213], v210 offset:32768
	s_waitcnt lgkmcnt(6)
	v_mfma_f32_32x32x16_bf16 v[114:129], v[166:169], v[174:177], v[114:129]
	v_mfma_f32_32x32x16_bf16 v[98:113], v[166:169], v[178:181], v[98:113]
	v_mfma_f32_32x32x16_bf16 v[50:65], v[166:169], v[182:185], v[50:65]
	v_mfma_f32_32x32x16_bf16 v[34:49], v[166:169], v[186:189], v[34:49]
	v_mfma_f32_32x32x16_bf16 v[82:97], v[170:173], v[174:177], v[82:97]
	v_mfma_f32_32x32x16_bf16 v[66:81], v[170:173], v[178:181], v[66:81]
	v_mfma_f32_32x32x16_bf16 v[18:33], v[170:173], v[182:185], v[18:33]
	v_mfma_f32_32x32x16_bf16 v[2:17], v[170:173], v[186:189], v[2:17]
	s_add_u32 s30, s30, 0x80
	s_addc_u32 s31, s31, 0
	s_add_i32 s7, s7, 0x10000
	s_waitcnt vmcnt(0) lgkmcnt(0)
	s_barrier
	s_cmpk_eq_i32 s30, 0x780
	s_cbranch_scc1 .Lk439_exit
	s_add_i32 s37, s100, s3
	v_lshl_add_u64 v[214:215], v[130:131], 0, s[30:31]
	v_lshl_add_u64 v[226:227], v[132:133], 0, s[30:31]
	s_add_i32 m0, s37, 0x8000
	v_lshl_add_u64 v[228:229], v[226:227], 0, s[28:29]
	v_mfma_f32_32x32x16_bf16 v[114:129], v[190:193], v[198:201], v[114:129]
	global_load_lds_dwordx4 v[228:229], off
	v_add3_u32 v166, s40, v140, v141
	v_add3_u32 v170, s40, v142, v144
	ds_read_b128 v[166:169], v166
	v_add3_u32 v174, s40, v143, v151
	ds_read_b128 v[170:173], v170
	v_add3_u32 v178, s40, v152, v154
	ds_read_b128 v[174:177], v174 offset:32768
	v_add3_u32 v182, s40, v153, v155
	ds_read_b128 v[178:181], v178 offset:32768
	v_add3_u32 v186, s40, v156, v164
	ds_read_b128 v[182:185], v182 offset:32768
	ds_read_b128 v[186:189], v186 offset:32768
	s_add_i32 m0, s37, 0xa000
	v_lshl_add_u64 v[228:229], v[226:227], 0, s[24:25]
	v_mfma_f32_32x32x16_bf16 v[98:113], v[190:193], v[202:205], v[98:113]
	v_mfma_f32_32x32x16_bf16 v[50:65], v[190:193], v[206:209], v[50:65]
	global_load_lds_dwordx4 v[228:229], off
	s_add_i32 m0, s37, 0xc000
	v_lshl_add_u64 v[228:229], v[226:227], 0, s[26:27]
	v_mfma_f32_32x32x16_bf16 v[34:49], v[190:193], v[210:213], v[34:49]
	v_mfma_f32_32x32x16_bf16 v[82:97], v[194:197], v[198:201], v[82:97]
	global_load_lds_dwordx4 v[228:229], off
	s_add_i32 m0, s37, 0xe000
	v_lshl_add_u64 v[228:229], v[226:227], 0, s[38:39]
	v_mfma_f32_32x32x16_bf16 v[66:81], v[194:197], v[202:205], v[66:81]
	v_mfma_f32_32x32x16_bf16 v[18:33], v[194:197], v[206:209], v[18:33]
	global_load_lds_dwordx4 v[228:229], off
	v_mfma_f32_32x32x16_bf16 v[2:17], v[194:197], v[210:213], v[2:17]
	s_branch .LBB0_439
; DI f32x16 mfma(bf16x8 a, bf16x8 b, f32x16 c) { return __builtin_amdgcn_mfma_f32_32x32x16_bf16(a, b, c, 0, 0, 0); }
; template <int BK> DI int swz(int row) { constexpr int CPR = BK / 8; return (row / (16 / CPR)) % CPR; }
; DI void wait_vm0() { asm volatile("s_waitcnt vmcnt(0)" ::: "memory"); }
;   DI void pre(int grow0, int gcol0, int lane, int w, char* lds) { xpass(0, grow0, gcol0, lane, w, lds); }
;     ...
;   for (int kt = 0; kt < nk; ++kt) {
;     char* cur = lds + (kt & 1) * STG; char* nxt = lds + ((kt + 1) & 1) * STG;
;     const bool more = kt + 1 < nk;
;     const bf16_t* An = Ag + (kt + 1) * BK; const bf16_t* Bn = Bg + (kt + 1) * BK;
;     if (!more) epi.pre(row0 + wm * 64, col0 + wn * (32 * NTW), lane, w, lds);
;     bf16x8 fa[2][2], fb[2][NTW];
; #pragma unroll
;     for (int mt = 0; mt < 2; ++mt) { int row = wm * 64 + mt * 32 + l31; fa[0][mt] = *(const bf16x8*)(cur + row * (BK * 2) + ((hh ^ swz<BK>(row)) << 4)); }
; #pragma unroll
;     for (int nt = 0; nt < NTW; ++nt) { int row = wn * (32 * NTW) + nt * 32 + l31; fb[0][nt] = *(const bf16x8*)(cur + ABYTES + row * (BK * 2) + ((hh ^ swz<BK>(row)) << 4)); }
; #pragma unroll
;     for (int kk = 0; kk < NKK; ++kk) {
;       if (kk + 1 < NKK) {
;         const int ch = (kk + 1) * 2 + hh;
; #pragma unroll
;         for (int mt = 0; mt < 2; ++mt) { int row = wm * 64 + mt * 32 + l31; fa[(kk + 1) & 1][mt] = *(const bf16x8*)(cur + row * (BK * 2) + ((ch ^ swz<BK>(row)) << 4)); }
; #pragma unroll
;         for (int nt = 0; nt < NTW; ++nt) { int row = wn * (32 * NTW) + nt * 32 + l31; fb[(kk + 1) & 1][nt] = *(const bf16x8*)(cur + ABYTES + row * (BK * 2) + ((ch ^ swz<BK>(row)) << 4)); }
;       }
;       if (more) {
; #pragma unroll
;         for (int q = 0; q < PPK; ++q) {
;           const int pi = kk * PPK + q;
;           if (pi < NPA) stage_piece<BM, BK>(An, lda, nxt, tid, pi, wv);
;           else if (pi < NP) stage_piece<BN, BK>(Bn, ldb, nxt + ABYTES, tid, pi - NPA, wv);
;         }
;       }
;       __builtin_amdgcn_s_setprio(1);
; #pragma unroll
;       for (int mt = 0; mt < 2; ++mt)
; #pragma unroll
;         for (int nt = 0; nt < NTW; ++nt) acc[mt][nt] = mfma(fa[kk & 1][mt], fb[kk & 1][nt], acc[mt][nt]);
;       __builtin_amdgcn_s_setprio(0);
;       __builtin_amdgcn_sched_barrier(0);
;     }
;     wait_vm0();
;     __syncthreads();
;   }
.Lk439_exit:
	v_add3_u32 v166, s40, v140, v141
	v_add3_u32 v170, s40, v142, v144
	ds_read_b128 v[166:169], v166
	v_add3_u32 v174, s40, v143, v151
	ds_read_b128 v[170:173], v170
	v_add3_u32 v178, s40, v152, v154
	ds_read_b128 v[174:177], v174 offset:32768
	v_add3_u32 v182, s40, v153, v155
	ds_read_b128 v[178:181], v178 offset:32768
	v_add3_u32 v186, s40, v156, v164
	ds_read_b128 v[182:185], v182 offset:32768
	ds_read_b128 v[186:189], v186 offset:32768
	v_mfma_f32_32x32x16_bf16 v[114:129], v[190:193], v[198:201], v[114:129]
	v_mfma_f32_32x32x16_bf16 v[98:113], v[190:193], v[202:205], v[98:113]
	v_mfma_f32_32x32x16_bf16 v[50:65], v[190:193], v[206:209], v[50:65]
	v_mfma_f32_32x32x16_bf16 v[34:49], v[190:193], v[210:213], v[34:49]
	v_mfma_f32_32x32x16_bf16 v[82:97], v[194:197], v[198:201], v[82:97]
	v_mfma_f32_32x32x16_bf16 v[66:81], v[194:197], v[202:205], v[66:81]
	v_mfma_f32_32x32x16_bf16 v[18:33], v[194:197], v[206:209], v[18:33]
	v_mfma_f32_32x32x16_bf16 v[2:17], v[194:197], v[210:213], v[2:17]
	s_waitcnt lgkmcnt(0)
	v_add_u32_e32 v0, 0x10000, v140
	v_add_u32_e32 v198, 0x10000, v142
	v_add_u32_e32 v130, v0, v141
	v_add_u32_e32 v140, v198, v144
	v_add_u32_e32 v199, 0x18000, v143
	v_add_u32_e32 v200, 0x18000, v152
	ds_read_b128 v[130:133], v130
	ds_read_b128 v[166:169], v140
	v_add_u32_e32 v140, v199, v151
	v_add_u32_e32 v144, v200, v154
	v_add_u32_e32 v201, 0x18000, v153
	ds_read_b128 v[140:143], v140
	ds_read_b128 v[170:173], v144
	v_add_u32_e32 v144, v201, v155
	v_add_u32_e32 v202, 0x18000, v156
	v_add_u32_e32 v151, v202, v164
	ds_read_b128 v[152:155], v144
	ds_read_b128 v[174:177], v151
	v_add_u32_e32 v144, v0, v161
	v_add_u32_e32 v151, v198, v163
	ds_read_b128 v[178:181], v144
	ds_read_b128 v[182:185], v151
	v_add_u32_e32 v144, v199, v159
	v_add_u32_e32 v151, v200, v160
	ds_read_b128 v[186:189], v144
	ds_read_b128 v[190:193], v151
	v_add_u32_e32 v144, v201, v157
	v_add_u32_e32 v151, v202, v158
	ds_read_b128 v[156:159], v144
	ds_read_b128 v[194:197], v151
	s_add_i32 s36, s36, s94
	s_cmpk_gt_i32 s36, 0x5ff
	s_cselect_b64 s[42:43], -1, 0
	s_cmpk_lt_i32 s36, 0x600
	s_setprio 1
	s_waitcnt lgkmcnt(9)
	v_mfma_f32_32x32x16_bf16 v[114:129], v[130:133], v[140:143], v[114:129]
	s_waitcnt lgkmcnt(8)
	v_mfma_f32_32x32x16_bf16 v[98:113], v[130:133], v[170:173], v[98:113]
	s_waitcnt lgkmcnt(7)
	v_mfma_f32_32x32x16_bf16 v[50:65], v[130:133], v[152:155], v[50:65]
	s_waitcnt lgkmcnt(6)
	v_mfma_f32_32x32x16_bf16 v[34:49], v[130:133], v[174:177], v[34:49]
	v_mfma_f32_32x32x16_bf16 v[82:97], v[166:169], v[140:143], v[82:97]
	v_mfma_f32_32x32x16_bf16 v[66:81], v[166:169], v[170:173], v[66:81]
	v_mfma_f32_32x32x16_bf16 v[18:33], v[166:169], v[152:155], v[18:33]
	v_mfma_f32_32x32x16_bf16 v[2:17], v[166:169], v[174:177], v[2:17]
	s_setprio 0
	v_add_u32_e32 v130, v0, v149
	v_add_u32_e32 v140, v198, v150
	v_add_u32_e32 v144, v199, v147
	ds_read_b128 v[130:133], v130
	ds_read_b128 v[140:143], v140
	v_add_u32_e32 v147, v200, v148
	ds_read_b128 v[148:151], v144
	ds_read_b128 v[152:155], v147
	v_add_u32_e32 v144, v201, v145
	v_add_u32_e32 v160, v202, v146
	ds_read_b128 v[144:147], v144
	ds_read_b128 v[166:169], v160
	s_setprio 1
	s_waitcnt lgkmcnt(9)
	v_mfma_f32_32x32x16_bf16 v[114:129], v[178:181], v[186:189], v[114:129]
	s_waitcnt lgkmcnt(8)
	v_mfma_f32_32x32x16_bf16 v[98:113], v[178:181], v[190:193], v[98:113]
	s_waitcnt lgkmcnt(7)
	v_mfma_f32_32x32x16_bf16 v[50:65], v[178:181], v[156:159], v[50:65]
	s_waitcnt lgkmcnt(6)
	v_mfma_f32_32x32x16_bf16 v[34:49], v[178:181], v[194:197], v[34:49]
	v_mfma_f32_32x32x16_bf16 v[82:97], v[182:185], v[186:189], v[82:97]
	v_mfma_f32_32x32x16_bf16 v[66:81], v[182:185], v[190:193], v[66:81]
	v_mfma_f32_32x32x16_bf16 v[18:33], v[182:185], v[156:159], v[18:33]
	v_mfma_f32_32x32x16_bf16 v[2:17], v[182:185], v[194:197], v[2:17]
	s_setprio 0
	v_add_u32_e32 v0, v0, v138
	v_add_u32_e32 v138, v198, v139
	ds_read_b128 v[156:159], v0
	ds_read_b128 v[170:173], v138
	v_add_u32_e32 v0, v199, v136
	v_add_u32_e32 v160, v200, v137
	ds_read_b128 v[136:139], v0
	ds_read_b128 v[174:177], v160
	v_add_u32_e32 v0, v201, v134
	v_add_u32_e32 v134, v202, v135
	ds_read_b128 v[178:181], v0
	ds_read_b128 v[182:185], v134
	s_setprio 1
	s_waitcnt lgkmcnt(9)
	v_mfma_f32_32x32x16_bf16 v[114:129], v[130:133], v[148:151], v[114:129]
	s_waitcnt lgkmcnt(8)
	v_mfma_f32_32x32x16_bf16 v[98:113], v[130:133], v[152:155], v[98:113]
	s_waitcnt lgkmcnt(7)
	v_mfma_f32_32x32x16_bf16 v[50:65], v[130:133], v[144:147], v[50:65]
	s_waitcnt lgkmcnt(6)
	v_mfma_f32_32x32x16_bf16 v[34:49], v[130:133], v[166:169], v[34:49]
	v_mfma_f32_32x32x16_bf16 v[82:97], v[140:143], v[148:151], v[82:97]
	v_mfma_f32_32x32x16_bf16 v[66:81], v[140:143], v[152:155], v[66:81]
	v_mfma_f32_32x32x16_bf16 v[18:33], v[140:143], v[144:147], v[18:33]
	v_mfma_f32_32x32x16_bf16 v[2:17], v[140:143], v[166:169], v[2:17]
	s_setprio 0
	s_setprio 1
	s_waitcnt lgkmcnt(3)
	v_mfma_f32_32x32x16_bf16 v[114:129], v[156:159], v[136:139], v[114:129]
	s_waitcnt lgkmcnt(2)
	v_mfma_f32_32x32x16_bf16 v[98:113], v[156:159], v[174:177], v[98:113]
	s_waitcnt lgkmcnt(1)
	v_mfma_f32_32x32x16_bf16 v[50:65], v[156:159], v[178:181], v[50:65]
	s_waitcnt lgkmcnt(0)
	v_mfma_f32_32x32x16_bf16 v[34:49], v[156:159], v[182:185], v[34:49]
	v_mfma_f32_32x32x16_bf16 v[82:97], v[170:173], v[136:139], v[82:97]
	v_mfma_f32_32x32x16_bf16 v[66:81], v[170:173], v[174:177], v[66:81]
	v_mfma_f32_32x32x16_bf16 v[18:33], v[170:173], v[178:181], v[18:33]
	v_mfma_f32_32x32x16_bf16 v[2:17], v[170:173], v[182:185], v[2:17]
	s_setprio 0
	s_waitcnt vmcnt(0)
	s_barrier
; DI int launder(int x) { asm volatile("" : "+v"(x)); return x; }
;   DI void pre(int grow0, int gcol0, int lane, int w, char* lds) { xpass(0, grow0, gcol0, lane, w, lds); }
;     ...
;   if (has_next) { const int tid3 = launder(threadIdx.x); stage_tile<BM, BK>(A + (size_t)row0n * lda, lda, lds, tid3); stage_tile<BN, BK>(Bt + (size_t)col0n * ldb, ldb, lds + ABYTES, tid3); }
; template <class Epi>
; DI void gemm_phase256(const bf16_t* A, int lda, const bf16_t* Bt, int K, int nN, char* lds, Epi& epi, int vb) {
;     ...
;     const int x = t & 7, L = t >> 3; const int pm = 8 * x + (L & 7), pn = L >> 3;
;     const int t2 = t + gridDim.x; const bool hn = t2 < ntiles;
;     const int x2 = t2 & 7, L2 = t2 >> 3; const int pm2 = 8 * x2 + (L2 & 7), pn2 = L2 >> 3;
;     gemm_tile<4, 64>(A, lda, Bt, K, K, pm * 256, pn * 256, lds, epi, pre, hn, pm2 * 256, pn2 * 256);
	s_cbranch_scc0 .LBB0_442
	v_mov_b32_e32 v132, v216
	s_lshl_b32 s3, s36, 3
	v_ashrrev_i32_e32 v0, 31, v132
	v_lshrrev_b32_e32 v130, 29, v0
	v_lshrrev_b32_e32 v0, 28, v0
	v_add_u32_e32 v0, v132, v0
	v_ashrrev_i32_e32 v0, 4, v0
	s_and_b32 s3, s3, 56
	s_bfe_u32 s7, s36, 0x30003
	v_lshrrev_b32_e32 v133, 29, v0
	s_or_b32 s3, s3, s7
	s_lshl_b32 s7, s36, 2
	v_add_u32_e32 v130, v132, v130
	v_add_u32_e32 v133, v0, v133
	s_and_b32 s30, s7, 0xffffff00
	s_lshl_b32 s3, s3, 19
	v_and_b32_e32 v131, 0xffffff8, v130
	v_and_b32_e32 v133, 0xffffff8, v133
	s_add_u32 s40, s12, s3
	v_sub_u32_e32 v131, v132, v131
	v_sub_u32_e32 v0, v0, v133
	v_lshlrev_b32_e32 v130, 8, v130
	v_readfirstlane_b32 s3, v132
	s_addc_u32 s41, s13, 0
	v_xor_b32_e32 v0, v0, v131
	v_and_b32_e32 v130, 0xfffff800, v130
	s_lshl_b32 s3, s3, 4
	v_lshl_add_u32 v0, v0, 4, v130
	s_and_b32 s3, s3, 0xfffffc00
	s_load_dwordx4 s[44:47], s[0:1], 0x1a0
	v_lshl_add_u64 v[130:131], s[40:41], 0, v[0:1]
	s_mov_b32 m0, s3
	v_lshl_add_u64 v[132:133], v[130:131], 0, s[58:59]
	global_load_lds_dwordx4 v0, s[40:41]
	s_add_i32 m0, s3, 0x2000
	s_ashr_i32 s31, s30, 31
	global_load_lds_dwordx4 v[132:133], off
	v_lshl_add_u64 v[132:133], v[130:131], 0, s[48:49]
	s_add_i32 m0, s3, 0x4000
	s_lshl_b64 s[30:31], s[30:31], 11
	global_load_lds_dwordx4 v[132:133], off
	s_add_i32 m0, s3, 0x6000
	s_waitcnt lgkmcnt(0)
	s_add_u32 s30, s46, s30
	v_lshl_add_u64 v[130:131], v[130:131], 0, s[50:51]
	s_addc_u32 s31, s47, s31
	global_load_lds_dwordx4 v[130:131], off
	v_lshl_add_u64 v[130:131], s[30:31], 0, v[0:1]
	s_add_i32 m0, s3, 0x8000
	v_lshl_add_u64 v[132:133], v[130:131], 0, s[58:59]
	global_load_lds_dwordx4 v0, s[30:31]
	s_add_i32 m0, s3, 0xa000
	s_nop 0
	global_load_lds_dwordx4 v[132:133], off
	v_lshl_add_u64 v[132:133], v[130:131], 0, s[48:49]
	s_add_i32 m0, s3, 0xc000
	v_lshl_add_u64 v[130:131], v[130:131], 0, s[50:51]
	global_load_lds_dwordx4 v[132:133], off
	s_add_i32 m0, s3, 0xe000
	s_nop 0
	global_load_lds_dwordx4 v[130:131], off

; DI f32x16 mfma(bf16x8 a, bf16x8 b, f32x16 c) { return __builtin_amdgcn_mfma_f32_32x32x16_bf16(a, b, c, 0, 0, 0); }
; template <int BK> DI int swz(int row) { constexpr int CPR = BK / 8; return (row / (16 / CPR)) % CPR; }
; DI void wait_vm0() { asm volatile("s_waitcnt vmcnt(0)" ::: "memory"); }
;   DI void pre(int grow0, int gcol0, int lane, int w, char* lds) { xpass(0, grow0, gcol0, lane, w, lds); }
;     ...
;   for (int kt = 0; kt < nk; ++kt) {
;     char* cur = lds + (kt & 1) * STG; char* nxt = lds + ((kt + 1) & 1) * STG;
;     const bool more = kt + 1 < nk;
;     const bf16_t* An = Ag + (kt + 1) * BK; const bf16_t* Bn = Bg + (kt + 1) * BK;
;     if (!more) epi.pre(row0 + wm * 64, col0 + wn * (32 * NTW), lane, w, lds);
;     bf16x8 fa[2][2], fb[2][NTW];
; #pragma unroll
;     for (int mt = 0; mt < 2; ++mt) { int row = wm * 64 + mt * 32 + l31; fa[0][mt] = *(const bf16x8*)(cur + row * (BK * 2) + ((hh ^ swz<BK>(row)) << 4)); }
; #pragma unroll
;     for (int nt = 0; nt < NTW; ++nt) { int row = wn * (32 * NTW) + nt * 32 + l31; fb[0][nt] = *(const bf16x8*)(cur + ABYTES + row * (BK * 2) + ((hh ^ swz<BK>(row)) << 4)); }
; #pragma unroll
;     for (int kk = 0; kk < NKK; ++kk) {
;       if (kk + 1 < NKK) {
;         const int ch = (kk + 1) * 2 + hh;
; #pragma unroll
;         for (int mt = 0; mt < 2; ++mt) { int row = wm * 64 + mt * 32 + l31; fa[(kk + 1) & 1][mt] = *(const bf16x8*)(cur + row * (BK * 2) + ((ch ^ swz<BK>(row)) << 4)); }
; #pragma unroll
;         for (int nt = 0; nt < NTW; ++nt) { int row = wn * (32 * NTW) + nt * 32 + l31; fb[(kk + 1) & 1][nt] = *(const bf16x8*)(cur + ABYTES + row * (BK * 2) + ((ch ^ swz<BK>(row)) << 4)); }
;       }
;       if (more) {
; #pragma unroll
;         for (int q = 0; q < PPK; ++q) {
;           const int pi = kk * PPK + q;
;           if (pi < NPA) stage_piece<BM, BK>(An, lda, nxt, tid, pi, wv);
;           else if (pi < NP) stage_piece<BN, BK>(Bn, ldb, nxt + ABYTES, tid, pi - NPA, wv);
;         }
;       }
;       __builtin_amdgcn_s_setprio(1);
; #pragma unroll
;       for (int mt = 0; mt < 2; ++mt)
; #pragma unroll
;         for (int nt = 0; nt < NTW; ++nt) acc[mt][nt] = mfma(fa[kk & 1][mt], fb[kk & 1][nt], acc[mt][nt]);
;       __builtin_amdgcn_s_setprio(0);
;       __builtin_amdgcn_sched_barrier(0);
;     }
;     wait_vm0();
;     __syncthreads();
;   }
.Lk519_exit:
	v_add3_u32 v166, s42, v140, v141
	v_add3_u32 v170, s42, v142, v144
	ds_read_b128 v[166:169], v166
	v_add3_u32 v174, s42, v143, v151
	ds_read_b128 v[170:173], v170
	v_add3_u32 v178, s42, v152, v154
	ds_read_b128 v[174:177], v174 offset:32768
	v_add3_u32 v182, s42, v153, v155
	ds_read_b128 v[178:181], v178 offset:32768
	v_add3_u32 v186, s42, v156, v164
	ds_read_b128 v[182:185], v182 offset:32768
	ds_read_b128 v[186:189], v186 offset:32768
	v_mfma_f32_32x32x16_bf16 v[114:129], v[190:193], v[198:201], v[114:129]
	v_mfma_f32_32x32x16_bf16 v[98:113], v[190:193], v[202:205], v[98:113]
	v_mfma_f32_32x32x16_bf16 v[82:97], v[190:193], v[206:209], v[82:97]
	v_mfma_f32_32x32x16_bf16 v[66:81], v[190:193], v[210:213], v[66:81]
	v_mfma_f32_32x32x16_bf16 v[50:65], v[194:197], v[198:201], v[50:65]
	v_mfma_f32_32x32x16_bf16 v[34:49], v[194:197], v[202:205], v[34:49]
	v_mfma_f32_32x32x16_bf16 v[18:33], v[194:197], v[206:209], v[18:33]
	v_mfma_f32_32x32x16_bf16 v[2:17], v[194:197], v[210:213], v[2:17]
	s_waitcnt lgkmcnt(0)
	v_add_u32_e32 v0, 0x10000, v140
	v_add_u32_e32 v198, 0x10000, v142
	v_add_u32_e32 v130, v0, v141
	v_add_u32_e32 v140, v198, v144
	v_add_u32_e32 v199, 0x18000, v143
	v_add_u32_e32 v200, 0x18000, v152
	ds_read_b128 v[130:133], v130
	ds_read_b128 v[166:169], v140
	v_add_u32_e32 v140, v199, v151
	v_add_u32_e32 v144, v200, v154
	v_add_u32_e32 v201, 0x18000, v153
	ds_read_b128 v[140:143], v140
	ds_read_b128 v[170:173], v144
	v_add_u32_e32 v144, v201, v155
	v_add_u32_e32 v202, 0x18000, v156
	v_add_u32_e32 v151, v202, v164
	ds_read_b128 v[152:155], v144
	ds_read_b128 v[174:177], v151
	v_add_u32_e32 v144, v0, v161
	v_add_u32_e32 v151, v198, v163
	ds_read_b128 v[178:181], v144
	ds_read_b128 v[182:185], v151
	v_add_u32_e32 v144, v199, v159
	v_add_u32_e32 v151, v200, v160
	ds_read_b128 v[186:189], v144
	ds_read_b128 v[190:193], v151
	v_add_u32_e32 v144, v201, v157
	v_add_u32_e32 v151, v202, v158
	ds_read_b128 v[156:159], v144
	ds_read_b128 v[194:197], v151
	s_add_i32 s36, s36, s94
	s_cmpk_gt_i32 s36, 0x2ff
	s_cselect_b64 s[42:43], -1, 0
	s_cmpk_lt_i32 s36, 0x300
	s_setprio 1
	s_waitcnt lgkmcnt(9)
	v_mfma_f32_32x32x16_bf16 v[114:129], v[130:133], v[140:143], v[114:129]
	s_waitcnt lgkmcnt(8)
	v_mfma_f32_32x32x16_bf16 v[98:113], v[130:133], v[170:173], v[98:113]
	s_waitcnt lgkmcnt(7)
	v_mfma_f32_32x32x16_bf16 v[82:97], v[130:133], v[152:155], v[82:97]
	s_waitcnt lgkmcnt(6)
	v_mfma_f32_32x32x16_bf16 v[66:81], v[130:133], v[174:177], v[66:81]
	v_mfma_f32_32x32x16_bf16 v[50:65], v[166:169], v[140:143], v[50:65]
	v_mfma_f32_32x32x16_bf16 v[34:49], v[166:169], v[170:173], v[34:49]
	v_mfma_f32_32x32x16_bf16 v[18:33], v[166:169], v[152:155], v[18:33]
	v_mfma_f32_32x32x16_bf16 v[2:17], v[166:169], v[174:177], v[2:17]
	s_setprio 0
	v_add_u32_e32 v130, v0, v149
	v_add_u32_e32 v140, v198, v150
	v_add_u32_e32 v144, v199, v147
	ds_read_b128 v[130:133], v130
	ds_read_b128 v[140:143], v140
	v_add_u32_e32 v147, v200, v148
	ds_read_b128 v[148:151], v144
	ds_read_b128 v[152:155], v147
	v_add_u32_e32 v144, v201, v145
	v_add_u32_e32 v160, v202, v146
	ds_read_b128 v[144:147], v144
	ds_read_b128 v[166:169], v160
	s_setprio 1
	s_waitcnt lgkmcnt(9)
	v_mfma_f32_32x32x16_bf16 v[114:129], v[178:181], v[186:189], v[114:129]
	s_waitcnt lgkmcnt(8)
	v_mfma_f32_32x32x16_bf16 v[98:113], v[178:181], v[190:193], v[98:113]
	s_waitcnt lgkmcnt(7)
	v_mfma_f32_32x32x16_bf16 v[82:97], v[178:181], v[156:159], v[82:97]
	s_waitcnt lgkmcnt(6)
	v_mfma_f32_32x32x16_bf16 v[66:81], v[178:181], v[194:197], v[66:81]
	v_mfma_f32_32x32x16_bf16 v[50:65], v[182:185], v[186:189], v[50:65]
	v_mfma_f32_32x32x16_bf16 v[34:49], v[182:185], v[190:193], v[34:49]
	v_mfma_f32_32x32x16_bf16 v[18:33], v[182:185], v[156:159], v[18:33]
	v_mfma_f32_32x32x16_bf16 v[2:17], v[182:185], v[194:197], v[2:17]
	s_setprio 0
	v_add_u32_e32 v0, v0, v138
	v_add_u32_e32 v138, v198, v139
	ds_read_b128 v[156:159], v0
	ds_read_b128 v[170:173], v138
	v_add_u32_e32 v0, v199, v136
	v_add_u32_e32 v160, v200, v137
	ds_read_b128 v[136:139], v0
	ds_read_b128 v[174:177], v160
	v_add_u32_e32 v0, v201, v134
	v_add_u32_e32 v134, v202, v135
	ds_read_b128 v[178:181], v0
	ds_read_b128 v[182:185], v134
	s_setprio 1
	s_waitcnt lgkmcnt(9)
	v_mfma_f32_32x32x16_bf16 v[114:129], v[130:133], v[148:151], v[114:129]
	s_waitcnt lgkmcnt(8)
	v_mfma_f32_32x32x16_bf16 v[98:113], v[130:133], v[152:155], v[98:113]
	s_waitcnt lgkmcnt(7)
	v_mfma_f32_32x32x16_bf16 v[82:97], v[130:133], v[144:147], v[82:97]
	s_waitcnt lgkmcnt(6)
	v_mfma_f32_32x32x16_bf16 v[66:81], v[130:133], v[166:169], v[66:81]
	v_mfma_f32_32x32x16_bf16 v[50:65], v[140:143], v[148:151], v[50:65]
	v_mfma_f32_32x32x16_bf16 v[34:49], v[140:143], v[152:155], v[34:49]
	v_mfma_f32_32x32x16_bf16 v[18:33], v[140:143], v[144:147], v[18:33]
	v_mfma_f32_32x32x16_bf16 v[2:17], v[140:143], v[166:169], v[2:17]
	s_setprio 0
	s_setprio 1
	s_waitcnt lgkmcnt(3)
	v_mfma_f32_32x32x16_bf16 v[114:129], v[156:159], v[136:139], v[114:129]
	s_waitcnt lgkmcnt(2)
	v_mfma_f32_32x32x16_bf16 v[98:113], v[156:159], v[174:177], v[98:113]
	s_waitcnt lgkmcnt(1)
	v_mfma_f32_32x32x16_bf16 v[82:97], v[156:159], v[178:181], v[82:97]
	s_waitcnt lgkmcnt(0)
	v_mfma_f32_32x32x16_bf16 v[66:81], v[156:159], v[182:185], v[66:81]
	v_mfma_f32_32x32x16_bf16 v[50:65], v[170:173], v[136:139], v[50:65]
	v_mfma_f32_32x32x16_bf16 v[34:49], v[170:173], v[174:177], v[34:49]
	v_mfma_f32_32x32x16_bf16 v[18:33], v[170:173], v[178:181], v[18:33]
	v_mfma_f32_32x32x16_bf16 v[2:17], v[170:173], v[182:185], v[2:17]
	s_setprio 0
	s_waitcnt vmcnt(0)
	s_barrier
; DI int launder(int x) { asm volatile("" : "+v"(x)); return x; }
;   DI void pre(int grow0, int gcol0, int lane, int w, char* lds) { xpass(0, grow0, gcol0, lane, w, lds); }
;     ...
;   if (has_next) { const int tid3 = launder(threadIdx.x); stage_tile<BM, BK>(A + (size_t)row0n * lda, lda, lds, tid3); stage_tile<BN, BK>(Bt + (size_t)col0n * ldb, ldb, lds + ABYTES, tid3); }
; template <class Epi>
; DI void gemm_phase256(const bf16_t* A, int lda, const bf16_t* Bt, int K, int nN, char* lds, Epi& epi, int vb) {
;     ...
;     const int x = t & 7, L = t >> 3; const int pm = 8 * x + (L & 7), pn = L >> 3;
;     const int t2 = t + gridDim.x; const bool hn = t2 < ntiles;
;     const int x2 = t2 & 7, L2 = t2 >> 3; const int pm2 = 8 * x2 + (L2 & 7), pn2 = L2 >> 3;
;     gemm_tile<4, 64>(A, lda, Bt, K, K, pm * 256, pn * 256, lds, epi, pre, hn, pm2 * 256, pn2 * 256);
	s_cbranch_scc0 .LBB0_522
	v_mov_b32_e32 v132, v216
	s_lshl_b32 s3, s36, 3
	v_ashrrev_i32_e32 v0, 31, v132
	v_lshrrev_b32_e32 v130, 29, v0
	v_lshrrev_b32_e32 v0, 28, v0
	v_add_u32_e32 v0, v132, v0
	v_ashrrev_i32_e32 v0, 4, v0
	s_and_b32 s3, s3, 56
	s_bfe_u32 s7, s36, 0x30003
	v_lshrrev_b32_e32 v133, 29, v0
	s_or_b32 s3, s3, s7
	s_lshl_b32 s7, s36, 2
	v_add_u32_e32 v130, v132, v130
	v_add_u32_e32 v133, v0, v133
	s_and_b32 s30, s7, 0xffffff00
	s_lshl_b32 s3, s3, 19
	v_and_b32_e32 v131, 0xffffff8, v130
	v_and_b32_e32 v133, 0xffffff8, v133
	s_add_u32 s44, s12, s3
	v_sub_u32_e32 v131, v132, v131
	v_sub_u32_e32 v0, v0, v133
	v_lshlrev_b32_e32 v130, 8, v130
	v_readfirstlane_b32 s3, v132
	s_addc_u32 s45, s13, 0
	v_xor_b32_e32 v0, v0, v131
	v_and_b32_e32 v130, 0xfffff800, v130
	s_lshl_b32 s3, s3, 4
	v_lshl_add_u32 v0, v0, 4, v130
	s_and_b32 s3, s3, 0xfffffc00
	v_lshl_add_u64 v[130:131], s[44:45], 0, v[0:1]
	s_mov_b32 m0, s3
	v_lshl_add_u64 v[132:133], v[130:131], 0, s[58:59]
	global_load_lds_dwordx4 v0, s[44:45]
	s_add_i32 m0, s3, 0x2000
	s_ashr_i32 s31, s30, 31
	global_load_lds_dwordx4 v[132:133], off
	v_lshl_add_u64 v[132:133], v[130:131], 0, s[48:49]
	s_add_i32 m0, s3, 0x4000
	s_lshl_b64 s[30:31], s[30:31], 11
	global_load_lds_dwordx4 v[132:133], off
	s_add_i32 m0, s3, 0x6000
	s_add_u32 s30, s40, s30
	v_lshl_add_u64 v[130:131], v[130:131], 0, s[50:51]
	s_addc_u32 s31, s41, s31
	global_load_lds_dwordx4 v[130:131], off
	v_lshl_add_u64 v[130:131], s[30:31], 0, v[0:1]
	s_add_i32 m0, s3, 0x8000
	v_lshl_add_u64 v[132:133], v[130:131], 0, s[58:59]
	global_load_lds_dwordx4 v0, s[30:31]
	s_add_i32 m0, s3, 0xa000
	s_nop 0
	global_load_lds_dwordx4 v[132:133], off
	v_lshl_add_u64 v[132:133], v[130:131], 0, s[48:49]
	s_add_i32 m0, s3, 0xc000
	v_lshl_add_u64 v[130:131], v[130:131], 0, s[50:51]
	global_load_lds_dwordx4 v[132:133], off
	s_add_i32 m0, s3, 0xe000
	s_nop 0
	global_load_lds_dwordx4 v[130:131], off

; DI f32x16 mfma(bf16x8 a, bf16x8 b, f32x16 c) { return __builtin_amdgcn_mfma_f32_32x32x16_bf16(a, b, c, 0, 0, 0); }
; template <int BK> DI int swz(int row) { constexpr int CPR = BK / 8; return (row / (16 / CPR)) % CPR; }
;   DI void pre(int grow0, int gcol0, int lane, int w, char* lds) { xpass(0, grow0, gcol0, lane, w, lds); }
;     ...
;   for (int kt = 0; kt < nk; ++kt) {
;     char* cur = lds + (kt & 1) * STG; char* nxt = lds + ((kt + 1) & 1) * STG;
;     const bool more = kt + 1 < nk;
;     const bf16_t* An = Ag + (kt + 1) * BK; const bf16_t* Bn = Bg + (kt + 1) * BK;
;     if (!more) epi.pre(row0 + wm * 64, col0 + wn * (32 * NTW), lane, w, lds);
;     bf16x8 fa[2][2], fb[2][NTW];
; #pragma unroll
;     for (int mt = 0; mt < 2; ++mt) { int row = wm * 64 + mt * 32 + l31; fa[0][mt] = *(const bf16x8*)(cur + row * (BK * 2) + ((hh ^ swz<BK>(row)) << 4)); }
; #pragma unroll
;     for (int nt = 0; nt < NTW; ++nt) { int row = wn * (32 * NTW) + nt * 32 + l31; fb[0][nt] = *(const bf16x8*)(cur + ABYTES + row * (BK * 2) + ((hh ^ swz<BK>(row)) << 4)); }
; #pragma unroll
;     for (int kk = 0; kk < NKK; ++kk) {
;       if (kk + 1 < NKK) {
;         const int ch = (kk + 1) * 2 + hh;
; #pragma unroll
;         for (int mt = 0; mt < 2; ++mt) { int row = wm * 64 + mt * 32 + l31; fa[(kk + 1) & 1][mt] = *(const bf16x8*)(cur + row * (BK * 2) + ((ch ^ swz<BK>(row)) << 4)); }
; #pragma unroll
;         for (int nt = 0; nt < NTW; ++nt) { int row = wn * (32 * NTW) + nt * 32 + l31; fb[(kk + 1) & 1][nt] = *(const bf16x8*)(cur + ABYTES + row * (BK * 2) + ((ch ^ swz<BK>(row)) << 4)); }
;       }
;       if (more) {
; #pragma unroll
;         for (int q = 0; q < PPK; ++q) {
;           const int pi = kk * PPK + q;
;           if (pi < NPA) stage_piece<BM, BK>(An, lda, nxt, tid, pi, wv);
;           else if (pi < NP) stage_piece<BN, BK>(Bn, ldb, nxt + ABYTES, tid, pi - NPA, wv);
;         }
;       }
;       __builtin_amdgcn_s_setprio(1);
; #pragma unroll
;       for (int mt = 0; mt < 2; ++mt)
; #pragma unroll
;         for (int nt = 0; nt < NTW; ++nt) acc[mt][nt] = mfma(fa[kk & 1][mt], fb[kk & 1][nt], acc[mt][nt]);
;       __builtin_amdgcn_s_setprio(0);
;       __builtin_amdgcn_sched_barrier(0);
;     }
.LBB0_532:
	s_and_b32 s7, s3, 0x10000
	s_xor_b32 s100, s7, 0x10000
	v_add3_u32 v194, s100, v136, v166
	v_add3_u32 v198, s100, v144, v167
	ds_read_b128 v[194:197], v194
	v_add3_u32 v202, s100, v145, v163
	ds_read_b128 v[198:201], v198
	v_add3_u32 v206, s100, v150, v164
	ds_read_b128 v[202:205], v202 offset:32768
	v_add3_u32 v210, s100, v156, v159
	ds_read_b128 v[206:209], v206 offset:32768
	v_add3_u32 v226, s100, v158, v160
	ds_read_b128 v[210:213], v210 offset:32768
	ds_read_b128 v[226:229], v226 offset:32768
	s_waitcnt lgkmcnt(6)
	s_mov_b32 m0, s101
	v_mov_b64_e32 v[232:233], v[230:231]
	v_mfma_f32_32x32x16_bf16 v[114:129], v[170:173], v[178:181], v[114:129]
	global_load_lds_dwordx4 v[232:233], off
	v_mfma_f32_32x32x16_bf16 v[98:113], v[170:173], v[182:185], v[98:113]
	s_add_i32 m0, s101, 0x2000
	v_lshl_add_u64 v[232:233], v[230:231], 0, s[36:37]
	v_mfma_f32_32x32x16_bf16 v[82:97], v[170:173], v[186:189], v[82:97]
	global_load_lds_dwordx4 v[232:233], off
	v_mfma_f32_32x32x16_bf16 v[66:81], v[170:173], v[190:193], v[66:81]
	s_add_i32 m0, s101, 0x4000
	v_lshl_add_u64 v[232:233], v[230:231], 0, s[40:41]
	v_mfma_f32_32x32x16_bf16 v[50:65], v[174:177], v[178:181], v[50:65]
	global_load_lds_dwordx4 v[232:233], off
	v_mfma_f32_32x32x16_bf16 v[34:49], v[174:177], v[182:185], v[34:49]
	s_add_i32 m0, s101, 0x6000
	v_lshl_add_u64 v[232:233], v[230:231], 0, s[34:35]
	v_mfma_f32_32x32x16_bf16 v[18:33], v[174:177], v[186:189], v[18:33]
	global_load_lds_dwordx4 v[232:233], off
	v_mfma_f32_32x32x16_bf16 v[2:17], v[174:177], v[190:193], v[2:17]
	v_add3_u32 v170, s100, v136, v153
	v_add3_u32 v174, s100, v144, v154
	ds_read_b128 v[170:173], v170
	v_add3_u32 v178, s100, v145, v151
	ds_read_b128 v[174:177], v174
	v_add3_u32 v182, s100, v150, v152
	ds_read_b128 v[178:181], v178 offset:32768
	v_add3_u32 v186, s100, v156, v147
	ds_read_b128 v[182:185], v182 offset:32768
	v_add3_u32 v190, s100, v158, v148
	ds_read_b128 v[186:189], v186 offset:32768
	ds_read_b128 v[190:193], v190 offset:32768
	s_waitcnt lgkmcnt(6)
	v_mfma_f32_32x32x16_bf16 v[114:129], v[194:197], v[202:205], v[114:129]
	v_mfma_f32_32x32x16_bf16 v[98:113], v[194:197], v[206:209], v[98:113]
	v_mfma_f32_32x32x16_bf16 v[82:97], v[194:197], v[210:213], v[82:97]
	v_mfma_f32_32x32x16_bf16 v[66:81], v[194:197], v[226:229], v[66:81]
	v_mfma_f32_32x32x16_bf16 v[50:65], v[198:201], v[202:205], v[50:65]
	v_mfma_f32_32x32x16_bf16 v[34:49], v[198:201], v[206:209], v[34:49]
	v_mfma_f32_32x32x16_bf16 v[18:33], v[198:201], v[210:213], v[18:33]
	v_mfma_f32_32x32x16_bf16 v[2:17], v[198:201], v[226:229], v[2:17]
	v_add3_u32 v194, s100, v136, v141
	v_add3_u32 v198, s100, v144, v142
	ds_read_b128 v[194:197], v194
	v_add3_u32 v202, s100, v145, v139
	ds_read_b128 v[198:201], v198
	v_add3_u32 v206, s100, v150, v140
	ds_read_b128 v[202:205], v202 offset:32768
	v_add3_u32 v210, s100, v156, v137
	ds_read_b128 v[206:209], v206 offset:32768
	v_add3_u32 v226, s100, v158, v138
	ds_read_b128 v[210:213], v210 offset:32768
	ds_read_b128 v[226:229], v226 offset:32768
	s_waitcnt lgkmcnt(6)
	v_mfma_f32_32x32x16_bf16 v[114:129], v[170:173], v[178:181], v[114:129]
	v_mfma_f32_32x32x16_bf16 v[98:113], v[170:173], v[182:185], v[98:113]
	v_mfma_f32_32x32x16_bf16 v[82:97], v[170:173], v[186:189], v[82:97]
	v_mfma_f32_32x32x16_bf16 v[66:81], v[170:173], v[190:193], v[66:81]
	v_mfma_f32_32x32x16_bf16 v[50:65], v[174:177], v[178:181], v[50:65]
	v_mfma_f32_32x32x16_bf16 v[34:49], v[174:177], v[182:185], v[34:49]
	v_mfma_f32_32x32x16_bf16 v[18:33], v[174:177], v[186:189], v[18:33]
	v_mfma_f32_32x32x16_bf16 v[2:17], v[174:177], v[190:193], v[2:17]
	s_add_i32 s6, s6, -1
	s_add_i32 s92, s92, 64
	s_add_i32 s3, s3, 0x10000
	s_waitcnt vmcnt(0) lgkmcnt(0)
	s_barrier
	s_cmp_lg_u32 s6, 0
	s_cbranch_scc0 .Lk532_exit
	s_add_i32 s101, s100, s2
	s_lshl_b64 s[30:31], s[92:93], 1
	v_lshl_add_u64 v[230:231], v[130:131], 0, s[30:31]
	v_lshl_add_u64 v[214:215], v[132:133], 0, s[30:31]
	s_add_i32 m0, s101, 0x8000
	v_mov_b64_e32 v[232:233], v[214:215]
	v_mfma_f32_32x32x16_bf16 v[114:129], v[194:197], v[202:205], v[114:129]
	global_load_lds_dwordx4 v[232:233], off
	v_add3_u32 v170, s7, v136, v143
	v_add3_u32 v174, s7, v144, v146
	ds_read_b128 v[170:173], v170
	v_add3_u32 v178, s7, v145, v149
	ds_read_b128 v[174:177], v174
	v_add3_u32 v182, s7, v150, v155
	ds_read_b128 v[178:181], v178 offset:32768
	v_add3_u32 v186, s7, v156, v157
	ds_read_b128 v[182:185], v182 offset:32768
	v_add3_u32 v190, s7, v158, v168
	ds_read_b128 v[186:189], v186 offset:32768
	ds_read_b128 v[190:193], v190 offset:32768
	v_mfma_f32_32x32x16_bf16 v[98:113], v[194:197], v[206:209], v[98:113]
	s_add_i32 m0, s101, 0xa000
	v_lshl_add_u64 v[232:233], v[214:215], 0, s[36:37]
	v_mfma_f32_32x32x16_bf16 v[82:97], v[194:197], v[210:213], v[82:97]
	global_load_lds_dwordx4 v[232:233], off
	v_mfma_f32_32x32x16_bf16 v[66:81], v[194:197], v[226:229], v[66:81]
	s_add_i32 m0, s101, 0xc000
	v_lshl_add_u64 v[232:233], v[214:215], 0, s[40:41]
	v_mfma_f32_32x32x16_bf16 v[50:65], v[198:201], v[202:205], v[50:65]
	global_load_lds_dwordx4 v[232:233], off
	v_mfma_f32_32x32x16_bf16 v[34:49], v[198:201], v[206:209], v[34:49]
	s_add_i32 m0, s101, 0xe000
	v_lshl_add_u64 v[232:233], v[214:215], 0, s[34:35]
	v_mfma_f32_32x32x16_bf16 v[18:33], v[198:201], v[210:213], v[18:33]
	global_load_lds_dwordx4 v[232:233], off
	v_mfma_f32_32x32x16_bf16 v[2:17], v[198:201], v[226:229], v[2:17]
	s_branch .LBB0_532
; DI void wait_vm0() { asm volatile("s_waitcnt vmcnt(0)" ::: "memory"); }
;     ...
;     if (!more) epi.pre(row0 + wm * 64, col0 + wn * (32 * NTW), lane, w, lds);
;     bf16x8 fa[2][2], fb[2][NTW];
; #pragma unroll
;     for (int mt = 0; mt < 2; ++mt) { int row = wm * 64 + mt * 32 + l31; fa[0][mt] = *(const bf16x8*)(cur + row * (BK * 2) + ((hh ^ swz<BK>(row)) << 4)); }
; #pragma unroll
;     for (int nt = 0; nt < NTW; ++nt) { int row = wn * (32 * NTW) + nt * 32 + l31; fb[0][nt] = *(const bf16x8*)(cur + ABYTES + row * (BK * 2) + ((hh ^ swz<BK>(row)) << 4)); }
; #pragma unroll
;     for (int kk = 0; kk < NKK; ++kk) {
;       if (kk + 1 < NKK) {
;         const int ch = (kk + 1) * 2 + hh;
; #pragma unroll
;         for (int mt = 0; mt < 2; ++mt) { int row = wm * 64 + mt * 32 + l31; fa[(kk + 1) & 1][mt] = *(const bf16x8*)(cur + row * (BK * 2) + ((ch ^ swz<BK>(row)) << 4)); }
; #pragma unroll
;         for (int nt = 0; nt < NTW; ++nt) { int row = wn * (32 * NTW) + nt * 32 + l31; fb[(kk + 1) & 1][nt] = *(const bf16x8*)(cur + ABYTES + row * (BK * 2) + ((ch ^ swz<BK>(row)) << 4)); }
;       }
;       if (more) {
; #pragma unroll
;         for (int q = 0; q < PPK; ++q) {
;           const int pi = kk * PPK + q;
;           if (pi < NPA) stage_piece<BM, BK>(An, lda, nxt, tid, pi, wv);
;           else if (pi < NP) stage_piece<BN, BK>(Bn, ldb, nxt + ABYTES, tid, pi - NPA, wv);
;         }
;       }
;       __builtin_amdgcn_s_setprio(1);
; #pragma unroll
;       for (int mt = 0; mt < 2; ++mt)
; #pragma unroll
;         for (int nt = 0; nt < NTW; ++nt) acc[mt][nt] = mfma(fa[kk & 1][mt], fb[kk & 1][nt], acc[mt][nt]);
;       __builtin_amdgcn_s_setprio(0);
;       __builtin_amdgcn_sched_barrier(0);
;     }
;     wait_vm0();
;     __syncthreads();
;   }
;   DI void xpass(int ps, int grow0, int gcol0, int lane, int w, char* lds) const {
;     char* xs = lds + (ps & 1) * 65536 + __builtin_amdgcn_readfirstlane(w) * 8192;
;     const float* xsrc = Xin + (size_t)(grow0 + (ps >> 1) * 32 + (ps & 1) * 16 + (lane >> 5)) * D_ + gcol0 + (lane & 31) * 4;
; #pragma unroll
;     for (int pc = 0; pc < 8; ++pc)
;       __builtin_amdgcn_global_load_lds((const unsigned*)(xsrc + (size_t)(2 * pc) * D_), (__attribute__((address_space(3))) unsigned*)(xs + pc * 1024), 16, 0, 0);
;   }
;   DI void pre(int grow0, int gcol0, int lane, int w, char* lds) { xpass(0, grow0, gcol0, lane, w, lds); }
.Lk532_exit:
	v_add3_u32 v170, s7, v136, v143
	v_add3_u32 v174, s7, v144, v146
	ds_read_b128 v[170:173], v170
	v_add3_u32 v178, s7, v145, v149
	ds_read_b128 v[174:177], v174
	v_add3_u32 v182, s7, v150, v155
	ds_read_b128 v[178:181], v178 offset:32768
	v_add3_u32 v186, s7, v156, v157
	ds_read_b128 v[182:185], v182 offset:32768
	v_add3_u32 v190, s7, v158, v168
	ds_read_b128 v[186:189], v186 offset:32768
	ds_read_b128 v[190:193], v190 offset:32768
	v_mfma_f32_32x32x16_bf16 v[114:129], v[194:197], v[202:205], v[114:129]
	v_mfma_f32_32x32x16_bf16 v[98:113], v[194:197], v[206:209], v[98:113]
	v_mfma_f32_32x32x16_bf16 v[82:97], v[194:197], v[210:213], v[82:97]
	v_mfma_f32_32x32x16_bf16 v[66:81], v[194:197], v[226:229], v[66:81]
	v_mfma_f32_32x32x16_bf16 v[50:65], v[198:201], v[202:205], v[50:65]
	v_mfma_f32_32x32x16_bf16 v[34:49], v[198:201], v[206:209], v[34:49]
	v_mfma_f32_32x32x16_bf16 v[18:33], v[198:201], v[210:213], v[18:33]
	v_mfma_f32_32x32x16_bf16 v[2:17], v[198:201], v[226:229], v[2:17]
	s_waitcnt lgkmcnt(0)
	v_readlane_b32 s3, v253, 9
	v_readlane_b32 s30, v253, 27
	v_readfirstlane_b32 s2, v134
	v_or_b32_e32 v130, s3, v135
	v_add_u32_e32 v130, v130, v169
	v_ashrrev_i32_e32 v131, 31, v130
	v_lshlrev_b64 v[130:131], 12, v[130:131]
	v_add_u32_e32 v132, s30, v161
	v_ashrrev_i32_e32 v133, 31, v132
	v_lshl_add_u64 v[130:131], s[10:11], 0, v[130:131]
	v_lshlrev_b32_e32 v0, 4, v0
	s_lshl_b32 s2, s2, 13
	v_lshl_add_u64 v[130:131], v[132:133], 2, v[130:131]
	v_and_b32_e32 v132, 0x1f0, v0
	v_mov_b32_e32 v133, v1
	v_lshl_add_u64 v[130:131], v[130:131], 0, v[132:133]
	s_mov_b32 m0, s2
	s_mov_b64 s[34:35], 0x2000
	global_load_lds_dwordx4 v[130:131], off
	v_lshl_add_u64 v[132:133], v[130:131], 0, s[34:35]
	s_or_b32 m0, s2, 0x400
	s_mov_b64 s[36:37], 0x4000
	global_load_lds_dwordx4 v[132:133], off
	v_lshl_add_u64 v[132:133], v[130:131], 0, s[36:37]
	s_or_b32 m0, s2, 0x800
	s_mov_b64 s[40:41], 0x6000
	global_load_lds_dwordx4 v[132:133], off
	v_lshl_add_u64 v[132:133], v[130:131], 0, s[40:41]
	s_or_b32 m0, s2, 0xc00
	s_mov_b64 s[44:45], 0x8000
	global_load_lds_dwordx4 v[132:133], off
	v_lshl_add_u64 v[132:133], v[130:131], 0, s[44:45]
	s_or_b32 m0, s2, 0x1000
	s_mov_b64 s[46:47], 0xa000
	global_load_lds_dwordx4 v[132:133], off
	v_lshl_add_u64 v[132:133], v[130:131], 0, s[46:47]
	s_or_b32 m0, s2, 0x1400
	s_mov_b64 s[52:53], 0xc000
	global_load_lds_dwordx4 v[132:133], off
	v_lshl_add_u64 v[132:133], v[130:131], 0, s[52:53]
	s_or_b32 m0, s2, 0x1800
	s_mov_b64 s[54:55], 0xe000
	global_load_lds_dwordx4 v[132:133], off
	v_lshl_add_u64 v[130:131], v[130:131], 0, s[54:55]
	s_or_b32 m0, s2, 0x1c00
	v_add_u32_e32 v0, s7, v136
	global_load_lds_dwordx4 v[130:131], off
	v_add_u32_e32 v134, s7, v144
	v_add_u32_e32 v130, v0, v143
	v_add_u32_e32 v135, v134, v146
	ds_read_b128 v[130:133], v130
	ds_read_b128 v[170:173], v135
	v_add_u32_e32 v135, s7, v145
	v_add_u32_e32 v136, v135, v149
	v_add_u32_e32 v143, s7, v150
	v_add_u32_e32 v144, v143, v155
	ds_read_b128 v[174:177], v136 offset:32768
	ds_read_b128 v[178:181], v144 offset:32768
	v_add_u32_e32 v136, s7, v156
	v_add_u32_e32 v144, v136, v157
	v_add_u32_e32 v149, s7, v158
	v_add_u32_e32 v145, v149, v168
	ds_read_b128 v[182:185], v144 offset:32768
	ds_read_b128 v[186:189], v145 offset:32768
	v_add_u32_e32 v144, v0, v166
	v_add_u32_e32 v145, v134, v167
	ds_read_b128 v[166:169], v144
	ds_read_b128 v[190:193], v145
	v_add_u32_e32 v144, v135, v163
	v_add_u32_e32 v145, v143, v164
	ds_read_b128 v[194:197], v144 offset:32768
	ds_read_b128 v[198:201], v145 offset:32768
	v_add_u32_e32 v144, v136, v159
	v_add_u32_e32 v145, v149, v160
	ds_read_b128 v[156:159], v144 offset:32768
	ds_read_b128 v[202:205], v145 offset:32768
	v_readlane_b32 s31, v253, 28
	s_setprio 1
	s_waitcnt lgkmcnt(0)
	v_mfma_f32_32x32x16_bf16 v[114:129], v[130:133], v[174:177], v[114:129]
	v_mfma_f32_32x32x16_bf16 v[98:113], v[130:133], v[178:181], v[98:113]
	v_mfma_f32_32x32x16_bf16 v[82:97], v[130:133], v[182:185], v[82:97]
	v_mfma_f32_32x32x16_bf16 v[66:81], v[130:133], v[186:189], v[66:81]
	v_mfma_f32_32x32x16_bf16 v[50:65], v[170:173], v[174:177], v[50:65]
	v_mfma_f32_32x32x16_bf16 v[34:49], v[170:173], v[178:181], v[34:49]
	v_mfma_f32_32x32x16_bf16 v[18:33], v[170:173], v[182:185], v[18:33]
	v_mfma_f32_32x32x16_bf16 v[2:17], v[170:173], v[186:189], v[2:17]
	s_setprio 0
	v_add_u32_e32 v130, v0, v153
	v_add_u32_e32 v144, v134, v154
	ds_read_b128 v[130:133], v130
	ds_read_b128 v[170:173], v144
	v_add_u32_e32 v144, v135, v151
	v_add_u32_e32 v145, v143, v152
	ds_read_b128 v[150:153], v144 offset:32768
	ds_read_b128 v[174:177], v145 offset:32768
	v_add_u32_e32 v144, v136, v147
	v_add_u32_e32 v148, v149, v148
	ds_read_b128 v[144:147], v144 offset:32768
	ds_read_b128 v[178:181], v148 offset:32768
	s_setprio 1
	v_mfma_f32_32x32x16_bf16 v[114:129], v[166:169], v[194:197], v[114:129]
	v_mfma_f32_32x32x16_bf16 v[98:113], v[166:169], v[198:201], v[98:113]
	v_mfma_f32_32x32x16_bf16 v[82:97], v[166:169], v[156:159], v[82:97]
	v_mfma_f32_32x32x16_bf16 v[66:81], v[166:169], v[202:205], v[66:81]
	v_mfma_f32_32x32x16_bf16 v[50:65], v[190:193], v[194:197], v[50:65]
	v_mfma_f32_32x32x16_bf16 v[34:49], v[190:193], v[198:201], v[34:49]
	v_mfma_f32_32x32x16_bf16 v[18:33], v[190:193], v[156:159], v[18:33]
	v_mfma_f32_32x32x16_bf16 v[2:17], v[190:193], v[202:205], v[2:17]
	s_setprio 0
	v_add_u32_e32 v0, v0, v141
	v_add_u32_e32 v134, v134, v142
	ds_read_b128 v[154:157], v0
	ds_read_b128 v[158:161], v134
	v_add_u32_e32 v0, v135, v139
	v_add_u32_e32 v134, v143, v140
	ds_read_b128 v[140:143], v0 offset:32768
	ds_read_b128 v[166:169], v134 offset:32768
	v_add_u32_e32 v0, v136, v137
	v_add_u32_e32 v138, v149, v138
	ds_read_b128 v[134:137], v0 offset:32768
	ds_read_b128 v[182:185], v138 offset:32768
	s_setprio 1
	s_waitcnt lgkmcnt(9)
;   DI void operator()(f32x16 (&acc)[2][4], int grow0, int gcol0, int lane, int w, char* lds) {
;     ...
;     for (int ps = 0; ps < 4; ++ps) {
;       const int mt = ps >> 1;
;       if (ps + 1 < 4) {
;         if (ps >= 1) asm volatile("s_waitcnt lgkmcnt(0)" ::: "memory");
;         xpass(ps + 1, grow0, gcol0, lane, w, lds);
;         if (ps >= 1) asm volatile("s_waitcnt vmcnt(8)" ::: "memory");
;       } else asm volatile("s_waitcnt vmcnt(0)" ::: "memory");
;       const char* xs = lds + (ps & 1) * 65536 + w * 8192;
; #pragma unroll
;       for (int qq = 0; qq < 2; ++qq)
; #pragma unroll
;         for (int e = 0; e < 4; ++e) {
;           const int i = 4 * (2 * (ps & 1) + qq) + e;
;           const float* xr = (const float*)(xs + (8 * qq + 4 * hh + e) * 512) + l31;
;           float s1 = 0.f, s2 = 0.f;
; #pragma unroll
;           for (int nt = 0; nt < 4; ++nt) {
;             float v = (acc[mt][nt][i] + bia[nt]) * csc[nt];
;             float z = ALPHA * xr[nt * 32] + hs * v;
;             acc[mt][nt][i] = z; s1 += z; s2 += z * z;
;           }
;           s1 = row16_sum(s1); s2 = row16_sum(s2);
;           if ((lane & 15) == 0) { f32x2 sv = {s1, s2}; *(f32x2*)(redw + (mt * 32 + (i & 3) + 8 * (i >> 2)) * 2) = sv; }
;         }
	v_mfma_f32_32x32x16_bf16 v[114:129], v[130:133], v[150:153], v[114:129]
	s_waitcnt lgkmcnt(8)
	v_mfma_f32_32x32x16_bf16 v[98:113], v[130:133], v[174:177], v[98:113]
	s_waitcnt lgkmcnt(7)
	v_mfma_f32_32x32x16_bf16 v[82:97], v[130:133], v[144:147], v[82:97]
	s_waitcnt lgkmcnt(6)
	v_mfma_f32_32x32x16_bf16 v[66:81], v[130:133], v[178:181], v[66:81]
	v_mfma_f32_32x32x16_bf16 v[50:65], v[170:173], v[150:153], v[50:65]
	v_mfma_f32_32x32x16_bf16 v[34:49], v[170:173], v[174:177], v[34:49]
	v_mfma_f32_32x32x16_bf16 v[18:33], v[170:173], v[144:147], v[18:33]
	v_mfma_f32_32x32x16_bf16 v[2:17], v[170:173], v[178:181], v[2:17]
	s_setprio 0
	s_setprio 1
	s_waitcnt lgkmcnt(3)
	v_mfma_f32_32x32x16_bf16 v[114:129], v[154:157], v[140:143], v[114:129]
	s_waitcnt lgkmcnt(2)
	v_mfma_f32_32x32x16_bf16 v[98:113], v[154:157], v[166:169], v[98:113]
	s_waitcnt lgkmcnt(1)
	v_mfma_f32_32x32x16_bf16 v[82:97], v[154:157], v[134:137], v[82:97]
	s_waitcnt lgkmcnt(0)
	v_mfma_f32_32x32x16_bf16 v[66:81], v[154:157], v[182:185], v[66:81]
	v_mfma_f32_32x32x16_bf16 v[50:65], v[158:161], v[140:143], v[50:65]
	v_mfma_f32_32x32x16_bf16 v[34:49], v[158:161], v[166:169], v[34:49]
	v_mfma_f32_32x32x16_bf16 v[18:33], v[158:161], v[134:137], v[18:33]
	v_mfma_f32_32x32x16_bf16 v[2:17], v[158:161], v[182:185], v[2:17]
	s_setprio 0
	v_mov_b32_e32 v164, v216
	s_waitcnt vmcnt(0)
	s_barrier
	v_mov_b32_e32 v133, v1
	v_ashrrev_i32_e32 v158, 6, v164
	v_lshrrev_b32_e32 v0, 30, v158
	v_add_u32_e32 v0, v158, v0
	v_ashrrev_i32_e32 v134, 2, v0
	v_mul_i32_i24_e32 v0, 4, v134
	v_sub_u32_e32 v0, v158, v0
	v_lshlrev_b32_e32 v135, 6, v0
	v_add_u32_e32 v163, s3, v135
	v_bfe_u32 v0, v164, 5, 1
	v_or_b32_e32 v159, v163, v0
	v_or_b32_e32 v130, 16, v159
	v_lshlrev_b32_e32 v200, 2, v164
	v_ashrrev_i32_e32 v131, 31, v130
	v_lshl_add_u32 v182, v134, 7, s30
	v_and_b32_e32 v0, 0x7c, v200
	v_lshlrev_b64 v[130:131], 12, v[130:131]
	v_ashrrev_i32_e32 v183, 31, v182
	v_readfirstlane_b32 s2, v158
	v_lshl_add_u64 v[130:131], s[10:11], 0, v[130:131]
	v_lshlrev_b32_e32 v0, 2, v0
	s_lshl_b32 s2, s2, 13
	v_lshl_add_u64 v[130:131], v[182:183], 2, v[130:131]
	v_mov_b32_e32 v132, v0
	s_add_i32 m0, s2, 0x10000
	v_lshl_add_u64 v[130:131], v[130:131], 0, v[132:133]
	global_load_lds_dwordx4 v[130:131], off
	v_lshl_add_u64 v[132:133], v[130:131], 0, s[34:35]
	s_add_i32 m0, s2, 0x10400
	v_and_b32_e32 v210, 0xc0, v135
	global_load_lds_dwordx4 v[132:133], off
	v_lshl_add_u64 v[132:133], v[130:131], 0, s[36:37]
	s_add_i32 m0, s2, 0x10800
	v_mov_b32_e32 v136, v114
	global_load_lds_dwordx4 v[132:133], off
	v_lshl_add_u64 v[132:133], v[130:131], 0, s[40:41]
	s_add_i32 m0, s2, 0x10c00
	v_mov_b32_e32 v137, v82
	global_load_lds_dwordx4 v[132:133], off
	v_lshl_add_u64 v[132:133], v[130:131], 0, s[44:45]
	s_add_i32 m0, s2, 0x11000
	v_mov_b32_e32 v140, v98
	global_load_lds_dwordx4 v[132:133], off
	v_lshl_add_u64 v[132:133], v[130:131], 0, s[46:47]
	s_add_i32 m0, s2, 0x11400
	v_mov_b32_e32 v141, v82
	global_load_lds_dwordx4 v[132:133], off
	v_lshl_add_u64 v[132:133], v[130:131], 0, s[52:53]
	s_add_i32 m0, s2, 0x11800
	v_lshl_add_u64 v[130:131], v[130:131], 0, s[54:55]
	global_load_lds_dwordx4 v[132:133], off
	s_add_i32 m0, s2, 0x11c00
	v_bfe_u32 v132, v164, 4, 1
	global_load_lds_dwordx4 v[130:131], off
	v_and_b32_e32 v130, 31, v164
	v_lshlrev_b32_e32 v131, 1, v134
	v_bfe_u32 v134, v164, 3, 3
	v_and_or_b32 v131, v131, 2, v132
	v_and_b32_e32 v132, 4, v134
	v_lshlrev_b32_e32 v130, 2, v130
	v_lshl_or_b32 v138, v158, 13, v130
	v_lshlrev_b32_e32 v154, 9, v132
	v_or_b32_e32 v133, v210, v132
	v_and_b32_e32 v130, 15, v164
	v_or_b32_e32 v132, v138, v154
	v_lshlrev_b32_e32 v135, 3, v133
	v_lshl_or_b32 v139, v131, 11, v221
	v_cmp_eq_u32_e32 vcc, 0, v130
	s_waitcnt vmcnt(8)
	ds_read2_b32 v[130:131], v132 offset1:32
	ds_read2_b32 v[132:133], v132 offset0:64 offset1:96
	v_pk_add_f32 v[136:137], v[136:137], 0 op_sel_hi:[1,0]
	v_pk_add_f32 v[140:141], v[140:141], 0 op_sel_hi:[1,0]
	s_mov_b32 s2, s67
	s_waitcnt lgkmcnt(0)
	v_mov_b32_e32 v142, v130
	v_mov_b32_e32 v143, v132
	v_mov_b32_e32 v130, v131
	v_mov_b32_e32 v131, v132
	v_pk_fma_f32 v[186:187], v[142:143], s[2:3], v[136:137] op_sel_hi:[1,0,1]
	v_pk_fma_f32 v[188:189], v[130:131], s[2:3], v[140:141] op_sel_hi:[1,0,1]
	v_pk_mul_f32 v[144:145], v[142:143], s[2:3] op_sel_hi:[1,0]
	v_pk_mul_f32 v[142:143], v[186:187], v[186:187]
	v_pk_mul_f32 v[130:131], v[188:189], v[188:189]
	v_pk_mov_b32 v[136:137], v[136:137], v[142:143] op_sel:[1,0]
	v_pk_mov_b32 v[130:131], v[144:145], v[130:131] op_sel:[1,0]
	v_add_f32_e32 v178, 0, v66
	v_pk_add_f32 v[130:131], v[136:137], v[130:131]
	v_pk_add_f32 v[136:137], v[186:187], v[188:189]
	v_pk_mul_f32 v[140:141], v[186:187], v[188:189]
	v_fmac_f32_e32 v178, 0x3fd744fd, v133
	v_mov_b32_e32 v137, v141
	v_pk_add_f32 v[130:131], v[136:137], v[130:131]
	v_mul_f32_e32 v179, v178, v178
	v_pk_add_f32 v[130:131], v[130:131], v[178:179]
	v_add_u32_e32 v179, v139, v135
	s_nop 0
	v_mov_b32_dpp v132, v130 quad_perm:[1,0,3,2] row_mask:0xf bank_mask:0xf bound_ctrl:1
	v_mov_b32_dpp v133, v131 quad_perm:[1,0,3,2] row_mask:0xf bank_mask:0xf bound_ctrl:1
	v_pk_add_f32 v[130:131], v[130:131], v[132:133]
	s_nop 1
	v_mov_b32_dpp v132, v130 quad_perm:[2,3,0,1] row_mask:0xf bank_mask:0xf bound_ctrl:1
	v_mov_b32_dpp v133, v131 quad_perm:[2,3,0,1] row_mask:0xf bank_mask:0xf bound_ctrl:1
	v_pk_add_f32 v[130:131], v[130:131], v[132:133]
	s_nop 1
	v_mov_b32_dpp v132, v130 row_half_mirror row_mask:0xf bank_mask:0xf bound_ctrl:1
	v_mov_b32_dpp v133, v131 row_half_mirror row_mask:0xf bank_mask:0xf bound_ctrl:1
	v_pk_add_f32 v[130:131], v[130:131], v[132:133]
	s_nop 1
	v_mov_b32_dpp v132, v130 row_mirror row_mask:0xf bank_mask:0xf bound_ctrl:1
	v_mov_b32_dpp v133, v131 row_mirror row_mask:0xf bank_mask:0xf bound_ctrl:1
	s_and_saveexec_b64 s[6:7], vcc
	v_pk_add_f32 v[130:131], v[130:131], v[132:133]
	ds_write_b64 v179, v[130:131]
	s_or_b64 exec, exec, s[6:7]
	v_add_u32_e32 v168, v138, v154
	ds_read2_b32 v[130:131], v168 offset0:128 offset1:160
	ds_read2_b32 v[132:133], v168 offset0:192 offset1:224
	v_mov_b32_e32 v82, v115
	v_add_f32_e32 v152, 0, v67
	v_pk_add_f32 v[66:67], v[82:83], 0 op_sel_hi:[1,0]
	v_mov_b32_e32 v82, v99
	v_pk_add_f32 v[82:83], v[82:83], 0 op_sel_hi:[1,0]
	s_waitcnt lgkmcnt(1)
;   DI void operator()(f32x16 (&acc)[2][4], int grow0, int gcol0, int lane, int w, char* lds) {
;     ...
; #pragma unroll
;       for (int qq = 0; qq < 2; ++qq)
; #pragma unroll
;         for (int e = 0; e < 4; ++e) {
;           const int i = 4 * (2 * (ps & 1) + qq) + e;
;           const float* xr = (const float*)(xs + (8 * qq + 4 * hh + e) * 512) + l31;
;           float s1 = 0.f, s2 = 0.f;
; #pragma unroll
;           for (int nt = 0; nt < 4; ++nt) {
;             float v = (acc[mt][nt][i] + bia[nt]) * csc[nt];
;             float z = ALPHA * xr[nt * 32] + hs * v;
;             acc[mt][nt][i] = z; s1 += z; s2 += z * z;
;           }
;           s1 = row16_sum(s1); s2 = row16_sum(s2);
;           if ((lane & 15) == 0) { f32x2 sv = {s1, s2}; *(f32x2*)(redw + (mt * 32 + (i & 3) + 8 * (i >> 2)) * 2) = sv; }
;         }
	v_mov_b32_e32 v98, v130
	s_waitcnt lgkmcnt(0)
	v_mov_b32_e32 v99, v132
	s_mov_b32 s2, s67
	v_mov_b32_e32 v130, v131
	v_mov_b32_e32 v131, v132
	v_pk_fma_f32 v[166:167], v[98:99], s[2:3], v[66:67] op_sel_hi:[1,0,1]
	v_pk_fma_f32 v[172:173], v[130:131], s[2:3], v[82:83] op_sel_hi:[1,0,1]
	v_pk_mul_f32 v[114:115], v[98:99], s[2:3] op_sel_hi:[1,0]
	v_pk_mul_f32 v[98:99], v[166:167], v[166:167]
	v_pk_mul_f32 v[82:83], v[172:173], v[172:173]
	v_pk_mov_b32 v[66:67], v[66:67], v[98:99] op_sel:[1,0]
	v_pk_mov_b32 v[82:83], v[114:115], v[82:83] op_sel:[1,0]
	v_pk_mul_f32 v[98:99], v[166:167], v[172:173]
	v_pk_add_f32 v[66:67], v[66:67], v[82:83]
	v_pk_add_f32 v[82:83], v[166:167], v[172:173]
	v_fmac_f32_e32 v152, 0x3fd744fd, v133
	v_mov_b32_e32 v83, v99
	v_pk_add_f32 v[66:67], v[82:83], v[66:67]
	v_mul_f32_e32 v153, v152, v152
	v_pk_add_f32 v[66:67], v[66:67], v[152:153]
	s_nop 1
	v_mov_b32_dpp v82, v66 quad_perm:[1,0,3,2] row_mask:0xf bank_mask:0xf bound_ctrl:1
	v_mov_b32_dpp v83, v67 quad_perm:[1,0,3,2] row_mask:0xf bank_mask:0xf bound_ctrl:1
	v_pk_add_f32 v[66:67], v[66:67], v[82:83]
	s_nop 1
	v_mov_b32_dpp v82, v66 quad_perm:[2,3,0,1] row_mask:0xf bank_mask:0xf bound_ctrl:1
	v_mov_b32_dpp v83, v67 quad_perm:[2,3,0,1] row_mask:0xf bank_mask:0xf bound_ctrl:1
	v_pk_add_f32 v[66:67], v[66:67], v[82:83]
	s_nop 1
	v_mov_b32_dpp v82, v66 row_half_mirror row_mask:0xf bank_mask:0xf bound_ctrl:1
	v_mov_b32_dpp v83, v67 row_half_mirror row_mask:0xf bank_mask:0xf bound_ctrl:1
	v_pk_add_f32 v[66:67], v[66:67], v[82:83]
	s_nop 1
	v_mov_b32_dpp v82, v66 row_mirror row_mask:0xf bank_mask:0xf bound_ctrl:1
	v_mov_b32_dpp v83, v67 row_mirror row_mask:0xf bank_mask:0xf bound_ctrl:1
	s_and_saveexec_b64 s[6:7], vcc
	v_readlane_b32 s63, v254, 51
	v_readlane_b32 s65, v254, 48
	v_readlane_b32 s70, v254, 52
	v_readlane_b32 s71, v255, 50
	v_pk_add_f32 v[66:67], v[66:67], v[82:83]
	ds_write_b64 v179, v[66:67] offset:8
	s_or_b64 exec, exec, s[6:7]
	v_add_u32_e32 v153, 0x400, v168
	ds_read2_b32 v[82:83], v153 offset1:32
	ds_read2_b32 v[98:99], v153 offset0:64 offset1:96
	v_mov_b32_e32 v114, v116
	v_mov_b32_e32 v115, v84
	v_mov_b32_e32 v130, v100
	v_mov_b32_e32 v131, v84
	v_pk_add_f32 v[114:115], v[114:115], 0 op_sel_hi:[1,0]
	v_pk_add_f32 v[130:131], v[130:131], 0 op_sel_hi:[1,0]
	s_waitcnt lgkmcnt(1)
	v_mov_b32_e32 v132, v82
	s_waitcnt lgkmcnt(0)
	v_mov_b32_e32 v133, v98
	s_mov_b32 s2, s67
	v_mov_b32_e32 v140, v83
	v_mov_b32_e32 v141, v98
	v_pk_fma_f32 v[82:83], v[132:133], s[2:3], v[114:115] op_sel_hi:[1,0,1]
	v_pk_fma_f32 v[150:151], v[140:141], s[2:3], v[130:131] op_sel_hi:[1,0,1]
	v_pk_mul_f32 v[136:137], v[132:133], s[2:3] op_sel_hi:[1,0]
	v_pk_mul_f32 v[132:133], v[82:83], v[82:83]
	v_pk_mul_f32 v[130:131], v[150:151], v[150:151]
	v_pk_mov_b32 v[114:115], v[114:115], v[132:133] op_sel:[1,0]
	v_pk_mov_b32 v[130:131], v[136:137], v[130:131] op_sel:[1,0]
	v_add_f32_e32 v66, 0, v68
	v_pk_add_f32 v[114:115], v[114:115], v[130:131]
	v_pk_add_f32 v[130:131], v[82:83], v[150:151]
	v_pk_mul_f32 v[132:133], v[82:83], v[150:151]
	v_fmac_f32_e32 v66, 0x3fd744fd, v99
	v_mov_b32_e32 v131, v133
	v_pk_add_f32 v[114:115], v[130:131], v[114:115]
	v_mul_f32_e32 v67, v66, v66
	v_pk_add_f32 v[98:99], v[114:115], v[66:67]
	s_nop 1
	v_mov_b32_dpp v114, v98 quad_perm:[1,0,3,2] row_mask:0xf bank_mask:0xf bound_ctrl:1
	v_mov_b32_dpp v115, v99 quad_perm:[1,0,3,2] row_mask:0xf bank_mask:0xf bound_ctrl:1
	v_pk_add_f32 v[98:99], v[98:99], v[114:115]
	s_nop 1
	v_mov_b32_dpp v114, v98 quad_perm:[2,3,0,1] row_mask:0xf bank_mask:0xf bound_ctrl:1
	v_mov_b32_dpp v115, v99 quad_perm:[2,3,0,1] row_mask:0xf bank_mask:0xf bound_ctrl:1
	v_pk_add_f32 v[98:99], v[98:99], v[114:115]
	s_nop 1
	v_mov_b32_dpp v114, v98 row_half_mirror row_mask:0xf bank_mask:0xf bound_ctrl:1
	v_mov_b32_dpp v115, v99 row_half_mirror row_mask:0xf bank_mask:0xf bound_ctrl:1
	v_pk_add_f32 v[98:99], v[98:99], v[114:115]
	s_nop 1
	v_mov_b32_dpp v114, v98 row_mirror row_mask:0xf bank_mask:0xf bound_ctrl:1
	v_mov_b32_dpp v115, v99 row_mirror row_mask:0xf bank_mask:0xf bound_ctrl:1
	s_and_saveexec_b64 s[6:7], vcc
	v_pk_add_f32 v[98:99], v[98:99], v[114:115]
	ds_write_b64 v179, v[98:99] offset:16
	s_or_b64 exec, exec, s[6:7]
	v_lshlrev_b32_e32 v139, 9, v134
	v_or_b32_e32 v146, 0x600, v139
	v_add_u32_e32 v151, v138, v146
	ds_read2_b32 v[98:99], v151 offset1:32
	ds_read2_b32 v[114:115], v151 offset0:64 offset1:96
	v_mov_b32_e32 v84, v117
	v_pk_add_f32 v[116:117], v[84:85], 0 op_sel_hi:[1,0]
	v_mov_b32_e32 v84, v101
	v_pk_add_f32 v[84:85], v[84:85], 0 op_sel_hi:[1,0]
	s_waitcnt lgkmcnt(1)
	v_mov_b32_e32 v100, v98
	s_waitcnt lgkmcnt(0)
;   DI void operator()(f32x16 (&acc)[2][4], int grow0, int gcol0, int lane, int w, char* lds) {
;     ...
; #pragma unroll
;       for (int qq = 0; qq < 2; ++qq)
; #pragma unroll
;         for (int e = 0; e < 4; ++e) {
;           const int i = 4 * (2 * (ps & 1) + qq) + e;
;           const float* xr = (const float*)(xs + (8 * qq + 4 * hh + e) * 512) + l31;
;           float s1 = 0.f, s2 = 0.f;
; #pragma unroll
;           for (int nt = 0; nt < 4; ++nt) {
;             float v = (acc[mt][nt][i] + bia[nt]) * csc[nt];
;             float z = ALPHA * xr[nt * 32] + hs * v;
;             acc[mt][nt][i] = z; s1 += z; s2 += z * z;
;           }
;           s1 = row16_sum(s1); s2 = row16_sum(s2);
;           if ((lane & 15) == 0) { f32x2 sv = {s1, s2}; *(f32x2*)(redw + (mt * 32 + (i & 3) + 8 * (i >> 2)) * 2) = sv; }
;         }
	v_mov_b32_e32 v101, v114
	s_mov_b32 s2, s67
	v_mov_b32_e32 v132, v99
	v_mov_b32_e32 v133, v114
	v_pk_mul_f32 v[130:131], v[100:101], s[2:3] op_sel_hi:[1,0]
	v_pk_fma_f32 v[98:99], v[100:101], s[2:3], v[116:117] op_sel_hi:[1,0,1]
	v_pk_fma_f32 v[100:101], v[132:133], s[2:3], v[84:85] op_sel_hi:[1,0,1]
	v_pk_mul_f32 v[134:135], v[98:99], v[98:99]
	v_pk_mul_f32 v[84:85], v[100:101], v[100:101]
	v_pk_mov_b32 v[116:117], v[116:117], v[134:135] op_sel:[1,0]
	v_pk_mov_b32 v[84:85], v[130:131], v[84:85] op_sel:[1,0]
	v_add_f32_e32 v68, 0, v69
	v_pk_add_f32 v[84:85], v[116:117], v[84:85]
	v_pk_add_f32 v[116:117], v[98:99], v[100:101]
	v_pk_mul_f32 v[130:131], v[98:99], v[100:101]
	v_fmac_f32_e32 v68, 0x3fd744fd, v115
	v_mov_b32_e32 v117, v131
	v_pk_add_f32 v[84:85], v[116:117], v[84:85]
	v_mul_f32_e32 v69, v68, v68
	v_pk_add_f32 v[84:85], v[84:85], v[68:69]
	s_nop 1
	v_mov_b32_dpp v114, v84 quad_perm:[1,0,3,2] row_mask:0xf bank_mask:0xf bound_ctrl:1
	v_mov_b32_dpp v115, v85 quad_perm:[1,0,3,2] row_mask:0xf bank_mask:0xf bound_ctrl:1
	v_pk_add_f32 v[84:85], v[84:85], v[114:115]
	s_nop 1
	v_mov_b32_dpp v114, v84 quad_perm:[2,3,0,1] row_mask:0xf bank_mask:0xf bound_ctrl:1
	v_mov_b32_dpp v115, v85 quad_perm:[2,3,0,1] row_mask:0xf bank_mask:0xf bound_ctrl:1
	v_pk_add_f32 v[84:85], v[84:85], v[114:115]
	s_nop 1
	v_mov_b32_dpp v114, v84 row_half_mirror row_mask:0xf bank_mask:0xf bound_ctrl:1
	v_mov_b32_dpp v115, v85 row_half_mirror row_mask:0xf bank_mask:0xf bound_ctrl:1
	v_pk_add_f32 v[84:85], v[84:85], v[114:115]
	s_nop 1
	v_mov_b32_dpp v114, v84 row_mirror row_mask:0xf bank_mask:0xf bound_ctrl:1
	v_mov_b32_dpp v115, v85 row_mirror row_mask:0xf bank_mask:0xf bound_ctrl:1
	s_and_saveexec_b64 s[6:7], vcc
	v_pk_add_f32 v[84:85], v[84:85], v[114:115]
	ds_write_b64 v179, v[84:85] offset:24
	s_or_b64 exec, exec, s[6:7]
	v_add_u32_e32 v67, 0x1000, v168
	ds_read2_b32 v[114:115], v67 offset1:32
	ds_read2_b32 v[130:131], v67 offset0:64 offset1:96
	v_mov_b32_e32 v116, v118
	v_mov_b32_e32 v117, v86
	v_pk_add_f32 v[132:133], v[116:117], 0 op_sel_hi:[1,0]
	v_mov_b32_e32 v116, v102
	v_pk_add_f32 v[116:117], v[116:117], 0 op_sel_hi:[1,0]
	s_waitcnt lgkmcnt(1)
	v_mov_b32_e32 v134, v114
	s_waitcnt lgkmcnt(0)
	v_mov_b32_e32 v135, v130
	s_mov_b32 s2, s67
	v_mov_b32_e32 v140, v115
	v_mov_b32_e32 v141, v130
	v_pk_fma_f32 v[114:115], v[134:135], s[2:3], v[132:133] op_sel_hi:[1,0,1]
	v_pk_fma_f32 v[116:117], v[140:141], s[2:3], v[116:117] op_sel_hi:[1,0,1]
	v_pk_mul_f32 v[136:137], v[134:135], s[2:3] op_sel_hi:[1,0]
	v_pk_mul_f32 v[134:135], v[114:115], v[114:115]
	v_pk_mul_f32 v[140:141], v[116:117], v[116:117]
	v_pk_mov_b32 v[132:133], v[132:133], v[134:135] op_sel:[1,0]
	v_pk_mov_b32 v[134:135], v[136:137], v[140:141] op_sel:[1,0]
	v_add_f32_e32 v84, 0, v70
	v_pk_add_f32 v[132:133], v[132:133], v[134:135]
	v_pk_add_f32 v[134:135], v[114:115], v[116:117]
	v_pk_mul_f32 v[136:137], v[114:115], v[116:117]
	v_fmac_f32_e32 v84, 0x3fd744fd, v131
	v_mov_b32_e32 v135, v137
	v_pk_add_f32 v[132:133], v[134:135], v[132:133]
	v_mul_f32_e32 v85, v84, v84
	v_pk_add_f32 v[130:131], v[132:133], v[84:85]
	s_nop 1
	v_mov_b32_dpp v132, v130 quad_perm:[1,0,3,2] row_mask:0xf bank_mask:0xf bound_ctrl:1
	v_mov_b32_dpp v133, v131 quad_perm:[1,0,3,2] row_mask:0xf bank_mask:0xf bound_ctrl:1
	v_pk_add_f32 v[130:131], v[130:131], v[132:133]
	s_nop 1
	v_mov_b32_dpp v132, v130 quad_perm:[2,3,0,1] row_mask:0xf bank_mask:0xf bound_ctrl:1
	v_mov_b32_dpp v133, v131 quad_perm:[2,3,0,1] row_mask:0xf bank_mask:0xf bound_ctrl:1
	v_pk_add_f32 v[130:131], v[130:131], v[132:133]
	s_nop 1
	v_mov_b32_dpp v132, v130 row_half_mirror row_mask:0xf bank_mask:0xf bound_ctrl:1
	v_mov_b32_dpp v133, v131 row_half_mirror row_mask:0xf bank_mask:0xf bound_ctrl:1
	v_pk_add_f32 v[130:131], v[130:131], v[132:133]
	s_nop 1
	v_mov_b32_dpp v132, v130 row_mirror row_mask:0xf bank_mask:0xf bound_ctrl:1
	v_mov_b32_dpp v133, v131 row_mirror row_mask:0xf bank_mask:0xf bound_ctrl:1
	s_and_saveexec_b64 s[6:7], vcc
	v_pk_add_f32 v[130:131], v[130:131], v[132:133]
	ds_write_b64 v179, v[130:131] offset:64
	s_or_b64 exec, exec, s[6:7]
	ds_read2_b32 v[130:131], v67 offset0:128 offset1:160
	ds_read2_b32 v[132:133], v67 offset0:192 offset1:224
	v_mov_b32_e32 v86, v119
	v_pk_add_f32 v[134:135], v[86:87], 0 op_sel_hi:[1,0]
	v_mov_b32_e32 v86, v103
	v_pk_add_f32 v[86:87], v[86:87], 0 op_sel_hi:[1,0]
	s_waitcnt lgkmcnt(1)
	v_mov_b32_e32 v102, v130
	s_waitcnt lgkmcnt(0)
	v_mov_b32_e32 v103, v132
	s_mov_b32 s2, s67
	v_mov_b32_e32 v118, v131
	v_mov_b32_e32 v119, v132
	v_pk_mul_f32 v[136:137], v[102:103], s[2:3] op_sel_hi:[1,0]
	v_pk_fma_f32 v[102:103], v[102:103], s[2:3], v[134:135] op_sel_hi:[1,0,1]
	v_pk_fma_f32 v[118:119], v[118:119], s[2:3], v[86:87] op_sel_hi:[1,0,1]
	v_pk_mul_f32 v[130:131], v[102:103], v[102:103]
	v_pk_mul_f32 v[86:87], v[118:119], v[118:119]
	v_pk_mov_b32 v[130:131], v[134:135], v[130:131] op_sel:[1,0]
	v_pk_mov_b32 v[86:87], v[136:137], v[86:87] op_sel:[1,0]
	v_add_f32_e32 v70, 0, v71
	v_pk_add_f32 v[86:87], v[130:131], v[86:87]
	v_pk_add_f32 v[130:131], v[102:103], v[118:119]
	v_pk_mul_f32 v[134:135], v[102:103], v[118:119]
	v_fmac_f32_e32 v70, 0x3fd744fd, v133
	v_mov_b32_e32 v131, v135
	v_pk_add_f32 v[86:87], v[130:131], v[86:87]
	v_mul_f32_e32 v71, v70, v70
	v_pk_add_f32 v[86:87], v[86:87], v[70:71]
	s_nop 1
	v_mov_b32_dpp v130, v86 quad_perm:[1,0,3,2] row_mask:0xf bank_mask:0xf bound_ctrl:1
	v_mov_b32_dpp v131, v87 quad_perm:[1,0,3,2] row_mask:0xf bank_mask:0xf bound_ctrl:1
	v_pk_add_f32 v[86:87], v[86:87], v[130:131]
	s_nop 1
	v_mov_b32_dpp v130, v86 quad_perm:[2,3,0,1] row_mask:0xf bank_mask:0xf bound_ctrl:1
	v_mov_b32_dpp v131, v87 quad_perm:[2,3,0,1] row_mask:0xf bank_mask:0xf bound_ctrl:1
	v_pk_add_f32 v[86:87], v[86:87], v[130:131]
	s_nop 1
	v_mov_b32_dpp v130, v86 row_half_mirror row_mask:0xf bank_mask:0xf bound_ctrl:1
	v_mov_b32_dpp v131, v87 row_half_mirror row_mask:0xf bank_mask:0xf bound_ctrl:1
	v_pk_add_f32 v[86:87], v[86:87], v[130:131]
	s_nop 1
	v_mov_b32_dpp v130, v86 row_mirror row_mask:0xf bank_mask:0xf bound_ctrl:1
	v_mov_b32_dpp v131, v87 row_mirror row_mask:0xf bank_mask:0xf bound_ctrl:1
	s_and_saveexec_b64 s[6:7], vcc
	v_pk_add_f32 v[86:87], v[86:87], v[130:131]
	ds_write_b64 v179, v[86:87] offset:72
	s_or_b64 exec, exec, s[6:7]
	v_add_u32_e32 v69, 0x1400, v168
	ds_read2_b32 v[130:131], v69 offset1:32
	ds_read2_b32 v[134:135], v69 offset0:64 offset1:96
	v_mov_b32_e32 v132, v120
	v_mov_b32_e32 v133, v88
	v_pk_add_f32 v[136:137], v[132:133], 0 op_sel_hi:[1,0]
	v_mov_b32_e32 v132, v104
	v_pk_add_f32 v[132:133], v[132:133], 0 op_sel_hi:[1,0]
	s_waitcnt lgkmcnt(1)
;   DI void operator()(f32x16 (&acc)[2][4], int grow0, int gcol0, int lane, int w, char* lds) {
;     ...
;     for (int ps = 0; ps < 4; ++ps) {
;       const int mt = ps >> 1;
;       if (ps + 1 < 4) {
;         if (ps >= 1) asm volatile("s_waitcnt lgkmcnt(0)" ::: "memory");
;         xpass(ps + 1, grow0, gcol0, lane, w, lds);
;         if (ps >= 1) asm volatile("s_waitcnt vmcnt(8)" ::: "memory");
;       } else asm volatile("s_waitcnt vmcnt(0)" ::: "memory");
;       const char* xs = lds + (ps & 1) * 65536 + w * 8192;
; #pragma unroll
;       for (int qq = 0; qq < 2; ++qq)
; #pragma unroll
;         for (int e = 0; e < 4; ++e) {
;           const int i = 4 * (2 * (ps & 1) + qq) + e;
;           const float* xr = (const float*)(xs + (8 * qq + 4 * hh + e) * 512) + l31;
;           float s1 = 0.f, s2 = 0.f;
; #pragma unroll
;           for (int nt = 0; nt < 4; ++nt) {
;             float v = (acc[mt][nt][i] + bia[nt]) * csc[nt];
;             float z = ALPHA * xr[nt * 32] + hs * v;
;             acc[mt][nt][i] = z; s1 += z; s2 += z * z;
;           }
;           s1 = row16_sum(s1); s2 = row16_sum(s2);
;           if ((lane & 15) == 0) { f32x2 sv = {s1, s2}; *(f32x2*)(redw + (mt * 32 + (i & 3) + 8 * (i >> 2)) * 2) = sv; }
;         }
	v_mov_b32_e32 v140, v130
	s_waitcnt lgkmcnt(0)
	v_mov_b32_e32 v141, v134
	s_mov_b32 s2, s67
	v_mov_b32_e32 v144, v131
	v_mov_b32_e32 v145, v134
	v_pk_fma_f32 v[130:131], v[140:141], s[2:3], v[136:137] op_sel_hi:[1,0,1]
	v_pk_fma_f32 v[132:133], v[144:145], s[2:3], v[132:133] op_sel_hi:[1,0,1]
	v_pk_mul_f32 v[142:143], v[140:141], s[2:3] op_sel_hi:[1,0]
	v_pk_mul_f32 v[140:141], v[130:131], v[130:131]
	v_pk_mul_f32 v[144:145], v[132:133], v[132:133]
	v_pk_mov_b32 v[136:137], v[136:137], v[140:141] op_sel:[1,0]
	v_pk_mov_b32 v[140:141], v[142:143], v[144:145] op_sel:[1,0]
	v_add_f32_e32 v86, 0, v72
	v_pk_add_f32 v[136:137], v[136:137], v[140:141]
	v_pk_add_f32 v[140:141], v[130:131], v[132:133]
	v_pk_mul_f32 v[142:143], v[130:131], v[132:133]
	v_fmac_f32_e32 v86, 0x3fd744fd, v135
	v_mov_b32_e32 v141, v143
	v_pk_add_f32 v[136:137], v[140:141], v[136:137]
	v_mul_f32_e32 v87, v86, v86
	v_pk_add_f32 v[134:135], v[136:137], v[86:87]
	s_nop 1
	v_mov_b32_dpp v136, v134 quad_perm:[1,0,3,2] row_mask:0xf bank_mask:0xf bound_ctrl:1
	v_mov_b32_dpp v137, v135 quad_perm:[1,0,3,2] row_mask:0xf bank_mask:0xf bound_ctrl:1
	v_pk_add_f32 v[134:135], v[134:135], v[136:137]
	s_nop 1
	v_mov_b32_dpp v136, v134 quad_perm:[2,3,0,1] row_mask:0xf bank_mask:0xf bound_ctrl:1
	v_mov_b32_dpp v137, v135 quad_perm:[2,3,0,1] row_mask:0xf bank_mask:0xf bound_ctrl:1
	v_pk_add_f32 v[134:135], v[134:135], v[136:137]
	s_nop 1
	v_mov_b32_dpp v136, v134 row_half_mirror row_mask:0xf bank_mask:0xf bound_ctrl:1
	v_mov_b32_dpp v137, v135 row_half_mirror row_mask:0xf bank_mask:0xf bound_ctrl:1
	v_pk_add_f32 v[134:135], v[134:135], v[136:137]
	s_nop 1
	v_mov_b32_dpp v136, v134 row_mirror row_mask:0xf bank_mask:0xf bound_ctrl:1
	v_mov_b32_dpp v137, v135 row_mirror row_mask:0xf bank_mask:0xf bound_ctrl:1
	s_and_saveexec_b64 s[6:7], vcc
	v_pk_add_f32 v[134:135], v[134:135], v[136:137]
	ds_write_b64 v179, v[134:135] offset:80
	s_or_b64 exec, exec, s[6:7]
	v_or_b32_e32 v101, 0x1600, v139
	v_add_u32_e32 v71, v138, v101
	ds_read2_b32 v[134:135], v71 offset1:32
	ds_read2_b32 v[136:137], v71 offset0:64 offset1:96
	v_mov_b32_e32 v88, v121
	v_pk_add_f32 v[120:121], v[88:89], 0 op_sel_hi:[1,0]
	v_mov_b32_e32 v88, v105
	v_pk_add_f32 v[104:105], v[88:89], 0 op_sel_hi:[1,0]
	s_waitcnt lgkmcnt(1)
	v_mov_b32_e32 v88, v134
	s_waitcnt lgkmcnt(0)
	v_mov_b32_e32 v89, v136
	s_mov_b32 s2, s67
	v_mov_b32_e32 v134, v135
	v_mov_b32_e32 v135, v136
	v_pk_mul_f32 v[140:141], v[88:89], s[2:3] op_sel_hi:[1,0]
	v_pk_fma_f32 v[88:89], v[88:89], s[2:3], v[120:121] op_sel_hi:[1,0,1]
	v_pk_fma_f32 v[104:105], v[134:135], s[2:3], v[104:105] op_sel_hi:[1,0,1]
	v_pk_mul_f32 v[142:143], v[88:89], v[88:89]
	v_pk_mul_f32 v[134:135], v[104:105], v[104:105]
	v_pk_mov_b32 v[120:121], v[120:121], v[142:143] op_sel:[1,0]
	v_pk_mov_b32 v[134:135], v[140:141], v[134:135] op_sel:[1,0]
	v_add_f32_e32 v72, 0, v73
	v_pk_add_f32 v[120:121], v[120:121], v[134:135]
	v_pk_add_f32 v[134:135], v[88:89], v[104:105]
	v_pk_mul_f32 v[140:141], v[88:89], v[104:105]
	v_fmac_f32_e32 v72, 0x3fd744fd, v137
	v_mov_b32_e32 v135, v141
	v_pk_add_f32 v[120:121], v[134:135], v[120:121]
	v_mul_f32_e32 v73, v72, v72
	v_pk_add_f32 v[120:121], v[120:121], v[72:73]
	s_nop 1
	v_mov_b32_dpp v134, v120 quad_perm:[1,0,3,2] row_mask:0xf bank_mask:0xf bound_ctrl:1
	v_mov_b32_dpp v135, v121 quad_perm:[1,0,3,2] row_mask:0xf bank_mask:0xf bound_ctrl:1
	v_pk_add_f32 v[120:121], v[120:121], v[134:135]
	s_nop 1
	v_mov_b32_dpp v134, v120 quad_perm:[2,3,0,1] row_mask:0xf bank_mask:0xf bound_ctrl:1
	v_mov_b32_dpp v135, v121 quad_perm:[2,3,0,1] row_mask:0xf bank_mask:0xf bound_ctrl:1
	v_pk_add_f32 v[120:121], v[120:121], v[134:135]
	s_nop 1
	v_mov_b32_dpp v134, v120 row_half_mirror row_mask:0xf bank_mask:0xf bound_ctrl:1
	v_mov_b32_dpp v135, v121 row_half_mirror row_mask:0xf bank_mask:0xf bound_ctrl:1
	v_pk_add_f32 v[120:121], v[120:121], v[134:135]
	s_nop 1
	v_mov_b32_dpp v134, v120 row_mirror row_mask:0xf bank_mask:0xf bound_ctrl:1
	v_mov_b32_dpp v135, v121 row_mirror row_mask:0xf bank_mask:0xf bound_ctrl:1
	s_and_saveexec_b64 s[6:7], vcc
	v_pk_add_f32 v[120:121], v[120:121], v[134:135]
	ds_write_b64 v179, v[120:121] offset:88
	s_or_b64 exec, exec, s[6:7]
	v_or_b32_e32 v120, 32, v159
	v_ashrrev_i32_e32 v121, 31, v120
	v_lshlrev_b64 v[120:121], 12, v[120:121]
	v_readfirstlane_b32 s2, v158
	v_lshl_add_u64 v[120:121], s[10:11], 0, v[120:121]
	s_lshl_b32 s2, s2, 13
	v_lshl_add_u64 v[120:121], v[182:183], 2, v[120:121]
	s_waitcnt lgkmcnt(0)
	v_lshl_add_u64 v[120:121], v[120:121], 0, v[0:1]
	s_mov_b32 m0, s2
	s_mov_b64 s[6:7], 0x2000
	global_load_lds_dwordx4 v[120:121], off
	v_lshl_add_u64 v[134:135], v[120:121], 0, s[6:7]
	s_or_b32 m0, s2, 0x400
	s_mov_b64 s[6:7], 0x4000
	global_load_lds_dwordx4 v[134:135], off
	v_lshl_add_u64 v[134:135], v[120:121], 0, s[6:7]
	s_or_b32 m0, s2, 0x800
	s_mov_b64 s[6:7], 0x6000
	global_load_lds_dwordx4 v[134:135], off
	v_lshl_add_u64 v[134:135], v[120:121], 0, s[6:7]
	s_or_b32 m0, s2, 0xc00
	s_mov_b64 s[6:7], 0x8000
	global_load_lds_dwordx4 v[134:135], off
	v_lshl_add_u64 v[134:135], v[120:121], 0, s[6:7]
	s_or_b32 m0, s2, 0x1000
	s_mov_b64 s[6:7], 0xa000
	global_load_lds_dwordx4 v[134:135], off
	v_lshl_add_u64 v[134:135], v[120:121], 0, s[6:7]
	s_or_b32 m0, s2, 0x1400
	s_mov_b64 s[6:7], 0xc000
	global_load_lds_dwordx4 v[134:135], off
	v_lshl_add_u64 v[134:135], v[120:121], 0, s[6:7]
	s_or_b32 m0, s2, 0x1800
	s_mov_b64 s[6:7], 0xe000
	global_load_lds_dwordx4 v[134:135], off
	v_lshl_add_u64 v[120:121], v[120:121], 0, s[6:7]
	s_or_b32 m0, s2, 0x1c00
	v_add_u32_e32 v105, 0x10000, v138
	global_load_lds_dwordx4 v[120:121], off
	s_waitcnt vmcnt(8)
;   DI void operator()(f32x16 (&acc)[2][4], int grow0, int gcol0, int lane, int w, char* lds) {
;     ...
; #pragma unroll
;       for (int qq = 0; qq < 2; ++qq)
; #pragma unroll
;         for (int e = 0; e < 4; ++e) {
;           const int i = 4 * (2 * (ps & 1) + qq) + e;
;           const float* xr = (const float*)(xs + (8 * qq + 4 * hh + e) * 512) + l31;
;           float s1 = 0.f, s2 = 0.f;
; #pragma unroll
;           for (int nt = 0; nt < 4; ++nt) {
;             float v = (acc[mt][nt][i] + bia[nt]) * csc[nt];
;             float z = ALPHA * xr[nt * 32] + hs * v;
;             acc[mt][nt][i] = z; s1 += z; s2 += z * z;
;           }
;           s1 = row16_sum(s1); s2 = row16_sum(s2);
;           if ((lane & 15) == 0) { f32x2 sv = {s1, s2}; *(f32x2*)(redw + (mt * 32 + (i & 3) + 8 * (i >> 2)) * 2) = sv; }
;         }
	v_add_u32_e32 v73, v105, v154
	ds_read2_b32 v[134:135], v73 offset1:32
	ds_read2_b32 v[138:139], v73 offset0:64 offset1:96
	v_mov_b32_e32 v136, v122
	v_mov_b32_e32 v137, v90
	v_pk_add_f32 v[140:141], v[136:137], 0 op_sel_hi:[1,0]
	v_mov_b32_e32 v136, v106
	v_pk_add_f32 v[136:137], v[136:137], 0 op_sel_hi:[1,0]
	s_waitcnt lgkmcnt(0)
	v_mov_b32_e32 v142, v134
	v_mov_b32_e32 v143, v138
	s_mov_b32 s2, s67
	v_mov_b32_e32 v148, v135
	v_mov_b32_e32 v149, v138
	v_pk_fma_f32 v[134:135], v[142:143], s[2:3], v[140:141] op_sel_hi:[1,0,1]
	v_pk_fma_f32 v[136:137], v[148:149], s[2:3], v[136:137] op_sel_hi:[1,0,1]
	v_pk_mul_f32 v[144:145], v[142:143], s[2:3] op_sel_hi:[1,0]
	v_pk_mul_f32 v[142:143], v[134:135], v[134:135]
	v_pk_mul_f32 v[148:149], v[136:137], v[136:137]
	v_pk_mov_b32 v[140:141], v[140:141], v[142:143] op_sel:[1,0]
	v_pk_mov_b32 v[142:143], v[144:145], v[148:149] op_sel:[1,0]
	v_add_f32_e32 v120, 0, v74
	v_pk_add_f32 v[140:141], v[140:141], v[142:143]
	v_pk_add_f32 v[142:143], v[134:135], v[136:137]
	v_pk_mul_f32 v[144:145], v[134:135], v[136:137]
	v_fmac_f32_e32 v120, 0x3fd744fd, v139
	v_mov_b32_e32 v143, v145
	v_pk_add_f32 v[140:141], v[142:143], v[140:141]
	v_mul_f32_e32 v121, v120, v120
	v_pk_add_f32 v[138:139], v[140:141], v[120:121]
	s_nop 1
	v_mov_b32_dpp v140, v138 quad_perm:[1,0,3,2] row_mask:0xf bank_mask:0xf bound_ctrl:1
	v_mov_b32_dpp v141, v139 quad_perm:[1,0,3,2] row_mask:0xf bank_mask:0xf bound_ctrl:1
	v_pk_add_f32 v[138:139], v[138:139], v[140:141]
	s_nop 1
	v_mov_b32_dpp v140, v138 quad_perm:[2,3,0,1] row_mask:0xf bank_mask:0xf bound_ctrl:1
	v_mov_b32_dpp v141, v139 quad_perm:[2,3,0,1] row_mask:0xf bank_mask:0xf bound_ctrl:1
	v_pk_add_f32 v[138:139], v[138:139], v[140:141]
	s_nop 1
	v_mov_b32_dpp v140, v138 row_half_mirror row_mask:0xf bank_mask:0xf bound_ctrl:1
	v_mov_b32_dpp v141, v139 row_half_mirror row_mask:0xf bank_mask:0xf bound_ctrl:1
	v_pk_add_f32 v[138:139], v[138:139], v[140:141]
	s_nop 1
	v_mov_b32_dpp v140, v138 row_mirror row_mask:0xf bank_mask:0xf bound_ctrl:1
	v_mov_b32_dpp v141, v139 row_mirror row_mask:0xf bank_mask:0xf bound_ctrl:1
	s_and_saveexec_b64 s[6:7], vcc
	v_pk_add_f32 v[138:139], v[138:139], v[140:141]
	ds_write_b64 v179, v[138:139] offset:128
	s_or_b64 exec, exec, s[6:7]
	v_or_b32_e32 v74, 0x200, v154
	v_add_u32_e32 v85, v105, v74
	ds_read2_b32 v[138:139], v85 offset1:32
	ds_read2_b32 v[140:141], v85 offset0:64 offset1:96
	v_mov_b32_e32 v90, v123
	v_pk_add_f32 v[142:143], v[90:91], 0 op_sel_hi:[1,0]
	v_mov_b32_e32 v90, v107
	v_pk_add_f32 v[90:91], v[90:91], 0 op_sel_hi:[1,0]
	s_waitcnt lgkmcnt(1)
	v_mov_b32_e32 v106, v138
	s_waitcnt lgkmcnt(0)
	v_mov_b32_e32 v107, v140
	s_mov_b32 s2, s67
	v_mov_b32_e32 v122, v139
	v_mov_b32_e32 v123, v140
	v_pk_mul_f32 v[144:145], v[106:107], s[2:3] op_sel_hi:[1,0]
	v_pk_fma_f32 v[106:107], v[106:107], s[2:3], v[142:143] op_sel_hi:[1,0,1]
	v_pk_fma_f32 v[122:123], v[122:123], s[2:3], v[90:91] op_sel_hi:[1,0,1]
	v_pk_mul_f32 v[138:139], v[106:107], v[106:107]
	v_pk_mul_f32 v[90:91], v[122:123], v[122:123]
	v_pk_mov_b32 v[138:139], v[142:143], v[138:139] op_sel:[1,0]
	v_pk_mov_b32 v[90:91], v[144:145], v[90:91] op_sel:[1,0]
	v_add_f32_e32 v74, 0, v75
	v_pk_add_f32 v[90:91], v[138:139], v[90:91]
	v_pk_add_f32 v[138:139], v[106:107], v[122:123]
	v_pk_mul_f32 v[142:143], v[106:107], v[122:123]
	v_fmac_f32_e32 v74, 0x3fd744fd, v141
	v_mov_b32_e32 v139, v143
	v_pk_add_f32 v[90:91], v[138:139], v[90:91]
	v_mul_f32_e32 v75, v74, v74
	v_pk_add_f32 v[90:91], v[90:91], v[74:75]
	s_nop 1
	v_mov_b32_dpp v138, v90 quad_perm:[1,0,3,2] row_mask:0xf bank_mask:0xf bound_ctrl:1
	v_mov_b32_dpp v139, v91 quad_perm:[1,0,3,2] row_mask:0xf bank_mask:0xf bound_ctrl:1
	v_pk_add_f32 v[90:91], v[90:91], v[138:139]
	s_nop 1
	v_mov_b32_dpp v138, v90 quad_perm:[2,3,0,1] row_mask:0xf bank_mask:0xf bound_ctrl:1
	v_mov_b32_dpp v139, v91 quad_perm:[2,3,0,1] row_mask:0xf bank_mask:0xf bound_ctrl:1
	v_pk_add_f32 v[90:91], v[90:91], v[138:139]
	s_nop 1
	v_mov_b32_dpp v138, v90 row_half_mirror row_mask:0xf bank_mask:0xf bound_ctrl:1
	v_mov_b32_dpp v139, v91 row_half_mirror row_mask:0xf bank_mask:0xf bound_ctrl:1
	v_pk_add_f32 v[90:91], v[90:91], v[138:139]
	s_nop 1
	v_mov_b32_dpp v138, v90 row_mirror row_mask:0xf bank_mask:0xf bound_ctrl:1
	v_mov_b32_dpp v139, v91 row_mirror row_mask:0xf bank_mask:0xf bound_ctrl:1
	s_and_saveexec_b64 s[6:7], vcc
	v_pk_add_f32 v[90:91], v[90:91], v[138:139]
	ds_write_b64 v179, v[90:91] offset:136
	s_or_b64 exec, exec, s[6:7]
	v_or_b32_e32 v75, 0x400, v154
	v_add_u32_e32 v75, v105, v75
	ds_read2_b32 v[138:139], v75 offset1:32
	ds_read2_b32 v[142:143], v75 offset0:64 offset1:96
	v_mov_b32_e32 v140, v124
	v_mov_b32_e32 v141, v92
	v_pk_add_f32 v[144:145], v[140:141], 0 op_sel_hi:[1,0]
	v_mov_b32_e32 v140, v108
	v_pk_add_f32 v[140:141], v[140:141], 0 op_sel_hi:[1,0]
	s_waitcnt lgkmcnt(1)
	v_mov_b32_e32 v148, v138
	s_waitcnt lgkmcnt(0)
;   DI void operator()(f32x16 (&acc)[2][4], int grow0, int gcol0, int lane, int w, char* lds) {
;     ...
; #pragma unroll
;       for (int qq = 0; qq < 2; ++qq)
; #pragma unroll
;         for (int e = 0; e < 4; ++e) {
;           const int i = 4 * (2 * (ps & 1) + qq) + e;
;           const float* xr = (const float*)(xs + (8 * qq + 4 * hh + e) * 512) + l31;
;           float s1 = 0.f, s2 = 0.f;
; #pragma unroll
;           for (int nt = 0; nt < 4; ++nt) {
;             float v = (acc[mt][nt][i] + bia[nt]) * csc[nt];
;             float z = ALPHA * xr[nt * 32] + hs * v;
;             acc[mt][nt][i] = z; s1 += z; s2 += z * z;
;           }
;           s1 = row16_sum(s1); s2 = row16_sum(s2);
;           if ((lane & 15) == 0) { f32x2 sv = {s1, s2}; *(f32x2*)(redw + (mt * 32 + (i & 3) + 8 * (i >> 2)) * 2) = sv; }
;         }
	v_mov_b32_e32 v149, v142
	s_mov_b32 s2, s67
	v_mov_b32_e32 v160, v139
	v_mov_b32_e32 v161, v142
	v_pk_fma_f32 v[138:139], v[148:149], s[2:3], v[144:145] op_sel_hi:[1,0,1]
	v_pk_fma_f32 v[140:141], v[160:161], s[2:3], v[140:141] op_sel_hi:[1,0,1]
	v_pk_mul_f32 v[156:157], v[148:149], s[2:3] op_sel_hi:[1,0]
	v_pk_mul_f32 v[148:149], v[138:139], v[138:139]
	v_pk_mul_f32 v[160:161], v[140:141], v[140:141]
	v_pk_mov_b32 v[144:145], v[144:145], v[148:149] op_sel:[1,0]
	v_pk_mov_b32 v[148:149], v[156:157], v[160:161] op_sel:[1,0]
	v_add_f32_e32 v90, 0, v76
	v_pk_add_f32 v[144:145], v[144:145], v[148:149]
	v_pk_add_f32 v[148:149], v[138:139], v[140:141]
	v_pk_mul_f32 v[156:157], v[138:139], v[140:141]
	v_fmac_f32_e32 v90, 0x3fd744fd, v143
	v_mov_b32_e32 v149, v157
	v_pk_add_f32 v[144:145], v[148:149], v[144:145]
	v_mul_f32_e32 v91, v90, v90
	v_pk_add_f32 v[142:143], v[144:145], v[90:91]
	s_nop 1
	v_mov_b32_dpp v144, v142 quad_perm:[1,0,3,2] row_mask:0xf bank_mask:0xf bound_ctrl:1
	v_mov_b32_dpp v145, v143 quad_perm:[1,0,3,2] row_mask:0xf bank_mask:0xf bound_ctrl:1
	v_pk_add_f32 v[142:143], v[142:143], v[144:145]
	s_nop 1
	v_mov_b32_dpp v144, v142 quad_perm:[2,3,0,1] row_mask:0xf bank_mask:0xf bound_ctrl:1
	v_mov_b32_dpp v145, v143 quad_perm:[2,3,0,1] row_mask:0xf bank_mask:0xf bound_ctrl:1
	v_pk_add_f32 v[142:143], v[142:143], v[144:145]
	s_nop 1
	v_mov_b32_dpp v144, v142 row_half_mirror row_mask:0xf bank_mask:0xf bound_ctrl:1
	v_mov_b32_dpp v145, v143 row_half_mirror row_mask:0xf bank_mask:0xf bound_ctrl:1
	v_pk_add_f32 v[142:143], v[142:143], v[144:145]
	s_nop 1
	v_mov_b32_dpp v144, v142 row_mirror row_mask:0xf bank_mask:0xf bound_ctrl:1
	v_mov_b32_dpp v145, v143 row_mirror row_mask:0xf bank_mask:0xf bound_ctrl:1
	s_and_saveexec_b64 s[6:7], vcc
	v_pk_add_f32 v[142:143], v[142:143], v[144:145]
	ds_write_b64 v179, v[142:143] offset:144
	s_or_b64 exec, exec, s[6:7]
	v_add_u32_e32 v87, v105, v146
	ds_read2_b32 v[142:143], v87 offset1:32
	ds_read2_b32 v[144:145], v87 offset0:64 offset1:96
	v_mov_b32_e32 v92, v125
	v_pk_add_f32 v[146:147], v[92:93], 0 op_sel_hi:[1,0]
	v_mov_b32_e32 v92, v109
	v_pk_add_f32 v[92:93], v[92:93], 0 op_sel_hi:[1,0]
	s_waitcnt lgkmcnt(1)
	v_mov_b32_e32 v108, v142
	s_waitcnt lgkmcnt(0)
	v_mov_b32_e32 v109, v144
	s_mov_b32 s2, s67
	v_mov_b32_e32 v124, v143
	v_mov_b32_e32 v125, v144
	v_pk_mul_f32 v[148:149], v[108:109], s[2:3] op_sel_hi:[1,0]
	v_pk_fma_f32 v[108:109], v[108:109], s[2:3], v[146:147] op_sel_hi:[1,0,1]
	v_pk_fma_f32 v[124:125], v[124:125], s[2:3], v[92:93] op_sel_hi:[1,0,1]
	v_pk_mul_f32 v[142:143], v[108:109], v[108:109]
	v_pk_mul_f32 v[92:93], v[124:125], v[124:125]
	v_pk_mov_b32 v[142:143], v[146:147], v[142:143] op_sel:[1,0]
	v_pk_mov_b32 v[92:93], v[148:149], v[92:93] op_sel:[1,0]
	v_add_f32_e32 v76, 0, v77
	v_pk_add_f32 v[92:93], v[142:143], v[92:93]
	v_pk_add_f32 v[142:143], v[108:109], v[124:125]
	v_pk_mul_f32 v[146:147], v[108:109], v[124:125]
	v_fmac_f32_e32 v76, 0x3fd744fd, v145
	v_mov_b32_e32 v143, v147
	v_pk_add_f32 v[92:93], v[142:143], v[92:93]
	v_mul_f32_e32 v77, v76, v76
	v_pk_add_f32 v[92:93], v[92:93], v[76:77]
	s_nop 1
	v_mov_b32_dpp v142, v92 quad_perm:[1,0,3,2] row_mask:0xf bank_mask:0xf bound_ctrl:1
	v_mov_b32_dpp v143, v93 quad_perm:[1,0,3,2] row_mask:0xf bank_mask:0xf bound_ctrl:1
	v_pk_add_f32 v[92:93], v[92:93], v[142:143]
	s_nop 1
	v_mov_b32_dpp v142, v92 quad_perm:[2,3,0,1] row_mask:0xf bank_mask:0xf bound_ctrl:1
	v_mov_b32_dpp v143, v93 quad_perm:[2,3,0,1] row_mask:0xf bank_mask:0xf bound_ctrl:1
	v_pk_add_f32 v[92:93], v[92:93], v[142:143]
	s_nop 1
	v_mov_b32_dpp v142, v92 row_half_mirror row_mask:0xf bank_mask:0xf bound_ctrl:1
	v_mov_b32_dpp v143, v93 row_half_mirror row_mask:0xf bank_mask:0xf bound_ctrl:1
	v_pk_add_f32 v[92:93], v[92:93], v[142:143]
	s_nop 1
	v_mov_b32_dpp v142, v92 row_mirror row_mask:0xf bank_mask:0xf bound_ctrl:1
	v_mov_b32_dpp v143, v93 row_mirror row_mask:0xf bank_mask:0xf bound_ctrl:1
	s_and_saveexec_b64 s[6:7], vcc
	v_pk_add_f32 v[92:93], v[92:93], v[142:143]
	ds_write_b64 v179, v[92:93] offset:152
	s_or_b64 exec, exec, s[6:7]
	v_or_b32_e32 v77, 0x1000, v154
	v_add_u32_e32 v77, v105, v77
	ds_read2_b32 v[142:143], v77 offset1:32
	ds_read2_b32 v[146:147], v77 offset0:64 offset1:96
	v_mov_b32_e32 v144, v126
	v_mov_b32_e32 v145, v94
	v_pk_add_f32 v[148:149], v[144:145], 0 op_sel_hi:[1,0]
	v_mov_b32_e32 v144, v110
	v_pk_add_f32 v[144:145], v[144:145], 0 op_sel_hi:[1,0]
	s_waitcnt lgkmcnt(1)
	v_mov_b32_e32 v156, v142
	s_waitcnt lgkmcnt(0)
	v_mov_b32_e32 v157, v146
	s_mov_b32 s2, s67
	v_mov_b32_e32 v170, v143
	v_mov_b32_e32 v171, v146
	v_pk_fma_f32 v[142:143], v[156:157], s[2:3], v[148:149] op_sel_hi:[1,0,1]
	v_pk_fma_f32 v[144:145], v[170:171], s[2:3], v[144:145] op_sel_hi:[1,0,1]
	v_pk_mul_f32 v[160:161], v[156:157], s[2:3] op_sel_hi:[1,0]
	v_pk_mul_f32 v[156:157], v[142:143], v[142:143]
	v_pk_mul_f32 v[170:171], v[144:145], v[144:145]
	v_pk_mov_b32 v[148:149], v[148:149], v[156:157] op_sel:[1,0]
	v_pk_mov_b32 v[156:157], v[160:161], v[170:171] op_sel:[1,0]
	v_add_f32_e32 v92, 0, v78
	v_pk_add_f32 v[148:149], v[148:149], v[156:157]
	v_pk_add_f32 v[156:157], v[142:143], v[144:145]
	v_pk_mul_f32 v[160:161], v[142:143], v[144:145]
	v_fmac_f32_e32 v92, 0x3fd744fd, v147
	v_mov_b32_e32 v157, v161
	v_pk_add_f32 v[148:149], v[156:157], v[148:149]
	v_mul_f32_e32 v93, v92, v92
	v_pk_add_f32 v[146:147], v[148:149], v[92:93]
	s_nop 1
	v_mov_b32_dpp v148, v146 quad_perm:[1,0,3,2] row_mask:0xf bank_mask:0xf bound_ctrl:1
	v_mov_b32_dpp v149, v147 quad_perm:[1,0,3,2] row_mask:0xf bank_mask:0xf bound_ctrl:1
	v_pk_add_f32 v[146:147], v[146:147], v[148:149]
	s_nop 1
	v_mov_b32_dpp v148, v146 quad_perm:[2,3,0,1] row_mask:0xf bank_mask:0xf bound_ctrl:1
	v_mov_b32_dpp v149, v147 quad_perm:[2,3,0,1] row_mask:0xf bank_mask:0xf bound_ctrl:1
	v_pk_add_f32 v[146:147], v[146:147], v[148:149]
	s_nop 1
	v_mov_b32_dpp v148, v146 row_half_mirror row_mask:0xf bank_mask:0xf bound_ctrl:1
	v_mov_b32_dpp v149, v147 row_half_mirror row_mask:0xf bank_mask:0xf bound_ctrl:1
	v_pk_add_f32 v[146:147], v[146:147], v[148:149]
	s_nop 1
	v_mov_b32_dpp v148, v146 row_mirror row_mask:0xf bank_mask:0xf bound_ctrl:1
	v_mov_b32_dpp v149, v147 row_mirror row_mask:0xf bank_mask:0xf bound_ctrl:1
	s_and_saveexec_b64 s[6:7], vcc
	v_pk_add_f32 v[146:147], v[146:147], v[148:149]
	ds_write_b64 v179, v[146:147] offset:192
	s_or_b64 exec, exec, s[6:7]
	v_or_b32_e32 v78, 0x1200, v154
	v_add_u32_e32 v91, v105, v78
	ds_read2_b32 v[146:147], v91 offset1:32
	ds_read2_b32 v[148:149], v91 offset0:64 offset1:96
	v_mov_b32_e32 v94, v127
	v_pk_add_f32 v[156:157], v[94:95], 0 op_sel_hi:[1,0]
	v_mov_b32_e32 v94, v111
	v_pk_add_f32 v[94:95], v[94:95], 0 op_sel_hi:[1,0]
	s_waitcnt lgkmcnt(1)
;   DI void operator()(f32x16 (&acc)[2][4], int grow0, int gcol0, int lane, int w, char* lds) {
;     ...
; #pragma unroll
;       for (int qq = 0; qq < 2; ++qq)
; #pragma unroll
;         for (int e = 0; e < 4; ++e) {
;           const int i = 4 * (2 * (ps & 1) + qq) + e;
;           const float* xr = (const float*)(xs + (8 * qq + 4 * hh + e) * 512) + l31;
;           float s1 = 0.f, s2 = 0.f;
; #pragma unroll
;           for (int nt = 0; nt < 4; ++nt) {
;             float v = (acc[mt][nt][i] + bia[nt]) * csc[nt];
;             float z = ALPHA * xr[nt * 32] + hs * v;
;             acc[mt][nt][i] = z; s1 += z; s2 += z * z;
;           }
;           s1 = row16_sum(s1); s2 = row16_sum(s2);
;           if ((lane & 15) == 0) { f32x2 sv = {s1, s2}; *(f32x2*)(redw + (mt * 32 + (i & 3) + 8 * (i >> 2)) * 2) = sv; }
;         }
	v_mov_b32_e32 v110, v146
	s_waitcnt lgkmcnt(0)
	v_mov_b32_e32 v111, v148
	s_mov_b32 s2, s67
	v_mov_b32_e32 v126, v147
	v_mov_b32_e32 v127, v148
	v_pk_mul_f32 v[160:161], v[110:111], s[2:3] op_sel_hi:[1,0]
	v_pk_fma_f32 v[110:111], v[110:111], s[2:3], v[156:157] op_sel_hi:[1,0,1]
	v_pk_fma_f32 v[126:127], v[126:127], s[2:3], v[94:95] op_sel_hi:[1,0,1]
	v_pk_mul_f32 v[146:147], v[110:111], v[110:111]
	v_pk_mul_f32 v[94:95], v[126:127], v[126:127]
	v_pk_mov_b32 v[146:147], v[156:157], v[146:147] op_sel:[1,0]
	v_pk_mov_b32 v[94:95], v[160:161], v[94:95] op_sel:[1,0]
	v_add_f32_e32 v78, 0, v79
	v_pk_add_f32 v[94:95], v[146:147], v[94:95]
	v_pk_add_f32 v[146:147], v[110:111], v[126:127]
	v_pk_mul_f32 v[156:157], v[110:111], v[126:127]
	v_fmac_f32_e32 v78, 0x3fd744fd, v149
	v_mov_b32_e32 v147, v157
	v_pk_add_f32 v[94:95], v[146:147], v[94:95]
	v_mul_f32_e32 v79, v78, v78
	v_pk_add_f32 v[94:95], v[94:95], v[78:79]
	s_nop 1
	v_mov_b32_dpp v146, v94 quad_perm:[1,0,3,2] row_mask:0xf bank_mask:0xf bound_ctrl:1
	v_mov_b32_dpp v147, v95 quad_perm:[1,0,3,2] row_mask:0xf bank_mask:0xf bound_ctrl:1
	v_pk_add_f32 v[94:95], v[94:95], v[146:147]
	s_nop 1
	v_mov_b32_dpp v146, v94 quad_perm:[2,3,0,1] row_mask:0xf bank_mask:0xf bound_ctrl:1
	v_mov_b32_dpp v147, v95 quad_perm:[2,3,0,1] row_mask:0xf bank_mask:0xf bound_ctrl:1
	v_pk_add_f32 v[94:95], v[94:95], v[146:147]
	s_nop 1
	v_mov_b32_dpp v146, v94 row_half_mirror row_mask:0xf bank_mask:0xf bound_ctrl:1
	v_mov_b32_dpp v147, v95 row_half_mirror row_mask:0xf bank_mask:0xf bound_ctrl:1
	v_pk_add_f32 v[94:95], v[94:95], v[146:147]
	s_nop 1
	v_mov_b32_dpp v146, v94 row_mirror row_mask:0xf bank_mask:0xf bound_ctrl:1
	v_mov_b32_dpp v147, v95 row_mirror row_mask:0xf bank_mask:0xf bound_ctrl:1
	s_and_saveexec_b64 s[6:7], vcc
	v_pk_add_f32 v[94:95], v[94:95], v[146:147]
	ds_write_b64 v179, v[94:95] offset:200
	s_or_b64 exec, exec, s[6:7]
	v_or_b32_e32 v79, 0x1400, v154
	v_add_u32_e32 v79, v105, v79
	ds_read2_b32 v[146:147], v79 offset1:32
	ds_read2_b32 v[154:155], v79 offset0:64 offset1:96
	v_mov_b32_e32 v148, v128
	v_mov_b32_e32 v149, v96
	v_pk_add_f32 v[156:157], v[148:149], 0 op_sel_hi:[1,0]
	v_mov_b32_e32 v148, v112
	v_pk_add_f32 v[148:149], v[148:149], 0 op_sel_hi:[1,0]
	s_waitcnt lgkmcnt(1)
	v_mov_b32_e32 v160, v146
	s_waitcnt lgkmcnt(0)
	v_mov_b32_e32 v161, v154
	s_mov_b32 s2, s67
	v_mov_b32_e32 v174, v147
	v_mov_b32_e32 v175, v154
	v_pk_fma_f32 v[146:147], v[160:161], s[2:3], v[156:157] op_sel_hi:[1,0,1]
	v_pk_fma_f32 v[148:149], v[174:175], s[2:3], v[148:149] op_sel_hi:[1,0,1]
	v_pk_mul_f32 v[170:171], v[160:161], s[2:3] op_sel_hi:[1,0]
	v_pk_mul_f32 v[160:161], v[146:147], v[146:147]
	v_pk_mul_f32 v[174:175], v[148:149], v[148:149]
	v_pk_mov_b32 v[156:157], v[156:157], v[160:161] op_sel:[1,0]
	v_pk_mov_b32 v[160:161], v[170:171], v[174:175] op_sel:[1,0]
	v_add_f32_e32 v94, 0, v80
	v_pk_add_f32 v[156:157], v[156:157], v[160:161]
	v_pk_add_f32 v[160:161], v[146:147], v[148:149]
	v_pk_mul_f32 v[170:171], v[146:147], v[148:149]
	v_fmac_f32_e32 v94, 0x3fd744fd, v155
	v_mov_b32_e32 v161, v171
	v_pk_add_f32 v[156:157], v[160:161], v[156:157]
	v_mul_f32_e32 v95, v94, v94
	v_pk_add_f32 v[154:155], v[156:157], v[94:95]
	s_nop 1
	v_mov_b32_dpp v156, v154 quad_perm:[1,0,3,2] row_mask:0xf bank_mask:0xf bound_ctrl:1
	v_mov_b32_dpp v157, v155 quad_perm:[1,0,3,2] row_mask:0xf bank_mask:0xf bound_ctrl:1
	v_pk_add_f32 v[154:155], v[154:155], v[156:157]
	s_nop 1
	v_mov_b32_dpp v156, v154 quad_perm:[2,3,0,1] row_mask:0xf bank_mask:0xf bound_ctrl:1
	v_mov_b32_dpp v157, v155 quad_perm:[2,3,0,1] row_mask:0xf bank_mask:0xf bound_ctrl:1
	v_pk_add_f32 v[154:155], v[154:155], v[156:157]
	s_nop 1
	v_mov_b32_dpp v156, v154 row_half_mirror row_mask:0xf bank_mask:0xf bound_ctrl:1
	v_mov_b32_dpp v157, v155 row_half_mirror row_mask:0xf bank_mask:0xf bound_ctrl:1
	v_pk_add_f32 v[154:155], v[154:155], v[156:157]
	s_nop 1
	v_mov_b32_dpp v156, v154 row_mirror row_mask:0xf bank_mask:0xf bound_ctrl:1
	v_mov_b32_dpp v157, v155 row_mirror row_mask:0xf bank_mask:0xf bound_ctrl:1
	s_and_saveexec_b64 s[6:7], vcc
	v_pk_add_f32 v[154:155], v[154:155], v[156:157]
	ds_write_b64 v179, v[154:155] offset:208
	s_or_b64 exec, exec, s[6:7]
	v_add_u32_e32 v93, v105, v101
	ds_read2_b32 v[154:155], v93 offset1:32
	ds_read2_b32 v[156:157], v93 offset0:64 offset1:96
	v_mov_b32_e32 v96, v129
	v_pk_add_f32 v[128:129], v[96:97], 0 op_sel_hi:[1,0]
	v_mov_b32_e32 v96, v113
	v_pk_add_f32 v[112:113], v[96:97], 0 op_sel_hi:[1,0]
	s_waitcnt lgkmcnt(1)
	v_mov_b32_e32 v96, v154
	s_waitcnt lgkmcnt(0)
	v_mov_b32_e32 v97, v156
	s_mov_b32 s2, s67
	v_mov_b32_e32 v154, v155
	v_mov_b32_e32 v155, v156
	v_pk_mul_f32 v[160:161], v[96:97], s[2:3] op_sel_hi:[1,0]
	v_pk_fma_f32 v[96:97], v[96:97], s[2:3], v[128:129] op_sel_hi:[1,0,1]
	v_pk_fma_f32 v[112:113], v[154:155], s[2:3], v[112:113] op_sel_hi:[1,0,1]
	v_pk_mul_f32 v[170:171], v[96:97], v[96:97]
	v_pk_mul_f32 v[154:155], v[112:113], v[112:113]
	v_pk_mov_b32 v[128:129], v[128:129], v[170:171] op_sel:[1,0]
	v_pk_mov_b32 v[154:155], v[160:161], v[154:155] op_sel:[1,0]
	v_add_f32_e32 v80, 0, v81
	v_pk_add_f32 v[128:129], v[128:129], v[154:155]
	v_pk_add_f32 v[154:155], v[96:97], v[112:113]
	v_pk_mul_f32 v[160:161], v[96:97], v[112:113]
	v_fmac_f32_e32 v80, 0x3fd744fd, v157
	v_mov_b32_e32 v155, v161
	v_pk_add_f32 v[128:129], v[154:155], v[128:129]
	v_mul_f32_e32 v81, v80, v80
	v_pk_add_f32 v[128:129], v[128:129], v[80:81]
	s_nop 1
	v_mov_b32_dpp v154, v128 quad_perm:[1,0,3,2] row_mask:0xf bank_mask:0xf bound_ctrl:1
	v_mov_b32_dpp v155, v129 quad_perm:[1,0,3,2] row_mask:0xf bank_mask:0xf bound_ctrl:1
	v_pk_add_f32 v[128:129], v[128:129], v[154:155]
	s_nop 1
	v_mov_b32_dpp v154, v128 quad_perm:[2,3,0,1] row_mask:0xf bank_mask:0xf bound_ctrl:1
	v_mov_b32_dpp v155, v129 quad_perm:[2,3,0,1] row_mask:0xf bank_mask:0xf bound_ctrl:1
	v_pk_add_f32 v[128:129], v[128:129], v[154:155]
	s_nop 1
	v_mov_b32_dpp v154, v128 row_half_mirror row_mask:0xf bank_mask:0xf bound_ctrl:1
	v_mov_b32_dpp v155, v129 row_half_mirror row_mask:0xf bank_mask:0xf bound_ctrl:1
	v_pk_add_f32 v[128:129], v[128:129], v[154:155]
	s_nop 1
	v_mov_b32_dpp v154, v128 row_mirror row_mask:0xf bank_mask:0xf bound_ctrl:1
	v_mov_b32_dpp v155, v129 row_mirror row_mask:0xf bank_mask:0xf bound_ctrl:1
	s_and_saveexec_b64 s[6:7], vcc
	v_pk_add_f32 v[128:129], v[128:129], v[154:155]
	ds_write_b64 v179, v[128:129] offset:216
	s_or_b64 exec, exec, s[6:7]
	v_or_b32_e32 v128, 48, v159
	v_ashrrev_i32_e32 v129, 31, v128
	v_lshlrev_b64 v[128:129], 12, v[128:129]
	v_readfirstlane_b32 s2, v158
	v_lshl_add_u64 v[128:129], s[10:11], 0, v[128:129]
	s_lshl_b32 s2, s2, 13
	v_lshl_add_u64 v[128:129], v[182:183], 2, v[128:129]
	s_waitcnt lgkmcnt(0)
;   DI void xpass(int ps, int grow0, int gcol0, int lane, int w, char* lds) const {
;     char* xs = lds + (ps & 1) * 65536 + __builtin_amdgcn_readfirstlane(w) * 8192;
;     const float* xsrc = Xin + (size_t)(grow0 + (ps >> 1) * 32 + (ps & 1) * 16 + (lane >> 5)) * D_ + gcol0 + (lane & 31) * 4;
; #pragma unroll
;     for (int pc = 0; pc < 8; ++pc)
;       __builtin_amdgcn_global_load_lds((const unsigned*)(xsrc + (size_t)(2 * pc) * D_), (__attribute__((address_space(3))) unsigned*)(xs + pc * 1024), 16, 0, 0);
;   }
;   DI void operator()(f32x16 (&acc)[2][4], int grow0, int gcol0, int lane, int w, char* lds) {
;     ...
;       if (ps + 1 < 4) {
;         if (ps >= 1) asm volatile("s_waitcnt lgkmcnt(0)" ::: "memory");
;         xpass(ps + 1, grow0, gcol0, lane, w, lds);
;         if (ps >= 1) asm volatile("s_waitcnt vmcnt(8)" ::: "memory");
;       } else asm volatile("s_waitcnt vmcnt(0)" ::: "memory");
;       const char* xs = lds + (ps & 1) * 65536 + w * 8192;
; #pragma unroll
;       for (int qq = 0; qq < 2; ++qq)
; #pragma unroll
;         for (int e = 0; e < 4; ++e) {
;           const int i = 4 * (2 * (ps & 1) + qq) + e;
;           const float* xr = (const float*)(xs + (8 * qq + 4 * hh + e) * 512) + l31;
;           float s1 = 0.f, s2 = 0.f;
; #pragma unroll
;           for (int nt = 0; nt < 4; ++nt) {
;             float v = (acc[mt][nt][i] + bia[nt]) * csc[nt];
;             float z = ALPHA * xr[nt * 32] + hs * v;
;             acc[mt][nt][i] = z; s1 += z; s2 += z * z;
;           }
;           s1 = row16_sum(s1); s2 = row16_sum(s2);
;           if ((lane & 15) == 0) { f32x2 sv = {s1, s2}; *(f32x2*)(redw + (mt * 32 + (i & 3) + 8 * (i >> 2)) * 2) = sv; }
;         }
	s_add_i32 m0, s2, 0x10000
	v_lshl_add_u64 v[128:129], v[128:129], 0, v[0:1]
	s_mov_b64 s[6:7], 0x2000
	global_load_lds_dwordx4 v[128:129], off
	v_lshl_add_u64 v[154:155], v[128:129], 0, s[6:7]
	s_add_i32 m0, s2, 0x10400
	s_mov_b64 s[6:7], 0x4000
	global_load_lds_dwordx4 v[154:155], off
	v_lshl_add_u64 v[154:155], v[128:129], 0, s[6:7]
	s_add_i32 m0, s2, 0x10800
	s_mov_b64 s[6:7], 0x6000
	global_load_lds_dwordx4 v[154:155], off
	v_lshl_add_u64 v[154:155], v[128:129], 0, s[6:7]
	s_add_i32 m0, s2, 0x10c00
	s_mov_b64 s[6:7], 0x8000
	global_load_lds_dwordx4 v[154:155], off
	v_lshl_add_u64 v[154:155], v[128:129], 0, s[6:7]
	s_add_i32 m0, s2, 0x11000
	s_mov_b64 s[6:7], 0xa000
	global_load_lds_dwordx4 v[154:155], off
	v_lshl_add_u64 v[154:155], v[128:129], 0, s[6:7]
	s_add_i32 m0, s2, 0x11400
	s_mov_b64 s[6:7], 0xc000
	global_load_lds_dwordx4 v[154:155], off
	v_lshl_add_u64 v[154:155], v[128:129], 0, s[6:7]
	s_add_i32 m0, s2, 0x11800
	s_mov_b64 s[6:7], 0xe000
	global_load_lds_dwordx4 v[154:155], off
	v_lshl_add_u64 v[128:129], v[128:129], 0, s[6:7]
	s_add_i32 m0, s2, 0x11c00
	v_mov_b32_e32 v156, v50
	global_load_lds_dwordx4 v[128:129], off
	s_waitcnt vmcnt(8)
	ds_read2_b32 v[154:155], v168 offset1:32
	ds_read2_b32 v[158:159], v168 offset0:64 offset1:96
	v_mov_b32_e32 v157, v18
	v_pk_add_f32 v[160:161], v[156:157], 0 op_sel_hi:[1,0]
	v_mov_b32_e32 v156, v34
	v_pk_add_f32 v[156:157], v[156:157], 0 op_sel_hi:[1,0]
	s_waitcnt lgkmcnt(0)
	v_mov_b32_e32 v170, v154
	v_mov_b32_e32 v171, v158
	s_mov_b32 s2, s67
	v_mov_b32_e32 v176, v155
	v_mov_b32_e32 v177, v158
	v_pk_fma_f32 v[154:155], v[170:171], s[2:3], v[160:161] op_sel_hi:[1,0,1]
	v_pk_fma_f32 v[156:157], v[176:177], s[2:3], v[156:157] op_sel_hi:[1,0,1]
	v_pk_mul_f32 v[174:175], v[170:171], s[2:3] op_sel_hi:[1,0]
	v_pk_mul_f32 v[170:171], v[154:155], v[154:155]
	v_pk_mul_f32 v[176:177], v[156:157], v[156:157]
	v_pk_mov_b32 v[160:161], v[160:161], v[170:171] op_sel:[1,0]
	v_pk_mov_b32 v[170:171], v[174:175], v[176:177] op_sel:[1,0]
	v_add_f32_e32 v128, 0, v2
	v_pk_add_f32 v[160:161], v[160:161], v[170:171]
	v_pk_add_f32 v[170:171], v[154:155], v[156:157]
	v_pk_mul_f32 v[174:175], v[154:155], v[156:157]
	v_fmac_f32_e32 v128, 0x3fd744fd, v159
	v_mov_b32_e32 v171, v175
	v_pk_add_f32 v[160:161], v[170:171], v[160:161]
	v_mul_f32_e32 v129, v128, v128
	v_pk_add_f32 v[158:159], v[160:161], v[128:129]
	s_nop 1
	v_mov_b32_dpp v160, v158 quad_perm:[1,0,3,2] row_mask:0xf bank_mask:0xf bound_ctrl:1
	v_mov_b32_dpp v161, v159 quad_perm:[1,0,3,2] row_mask:0xf bank_mask:0xf bound_ctrl:1
	v_pk_add_f32 v[158:159], v[158:159], v[160:161]
	s_nop 1
	v_mov_b32_dpp v160, v158 quad_perm:[2,3,0,1] row_mask:0xf bank_mask:0xf bound_ctrl:1
	v_mov_b32_dpp v161, v159 quad_perm:[2,3,0,1] row_mask:0xf bank_mask:0xf bound_ctrl:1
	v_pk_add_f32 v[158:159], v[158:159], v[160:161]
	s_nop 1
	v_mov_b32_dpp v160, v158 row_half_mirror row_mask:0xf bank_mask:0xf bound_ctrl:1
	v_mov_b32_dpp v161, v159 row_half_mirror row_mask:0xf bank_mask:0xf bound_ctrl:1
	v_pk_add_f32 v[158:159], v[158:159], v[160:161]
	s_nop 1
	v_mov_b32_dpp v160, v158 row_mirror row_mask:0xf bank_mask:0xf bound_ctrl:1
	v_mov_b32_dpp v161, v159 row_mirror row_mask:0xf bank_mask:0xf bound_ctrl:1
	s_and_saveexec_b64 s[6:7], vcc
	v_pk_add_f32 v[158:159], v[158:159], v[160:161]
	ds_write_b64 v179, v[158:159] offset:256
	s_or_b64 exec, exec, s[6:7]
	ds_read2_b32 v[158:159], v168 offset0:128 offset1:160
	ds_read2_b32 v[160:161], v168 offset0:192 offset1:224
	v_mov_b32_e32 v18, v51
	v_pk_add_f32 v[168:169], v[18:19], 0 op_sel_hi:[1,0]
	v_mov_b32_e32 v18, v35
	v_pk_add_f32 v[18:19], v[18:19], 0 op_sel_hi:[1,0]
	s_waitcnt lgkmcnt(1)
	v_mov_b32_e32 v34, v158
	s_waitcnt lgkmcnt(0)
	v_mov_b32_e32 v35, v160
	s_mov_b32 s2, s67
	v_mov_b32_e32 v50, v159
	v_mov_b32_e32 v51, v160
	v_pk_mul_f32 v[170:171], v[34:35], s[2:3] op_sel_hi:[1,0]
	v_pk_fma_f32 v[34:35], v[34:35], s[2:3], v[168:169] op_sel_hi:[1,0,1]
	v_pk_fma_f32 v[50:51], v[50:51], s[2:3], v[18:19] op_sel_hi:[1,0,1]
	v_pk_mul_f32 v[158:159], v[34:35], v[34:35]
	v_pk_mul_f32 v[18:19], v[50:51], v[50:51]
	v_pk_mov_b32 v[158:159], v[168:169], v[158:159] op_sel:[1,0]
	v_pk_mov_b32 v[18:19], v[170:171], v[18:19] op_sel:[1,0]
	v_add_f32_e32 v2, 0, v3
	v_pk_add_f32 v[18:19], v[158:159], v[18:19]
	v_pk_add_f32 v[158:159], v[34:35], v[50:51]
	v_pk_mul_f32 v[168:169], v[34:35], v[50:51]
	v_fmac_f32_e32 v2, 0x3fd744fd, v161
	v_mov_b32_e32 v159, v169
	v_pk_add_f32 v[18:19], v[158:159], v[18:19]
	v_mul_f32_e32 v3, v2, v2
	v_pk_add_f32 v[18:19], v[18:19], v[2:3]
	s_nop 1
	v_mov_b32_dpp v158, v18 quad_perm:[1,0,3,2] row_mask:0xf bank_mask:0xf bound_ctrl:1
	v_mov_b32_dpp v159, v19 quad_perm:[1,0,3,2] row_mask:0xf bank_mask:0xf bound_ctrl:1
	v_pk_add_f32 v[18:19], v[18:19], v[158:159]
	s_nop 1
	v_mov_b32_dpp v158, v18 quad_perm:[2,3,0,1] row_mask:0xf bank_mask:0xf bound_ctrl:1
	v_mov_b32_dpp v159, v19 quad_perm:[2,3,0,1] row_mask:0xf bank_mask:0xf bound_ctrl:1
	v_pk_add_f32 v[18:19], v[18:19], v[158:159]
	s_nop 1
	v_mov_b32_dpp v158, v18 row_half_mirror row_mask:0xf bank_mask:0xf bound_ctrl:1
	v_mov_b32_dpp v159, v19 row_half_mirror row_mask:0xf bank_mask:0xf bound_ctrl:1
	v_pk_add_f32 v[18:19], v[18:19], v[158:159]
	s_nop 1
	v_mov_b32_dpp v158, v18 row_mirror row_mask:0xf bank_mask:0xf bound_ctrl:1
	v_mov_b32_dpp v159, v19 row_mirror row_mask:0xf bank_mask:0xf bound_ctrl:1
	s_and_saveexec_b64 s[6:7], vcc
	v_pk_add_f32 v[18:19], v[18:19], v[158:159]
	ds_write_b64 v179, v[18:19] offset:264
	s_or_b64 exec, exec, s[6:7]
	ds_read2_b32 v[158:159], v153 offset1:32
	ds_read2_b32 v[168:169], v153 offset0:64 offset1:96
	v_mov_b32_e32 v160, v52
	v_mov_b32_e32 v161, v20
	v_pk_add_f32 v[170:171], v[160:161], 0 op_sel_hi:[1,0]
	v_mov_b32_e32 v160, v36
	v_pk_add_f32 v[160:161], v[160:161], 0 op_sel_hi:[1,0]
	s_waitcnt lgkmcnt(1)
;   DI void operator()(f32x16 (&acc)[2][4], int grow0, int gcol0, int lane, int w, char* lds) {
;     ...
; #pragma unroll
;       for (int qq = 0; qq < 2; ++qq)
; #pragma unroll
;         for (int e = 0; e < 4; ++e) {
;           const int i = 4 * (2 * (ps & 1) + qq) + e;
;           const float* xr = (const float*)(xs + (8 * qq + 4 * hh + e) * 512) + l31;
;           float s1 = 0.f, s2 = 0.f;
; #pragma unroll
;           for (int nt = 0; nt < 4; ++nt) {
;             float v = (acc[mt][nt][i] + bia[nt]) * csc[nt];
;             float z = ALPHA * xr[nt * 32] + hs * v;
;             acc[mt][nt][i] = z; s1 += z; s2 += z * z;
;           }
;           s1 = row16_sum(s1); s2 = row16_sum(s2);
;           if ((lane & 15) == 0) { f32x2 sv = {s1, s2}; *(f32x2*)(redw + (mt * 32 + (i & 3) + 8 * (i >> 2)) * 2) = sv; }
;         }
	v_mov_b32_e32 v174, v158
	s_waitcnt lgkmcnt(0)
	v_mov_b32_e32 v175, v168
	s_mov_b32 s2, s67
	v_mov_b32_e32 v180, v159
	v_mov_b32_e32 v181, v168
	v_pk_fma_f32 v[158:159], v[174:175], s[2:3], v[170:171] op_sel_hi:[1,0,1]
	v_pk_fma_f32 v[160:161], v[180:181], s[2:3], v[160:161] op_sel_hi:[1,0,1]
	v_pk_mul_f32 v[176:177], v[174:175], s[2:3] op_sel_hi:[1,0]
	v_pk_mul_f32 v[174:175], v[158:159], v[158:159]
	v_pk_mul_f32 v[180:181], v[160:161], v[160:161]
	v_pk_mov_b32 v[170:171], v[170:171], v[174:175] op_sel:[1,0]
	v_pk_mov_b32 v[174:175], v[176:177], v[180:181] op_sel:[1,0]
	v_add_f32_e32 v18, 0, v4
	v_pk_add_f32 v[170:171], v[170:171], v[174:175]
	v_pk_add_f32 v[174:175], v[158:159], v[160:161]
	v_pk_mul_f32 v[176:177], v[158:159], v[160:161]
	v_fmac_f32_e32 v18, 0x3fd744fd, v169
	v_mov_b32_e32 v175, v177
	v_pk_add_f32 v[170:171], v[174:175], v[170:171]
	v_mul_f32_e32 v19, v18, v18
	v_pk_add_f32 v[168:169], v[170:171], v[18:19]
	s_nop 1
	v_mov_b32_dpp v170, v168 quad_perm:[1,0,3,2] row_mask:0xf bank_mask:0xf bound_ctrl:1
	v_mov_b32_dpp v171, v169 quad_perm:[1,0,3,2] row_mask:0xf bank_mask:0xf bound_ctrl:1
	v_pk_add_f32 v[168:169], v[168:169], v[170:171]
	s_nop 1
	v_mov_b32_dpp v170, v168 quad_perm:[2,3,0,1] row_mask:0xf bank_mask:0xf bound_ctrl:1
	v_mov_b32_dpp v171, v169 quad_perm:[2,3,0,1] row_mask:0xf bank_mask:0xf bound_ctrl:1
	v_pk_add_f32 v[168:169], v[168:169], v[170:171]
	s_nop 1
	v_mov_b32_dpp v170, v168 row_half_mirror row_mask:0xf bank_mask:0xf bound_ctrl:1
	v_mov_b32_dpp v171, v169 row_half_mirror row_mask:0xf bank_mask:0xf bound_ctrl:1
	v_pk_add_f32 v[168:169], v[168:169], v[170:171]
	s_nop 1
	v_mov_b32_dpp v170, v168 row_mirror row_mask:0xf bank_mask:0xf bound_ctrl:1
	v_mov_b32_dpp v171, v169 row_mirror row_mask:0xf bank_mask:0xf bound_ctrl:1
	s_and_saveexec_b64 s[6:7], vcc
	v_pk_add_f32 v[168:169], v[168:169], v[170:171]
	ds_write_b64 v179, v[168:169] offset:272
	s_or_b64 exec, exec, s[6:7]
	ds_read2_b32 v[168:169], v151 offset1:32
	ds_read2_b32 v[170:171], v151 offset0:64 offset1:96
	v_mov_b32_e32 v20, v53
	v_pk_add_f32 v[174:175], v[20:21], 0 op_sel_hi:[1,0]
	v_mov_b32_e32 v20, v37
	v_pk_add_f32 v[20:21], v[20:21], 0 op_sel_hi:[1,0]
	s_waitcnt lgkmcnt(1)
	v_mov_b32_e32 v36, v168
	s_waitcnt lgkmcnt(0)
	v_mov_b32_e32 v37, v170
	s_mov_b32 s2, s67
	v_mov_b32_e32 v52, v169
	v_mov_b32_e32 v53, v170
	v_pk_mul_f32 v[176:177], v[36:37], s[2:3] op_sel_hi:[1,0]
	v_pk_fma_f32 v[36:37], v[36:37], s[2:3], v[174:175] op_sel_hi:[1,0,1]
	v_pk_fma_f32 v[52:53], v[52:53], s[2:3], v[20:21] op_sel_hi:[1,0,1]
	v_pk_mul_f32 v[168:169], v[36:37], v[36:37]
	v_pk_mul_f32 v[20:21], v[52:53], v[52:53]
	v_pk_mov_b32 v[168:169], v[174:175], v[168:169] op_sel:[1,0]
	v_pk_mov_b32 v[20:21], v[176:177], v[20:21] op_sel:[1,0]
	v_add_f32_e32 v4, 0, v5
	v_pk_add_f32 v[20:21], v[168:169], v[20:21]
	v_pk_add_f32 v[168:169], v[36:37], v[52:53]
	v_pk_mul_f32 v[174:175], v[36:37], v[52:53]
	v_fmac_f32_e32 v4, 0x3fd744fd, v171
	v_mov_b32_e32 v169, v175
	v_pk_add_f32 v[20:21], v[168:169], v[20:21]
	v_mul_f32_e32 v5, v4, v4
	v_pk_add_f32 v[20:21], v[20:21], v[4:5]
	s_nop 1
	v_mov_b32_dpp v168, v20 quad_perm:[1,0,3,2] row_mask:0xf bank_mask:0xf bound_ctrl:1
	v_mov_b32_dpp v169, v21 quad_perm:[1,0,3,2] row_mask:0xf bank_mask:0xf bound_ctrl:1
	v_pk_add_f32 v[20:21], v[20:21], v[168:169]
	s_nop 1
	v_mov_b32_dpp v168, v20 quad_perm:[2,3,0,1] row_mask:0xf bank_mask:0xf bound_ctrl:1
	v_mov_b32_dpp v169, v21 quad_perm:[2,3,0,1] row_mask:0xf bank_mask:0xf bound_ctrl:1
	v_pk_add_f32 v[20:21], v[20:21], v[168:169]
	s_nop 1
	v_mov_b32_dpp v168, v20 row_half_mirror row_mask:0xf bank_mask:0xf bound_ctrl:1
	v_mov_b32_dpp v169, v21 row_half_mirror row_mask:0xf bank_mask:0xf bound_ctrl:1
	v_pk_add_f32 v[20:21], v[20:21], v[168:169]
	s_nop 1
	v_mov_b32_dpp v168, v20 row_mirror row_mask:0xf bank_mask:0xf bound_ctrl:1
	v_mov_b32_dpp v169, v21 row_mirror row_mask:0xf bank_mask:0xf bound_ctrl:1
	s_and_saveexec_b64 s[6:7], vcc
	v_pk_add_f32 v[20:21], v[20:21], v[168:169]
	ds_write_b64 v179, v[20:21] offset:280
	s_or_b64 exec, exec, s[6:7]
	ds_read2_b32 v[168:169], v67 offset1:32
	ds_read2_b32 v[174:175], v67 offset0:64 offset1:96
	v_mov_b32_e32 v170, v54
	v_mov_b32_e32 v171, v22
	v_pk_add_f32 v[176:177], v[170:171], 0 op_sel_hi:[1,0]
	v_mov_b32_e32 v170, v38
	v_pk_add_f32 v[170:171], v[170:171], 0 op_sel_hi:[1,0]
	s_waitcnt lgkmcnt(1)
	v_mov_b32_e32 v180, v168
	s_waitcnt lgkmcnt(0)
	v_mov_b32_e32 v181, v174
	s_mov_b32 s2, s67
	v_mov_b32_e32 v190, v169
	v_mov_b32_e32 v191, v174
	v_pk_fma_f32 v[168:169], v[180:181], s[2:3], v[176:177] op_sel_hi:[1,0,1]
	v_pk_fma_f32 v[170:171], v[190:191], s[2:3], v[170:171] op_sel_hi:[1,0,1]
	v_pk_mul_f32 v[184:185], v[180:181], s[2:3] op_sel_hi:[1,0]
	v_pk_mul_f32 v[180:181], v[168:169], v[168:169]
	v_pk_mul_f32 v[190:191], v[170:171], v[170:171]
	v_pk_mov_b32 v[176:177], v[176:177], v[180:181] op_sel:[1,0]
	v_pk_mov_b32 v[180:181], v[184:185], v[190:191] op_sel:[1,0]
	v_add_f32_e32 v20, 0, v6
	v_pk_add_f32 v[176:177], v[176:177], v[180:181]
	v_pk_add_f32 v[180:181], v[168:169], v[170:171]
	v_pk_mul_f32 v[184:185], v[168:169], v[170:171]
	v_fmac_f32_e32 v20, 0x3fd744fd, v175
	v_mov_b32_e32 v181, v185
	v_pk_add_f32 v[176:177], v[180:181], v[176:177]
	v_mul_f32_e32 v21, v20, v20
	v_pk_add_f32 v[174:175], v[176:177], v[20:21]
	s_nop 1
	v_mov_b32_dpp v176, v174 quad_perm:[1,0,3,2] row_mask:0xf bank_mask:0xf bound_ctrl:1
	v_mov_b32_dpp v177, v175 quad_perm:[1,0,3,2] row_mask:0xf bank_mask:0xf bound_ctrl:1
	v_pk_add_f32 v[174:175], v[174:175], v[176:177]
	s_nop 1
	v_mov_b32_dpp v176, v174 quad_perm:[2,3,0,1] row_mask:0xf bank_mask:0xf bound_ctrl:1
	v_mov_b32_dpp v177, v175 quad_perm:[2,3,0,1] row_mask:0xf bank_mask:0xf bound_ctrl:1
	v_pk_add_f32 v[174:175], v[174:175], v[176:177]
	s_nop 1
	v_mov_b32_dpp v176, v174 row_half_mirror row_mask:0xf bank_mask:0xf bound_ctrl:1
	v_mov_b32_dpp v177, v175 row_half_mirror row_mask:0xf bank_mask:0xf bound_ctrl:1
	v_pk_add_f32 v[174:175], v[174:175], v[176:177]
	s_nop 1
	v_mov_b32_dpp v176, v174 row_mirror row_mask:0xf bank_mask:0xf bound_ctrl:1
	v_mov_b32_dpp v177, v175 row_mirror row_mask:0xf bank_mask:0xf bound_ctrl:1
	s_and_saveexec_b64 s[6:7], vcc
	v_pk_add_f32 v[174:175], v[174:175], v[176:177]
	ds_write_b64 v179, v[174:175] offset:320
	s_or_b64 exec, exec, s[6:7]
	ds_read2_b32 v[174:175], v67 offset0:128 offset1:160
	ds_read2_b32 v[176:177], v67 offset0:192 offset1:224
	v_mov_b32_e32 v22, v55
	v_pk_add_f32 v[180:181], v[22:23], 0 op_sel_hi:[1,0]
	v_mov_b32_e32 v22, v39
	v_pk_add_f32 v[22:23], v[22:23], 0 op_sel_hi:[1,0]
	s_waitcnt lgkmcnt(1)
;   DI void operator()(f32x16 (&acc)[2][4], int grow0, int gcol0, int lane, int w, char* lds) {
;     ...
;       if (ps + 1 < 4) {
;         if (ps >= 1) asm volatile("s_waitcnt lgkmcnt(0)" ::: "memory");
;         xpass(ps + 1, grow0, gcol0, lane, w, lds);
;         if (ps >= 1) asm volatile("s_waitcnt vmcnt(8)" ::: "memory");
;       } else asm volatile("s_waitcnt vmcnt(0)" ::: "memory");
;       const char* xs = lds + (ps & 1) * 65536 + w * 8192;
; #pragma unroll
;       for (int qq = 0; qq < 2; ++qq)
; #pragma unroll
;         for (int e = 0; e < 4; ++e) {
;           const int i = 4 * (2 * (ps & 1) + qq) + e;
;           const float* xr = (const float*)(xs + (8 * qq + 4 * hh + e) * 512) + l31;
;           float s1 = 0.f, s2 = 0.f;
; #pragma unroll
;           for (int nt = 0; nt < 4; ++nt) {
;             float v = (acc[mt][nt][i] + bia[nt]) * csc[nt];
;             float z = ALPHA * xr[nt * 32] + hs * v;
;             acc[mt][nt][i] = z; s1 += z; s2 += z * z;
;           }
;           s1 = row16_sum(s1); s2 = row16_sum(s2);
;           if ((lane & 15) == 0) { f32x2 sv = {s1, s2}; *(f32x2*)(redw + (mt * 32 + (i & 3) + 8 * (i >> 2)) * 2) = sv; }
;         }
	v_mov_b32_e32 v38, v174
	s_waitcnt lgkmcnt(0)
	v_mov_b32_e32 v39, v176
	s_mov_b32 s2, s67
	v_mov_b32_e32 v54, v175
	v_mov_b32_e32 v55, v176
	v_pk_mul_f32 v[184:185], v[38:39], s[2:3] op_sel_hi:[1,0]
	v_pk_fma_f32 v[38:39], v[38:39], s[2:3], v[180:181] op_sel_hi:[1,0,1]
	v_pk_fma_f32 v[54:55], v[54:55], s[2:3], v[22:23] op_sel_hi:[1,0,1]
	v_pk_mul_f32 v[174:175], v[38:39], v[38:39]
	v_pk_mul_f32 v[22:23], v[54:55], v[54:55]
	v_pk_mov_b32 v[174:175], v[180:181], v[174:175] op_sel:[1,0]
	v_pk_mov_b32 v[22:23], v[184:185], v[22:23] op_sel:[1,0]
	v_add_f32_e32 v6, 0, v7
	v_pk_add_f32 v[22:23], v[174:175], v[22:23]
	v_pk_add_f32 v[174:175], v[38:39], v[54:55]
	v_pk_mul_f32 v[180:181], v[38:39], v[54:55]
	v_fmac_f32_e32 v6, 0x3fd744fd, v177
	v_mov_b32_e32 v175, v181
	v_pk_add_f32 v[22:23], v[174:175], v[22:23]
	v_mul_f32_e32 v7, v6, v6
	v_pk_add_f32 v[22:23], v[22:23], v[6:7]
	s_nop 1
	v_mov_b32_dpp v174, v22 quad_perm:[1,0,3,2] row_mask:0xf bank_mask:0xf bound_ctrl:1
	v_mov_b32_dpp v175, v23 quad_perm:[1,0,3,2] row_mask:0xf bank_mask:0xf bound_ctrl:1
	v_pk_add_f32 v[22:23], v[22:23], v[174:175]
	s_nop 1
	v_mov_b32_dpp v174, v22 quad_perm:[2,3,0,1] row_mask:0xf bank_mask:0xf bound_ctrl:1
	v_mov_b32_dpp v175, v23 quad_perm:[2,3,0,1] row_mask:0xf bank_mask:0xf bound_ctrl:1
	v_pk_add_f32 v[22:23], v[22:23], v[174:175]
	s_nop 1
	v_mov_b32_dpp v174, v22 row_half_mirror row_mask:0xf bank_mask:0xf bound_ctrl:1
	v_mov_b32_dpp v175, v23 row_half_mirror row_mask:0xf bank_mask:0xf bound_ctrl:1
	v_pk_add_f32 v[22:23], v[22:23], v[174:175]
	s_nop 1
	v_mov_b32_dpp v174, v22 row_mirror row_mask:0xf bank_mask:0xf bound_ctrl:1
	v_mov_b32_dpp v175, v23 row_mirror row_mask:0xf bank_mask:0xf bound_ctrl:1
	s_and_saveexec_b64 s[6:7], vcc
	v_pk_add_f32 v[22:23], v[22:23], v[174:175]
	ds_write_b64 v179, v[22:23] offset:328
	s_or_b64 exec, exec, s[6:7]
	ds_read2_b32 v[174:175], v69 offset1:32
	ds_read2_b32 v[180:181], v69 offset0:64 offset1:96
	v_mov_b32_e32 v176, v56
	v_mov_b32_e32 v177, v24
	v_pk_add_f32 v[184:185], v[176:177], 0 op_sel_hi:[1,0]
	v_mov_b32_e32 v176, v40
	v_pk_add_f32 v[176:177], v[176:177], 0 op_sel_hi:[1,0]
	s_waitcnt lgkmcnt(1)
	v_mov_b32_e32 v190, v174
	s_waitcnt lgkmcnt(0)
	v_mov_b32_e32 v191, v180
	s_mov_b32 s2, s67
	v_mov_b32_e32 v194, v175
	v_mov_b32_e32 v195, v180
	v_pk_fma_f32 v[174:175], v[190:191], s[2:3], v[184:185] op_sel_hi:[1,0,1]
	v_pk_fma_f32 v[176:177], v[194:195], s[2:3], v[176:177] op_sel_hi:[1,0,1]
	v_pk_mul_f32 v[192:193], v[190:191], s[2:3] op_sel_hi:[1,0]
	v_pk_mul_f32 v[190:191], v[174:175], v[174:175]
	v_pk_mul_f32 v[194:195], v[176:177], v[176:177]
	v_pk_mov_b32 v[184:185], v[184:185], v[190:191] op_sel:[1,0]
	v_pk_mov_b32 v[190:191], v[192:193], v[194:195] op_sel:[1,0]
	v_add_f32_e32 v22, 0, v8
	v_pk_add_f32 v[184:185], v[184:185], v[190:191]
	v_pk_add_f32 v[190:191], v[174:175], v[176:177]
	v_pk_mul_f32 v[192:193], v[174:175], v[176:177]
	v_fmac_f32_e32 v22, 0x3fd744fd, v181
	v_mov_b32_e32 v191, v193
	v_pk_add_f32 v[184:185], v[190:191], v[184:185]
	v_mul_f32_e32 v23, v22, v22
	v_pk_add_f32 v[180:181], v[184:185], v[22:23]
	s_nop 1
	v_mov_b32_dpp v184, v180 quad_perm:[1,0,3,2] row_mask:0xf bank_mask:0xf bound_ctrl:1
	v_mov_b32_dpp v185, v181 quad_perm:[1,0,3,2] row_mask:0xf bank_mask:0xf bound_ctrl:1
	v_pk_add_f32 v[180:181], v[180:181], v[184:185]
	s_nop 1
	v_mov_b32_dpp v184, v180 quad_perm:[2,3,0,1] row_mask:0xf bank_mask:0xf bound_ctrl:1
	v_mov_b32_dpp v185, v181 quad_perm:[2,3,0,1] row_mask:0xf bank_mask:0xf bound_ctrl:1
	v_pk_add_f32 v[180:181], v[180:181], v[184:185]
	s_nop 1
	v_mov_b32_dpp v184, v180 row_half_mirror row_mask:0xf bank_mask:0xf bound_ctrl:1
	v_mov_b32_dpp v185, v181 row_half_mirror row_mask:0xf bank_mask:0xf bound_ctrl:1
	v_pk_add_f32 v[180:181], v[180:181], v[184:185]
	s_nop 1
	v_mov_b32_dpp v184, v180 row_mirror row_mask:0xf bank_mask:0xf bound_ctrl:1
	v_mov_b32_dpp v185, v181 row_mirror row_mask:0xf bank_mask:0xf bound_ctrl:1
	s_and_saveexec_b64 s[6:7], vcc
	v_pk_add_f32 v[180:181], v[180:181], v[184:185]
	ds_write_b64 v179, v[180:181] offset:336
	s_or_b64 exec, exec, s[6:7]
	ds_read2_b32 v[180:181], v71 offset1:32
	ds_read2_b32 v[184:185], v71 offset0:64 offset1:96
	v_mov_b32_e32 v24, v57
	v_pk_add_f32 v[190:191], v[24:25], 0 op_sel_hi:[1,0]
	v_mov_b32_e32 v24, v41
	v_pk_add_f32 v[24:25], v[24:25], 0 op_sel_hi:[1,0]
	s_waitcnt lgkmcnt(1)
	v_mov_b32_e32 v40, v180
	s_waitcnt lgkmcnt(0)
	v_mov_b32_e32 v41, v184
	s_mov_b32 s2, s67
	v_mov_b32_e32 v56, v181
	v_mov_b32_e32 v57, v184
	v_pk_mul_f32 v[192:193], v[40:41], s[2:3] op_sel_hi:[1,0]
	v_pk_fma_f32 v[40:41], v[40:41], s[2:3], v[190:191] op_sel_hi:[1,0,1]
	v_pk_fma_f32 v[56:57], v[56:57], s[2:3], v[24:25] op_sel_hi:[1,0,1]
	v_pk_mul_f32 v[180:181], v[40:41], v[40:41]
	v_pk_mul_f32 v[24:25], v[56:57], v[56:57]
	v_pk_mov_b32 v[180:181], v[190:191], v[180:181] op_sel:[1,0]
	v_pk_mov_b32 v[24:25], v[192:193], v[24:25] op_sel:[1,0]
	v_add_f32_e32 v8, 0, v9
	v_pk_add_f32 v[24:25], v[180:181], v[24:25]
	v_pk_add_f32 v[180:181], v[40:41], v[56:57]
	v_pk_mul_f32 v[190:191], v[40:41], v[56:57]
	v_fmac_f32_e32 v8, 0x3fd744fd, v185
	v_mov_b32_e32 v181, v191
	v_pk_add_f32 v[24:25], v[180:181], v[24:25]
	v_mul_f32_e32 v9, v8, v8
	v_pk_add_f32 v[24:25], v[24:25], v[8:9]
	s_nop 1
	v_mov_b32_dpp v180, v24 quad_perm:[1,0,3,2] row_mask:0xf bank_mask:0xf bound_ctrl:1
	v_mov_b32_dpp v181, v25 quad_perm:[1,0,3,2] row_mask:0xf bank_mask:0xf bound_ctrl:1
	v_pk_add_f32 v[24:25], v[24:25], v[180:181]
	s_nop 1
	v_mov_b32_dpp v180, v24 quad_perm:[2,3,0,1] row_mask:0xf bank_mask:0xf bound_ctrl:1
	v_mov_b32_dpp v181, v25 quad_perm:[2,3,0,1] row_mask:0xf bank_mask:0xf bound_ctrl:1
	v_pk_add_f32 v[24:25], v[24:25], v[180:181]
	s_nop 1
	v_mov_b32_dpp v180, v24 row_half_mirror row_mask:0xf bank_mask:0xf bound_ctrl:1
	v_mov_b32_dpp v181, v25 row_half_mirror row_mask:0xf bank_mask:0xf bound_ctrl:1
	v_pk_add_f32 v[24:25], v[24:25], v[180:181]
	s_nop 1
	v_mov_b32_dpp v180, v24 row_mirror row_mask:0xf bank_mask:0xf bound_ctrl:1
	v_mov_b32_dpp v181, v25 row_mirror row_mask:0xf bank_mask:0xf bound_ctrl:1
	s_and_saveexec_b64 s[6:7], vcc
	v_pk_add_f32 v[24:25], v[24:25], v[180:181]
	ds_write_b64 v179, v[24:25] offset:344
	s_or_b64 exec, exec, s[6:7]
	s_waitcnt vmcnt(0)
;   DI void operator()(f32x16 (&acc)[2][4], int grow0, int gcol0, int lane, int w, char* lds) {
;     ...
; #pragma unroll
;       for (int qq = 0; qq < 2; ++qq)
; #pragma unroll
;         for (int e = 0; e < 4; ++e) {
;           const int i = 4 * (2 * (ps & 1) + qq) + e;
;           const float* xr = (const float*)(xs + (8 * qq + 4 * hh + e) * 512) + l31;
;           float s1 = 0.f, s2 = 0.f;
; #pragma unroll
;           for (int nt = 0; nt < 4; ++nt) {
;             float v = (acc[mt][nt][i] + bia[nt]) * csc[nt];
;             float z = ALPHA * xr[nt * 32] + hs * v;
;             acc[mt][nt][i] = z; s1 += z; s2 += z * z;
;           }
;           s1 = row16_sum(s1); s2 = row16_sum(s2);
;           if ((lane & 15) == 0) { f32x2 sv = {s1, s2}; *(f32x2*)(redw + (mt * 32 + (i & 3) + 8 * (i >> 2)) * 2) = sv; }
;         }
	ds_read2_b32 v[184:185], v73 offset1:32
	ds_read2_b32 v[192:193], v73 offset0:64 offset1:96
	v_add_f32_e32 v181, 0, v42
	v_mov_b32_e32 v190, v58
	v_mov_b32_e32 v191, v26
	s_waitcnt lgkmcnt(1)
	v_fmac_f32_e32 v181, 0x3fd744fd, v185
	v_pk_add_f32 v[194:195], v[190:191], 0 op_sel_hi:[1,0]
	s_waitcnt lgkmcnt(0)
	v_mov_b32_e32 v185, v192
	s_mov_b32 s2, s67
	v_pk_fma_f32 v[190:191], v[184:185], s[2:3], v[194:195] op_sel_hi:[1,0,1]
	v_mov_b32_e32 v180, v192
	v_pk_mul_f32 v[184:185], v[190:191], v[190:191]
	v_mov_b32_e32 v196, v165
	v_mov_b32_e32 v197, v181
	v_pk_mov_b32 v[184:185], v[194:195], v[184:185] op_sel:[1,0]
	v_add_f32_e32 v24, 0, v10
	v_pk_fma_f32 v[184:185], v[180:181], v[196:197], v[184:185]
	v_fmac_f32_e32 v24, 0x3fd744fd, v193
	v_pk_mov_b32 v[194:195], v[180:181], v[184:185] op_sel:[1,0]
	v_mul_f32_e32 v25, v24, v24
	v_pk_add_f32 v[196:197], v[190:191], v[194:195]
	v_pk_mul_f32 v[194:195], v[190:191], v[194:195]
	s_nop 0
	v_mov_b32_e32 v197, v195
	v_pk_add_f32 v[194:195], v[184:185], v[196:197]
	s_nop 0
	v_pk_add_f32 v[192:193], v[194:195], v[24:25]
	s_nop 1
	v_mov_b32_dpp v194, v192 quad_perm:[1,0,3,2] row_mask:0xf bank_mask:0xf bound_ctrl:1
	v_mov_b32_dpp v195, v193 quad_perm:[1,0,3,2] row_mask:0xf bank_mask:0xf bound_ctrl:1
	v_pk_add_f32 v[192:193], v[192:193], v[194:195]
	s_nop 1
	v_mov_b32_dpp v194, v192 quad_perm:[2,3,0,1] row_mask:0xf bank_mask:0xf bound_ctrl:1
	v_mov_b32_dpp v195, v193 quad_perm:[2,3,0,1] row_mask:0xf bank_mask:0xf bound_ctrl:1
	v_pk_add_f32 v[192:193], v[192:193], v[194:195]
	s_nop 1
	v_mov_b32_dpp v194, v192 row_half_mirror row_mask:0xf bank_mask:0xf bound_ctrl:1
	v_mov_b32_dpp v195, v193 row_half_mirror row_mask:0xf bank_mask:0xf bound_ctrl:1
	v_pk_add_f32 v[192:193], v[192:193], v[194:195]
	s_nop 1
	v_mov_b32_dpp v194, v192 row_mirror row_mask:0xf bank_mask:0xf bound_ctrl:1
	v_mov_b32_dpp v195, v193 row_mirror row_mask:0xf bank_mask:0xf bound_ctrl:1
	s_and_saveexec_b64 s[6:7], vcc
	v_pk_add_f32 v[192:193], v[192:193], v[194:195]
	ds_write_b64 v179, v[192:193] offset:384
	s_or_b64 exec, exec, s[6:7]
	ds_read2_b32 v[192:193], v85 offset1:32
	ds_read2_b32 v[194:195], v85 offset0:64 offset1:96
	v_mov_b32_e32 v26, v59
	v_pk_add_f32 v[196:197], v[26:27], 0 op_sel_hi:[1,0]
	v_mov_b32_e32 v26, v43
	v_pk_add_f32 v[26:27], v[26:27], 0 op_sel_hi:[1,0]
	s_waitcnt lgkmcnt(1)
	v_mov_b32_e32 v42, v192
	s_waitcnt lgkmcnt(0)
	v_mov_b32_e32 v43, v194
	s_mov_b32 s2, s67
	v_mov_b32_e32 v58, v193
	v_mov_b32_e32 v59, v194
	v_pk_mul_f32 v[198:199], v[42:43], s[2:3] op_sel_hi:[1,0]
	v_pk_fma_f32 v[42:43], v[42:43], s[2:3], v[196:197] op_sel_hi:[1,0,1]
	v_pk_fma_f32 v[58:59], v[58:59], s[2:3], v[26:27] op_sel_hi:[1,0,1]
	v_pk_mul_f32 v[192:193], v[42:43], v[42:43]
	v_pk_mul_f32 v[26:27], v[58:59], v[58:59]
	v_pk_mov_b32 v[192:193], v[196:197], v[192:193] op_sel:[1,0]
	v_pk_mov_b32 v[26:27], v[198:199], v[26:27] op_sel:[1,0]
	v_add_f32_e32 v10, 0, v11
	v_pk_add_f32 v[26:27], v[192:193], v[26:27]
	v_pk_add_f32 v[192:193], v[42:43], v[58:59]
	v_pk_mul_f32 v[196:197], v[42:43], v[58:59]
	v_fmac_f32_e32 v10, 0x3fd744fd, v195
	v_mov_b32_e32 v193, v197
	v_pk_add_f32 v[26:27], v[192:193], v[26:27]
	v_mul_f32_e32 v11, v10, v10
	v_pk_add_f32 v[26:27], v[26:27], v[10:11]
	s_nop 1
	v_mov_b32_dpp v192, v26 quad_perm:[1,0,3,2] row_mask:0xf bank_mask:0xf bound_ctrl:1
	v_mov_b32_dpp v193, v27 quad_perm:[1,0,3,2] row_mask:0xf bank_mask:0xf bound_ctrl:1
	v_pk_add_f32 v[26:27], v[26:27], v[192:193]
	s_nop 1
	v_mov_b32_dpp v192, v26 quad_perm:[2,3,0,1] row_mask:0xf bank_mask:0xf bound_ctrl:1
	v_mov_b32_dpp v193, v27 quad_perm:[2,3,0,1] row_mask:0xf bank_mask:0xf bound_ctrl:1
	v_pk_add_f32 v[26:27], v[26:27], v[192:193]
	s_nop 1
	v_mov_b32_dpp v192, v26 row_half_mirror row_mask:0xf bank_mask:0xf bound_ctrl:1
	v_mov_b32_dpp v193, v27 row_half_mirror row_mask:0xf bank_mask:0xf bound_ctrl:1
	v_pk_add_f32 v[26:27], v[26:27], v[192:193]
	s_nop 1
	v_mov_b32_dpp v192, v26 row_mirror row_mask:0xf bank_mask:0xf bound_ctrl:1
	v_mov_b32_dpp v193, v27 row_mirror row_mask:0xf bank_mask:0xf bound_ctrl:1
	s_and_saveexec_b64 s[6:7], vcc
	v_pk_add_f32 v[26:27], v[26:27], v[192:193]
	ds_write_b64 v179, v[26:27] offset:392
	s_or_b64 exec, exec, s[6:7]
	ds_read2_b32 v[192:193], v75 offset1:32
	ds_read2_b32 v[196:197], v75 offset0:64 offset1:96
	v_mov_b32_e32 v194, v60
	v_mov_b32_e32 v195, v28
	v_pk_add_f32 v[198:199], v[194:195], 0 op_sel_hi:[1,0]
	v_mov_b32_e32 v194, v44
	v_pk_add_f32 v[194:195], v[194:195], 0 op_sel_hi:[1,0]
	s_waitcnt lgkmcnt(1)
	v_mov_b32_e32 v202, v192
	s_waitcnt lgkmcnt(0)
	v_mov_b32_e32 v203, v196
	s_mov_b32 s2, s67
	v_mov_b32_e32 v206, v193
	v_mov_b32_e32 v207, v196
	v_pk_fma_f32 v[192:193], v[202:203], s[2:3], v[198:199] op_sel_hi:[1,0,1]
	v_pk_fma_f32 v[194:195], v[206:207], s[2:3], v[194:195] op_sel_hi:[1,0,1]
	v_pk_mul_f32 v[204:205], v[202:203], s[2:3] op_sel_hi:[1,0]
	v_pk_mul_f32 v[202:203], v[192:193], v[192:193]
	v_pk_mul_f32 v[206:207], v[194:195], v[194:195]
	v_pk_mov_b32 v[198:199], v[198:199], v[202:203] op_sel:[1,0]
	v_pk_mov_b32 v[202:203], v[204:205], v[206:207] op_sel:[1,0]
	v_add_f32_e32 v26, 0, v12
	v_pk_add_f32 v[198:199], v[198:199], v[202:203]
	v_pk_add_f32 v[202:203], v[192:193], v[194:195]
	v_pk_mul_f32 v[204:205], v[192:193], v[194:195]
	v_fmac_f32_e32 v26, 0x3fd744fd, v197
	v_mov_b32_e32 v203, v205
	v_pk_add_f32 v[198:199], v[202:203], v[198:199]
	v_mul_f32_e32 v27, v26, v26
	v_pk_add_f32 v[196:197], v[198:199], v[26:27]
	s_nop 1
	v_mov_b32_dpp v198, v196 quad_perm:[1,0,3,2] row_mask:0xf bank_mask:0xf bound_ctrl:1
	v_mov_b32_dpp v199, v197 quad_perm:[1,0,3,2] row_mask:0xf bank_mask:0xf bound_ctrl:1
	v_pk_add_f32 v[196:197], v[196:197], v[198:199]
	s_nop 1
	v_mov_b32_dpp v198, v196 quad_perm:[2,3,0,1] row_mask:0xf bank_mask:0xf bound_ctrl:1
	v_mov_b32_dpp v199, v197 quad_perm:[2,3,0,1] row_mask:0xf bank_mask:0xf bound_ctrl:1
	v_pk_add_f32 v[196:197], v[196:197], v[198:199]
	s_nop 1
	v_mov_b32_dpp v198, v196 row_half_mirror row_mask:0xf bank_mask:0xf bound_ctrl:1
	v_mov_b32_dpp v199, v197 row_half_mirror row_mask:0xf bank_mask:0xf bound_ctrl:1
	v_pk_add_f32 v[196:197], v[196:197], v[198:199]
	s_nop 1
	v_mov_b32_dpp v198, v196 row_mirror row_mask:0xf bank_mask:0xf bound_ctrl:1
	v_mov_b32_dpp v199, v197 row_mirror row_mask:0xf bank_mask:0xf bound_ctrl:1
	s_and_saveexec_b64 s[6:7], vcc
	v_pk_add_f32 v[196:197], v[196:197], v[198:199]
	ds_write_b64 v179, v[196:197] offset:400
	s_or_b64 exec, exec, s[6:7]
	ds_read2_b32 v[196:197], v87 offset1:32
	ds_read2_b32 v[198:199], v87 offset0:64 offset1:96
	v_mov_b32_e32 v28, v61
	v_pk_add_f32 v[202:203], v[28:29], 0 op_sel_hi:[1,0]
	v_mov_b32_e32 v28, v45
	v_pk_add_f32 v[28:29], v[28:29], 0 op_sel_hi:[1,0]
	s_waitcnt lgkmcnt(1)
;   DI void operator()(f32x16 (&acc)[2][4], int grow0, int gcol0, int lane, int w, char* lds) {
;     ...
; #pragma unroll
;       for (int qq = 0; qq < 2; ++qq)
; #pragma unroll
;         for (int e = 0; e < 4; ++e) {
;           const int i = 4 * (2 * (ps & 1) + qq) + e;
;           const float* xr = (const float*)(xs + (8 * qq + 4 * hh + e) * 512) + l31;
;           float s1 = 0.f, s2 = 0.f;
; #pragma unroll
;           for (int nt = 0; nt < 4; ++nt) {
;             float v = (acc[mt][nt][i] + bia[nt]) * csc[nt];
;             float z = ALPHA * xr[nt * 32] + hs * v;
;             acc[mt][nt][i] = z; s1 += z; s2 += z * z;
;           }
;           s1 = row16_sum(s1); s2 = row16_sum(s2);
;           if ((lane & 15) == 0) { f32x2 sv = {s1, s2}; *(f32x2*)(redw + (mt * 32 + (i & 3) + 8 * (i >> 2)) * 2) = sv; }
;         }
	v_mov_b32_e32 v44, v196
	s_waitcnt lgkmcnt(0)
	v_mov_b32_e32 v45, v198
	s_mov_b32 s2, s67
	v_mov_b32_e32 v60, v197
	v_mov_b32_e32 v61, v198
	v_pk_mul_f32 v[204:205], v[44:45], s[2:3] op_sel_hi:[1,0]
	v_pk_fma_f32 v[44:45], v[44:45], s[2:3], v[202:203] op_sel_hi:[1,0,1]
	v_pk_fma_f32 v[60:61], v[60:61], s[2:3], v[28:29] op_sel_hi:[1,0,1]
	v_pk_mul_f32 v[196:197], v[44:45], v[44:45]
	v_pk_mul_f32 v[28:29], v[60:61], v[60:61]
	v_pk_mov_b32 v[196:197], v[202:203], v[196:197] op_sel:[1,0]
	v_pk_mov_b32 v[28:29], v[204:205], v[28:29] op_sel:[1,0]
	v_add_f32_e32 v12, 0, v13
	v_pk_add_f32 v[28:29], v[196:197], v[28:29]
	v_pk_add_f32 v[196:197], v[44:45], v[60:61]
	v_pk_mul_f32 v[202:203], v[44:45], v[60:61]
	v_fmac_f32_e32 v12, 0x3fd744fd, v199
	v_mov_b32_e32 v197, v203
	v_pk_add_f32 v[28:29], v[196:197], v[28:29]
	v_mul_f32_e32 v13, v12, v12
	v_pk_add_f32 v[28:29], v[28:29], v[12:13]
	s_nop 1
	v_mov_b32_dpp v196, v28 quad_perm:[1,0,3,2] row_mask:0xf bank_mask:0xf bound_ctrl:1
	v_mov_b32_dpp v197, v29 quad_perm:[1,0,3,2] row_mask:0xf bank_mask:0xf bound_ctrl:1
	v_pk_add_f32 v[28:29], v[28:29], v[196:197]
	s_nop 1
	v_mov_b32_dpp v196, v28 quad_perm:[2,3,0,1] row_mask:0xf bank_mask:0xf bound_ctrl:1
	v_mov_b32_dpp v197, v29 quad_perm:[2,3,0,1] row_mask:0xf bank_mask:0xf bound_ctrl:1
	v_pk_add_f32 v[28:29], v[28:29], v[196:197]
	s_nop 1
	v_mov_b32_dpp v196, v28 row_half_mirror row_mask:0xf bank_mask:0xf bound_ctrl:1
	v_mov_b32_dpp v197, v29 row_half_mirror row_mask:0xf bank_mask:0xf bound_ctrl:1
	v_pk_add_f32 v[28:29], v[28:29], v[196:197]
	s_nop 1
	v_mov_b32_dpp v196, v28 row_mirror row_mask:0xf bank_mask:0xf bound_ctrl:1
	v_mov_b32_dpp v197, v29 row_mirror row_mask:0xf bank_mask:0xf bound_ctrl:1
	s_and_saveexec_b64 s[6:7], vcc
	v_pk_add_f32 v[28:29], v[28:29], v[196:197]
	ds_write_b64 v179, v[28:29] offset:408
	s_or_b64 exec, exec, s[6:7]
	ds_read2_b32 v[196:197], v77 offset1:32
	ds_read2_b32 v[202:203], v77 offset0:64 offset1:96
	v_mov_b32_e32 v198, v62
	v_mov_b32_e32 v199, v30
	v_pk_add_f32 v[204:205], v[198:199], 0 op_sel_hi:[1,0]
	v_mov_b32_e32 v198, v46
	v_pk_add_f32 v[198:199], v[198:199], 0 op_sel_hi:[1,0]
	s_waitcnt lgkmcnt(1)
	v_mov_b32_e32 v206, v196
	s_waitcnt lgkmcnt(0)
	v_mov_b32_e32 v207, v202
	s_mov_b32 s2, s67
	v_mov_b32_e32 v212, v197
	v_mov_b32_e32 v213, v202
	v_pk_fma_f32 v[196:197], v[206:207], s[2:3], v[204:205] op_sel_hi:[1,0,1]
	v_pk_fma_f32 v[198:199], v[212:213], s[2:3], v[198:199] op_sel_hi:[1,0,1]
	v_pk_mul_f32 v[208:209], v[206:207], s[2:3] op_sel_hi:[1,0]
	v_pk_mul_f32 v[206:207], v[196:197], v[196:197]
	v_pk_mul_f32 v[212:213], v[198:199], v[198:199]
	v_pk_mov_b32 v[204:205], v[204:205], v[206:207] op_sel:[1,0]
	v_pk_mov_b32 v[206:207], v[208:209], v[212:213] op_sel:[1,0]
	v_add_f32_e32 v28, 0, v14
	v_pk_add_f32 v[204:205], v[204:205], v[206:207]
	v_pk_add_f32 v[206:207], v[196:197], v[198:199]
	v_pk_mul_f32 v[208:209], v[196:197], v[198:199]
	v_fmac_f32_e32 v28, 0x3fd744fd, v203
	v_mov_b32_e32 v207, v209
	v_pk_add_f32 v[204:205], v[206:207], v[204:205]
	v_mul_f32_e32 v29, v28, v28
	v_pk_add_f32 v[202:203], v[204:205], v[28:29]
	s_nop 1
	v_mov_b32_dpp v204, v202 quad_perm:[1,0,3,2] row_mask:0xf bank_mask:0xf bound_ctrl:1
	v_mov_b32_dpp v205, v203 quad_perm:[1,0,3,2] row_mask:0xf bank_mask:0xf bound_ctrl:1
	v_pk_add_f32 v[202:203], v[202:203], v[204:205]
	s_nop 1
	v_mov_b32_dpp v204, v202 quad_perm:[2,3,0,1] row_mask:0xf bank_mask:0xf bound_ctrl:1
	v_mov_b32_dpp v205, v203 quad_perm:[2,3,0,1] row_mask:0xf bank_mask:0xf bound_ctrl:1
	v_pk_add_f32 v[202:203], v[202:203], v[204:205]
	s_nop 1
	v_mov_b32_dpp v204, v202 row_half_mirror row_mask:0xf bank_mask:0xf bound_ctrl:1
	v_mov_b32_dpp v205, v203 row_half_mirror row_mask:0xf bank_mask:0xf bound_ctrl:1
	v_pk_add_f32 v[202:203], v[202:203], v[204:205]
	s_nop 1
	v_mov_b32_dpp v204, v202 row_mirror row_mask:0xf bank_mask:0xf bound_ctrl:1
	v_mov_b32_dpp v205, v203 row_mirror row_mask:0xf bank_mask:0xf bound_ctrl:1
	s_and_saveexec_b64 s[6:7], vcc
	v_pk_add_f32 v[202:203], v[202:203], v[204:205]
	ds_write_b64 v179, v[202:203] offset:448
	s_or_b64 exec, exec, s[6:7]
	ds_read2_b32 v[202:203], v91 offset1:32
	ds_read2_b32 v[204:205], v91 offset0:64 offset1:96
	v_mov_b32_e32 v30, v63
	v_pk_add_f32 v[206:207], v[30:31], 0 op_sel_hi:[1,0]
	v_mov_b32_e32 v30, v47
	v_pk_add_f32 v[30:31], v[30:31], 0 op_sel_hi:[1,0]
	s_waitcnt lgkmcnt(1)
	v_mov_b32_e32 v46, v202
	s_waitcnt lgkmcnt(0)
	v_mov_b32_e32 v47, v204
	s_mov_b32 s2, s67
	v_mov_b32_e32 v62, v203
	v_mov_b32_e32 v63, v204
	v_pk_mul_f32 v[208:209], v[46:47], s[2:3] op_sel_hi:[1,0]
	v_pk_fma_f32 v[46:47], v[46:47], s[2:3], v[206:207] op_sel_hi:[1,0,1]
	v_pk_fma_f32 v[62:63], v[62:63], s[2:3], v[30:31] op_sel_hi:[1,0,1]
	v_pk_mul_f32 v[202:203], v[46:47], v[46:47]
	v_pk_mul_f32 v[30:31], v[62:63], v[62:63]
	v_pk_mov_b32 v[202:203], v[206:207], v[202:203] op_sel:[1,0]
	v_pk_mov_b32 v[30:31], v[208:209], v[30:31] op_sel:[1,0]
	v_add_f32_e32 v14, 0, v15
	v_pk_add_f32 v[30:31], v[202:203], v[30:31]
	v_pk_add_f32 v[202:203], v[46:47], v[62:63]
	v_pk_mul_f32 v[206:207], v[46:47], v[62:63]
	v_fmac_f32_e32 v14, 0x3fd744fd, v205
	v_mov_b32_e32 v203, v207
	v_pk_add_f32 v[30:31], v[202:203], v[30:31]
	v_mul_f32_e32 v15, v14, v14
	v_pk_add_f32 v[30:31], v[30:31], v[14:15]
	s_nop 1
	v_mov_b32_dpp v202, v30 quad_perm:[1,0,3,2] row_mask:0xf bank_mask:0xf bound_ctrl:1
	v_mov_b32_dpp v203, v31 quad_perm:[1,0,3,2] row_mask:0xf bank_mask:0xf bound_ctrl:1
	v_pk_add_f32 v[30:31], v[30:31], v[202:203]
	s_nop 1
	v_mov_b32_dpp v202, v30 quad_perm:[2,3,0,1] row_mask:0xf bank_mask:0xf bound_ctrl:1
	v_mov_b32_dpp v203, v31 quad_perm:[2,3,0,1] row_mask:0xf bank_mask:0xf bound_ctrl:1
	v_pk_add_f32 v[30:31], v[30:31], v[202:203]
	s_nop 1
	v_mov_b32_dpp v202, v30 row_half_mirror row_mask:0xf bank_mask:0xf bound_ctrl:1
	v_mov_b32_dpp v203, v31 row_half_mirror row_mask:0xf bank_mask:0xf bound_ctrl:1
	v_pk_add_f32 v[30:31], v[30:31], v[202:203]
	s_nop 1
	v_mov_b32_dpp v202, v30 row_mirror row_mask:0xf bank_mask:0xf bound_ctrl:1
	v_mov_b32_dpp v203, v31 row_mirror row_mask:0xf bank_mask:0xf bound_ctrl:1
	s_and_saveexec_b64 s[6:7], vcc
	v_pk_add_f32 v[30:31], v[30:31], v[202:203]
	ds_write_b64 v179, v[30:31] offset:456
	s_or_b64 exec, exec, s[6:7]
	ds_read2_b32 v[202:203], v79 offset1:32
	ds_read2_b32 v[206:207], v79 offset0:64 offset1:96
	v_mov_b32_e32 v204, v64
	v_mov_b32_e32 v205, v32
	v_pk_add_f32 v[208:209], v[204:205], 0 op_sel_hi:[1,0]
	v_mov_b32_e32 v204, v48
	v_pk_add_f32 v[204:205], v[204:205], 0 op_sel_hi:[1,0]
	s_waitcnt lgkmcnt(1)
; DI void ag_st64(u64_t* p, u64_t v) { __hip_atomic_store(p, v, __ATOMIC_RELAXED, __HIP_MEMORY_SCOPE_AGENT); }
;   DI void operator()(f32x16 (&acc)[2][4], int grow0, int gcol0, int lane, int w, char* lds) {
;     ...
; #pragma unroll
;           for (int nt = 0; nt < 4; ++nt) {
;             float v = (acc[mt][nt][i] + bia[nt]) * csc[nt];
;             float z = ALPHA * xr[nt * 32] + hs * v;
;             acc[mt][nt][i] = z; s1 += z; s2 += z * z;
;           }
;           s1 = row16_sum(s1); s2 = row16_sum(s2);
;           if ((lane & 15) == 0) { f32x2 sv = {s1, s2}; *(f32x2*)(redw + (mt * 32 + (i & 3) + 8 * (i >> 2)) * 2) = sv; }
;         }
;     }
;     __syncthreads();
;     u64_t* myslots = xstat + ((size_t)pm * 256) * 4;
;     if (tid < 256) {
;       float s1 = (red[tid * 2] + red[(256 + tid) * 2]) + (red[(512 + tid) * 2] + red[(768 + tid) * 2]);
;       float s2 = (red[tid * 2 + 1] + red[(256 + tid) * 2 + 1]) + (red[(512 + tid) * 2 + 1] + red[(768 + tid) * 2 + 1]);
;       ag_st64(myslots + tid * 4 + pn, ((u64_t)__float_as_uint(s2) << 32) | (u64_t)__float_as_uint(s1));
	v_mov_b32_e32 v212, v202
	s_waitcnt lgkmcnt(0)
	v_mov_b32_e32 v213, v206
	s_mov_b32 s2, s67
	v_mov_b32_e32 v226, v203
	v_mov_b32_e32 v227, v206
	v_pk_fma_f32 v[202:203], v[212:213], s[2:3], v[208:209] op_sel_hi:[1,0,1]
	v_pk_fma_f32 v[204:205], v[226:227], s[2:3], v[204:205] op_sel_hi:[1,0,1]
	v_pk_mul_f32 v[214:215], v[212:213], s[2:3] op_sel_hi:[1,0]
	v_pk_mul_f32 v[212:213], v[202:203], v[202:203]
	v_pk_mul_f32 v[226:227], v[204:205], v[204:205]
	v_pk_mov_b32 v[208:209], v[208:209], v[212:213] op_sel:[1,0]
	v_pk_mov_b32 v[212:213], v[214:215], v[226:227] op_sel:[1,0]
	v_add_f32_e32 v30, 0, v16
	v_pk_add_f32 v[208:209], v[208:209], v[212:213]
	v_pk_add_f32 v[212:213], v[202:203], v[204:205]
	v_pk_mul_f32 v[214:215], v[202:203], v[204:205]
	v_fmac_f32_e32 v30, 0x3fd744fd, v207
	v_mov_b32_e32 v213, v215
	v_pk_add_f32 v[208:209], v[212:213], v[208:209]
	v_mul_f32_e32 v31, v30, v30
	v_pk_add_f32 v[206:207], v[208:209], v[30:31]
	s_nop 1
	v_mov_b32_dpp v208, v206 quad_perm:[1,0,3,2] row_mask:0xf bank_mask:0xf bound_ctrl:1
	v_mov_b32_dpp v209, v207 quad_perm:[1,0,3,2] row_mask:0xf bank_mask:0xf bound_ctrl:1
	v_pk_add_f32 v[206:207], v[206:207], v[208:209]
	s_nop 1
	v_mov_b32_dpp v208, v206 quad_perm:[2,3,0,1] row_mask:0xf bank_mask:0xf bound_ctrl:1
	v_mov_b32_dpp v209, v207 quad_perm:[2,3,0,1] row_mask:0xf bank_mask:0xf bound_ctrl:1
	v_pk_add_f32 v[206:207], v[206:207], v[208:209]
	s_nop 1
	v_mov_b32_dpp v208, v206 row_half_mirror row_mask:0xf bank_mask:0xf bound_ctrl:1
	v_mov_b32_dpp v209, v207 row_half_mirror row_mask:0xf bank_mask:0xf bound_ctrl:1
	v_pk_add_f32 v[206:207], v[206:207], v[208:209]
	s_nop 1
	v_mov_b32_dpp v208, v206 row_mirror row_mask:0xf bank_mask:0xf bound_ctrl:1
	v_mov_b32_dpp v209, v207 row_mirror row_mask:0xf bank_mask:0xf bound_ctrl:1
	s_and_saveexec_b64 s[6:7], vcc
	v_pk_add_f32 v[206:207], v[206:207], v[208:209]
	ds_write_b64 v179, v[206:207] offset:464
	s_or_b64 exec, exec, s[6:7]
	ds_read2_b32 v[206:207], v93 offset1:32
	ds_read2_b32 v[208:209], v93 offset0:64 offset1:96
	v_mov_b32_e32 v32, v65
	v_pk_add_f32 v[64:65], v[32:33], 0 op_sel_hi:[1,0]
	v_mov_b32_e32 v32, v49
	v_pk_add_f32 v[48:49], v[32:33], 0 op_sel_hi:[1,0]
	s_waitcnt lgkmcnt(1)
	v_mov_b32_e32 v32, v206
	s_waitcnt lgkmcnt(0)
	v_mov_b32_e32 v33, v208
	s_mov_b32 s2, s67
	v_mov_b32_e32 v206, v207
	v_mov_b32_e32 v207, v208
	v_pk_mul_f32 v[212:213], v[32:33], s[2:3] op_sel_hi:[1,0]
	v_pk_fma_f32 v[32:33], v[32:33], s[2:3], v[64:65] op_sel_hi:[1,0,1]
	v_pk_fma_f32 v[48:49], v[206:207], s[2:3], v[48:49] op_sel_hi:[1,0,1]
	v_pk_mul_f32 v[214:215], v[32:33], v[32:33]
	v_pk_mul_f32 v[206:207], v[48:49], v[48:49]
	v_pk_mov_b32 v[64:65], v[64:65], v[214:215] op_sel:[1,0]
	v_pk_mov_b32 v[206:207], v[212:213], v[206:207] op_sel:[1,0]
	v_add_f32_e32 v16, 0, v17
	v_pk_add_f32 v[64:65], v[64:65], v[206:207]
	v_pk_add_f32 v[206:207], v[32:33], v[48:49]
	v_pk_mul_f32 v[212:213], v[32:33], v[48:49]
	v_fmac_f32_e32 v16, 0x3fd744fd, v209
	v_mov_b32_e32 v207, v213
	v_pk_add_f32 v[64:65], v[206:207], v[64:65]
	v_mul_f32_e32 v17, v16, v16
	v_pk_add_f32 v[64:65], v[64:65], v[16:17]
	s_nop 1
	v_mov_b32_dpp v206, v64 quad_perm:[1,0,3,2] row_mask:0xf bank_mask:0xf bound_ctrl:1
	v_mov_b32_dpp v207, v65 quad_perm:[1,0,3,2] row_mask:0xf bank_mask:0xf bound_ctrl:1
	v_pk_add_f32 v[64:65], v[64:65], v[206:207]
	s_nop 1
	v_mov_b32_dpp v206, v64 quad_perm:[2,3,0,1] row_mask:0xf bank_mask:0xf bound_ctrl:1
	v_mov_b32_dpp v207, v65 quad_perm:[2,3,0,1] row_mask:0xf bank_mask:0xf bound_ctrl:1
	v_pk_add_f32 v[64:65], v[64:65], v[206:207]
	s_nop 1
	v_mov_b32_dpp v206, v64 row_half_mirror row_mask:0xf bank_mask:0xf bound_ctrl:1
	v_mov_b32_dpp v207, v65 row_half_mirror row_mask:0xf bank_mask:0xf bound_ctrl:1
	v_pk_add_f32 v[64:65], v[64:65], v[206:207]
	s_nop 1
	v_mov_b32_dpp v206, v64 row_mirror row_mask:0xf bank_mask:0xf bound_ctrl:1
	v_mov_b32_dpp v207, v65 row_mirror row_mask:0xf bank_mask:0xf bound_ctrl:1
	s_and_saveexec_b64 s[6:7], vcc
	v_pk_add_f32 v[64:65], v[64:65], v[206:207]
	ds_write_b64 v179, v[64:65] offset:472
	s_or_b64 exec, exec, s[6:7]
	v_ashrrev_i32_e32 v206, 8, v163
	v_ashrrev_i32_e32 v207, 31, v206
	v_lshlrev_b64 v[64:65], 13, v[206:207]
	v_lshl_add_u64 v[64:65], s[8:9], 0, v[64:65]
	v_cmp_gt_i32_e64 s[40:41], s60, v164
	v_ashrrev_i32_e32 v201, 31, v200
	s_waitcnt lgkmcnt(0)
	s_barrier
	s_and_saveexec_b64 s[6:7], s[40:41]
	s_cbranch_execz .LBB0_599
	v_lshl_add_u32 v0, v164, 3, v221
	ds_read2st64_b64 v[212:215], v0 offset1:4
	ds_read2st64_b64 v[226:229], v0 offset0:8 offset1:12
	v_ashrrev_i32_e32 v208, 8, v182
	v_ashrrev_i32_e32 v209, 31, v208
	s_waitcnt lgkmcnt(1)
	v_mov_b32_e32 v230, v212
	s_waitcnt lgkmcnt(0)
	v_mov_b32_e32 v231, v226
	v_mov_b32_e32 v232, v214
	v_mov_b32_e32 v233, v228
	v_mov_b32_e32 v226, v213
	v_mov_b32_e32 v228, v215
	v_pk_add_f32 v[230:231], v[230:231], v[232:233]
	v_pk_add_f32 v[212:213], v[226:227], v[228:229]
	v_pk_add_f32 v[230:231], v[230:231], v[230:231] op_sel:[0,1] op_sel_hi:[1,0]
	v_pk_add_f32 v[212:213], v[212:213], v[212:213] op_sel:[0,1] op_sel_hi:[1,0]
	v_lshl_add_u64 v[214:215], v[200:201], 3, v[64:65]
	v_lshl_add_u64 v[208:209], v[208:209], 3, v[214:215]
	v_mov_b32_e32 v231, v212
	global_store_dwordx2 v[208:209], v[230:231], off sc1

; DI f32x16 mfma(bf16x8 a, bf16x8 b, f32x16 c) { return __builtin_amdgcn_mfma_f32_32x32x16_bf16(a, b, c, 0, 0, 0); }
; template <int BK> DI int swz(int row) { constexpr int CPR = BK / 8; return (row / (16 / CPR)) % CPR; }
; DI void wait_vm0() { asm volatile("s_waitcnt vmcnt(0)" ::: "memory"); }
;   DI void pre(int grow0, int gcol0, int lane, int w, char* lds) { xpass(0, grow0, gcol0, lane, w, lds); }
;     ...
;   for (int kt = 0; kt < nk; ++kt) {
;     char* cur = lds + (kt & 1) * STG; char* nxt = lds + ((kt + 1) & 1) * STG;
;     const bool more = kt + 1 < nk;
;     const bf16_t* An = Ag + (kt + 1) * BK; const bf16_t* Bn = Bg + (kt + 1) * BK;
;     if (!more) epi.pre(row0 + wm * 64, col0 + wn * (32 * NTW), lane, w, lds);
;     bf16x8 fa[2][2], fb[2][NTW];
; #pragma unroll
;     for (int mt = 0; mt < 2; ++mt) { int row = wm * 64 + mt * 32 + l31; fa[0][mt] = *(const bf16x8*)(cur + row * (BK * 2) + ((hh ^ swz<BK>(row)) << 4)); }
; #pragma unroll
;     for (int nt = 0; nt < NTW; ++nt) { int row = wn * (32 * NTW) + nt * 32 + l31; fb[0][nt] = *(const bf16x8*)(cur + ABYTES + row * (BK * 2) + ((hh ^ swz<BK>(row)) << 4)); }
; #pragma unroll
;     for (int kk = 0; kk < NKK; ++kk) {
;       if (kk + 1 < NKK) {
;         const int ch = (kk + 1) * 2 + hh;
; #pragma unroll
;         for (int mt = 0; mt < 2; ++mt) { int row = wm * 64 + mt * 32 + l31; fa[(kk + 1) & 1][mt] = *(const bf16x8*)(cur + row * (BK * 2) + ((ch ^ swz<BK>(row)) << 4)); }
; #pragma unroll
;         for (int nt = 0; nt < NTW; ++nt) { int row = wn * (32 * NTW) + nt * 32 + l31; fb[(kk + 1) & 1][nt] = *(const bf16x8*)(cur + ABYTES + row * (BK * 2) + ((ch ^ swz<BK>(row)) << 4)); }
;       }
;       if (more) {
; #pragma unroll
;         for (int q = 0; q < PPK; ++q) {
;           const int pi = kk * PPK + q;
;           if (pi < NPA) stage_piece<BM, BK>(An, lda, nxt, tid, pi, wv);
;           else if (pi < NP) stage_piece<BN, BK>(Bn, ldb, nxt + ABYTES, tid, pi - NPA, wv);
;         }
;       }
;       __builtin_amdgcn_s_setprio(1);
; #pragma unroll
;       for (int mt = 0; mt < 2; ++mt)
; #pragma unroll
;         for (int nt = 0; nt < NTW; ++nt) acc[mt][nt] = mfma(fa[kk & 1][mt], fb[kk & 1][nt], acc[mt][nt]);
;       __builtin_amdgcn_s_setprio(0);
;       __builtin_amdgcn_sched_barrier(0);
;     }
;     wait_vm0();
;     __syncthreads();
.LBB0_627:
	s_and_b32 s42, s35, 0x10000
	s_xor_b32 s100, s42, 0x10000
	v_add3_u32 v190, s100, v136, v161
	v_add3_u32 v194, s100, v142, v163
	ds_read_b128 v[190:193], v190
	v_add3_u32 v198, s100, v143, v159
	ds_read_b128 v[194:197], v194
	v_add3_u32 v202, s100, v152, v160
	ds_read_b128 v[198:201], v198 offset:32768
	v_add3_u32 v206, s100, v153, v157
	ds_read_b128 v[202:205], v202 offset:32768
	v_add3_u32 v210, s100, v156, v158
	ds_read_b128 v[206:209], v206 offset:32768
	ds_read_b128 v[210:213], v210 offset:32768
	s_waitcnt lgkmcnt(6)
	s_mov_b32 m0, s41
	v_lshl_add_u64 v[228:229], v[214:215], 0, s[28:29]
	v_mfma_f32_32x32x16_bf16 v[114:129], v[166:169], v[174:177], v[114:129]
	global_load_lds_dwordx4 v[228:229], off
	s_add_i32 m0, s41, 0x2000
	v_lshl_add_u64 v[228:229], v[214:215], 0, s[24:25]
	v_mfma_f32_32x32x16_bf16 v[98:113], v[166:169], v[178:181], v[98:113]
	v_mfma_f32_32x32x16_bf16 v[82:97], v[166:169], v[182:185], v[82:97]
	global_load_lds_dwordx4 v[228:229], off
	s_add_i32 m0, s41, 0x4000
	v_lshl_add_u64 v[228:229], v[214:215], 0, s[26:27]
	v_mfma_f32_32x32x16_bf16 v[66:81], v[166:169], v[186:189], v[66:81]
	v_mfma_f32_32x32x16_bf16 v[50:65], v[170:173], v[174:177], v[50:65]
	global_load_lds_dwordx4 v[228:229], off
	s_add_i32 m0, s41, 0x6000
	v_lshl_add_u64 v[228:229], v[214:215], 0, s[38:39]
	v_mfma_f32_32x32x16_bf16 v[34:49], v[170:173], v[178:181], v[34:49]
	v_mfma_f32_32x32x16_bf16 v[18:33], v[170:173], v[182:185], v[18:33]
	global_load_lds_dwordx4 v[228:229], off
	v_mfma_f32_32x32x16_bf16 v[2:17], v[170:173], v[186:189], v[2:17]
	v_add3_u32 v166, s100, v136, v149
	v_add3_u32 v170, s100, v142, v150
	ds_read_b128 v[166:169], v166
	v_add3_u32 v174, s100, v143, v147
	ds_read_b128 v[170:173], v170
	v_add3_u32 v178, s100, v152, v148
	ds_read_b128 v[174:177], v174 offset:32768
	v_add3_u32 v182, s100, v153, v145
	ds_read_b128 v[178:181], v178 offset:32768
	v_add3_u32 v186, s100, v156, v146
	ds_read_b128 v[182:185], v182 offset:32768
	ds_read_b128 v[186:189], v186 offset:32768
	s_waitcnt lgkmcnt(6)
	v_mfma_f32_32x32x16_bf16 v[114:129], v[190:193], v[198:201], v[114:129]
	v_mfma_f32_32x32x16_bf16 v[98:113], v[190:193], v[202:205], v[98:113]
	v_mfma_f32_32x32x16_bf16 v[82:97], v[190:193], v[206:209], v[82:97]
	v_mfma_f32_32x32x16_bf16 v[66:81], v[190:193], v[210:213], v[66:81]
	v_mfma_f32_32x32x16_bf16 v[50:65], v[194:197], v[198:201], v[50:65]
	v_mfma_f32_32x32x16_bf16 v[34:49], v[194:197], v[202:205], v[34:49]
	v_mfma_f32_32x32x16_bf16 v[18:33], v[194:197], v[206:209], v[18:33]
	v_mfma_f32_32x32x16_bf16 v[2:17], v[194:197], v[210:213], v[2:17]
	v_add3_u32 v190, s100, v136, v139
	v_add3_u32 v194, s100, v142, v140
	ds_read_b128 v[190:193], v190
	v_add3_u32 v198, s100, v143, v137
	ds_read_b128 v[194:197], v194
	v_add3_u32 v202, s100, v152, v138
	ds_read_b128 v[198:201], v198 offset:32768
	v_add3_u32 v206, s100, v153, v134
	ds_read_b128 v[202:205], v202 offset:32768
	v_add3_u32 v210, s100, v156, v135
	ds_read_b128 v[206:209], v206 offset:32768
	ds_read_b128 v[210:213], v210 offset:32768
	s_waitcnt lgkmcnt(6)
	v_mfma_f32_32x32x16_bf16 v[114:129], v[166:169], v[174:177], v[114:129]
	v_mfma_f32_32x32x16_bf16 v[98:113], v[166:169], v[178:181], v[98:113]
	v_mfma_f32_32x32x16_bf16 v[82:97], v[166:169], v[182:185], v[82:97]
	v_mfma_f32_32x32x16_bf16 v[66:81], v[166:169], v[186:189], v[66:81]
	v_mfma_f32_32x32x16_bf16 v[50:65], v[170:173], v[174:177], v[50:65]
	v_mfma_f32_32x32x16_bf16 v[34:49], v[170:173], v[178:181], v[34:49]
	v_mfma_f32_32x32x16_bf16 v[18:33], v[170:173], v[182:185], v[18:33]
	v_mfma_f32_32x32x16_bf16 v[2:17], v[170:173], v[186:189], v[2:17]
	s_add_u32 s30, s30, 0x80
	s_addc_u32 s31, s31, 0
	s_add_i32 s35, s35, 0x10000
	s_waitcnt vmcnt(0) lgkmcnt(0)
	s_barrier
	s_cmpk_lg_i32 s30, 0x780
	s_cbranch_scc0 .Lk627_exit
	s_add_i32 s41, s100, s34
	v_lshl_add_u64 v[214:215], v[130:131], 0, s[30:31]
	v_lshl_add_u64 v[226:227], v[132:133], 0, s[30:31]
	s_add_i32 m0, s41, 0x8000
	v_lshl_add_u64 v[228:229], v[226:227], 0, s[28:29]
	v_mfma_f32_32x32x16_bf16 v[114:129], v[190:193], v[198:201], v[114:129]
	global_load_lds_dwordx4 v[228:229], off
	v_add3_u32 v166, s42, v136, v141
	v_add3_u32 v170, s42, v142, v144
	ds_read_b128 v[166:169], v166
	v_add3_u32 v174, s42, v143, v151
	ds_read_b128 v[170:173], v170
	v_add3_u32 v178, s42, v152, v154
	ds_read_b128 v[174:177], v174 offset:32768
	v_add3_u32 v182, s42, v153, v155
	ds_read_b128 v[178:181], v178 offset:32768
	v_add3_u32 v186, s42, v156, v164
	ds_read_b128 v[182:185], v182 offset:32768
	ds_read_b128 v[186:189], v186 offset:32768
	s_add_i32 m0, s41, 0xa000
	v_lshl_add_u64 v[228:229], v[226:227], 0, s[24:25]
	v_mfma_f32_32x32x16_bf16 v[98:113], v[190:193], v[202:205], v[98:113]
	v_mfma_f32_32x32x16_bf16 v[82:97], v[190:193], v[206:209], v[82:97]
	global_load_lds_dwordx4 v[228:229], off
	s_add_i32 m0, s41, 0xc000
	v_lshl_add_u64 v[228:229], v[226:227], 0, s[26:27]
	v_mfma_f32_32x32x16_bf16 v[66:81], v[190:193], v[210:213], v[66:81]
	v_mfma_f32_32x32x16_bf16 v[50:65], v[194:197], v[198:201], v[50:65]
	global_load_lds_dwordx4 v[228:229], off
	s_add_i32 m0, s41, 0xe000
	v_lshl_add_u64 v[228:229], v[226:227], 0, s[38:39]
	v_mfma_f32_32x32x16_bf16 v[34:49], v[194:197], v[202:205], v[34:49]
	v_mfma_f32_32x32x16_bf16 v[18:33], v[194:197], v[206:209], v[18:33]
	global_load_lds_dwordx4 v[228:229], off
	v_mfma_f32_32x32x16_bf16 v[2:17], v[194:197], v[210:213], v[2:17]
	s_branch .LBB0_627
; DI f32x16 mfma(bf16x8 a, bf16x8 b, f32x16 c) { return __builtin_amdgcn_mfma_f32_32x32x16_bf16(a, b, c, 0, 0, 0); }
; template <int BK> DI int swz(int row) { constexpr int CPR = BK / 8; return (row / (16 / CPR)) % CPR; }
; DI void wait_vm0() { asm volatile("s_waitcnt vmcnt(0)" ::: "memory"); }
;   DI void pre(int grow0, int gcol0, int lane, int w, char* lds) { xpass(0, grow0, gcol0, lane, w, lds); }
;     ...
;   for (int kt = 0; kt < nk; ++kt) {
;     char* cur = lds + (kt & 1) * STG; char* nxt = lds + ((kt + 1) & 1) * STG;
;     const bool more = kt + 1 < nk;
;     const bf16_t* An = Ag + (kt + 1) * BK; const bf16_t* Bn = Bg + (kt + 1) * BK;
;     if (!more) epi.pre(row0 + wm * 64, col0 + wn * (32 * NTW), lane, w, lds);
;     bf16x8 fa[2][2], fb[2][NTW];
; #pragma unroll
;     for (int mt = 0; mt < 2; ++mt) { int row = wm * 64 + mt * 32 + l31; fa[0][mt] = *(const bf16x8*)(cur + row * (BK * 2) + ((hh ^ swz<BK>(row)) << 4)); }
; #pragma unroll
;     for (int nt = 0; nt < NTW; ++nt) { int row = wn * (32 * NTW) + nt * 32 + l31; fb[0][nt] = *(const bf16x8*)(cur + ABYTES + row * (BK * 2) + ((hh ^ swz<BK>(row)) << 4)); }
; #pragma unroll
;     for (int kk = 0; kk < NKK; ++kk) {
;       if (kk + 1 < NKK) {
;         const int ch = (kk + 1) * 2 + hh;
; #pragma unroll
;         for (int mt = 0; mt < 2; ++mt) { int row = wm * 64 + mt * 32 + l31; fa[(kk + 1) & 1][mt] = *(const bf16x8*)(cur + row * (BK * 2) + ((ch ^ swz<BK>(row)) << 4)); }
; #pragma unroll
;         for (int nt = 0; nt < NTW; ++nt) { int row = wn * (32 * NTW) + nt * 32 + l31; fb[(kk + 1) & 1][nt] = *(const bf16x8*)(cur + ABYTES + row * (BK * 2) + ((ch ^ swz<BK>(row)) << 4)); }
;       }
;       if (more) {
; #pragma unroll
;         for (int q = 0; q < PPK; ++q) {
;           const int pi = kk * PPK + q;
;           if (pi < NPA) stage_piece<BM, BK>(An, lda, nxt, tid, pi, wv);
;           else if (pi < NP) stage_piece<BN, BK>(Bn, ldb, nxt + ABYTES, tid, pi - NPA, wv);
;         }
;       }
;       __builtin_amdgcn_s_setprio(1);
; #pragma unroll
;       for (int mt = 0; mt < 2; ++mt)
; #pragma unroll
;         for (int nt = 0; nt < NTW; ++nt) acc[mt][nt] = mfma(fa[kk & 1][mt], fb[kk & 1][nt], acc[mt][nt]);
;       __builtin_amdgcn_s_setprio(0);
;       __builtin_amdgcn_sched_barrier(0);
;     }
;     wait_vm0();
;     __syncthreads();
.Lk627_exit:
	v_add3_u32 v166, s42, v136, v141
	v_add3_u32 v170, s42, v142, v144
	ds_read_b128 v[166:169], v166
	v_add3_u32 v174, s42, v143, v151
	ds_read_b128 v[170:173], v170
	v_add3_u32 v178, s42, v152, v154
	ds_read_b128 v[174:177], v174 offset:32768
	v_add3_u32 v182, s42, v153, v155
	ds_read_b128 v[178:181], v178 offset:32768
	v_add3_u32 v186, s42, v156, v164
	ds_read_b128 v[182:185], v182 offset:32768
	ds_read_b128 v[186:189], v186 offset:32768
	v_mfma_f32_32x32x16_bf16 v[114:129], v[190:193], v[198:201], v[114:129]
	v_mfma_f32_32x32x16_bf16 v[98:113], v[190:193], v[202:205], v[98:113]
	v_mfma_f32_32x32x16_bf16 v[82:97], v[190:193], v[206:209], v[82:97]
	v_mfma_f32_32x32x16_bf16 v[66:81], v[190:193], v[210:213], v[66:81]
	v_mfma_f32_32x32x16_bf16 v[50:65], v[194:197], v[198:201], v[50:65]
	v_mfma_f32_32x32x16_bf16 v[34:49], v[194:197], v[202:205], v[34:49]
	v_mfma_f32_32x32x16_bf16 v[18:33], v[194:197], v[206:209], v[18:33]
	v_mfma_f32_32x32x16_bf16 v[2:17], v[194:197], v[210:213], v[2:17]
	s_waitcnt lgkmcnt(0)
	v_add_u32_e32 v0, 0x10000, v136
	v_add_u32_e32 v136, 0x10000, v142
	v_add_u32_e32 v130, v0, v141
	v_add_u32_e32 v141, v136, v144
	ds_read_b128 v[130:133], v130
	ds_read_b128 v[166:169], v141
	v_add_u32_e32 v141, 0x18000, v143
	v_add_u32_e32 v142, v141, v151
	v_add_u32_e32 v202, 0x18000, v152
	v_add_u32_e32 v203, 0x18000, v153
	v_add_u32_e32 v143, v202, v154
	ds_read_b128 v[170:173], v142
	ds_read_b128 v[174:177], v143
	v_add_u32_e32 v142, v203, v155
	v_add_u32_e32 v204, 0x18000, v156
	v_add_u32_e32 v143, v204, v164
	ds_read_b128 v[152:155], v142
	ds_read_b128 v[178:181], v143
	v_add_u32_e32 v142, v0, v161
	v_add_u32_e32 v143, v136, v163
	ds_read_b128 v[182:185], v142
	ds_read_b128 v[186:189], v143
	v_add_u32_e32 v142, v141, v159
	v_add_u32_e32 v143, v202, v160
	ds_read_b128 v[190:193], v142
	ds_read_b128 v[194:197], v143
	v_add_u32_e32 v142, v203, v157
	v_add_u32_e32 v143, v204, v158
	ds_read_b128 v[156:159], v142
	ds_read_b128 v[198:201], v143
	s_lshl_b64 s[30:31], s[6:7], 22
	s_setprio 1
	s_waitcnt lgkmcnt(9)
	v_mfma_f32_32x32x16_bf16 v[114:129], v[130:133], v[170:173], v[114:129]
	s_waitcnt lgkmcnt(8)
	v_mfma_f32_32x32x16_bf16 v[98:113], v[130:133], v[174:177], v[98:113]
	s_waitcnt lgkmcnt(7)
	v_mfma_f32_32x32x16_bf16 v[82:97], v[130:133], v[152:155], v[82:97]
	s_waitcnt lgkmcnt(6)
	v_mfma_f32_32x32x16_bf16 v[66:81], v[130:133], v[178:181], v[66:81]
	v_mfma_f32_32x32x16_bf16 v[50:65], v[166:169], v[170:173], v[50:65]
	v_mfma_f32_32x32x16_bf16 v[34:49], v[166:169], v[174:177], v[34:49]
	v_mfma_f32_32x32x16_bf16 v[18:33], v[166:169], v[152:155], v[18:33]
	v_mfma_f32_32x32x16_bf16 v[2:17], v[166:169], v[178:181], v[2:17]
	s_setprio 0
	v_add_u32_e32 v130, v0, v149
	v_add_u32_e32 v142, v136, v150
	ds_read_b128 v[130:133], v130
	ds_read_b128 v[150:153], v142
	v_add_u32_e32 v142, v141, v147
	v_add_u32_e32 v143, v202, v148
	ds_read_b128 v[166:169], v142
	ds_read_b128 v[170:173], v143
	v_add_u32_e32 v142, v203, v145
	v_add_u32_e32 v146, v204, v146
	ds_read_b128 v[142:145], v142
	ds_read_b128 v[146:149], v146
	s_setprio 1
	s_waitcnt lgkmcnt(9)
	v_mfma_f32_32x32x16_bf16 v[114:129], v[182:185], v[190:193], v[114:129]
	s_waitcnt lgkmcnt(8)
	v_mfma_f32_32x32x16_bf16 v[98:113], v[182:185], v[194:197], v[98:113]
	s_waitcnt lgkmcnt(7)
	v_mfma_f32_32x32x16_bf16 v[82:97], v[182:185], v[156:159], v[82:97]
	s_waitcnt lgkmcnt(6)
	v_mfma_f32_32x32x16_bf16 v[66:81], v[182:185], v[198:201], v[66:81]
	v_mfma_f32_32x32x16_bf16 v[50:65], v[186:189], v[190:193], v[50:65]
	v_mfma_f32_32x32x16_bf16 v[34:49], v[186:189], v[194:197], v[34:49]
	v_mfma_f32_32x32x16_bf16 v[18:33], v[186:189], v[156:159], v[18:33]
	v_mfma_f32_32x32x16_bf16 v[2:17], v[186:189], v[198:201], v[2:17]
	s_setprio 0
	v_add_u32_e32 v0, v0, v139
	v_add_u32_e32 v136, v136, v140
	ds_read_b128 v[154:157], v0
	ds_read_b128 v[158:161], v136
	v_add_u32_e32 v0, v141, v137
	v_add_u32_e32 v140, v202, v138
	ds_read_b128 v[136:139], v0
	ds_read_b128 v[174:177], v140
	v_add_u32_e32 v0, v203, v134
	v_add_u32_e32 v134, v204, v135
	ds_read_b128 v[178:181], v0
	ds_read_b128 v[182:185], v134
	s_setprio 1
	s_waitcnt lgkmcnt(9)
	v_mfma_f32_32x32x16_bf16 v[114:129], v[130:133], v[166:169], v[114:129]
	s_waitcnt lgkmcnt(8)
	v_mfma_f32_32x32x16_bf16 v[98:113], v[130:133], v[170:173], v[98:113]
	s_waitcnt lgkmcnt(7)
	v_mfma_f32_32x32x16_bf16 v[82:97], v[130:133], v[142:145], v[82:97]
	s_waitcnt lgkmcnt(6)
	v_mfma_f32_32x32x16_bf16 v[66:81], v[130:133], v[146:149], v[66:81]
	v_mfma_f32_32x32x16_bf16 v[50:65], v[150:153], v[166:169], v[50:65]
	v_mfma_f32_32x32x16_bf16 v[34:49], v[150:153], v[170:173], v[34:49]
	v_mfma_f32_32x32x16_bf16 v[18:33], v[150:153], v[142:145], v[18:33]
	v_mfma_f32_32x32x16_bf16 v[2:17], v[150:153], v[146:149], v[2:17]
	s_setprio 0
	s_setprio 1
	s_waitcnt lgkmcnt(3)
	v_mfma_f32_32x32x16_bf16 v[114:129], v[154:157], v[136:139], v[114:129]
	s_waitcnt lgkmcnt(2)
	v_mfma_f32_32x32x16_bf16 v[98:113], v[154:157], v[174:177], v[98:113]
	s_waitcnt lgkmcnt(1)
	v_mfma_f32_32x32x16_bf16 v[82:97], v[154:157], v[178:181], v[82:97]
	s_waitcnt lgkmcnt(0)
	v_mfma_f32_32x32x16_bf16 v[66:81], v[154:157], v[182:185], v[66:81]
	v_mfma_f32_32x32x16_bf16 v[50:65], v[158:161], v[136:139], v[50:65]
	v_mfma_f32_32x32x16_bf16 v[34:49], v[158:161], v[174:177], v[34:49]
	v_mfma_f32_32x32x16_bf16 v[18:33], v[158:161], v[178:181], v[18:33]
	v_mfma_f32_32x32x16_bf16 v[2:17], v[158:161], v[182:185], v[2:17]
	s_setprio 0
	v_mov_b32_e32 v135, v216
	s_waitcnt vmcnt(0)
	s_barrier
; DI int launder(int x) { asm volatile("" : "+v"(x)); return x; }
;     ...
;   { const int tid2 = launder(threadIdx.x); epi(acc, row0 + (((tid2 >> 6) % WM) * 64), col0 + (((tid2 >> 6) / WM) * (32 * NTW)), tid2 & 63, tid2 >> 6, lds); }
;   DI void operator()(f32x16 (&acc)[2][4], int grow0, int gcol0, int lane, int w, char* lds) {
;     const int l31 = lane & 31, hh = lane >> 5;
;     if (gcol0 < 1024) {
;     ...
;       const int cin = gcol0 - 1024, h = cin >> 8, b = grow0 >> 8, m0 = grow0 & 255;
	s_nop 0
	v_ashrrev_i32_e32 v134, 6, v135
	v_lshrrev_b32_e32 v0, 30, v134
	v_add_u32_e32 v0, v134, v0
	v_ashrrev_i32_e32 v130, 2, v0
	v_mul_i32_i24_e32 v0, 4, v130
	v_sub_u32_e32 v0, v134, v0
	v_lshlrev_b32_e32 v136, 6, v0
	v_lshl_add_u32 v132, v130, 7, s3
	v_add_u32_e32 v0, s2, v136
	v_and_b32_e32 v131, 31, v135
	v_bfe_u32 v133, v135, 5, 1
	v_cmp_lt_i32_e32 vcc, s57, v132
	s_and_saveexec_b64 s[2:3], vcc
	s_xor_b64 s[6:7], exec, s[2:3]
	s_cbranch_execz .LBB0_630
; DI unsigned pack2(float lo, float hi) { f32x2 v = {lo, hi}; bf2_t r = __builtin_convertvector(v, bf2_t); return __builtin_bit_cast(unsigned, r); }
; DI void tr_put(char* stg, int erow, const f32x16& v, int hh, float mul) {
; #pragma unroll
;   for (int qd = 0; qd < 4; ++qd) {
;     u32x2 pk; pk.x = pack2(v[4 * qd] * mul, v[4 * qd + 1] * mul); pk.y = pack2(v[4 * qd + 2] * mul, v[4 * qd + 3] * mul);
;     *(u32x2*)(stg + erow * 64 + (8 * qd + 4 * hh) * 2) = pk;
;   }
; }
; template <int R>
; DI void tr_flush(const char* stg, int row0, bf16_t* g, size_t grs, int lane) {
;   const int r0 = lane >> 2, ch = lane & 3;
; #pragma unroll
;   for (int it = 0; it < R / 16; ++it) {
;     const int r = it * 16 + r0;
;     u32x4 v = *(const u32x4*)(stg + (row0 + r) * 64 + ch * 16);
;     *(u32x4*)((char*)(g + (size_t)r * grs) + ch * 16) = v;
;   }
; }
;   DI void operator()(f32x16 (&acc)[2][4], int grow0, int gcol0, int lane, int w, char* lds) {
;     ...
;       const int cin = gcol0 - 1024, h = cin >> 8, b = grow0 >> 8, m0 = grow0 & 255;
;       char* stg = tr_stage(lds, w);
; #pragma unroll
;       for (int mt = 0; mt < 2; ++mt) {
; #pragma unroll
;         for (int nt = 0; nt < 4; ++nt) tr_put(stg, nt * 32 + l31, acc[mt][nt], hh, 1.f);
;         tr_flush<128>(stg, 0, Vxt + ((size_t)(b * 4 + h) * 256 + (cin & 255)) * 256 + m0 + mt * 32, 256, lane);
;       }
	v_add_u32_e32 v132, 0xfffffc00, v132
	v_lshl_add_u32 v134, v134, 13, v224
	v_lshlrev_b32_e32 v131, 6, v131
	v_lshlrev_b32_e32 v133, 3, v133
	v_ashrrev_i32_e32 v0, 6, v0
	v_lshrrev_b32_e32 v132, 8, v132
	v_or3_b32 v131, v134, v131, v133
	v_and_b32_e32 v0, -4, v0
	v_cvt_pk_bf16_f32 v66, v66, v67
	v_cvt_pk_bf16_f32 v67, v68, v69
	v_add_u32_e32 v132, v132, v0
	ds_write_b64 v131, v[66:67] offset:6144
	v_cvt_pk_bf16_f32 v66, v70, v71
	v_cvt_pk_bf16_f32 v67, v72, v73
	v_and_b32_e32 v135, 63, v135
	s_add_u32 s34, s74, s30
	v_ashrrev_i32_e32 v133, 31, v132
	v_cvt_pk_bf16_f32 v114, v114, v115
	v_cvt_pk_bf16_f32 v115, v116, v117
	ds_write_b64 v131, v[66:67] offset:6160
	v_cvt_pk_bf16_f32 v66, v74, v75
	v_cvt_pk_bf16_f32 v67, v76, v77
	s_addc_u32 s35, s75, s31
	v_lshlrev_b64 v[132:133], 17, v[132:133]
	v_lshlrev_b32_e32 v0, 4, v135
	ds_write_b64 v131, v[114:115]
	v_cvt_pk_bf16_f32 v114, v118, v119
	v_cvt_pk_bf16_f32 v115, v120, v121
	ds_write_b64 v131, v[66:67] offset:6176
	v_cvt_pk_bf16_f32 v66, v78, v79
	v_cvt_pk_bf16_f32 v67, v80, v81
	v_lshlrev_b32_e32 v68, 16, v130
	v_and_b32_e32 v136, 0xc0, v136
	v_lshrrev_b32_e32 v137, 2, v135
	v_and_b32_e32 v0, 48, v0
	ds_write_b64 v131, v[114:115] offset:16
	v_cvt_pk_bf16_f32 v114, v122, v123
	v_cvt_pk_bf16_f32 v115, v124, v125
	ds_write_b64 v131, v[66:67] offset:6192
	v_lshl_add_u64 v[66:67], s[34:35], 0, v[132:133]
	v_and_b32_e32 v68, 0x10000, v68
	v_mov_b32_e32 v69, v1
	v_or_b32_e32 v134, v134, v0
	v_or_b32_e32 v138, 16, v137
	ds_write_b64 v131, v[114:115] offset:32
	v_cvt_pk_bf16_f32 v114, v126, v127
	v_cvt_pk_bf16_f32 v115, v128, v129
	v_lshl_add_u64 v[66:67], v[66:67], 0, v[68:69]
	v_lshlrev_b32_e32 v68, 1, v136
	v_lshl_or_b32 v139, v138, 6, v134
	ds_write_b64 v131, v[114:115] offset:48
	v_lshl_add_u64 v[70:71], v[66:67], 0, v[68:69]
	v_cvt_pk_bf16_f32 v98, v98, v99
	v_cvt_pk_bf16_f32 v99, v100, v101
	v_lshl_add_u64 v[74:75], v[70:71], 0, v[0:1]
	ds_read_b128 v[70:73], v139
	ds_write_b64 v131, v[98:99] offset:2048
	v_cvt_pk_bf16_f32 v98, v102, v103
	v_cvt_pk_bf16_f32 v99, v104, v105
	ds_write_b64 v131, v[98:99] offset:2064
	v_cvt_pk_bf16_f32 v98, v106, v107
	v_cvt_pk_bf16_f32 v99, v108, v109
	v_lshlrev_b32_e32 v0, 9, v137
	v_or_b32_e32 v142, 48, v137
	ds_write_b64 v131, v[98:99] offset:2080
	v_cvt_pk_bf16_f32 v98, v110, v111
	v_cvt_pk_bf16_f32 v99, v112, v113
	v_lshl_add_u64 v[76:77], v[74:75], 0, v[0:1]
	v_lshlrev_b32_e32 v0, 9, v138
	v_lshl_or_b32 v143, v142, 6, v134
	ds_write_b64 v131, v[98:99] offset:2096
	v_lshl_add_u64 v[78:79], v[74:75], 0, v[0:1]
	v_cvt_pk_bf16_f32 v82, v82, v83
	v_cvt_pk_bf16_f32 v83, v84, v85
	s_waitcnt lgkmcnt(4)
	global_store_dwordx4 v[78:79], v[70:73], off
	ds_read_b128 v[70:73], v143
	v_or_b32_e32 v140, 32, v137
	ds_write_b64 v131, v[82:83] offset:4096
	v_cvt_pk_bf16_f32 v82, v86, v87
	v_cvt_pk_bf16_f32 v83, v88, v89
	ds_write_b64 v131, v[82:83] offset:4112
	v_cvt_pk_bf16_f32 v82, v90, v91
	v_cvt_pk_bf16_f32 v83, v92, v93
	v_lshlrev_b32_e32 v0, 9, v140
	v_or_b32_e32 v146, 0x50, v137
	ds_write_b64 v131, v[82:83] offset:4128
	v_cvt_pk_bf16_f32 v82, v94, v95
	v_cvt_pk_bf16_f32 v83, v96, v97
	v_lshl_add_u64 v[80:81], v[74:75], 0, v[0:1]
	v_lshlrev_b32_e32 v0, 9, v142
	v_lshl_or_b32 v135, v137, 6, v134
	v_lshl_or_b32 v147, v146, 6, v134
	ds_write_b64 v131, v[82:83] offset:4144
	v_lshl_add_u64 v[82:83], v[74:75], 0, v[0:1]
	ds_read_b128 v[66:69], v135
	s_waitcnt lgkmcnt(5)
	global_store_dwordx4 v[82:83], v[70:73], off
	ds_read_b128 v[70:73], v147
	v_or_b32_e32 v144, 64, v137
	v_lshlrev_b32_e32 v0, 9, v144
	v_or_b32_e32 v148, 0x60, v137
	v_or_b32_e32 v150, 0x70, v137
	v_lshl_add_u64 v[84:85], v[74:75], 0, v[0:1]
	v_lshlrev_b32_e32 v0, 9, v146
	v_lshl_or_b32 v141, v140, 6, v134
	v_lshl_or_b32 v145, v144, 6, v134
	v_lshl_or_b32 v149, v148, 6, v134
	v_lshl_or_b32 v134, v150, 6, v134
	v_lshl_add_u64 v[86:87], v[74:75], 0, v[0:1]
	s_waitcnt lgkmcnt(0)
	global_store_dwordx4 v[86:87], v[70:73], off
	ds_read_b128 v[70:73], v134
	global_store_dwordx4 v[76:77], v[66:69], off
	ds_read_b128 v[66:69], v141
	v_cvt_pk_bf16_f32 v50, v50, v51
	v_cvt_pk_bf16_f32 v51, v52, v53
	v_cvt_pk_bf16_f32 v34, v34, v35
	v_cvt_pk_bf16_f32 v35, v36, v37
	s_waitcnt lgkmcnt(0)
	global_store_dwordx4 v[80:81], v[66:69], off
	ds_read_b128 v[66:69], v145
	v_cvt_pk_bf16_f32 v18, v18, v19
	v_cvt_pk_bf16_f32 v19, v20, v21
	v_lshlrev_b32_e32 v0, 9, v148
	ds_write_b64 v131, v[50:51]
	s_waitcnt lgkmcnt(1)
	global_store_dwordx4 v[84:85], v[66:69], off
	ds_read_b128 v[66:69], v149
	v_cvt_pk_bf16_f32 v50, v54, v55
	v_cvt_pk_bf16_f32 v51, v56, v57
	ds_write_b64 v131, v[34:35] offset:2048
	v_cvt_pk_bf16_f32 v34, v38, v39
	v_cvt_pk_bf16_f32 v35, v40, v41
	ds_write_b64 v131, v[18:19] offset:4096
	v_cvt_pk_bf16_f32 v18, v22, v23
	v_cvt_pk_bf16_f32 v19, v24, v25
	v_cvt_pk_bf16_f32 v2, v2, v3
	v_cvt_pk_bf16_f32 v3, v4, v5
	v_lshl_add_u64 v[88:89], v[74:75], 0, v[0:1]
	v_lshlrev_b32_e32 v0, 9, v150
	ds_write_b64 v131, v[50:51] offset:16
	v_cvt_pk_bf16_f32 v50, v58, v59
	v_cvt_pk_bf16_f32 v51, v60, v61
	ds_write_b64 v131, v[34:35] offset:2064
	v_cvt_pk_bf16_f32 v34, v42, v43
	v_cvt_pk_bf16_f32 v35, v44, v45
	ds_write_b64 v131, v[18:19] offset:4112
	v_cvt_pk_bf16_f32 v18, v26, v27
	v_cvt_pk_bf16_f32 v19, v28, v29
	ds_write_b64 v131, v[2:3] offset:6144
	v_cvt_pk_bf16_f32 v2, v6, v7
	v_cvt_pk_bf16_f32 v3, v8, v9
	s_waitcnt lgkmcnt(6)
	global_store_dwordx4 v[88:89], v[66:69], off
	ds_write_b64 v131, v[50:51] offset:32
	v_cvt_pk_bf16_f32 v50, v62, v63
	v_lshl_add_u64 v[66:67], v[74:75], 0, v[0:1]
	v_cvt_pk_bf16_f32 v51, v64, v65
	ds_write_b64 v131, v[34:35] offset:2080
	v_cvt_pk_bf16_f32 v34, v46, v47
	v_cvt_pk_bf16_f32 v35, v48, v49
	ds_write_b64 v131, v[18:19] offset:4128
	v_cvt_pk_bf16_f32 v18, v30, v31
	v_cvt_pk_bf16_f32 v19, v32, v33
	ds_write_b64 v131, v[2:3] offset:6160
	v_cvt_pk_bf16_f32 v2, v10, v11
	v_cvt_pk_bf16_f32 v3, v12, v13
	global_store_dwordx4 v[66:67], v[70:73], off
	ds_write_b64 v131, v[50:51] offset:48
	ds_write_b64 v131, v[34:35] offset:2096
	ds_write_b64 v131, v[18:19] offset:4144
	ds_write_b64 v131, v[2:3] offset:6176
	ds_read_b128 v[2:5], v135
	ds_read_b128 v[6:9], v139
	ds_read_b128 v[10:13], v141
	v_cvt_pk_bf16_f32 v14, v14, v15
	v_cvt_pk_bf16_f32 v15, v16, v17
	ds_write_b64 v131, v[14:15] offset:6192
	s_waitcnt lgkmcnt(3)
	global_store_dwordx4 v[76:77], v[2:5], off offset:64
	s_waitcnt lgkmcnt(2)
	global_store_dwordx4 v[78:79], v[6:9], off offset:64
	s_waitcnt lgkmcnt(1)
	global_store_dwordx4 v[80:81], v[10:13], off offset:64
	ds_read_b128 v[2:5], v143
	ds_read_b128 v[6:9], v145
	ds_read_b128 v[10:13], v147
	ds_read_b128 v[14:17], v149
	ds_read_b128 v[18:21], v134
	s_waitcnt lgkmcnt(4)
	global_store_dwordx4 v[82:83], v[2:5], off offset:64
	s_waitcnt lgkmcnt(3)
	global_store_dwordx4 v[84:85], v[6:9], off offset:64
	s_waitcnt lgkmcnt(2)
	global_store_dwordx4 v[86:87], v[10:13], off offset:64
	s_waitcnt lgkmcnt(1)
	global_store_dwordx4 v[88:89], v[14:17], off offset:64
	s_waitcnt lgkmcnt(0)
	global_store_dwordx4 v[66:67], v[18:21], off offset:64
